# v059 + the trailing half's one-barrier offset (X in the prologue, R after each epilogue) is taken in front of the K-loop, behind the unit scheduler set-up, so the set-up no longer sits between the bar
# speedup vs baseline: 1.0048x; 1.0007x over previous
; #define PG8_STAGE(bufoff, gbase, voff) do { _Pragma("unroll") for (int _i = 0; _i < 2; ++_i) \
;         __builtin_amdgcn_global_load_lds((const unsigned*)((const char*)(gbase) + (voff)[_i]), (PG8_LAS unsigned*)(lds + (bufoff) + ldsw + _i * 8192), 16, 0, AUX_A); } while (0)
; #define PG8_WAIT_V(n) asm volatile("s_waitcnt vmcnt(" #n ")" ::: "memory")
; #define PG8_BAR __builtin_amdgcn_s_barrier()
; template <class Epi, class Sched, bool ALIGN_EPI = false, bool SP2 = false>
; __device__ __forceinline__ void gemm_phase(PG8_LAS unsigned char* lds, const Gemm g, const Sched& S, const Epi& E) {
;     int tid_l = threadIdx.x; asm volatile("" : "+v"(tid_l));
;     const int tid = tid_l, wid = __builtin_amdgcn_readfirstlane(tid >> 6), lane = tid & 63, wr = wid >> 2, wc = wid & 3, fr = lane & 15, fq = lane >> 4;
;     const int K = g.K;
;     unsigned voffA[2], voffB[2];
; #pragma unroll
;     for (int i = 0; i < 2; ++i) { int R, C; stage_rc(tid * 16 + i * 8192, R, C); const int Rb = Epi::PERM ? ((R & ~31) + perm32(R & 31)) : R;
;         voffA[i] = (unsigned)(R * K + C) * 2u; voffB[i] = (unsigned)(Rb * K + C) * 2u; }
;     const size_t kstep = (size_t)(BK * 2);
;     const size_t hstep = (size_t)HALF * K * 2;
;     const size_t tstep = 2 * hstep;
;     const unsigned ldsw = (unsigned)wid * 1024u;
;     const int aoff = lds_byte(wr * 64 + fr, fq * 8), boff = lds_byte(wc * 32 + fr, fq * 8);
;     ...
;     { const int rot0 = cur.krot, nt0 = cur.nkt; const char* sA0 = PG8_KP(cA, 0, rot0, nt0); const char* sA1 = PG8_KP(cA, 1, rot0, nt0); const char* sB0 = PG8_KP(cB, 0, rot0, nt0); const char* sB1 = PG8_KP(cB, 1, rot0, nt0);
;     if constexpr (SP2) {
;         PG8_STAGEB(PG8_SB(0, 0), sB0, voffB); PG8_STAGEB(PG8_SB(0, 1), sB0 + hstep, voffB); PG8_STAGE(PG8_SA(0, 0), sA0, voffA); PG8_STAGE(PG8_SA(0, 1), sA0 + hstep, voffA);
;         if (wr == 1) PG8_BAR;
;         PG8_WAIT_V(2); PG8_BAR;
;         PG8_STAGEB(PG8_SB(1, 0), sB1, voffB); PG8_STAGE(PG8_SA(1, 0), sA1, voffA); PG8_STAGEB(PG8_SB(1, 1), sB1 + hstep, voffB);
;         PG8_WAIT_V(6); PG8_BAR;
;     } else {
;         PG8_STAGEB(PG8_SB(0, 0), sB0, voffB); PG8_STAGE(PG8_SA(0, 0), sA0, voffA); PG8_STAGEB(PG8_SB(0, 1), sB0 + hstep, voffB); PG8_STAGE(PG8_SA(0, 1), sA0 + hstep, voffA);
;         if (wr == 1) PG8_BAR;
.LBB0_260:
	s_cmp_le_i32 s90, s30
	s_cselect_b64 s[0:1], -1, 0
	s_cmp_lt_i32 s30, s91
	s_cselect_b64 s[4:5], -1, 0
	s_and_b64 s[0:1], s[0:1], s[4:5]
	s_andn2_b64 vcc, exec, s[0:1]
	s_cbranch_vccnz .LBB0_741
	v_readlane_b32 s2, v254, 53
	v_readlane_b32 s3, v254, 54
	s_mov_b32 s3, s79
	s_mul_hi_u32 s0, s2, 0x1a00000
	v_writelane_b32 v254, s2, 53
	s_mul_i32 s1, s2, 0x1a00000
	s_mov_b64 s[82:83], s[66:67]
	s_add_u32 s1, s82, s1
	s_addc_u32 s0, s83, s0
	s_add_u32 s24, s1, 0x1000000
	s_addc_u32 s25, s0, 0
	v_readlane_b32 s0, v251, 53
	v_mov_b32_e32 v16, v0
	v_readlane_b32 s1, v251, 54
	v_writelane_b32 v254, s3, 54
	s_andn2_b64 vcc, exec, s[0:1]
	v_readfirstlane_b32 s16, v16
	s_cbranch_vccnz .LBB0_592
	v_lshlrev_b32_e32 v1, 4, v16
	v_add_u32_e32 v2, 0x2000, v1
	v_ashrrev_i32_e32 v3, 31, v2
	v_lshrrev_b32_e32 v3, 22, v3
	v_add_u32_e32 v3, v2, v3
	v_ashrrev_i32_e32 v10, 10, v3
	v_mul_i32_i24_e32 v3, 0x400, v10
	v_sub_u32_e32 v2, v2, v3
	v_lshrrev_b32_e32 v3, 4, v2
	v_bitop3_b32 v2, v3, v2, 32 bitop3:0x6c
	v_ashrrev_i32_e32 v3, 31, v2
	v_lshrrev_b32_e32 v3, 26, v3
	v_add_u32_e32 v3, v2, v3
	v_lshlrev_b32_e32 v4, 3, v10
	v_ashrrev_i32_e32 v11, 6, v3
	v_and_b32_e32 v4, -16, v4
	v_add_u32_e32 v4, v11, v4
	v_and_b32_e32 v5, 3, v11
	s_mov_b32 s2, 0xfffe0
	v_lshrrev_b32_e32 v6, 2, v4
	v_lshlrev_b32_e32 v7, 1, v4
	v_and_b32_e32 v3, 0xc0, v3
	v_and_or_b32 v5, v4, s2, v5
	v_and_b32_e32 v6, 4, v6
	v_and_b32_e32 v7, 24, v7
	v_sub_u32_e32 v2, v2, v3
	v_or3_b32 v5, v5, v6, v7
	v_lshlrev_b32_e32 v6, 5, v10
	v_ashrrev_i16_sdwa v2, v207, sext(v2) dst_sel:DWORD dst_unused:UNUSED_PAD src0_sel:DWORD src1_sel:BYTE_0
	v_and_b32_e32 v6, 32, v6
	v_bfe_i32 v12, v2, 0, 16
	v_add_lshl_u32 v2, v6, v12, 1
	v_lshl_add_u32 v180, v5, 12, v2
	v_lshl_add_u32 v182, v4, 12, v2
	v_bfe_i32 v2, v16, 27, 1
	v_lshrrev_b32_e32 v2, 22, v2
	v_add_u32_e32 v2, v1, v2
	v_and_b32_e32 v2, 0xfffffc00, v2
	v_sub_u32_e32 v1, v1, v2
	v_lshrrev_b32_e32 v2, 4, v1
	v_ashrrev_i32_e32 v3, 31, v16
	v_bitop3_b32 v1, v2, v1, 32 bitop3:0x6c
	v_lshrrev_b32_e32 v3, 26, v3
	v_ashrrev_i32_e32 v2, 31, v1
	v_add_u32_e32 v3, v16, v3
	v_lshrrev_b32_e32 v2, 26, v2
	v_ashrrev_i32_e32 v14, 6, v3
	v_add_u32_e32 v2, v1, v2
	v_lshlrev_b32_e32 v3, 3, v14
	v_ashrrev_i32_e32 v13, 6, v2
	v_and_b32_e32 v3, -16, v3
	v_add_u32_e32 v3, v13, v3
	s_add_u32 s88, s82, 0x1c800000
	v_and_b32_e32 v4, 3, v13
	v_lshrrev_b32_e32 v5, 2, v3
	v_lshlrev_b32_e32 v6, 1, v3
	v_and_b32_e32 v2, 0xc0, v2
	s_addc_u32 s8, s83, 0
	s_ashr_i32 s1, s16, 6
	v_and_or_b32 v4, v3, s2, v4
	v_and_b32_e32 v5, 4, v5
	v_and_b32_e32 v6, 24, v6
	v_sub_u32_e32 v1, v1, v2
	s_ashr_i32 s0, s16, 8
	s_lshl_b32 s70, s1, 10
	v_or3_b32 v4, v4, v5, v6
	v_lshlrev_b32_e32 v5, 5, v14
	v_ashrrev_i16_sdwa v1, v207, sext(v1) dst_sel:DWORD dst_unused:UNUSED_PAD src0_sel:DWORD src1_sel:BYTE_0
	v_readlane_b32 s2, v252, 47
	v_and_b32_e32 v5, 32, v5
	v_bfe_i32 v15, v1, 0, 16
	v_readlane_b32 s3, v252, 48
	s_add_u32 s38, s24, s2
	v_add_lshl_u32 v1, v5, v15, 1
	s_addc_u32 s39, s25, s3
	s_add_i32 s96, s70, 0
	v_lshl_add_u32 v184, v4, 12, v1
	s_add_i32 m0, s96, 0x10000
	v_readlane_b32 s2, v252, 51
	global_load_lds_dwordx4 v184, s[38:39]
	s_add_i32 m0, s96, 0x12000
	v_readlane_b32 s3, v252, 52
	s_add_u32 s40, s88, s2
	s_addc_u32 s41, s8, s3
	s_add_u32 s4, s38, 0x80000
	global_load_lds_dwordx4 v180, s[38:39]
	s_addc_u32 s5, s39, 0
	s_add_i32 m0, s96, 0x14000
	s_add_i32 s71, s96, 0x2000
	global_load_lds_dwordx4 v184, s[4:5]
	s_add_i32 m0, s96, 0x16000
	v_lshl_add_u32 v186, v3, 12, v1
	global_load_lds_dwordx4 v180, s[4:5]
	s_mov_b32 m0, s96
	s_add_u32 s4, s40, 0x80000
	global_load_lds_dwordx4 v186, s[40:41]
	s_mov_b32 m0, s71
	s_addc_u32 s5, s41, 0
	s_add_i32 s33, s96, 0x4000
	global_load_lds_dwordx4 v182, s[40:41]
	s_mov_b32 m0, s33
	s_add_i32 s30, s96, 0x6000
	global_load_lds_dwordx4 v186, s[4:5]
	s_mov_b32 m0, s30
	s_cmp_eq_u32 s0, 1
	global_load_lds_dwordx4 v182, s[4:5]
	s_cselect_b64 s[2:3], -1, 0
	v_mov_b32_e32 v185, v98
	v_mov_b32_e32 v181, v98
	v_mov_b32_e32 v187, v98
	v_mov_b32_e32 v183, v98
	v_writelane_b32 v254, s2, 58
	v_lshl_add_u64 v[6:7], s[38:39], 0, v[184:185]
	v_lshl_add_u64 v[4:5], s[38:39], 0, v[180:181]
	v_lshl_add_u64 v[2:3], s[40:41], 0, v[186:187]
	v_writelane_b32 v254, s3, 59
	s_cmp_lg_u32 s0, 1
	v_lshl_add_u64 v[8:9], s[40:41], 0, v[182:183]
	s_cbranch_scc1 .LBB0_264
; #define PG8_STAGE(bufoff, gbase, voff) do { _Pragma("unroll") for (int _i = 0; _i < 2; ++_i) \
;         __builtin_amdgcn_global_load_lds((const unsigned*)((const char*)(gbase) + (voff)[_i]), (PG8_LAS unsigned*)(lds + (bufoff) + ldsw + _i * 8192), 16, 0, AUX_A); } while (0)
; #define PG8_STAGEB(bufoff, gbase, voff) do { _Pragma("unroll") for (int _i = 0; _i < 2; ++_i) \
;         __builtin_amdgcn_global_load_lds((const unsigned*)((const char*)(gbase) + (voff)[_i]), (PG8_LAS unsigned*)(lds + (bufoff) + ldsw + _i * 8192), 16, 0, AUX_B); } while (0)
; #define PG8_WAIT_V(n) asm volatile("s_waitcnt vmcnt(" #n ")" ::: "memory")
; #define PG8_BAR __builtin_amdgcn_s_barrier()
; template <class Epi, class Sched, bool ALIGN_EPI = false, bool SP2 = false>
; __device__ __forceinline__ void gemm_phase(PG8_LAS unsigned char* lds, const Gemm g, const Sched& S, const Epi& E) {
;     ...
;         PG8_STAGEB(PG8_SB(1, 0), sB1, voffB); PG8_STAGE(PG8_SA(1, 0), sA1, voffA); PG8_STAGEB(PG8_SB(1, 1), sB1 + hstep, voffB);
;         PG8_WAIT_V(6); PG8_BAR;
;     } else {
;         PG8_STAGEB(PG8_SB(0, 0), sB0, voffB); PG8_STAGE(PG8_SA(0, 0), sA0, voffA); PG8_STAGEB(PG8_SB(0, 1), sB0 + hstep, voffB); PG8_STAGE(PG8_SA(0, 1), sA0 + hstep, voffA);
;         if (wr == 1) PG8_BAR;
;         PG8_WAIT_V(4); PG8_BAR;
;         PG8_STAGEB(PG8_SB(1, 0), sB1, voffB); PG8_STAGE(PG8_SA(1, 0), sA1, voffA); PG8_STAGEB(PG8_SB(1, 1), sB1 + hstep, voffB);
;         PG8_WAIT_V(6); PG8_BAR;
;     }
.LBB0_264:
	v_readlane_b32 s2, v254, 53
	v_readlane_b32 s3, v254, 54
	v_readlane_b32 s44, v249, 50
	s_lshl_b64 s[6:7], s[2:3], 14
	v_readlane_b32 s50, v249, 56
	v_readlane_b32 s51, v249, 57
	s_add_u32 s4, s50, s6
	s_addc_u32 s5, s51, s7
	s_lshl_b32 s78, s2, 6
	s_lshl_b32 s31, s2, 4
	s_lshl_b32 s75, s2, 2
	s_add_u32 s20, s82, 0x1ec00000
	s_addc_u32 s21, s83, 0
	v_writelane_b32 v254, s4, 60
	s_add_u32 s22, s82, 0x26100000
	s_addc_u32 s23, s83, 0
	v_writelane_b32 v254, s5, 61
	s_mov_b64 s[4:5], s[82:83]
	s_add_u32 s82, s4, 0x27300000
	s_addc_u32 s83, s5, 0
	v_bfe_u32 v99, v16, 4, 2
	s_add_u32 s2, s4, 0x800000
	v_and_b32_e32 v1, 15, v16
	v_lshlrev_b32_e32 v17, 4, v99
	v_lshlrev_b32_e32 v16, 2, v16
	v_writelane_b32 v254, s4, 62
	s_addc_u32 s3, s5, 0
	s_and_b32 s18, s1, 3
	s_lshl_b32 s6, s0, 6
	v_lshl_or_b32 v17, v1, 6, v17
	s_lshl_b32 s0, s0, 13
	v_and_b32_e32 v16, 32, v16
	v_bitop3_b32 v18, v17, s0, v16 bitop3:0xde
	s_lshl_b32 s0, s18, 5
	s_add_i32 m0, s96, 0x18000
	v_lshl_add_u64 v[6:7], v[6:7], 0, s[76:77]
	v_writelane_b32 v255, s0, 0
	s_lshl_b32 s0, s18, 12
	global_load_lds_dwordx4 v[6:7], off
	v_lshl_add_u64 v[4:5], v[4:5], 0, s[76:77]
	s_add_i32 m0, s96, 0x1a000
	s_add_i32 s90, s96, 0x8000
	s_add_i32 s91, s96, 0xa000
	v_bitop3_b32 v221, v17, s0, v16 bitop3:0xde
	global_load_lds_dwordx4 v[4:5], off
	v_lshl_add_u64 v[2:3], v[2:3], 0, s[76:77]
	s_mov_b32 m0, s90
	s_add_u32 s0, s38, 0x80080
	global_load_lds_dwordx4 v[2:3], off
	v_lshl_add_u64 v[2:3], v[8:9], 0, s[76:77]
	s_mov_b32 m0, s91
	s_addc_u32 s1, s39, 0
	global_load_lds_dwordx4 v[2:3], off
	s_add_i32 m0, s96, 0x1c000
	v_lshl_add_u64 v[2:3], s[0:1], 0, v[184:185]
	global_load_lds_dwordx4 v[2:3], off
	v_lshl_add_u64 v[2:3], s[0:1], 0, v[180:181]
	s_add_i32 m0, s96, 0x1e000
	s_cmpk_lt_u32 s16, 0x100
	global_load_lds_dwordx4 v[2:3], off
	s_waitcnt vmcnt(8)
	s_barrier
	v_lshlrev_b32_e32 v2, 15, v10
	v_and_b32_e32 v2, 0xffff0000, v2
	v_lshl_add_u32 v2, v11, 12, v2
	v_and_b32_e32 v3, 1, v10
	v_lshl_or_b32 v2, v3, 6, v2
	s_cselect_b64 s[10:11], -1, 0
	s_lshl_b32 s0, s18, 6
	v_lshl_add_u32 v188, v12, 1, v2
	v_lshlrev_b32_e32 v2, 15, v14
	v_writelane_b32 v255, s0, 1
	s_or_b32 s93, s0, 0xfffffc00
	v_and_b32_e32 v2, 0xffff0000, v2
	s_lshl_b64 s[0:1], s[78:79], 2
	s_waitcnt vmcnt(6)
	v_lshl_add_u32 v2, v13, 12, v2
	v_and_b32_e32 v3, 1, v14
	v_writelane_b32 v255, s0, 2
	v_lshl_or_b32 v2, v3, 6, v2
	v_writelane_b32 v254, s5, 63
	v_writelane_b32 v255, s1, 3
	v_readlane_b32 s0, v252, 49
	v_mov_b32_e32 v189, v98
	v_lshl_add_u32 v190, v15, 1, v2
	v_mov_b32_e32 v191, v98
	s_mov_b32 s94, 0
	v_add_u32_e32 v222, 0, v18
	v_readlane_b32 s95, v253, 5
	s_mov_b32 s78, s0
	v_readlane_b32 s45, v249, 51
	v_readlane_b32 s46, v249, 52
	v_readlane_b32 s47, v249, 53
	v_readlane_b32 s48, v249, 54
	v_readlane_b32 s49, v249, 55
	v_readlane_b32 s52, v249, 58
	v_readlane_b32 s53, v249, 59
	v_readlane_b32 s54, v249, 60
	v_readlane_b32 s55, v249, 61
	v_readlane_b32 s56, v249, 62
	v_readlane_b32 s57, v249, 63
	v_readlane_b32 s58, v250, 0
	v_readlane_b32 s59, v250, 1
	s_barrier
	v_readlane_b32 s1, v252, 50
	s_branch .LBB0_267

; #define PG8_STAGE(bufoff, gbase, voff) do { _Pragma("unroll") for (int _i = 0; _i < 2; ++_i) \
;         __builtin_amdgcn_global_load_lds((const unsigned*)((const char*)(gbase) + (voff)[_i]), (PG8_LAS unsigned*)(lds + (bufoff) + ldsw + _i * 8192), 16, 0, AUX_A); } while (0)
; #define PG8_STAGEB(bufoff, gbase, voff) do { _Pragma("unroll") for (int _i = 0; _i < 2; ++_i) \
;         __builtin_amdgcn_global_load_lds((const unsigned*)((const char*)(gbase) + (voff)[_i]), (PG8_LAS unsigned*)(lds + (bufoff) + ldsw + _i * 8192), 16, 0, AUX_B); } while (0)
; #define PG8_WAIT_V(n) asm volatile("s_waitcnt vmcnt(" #n ")" ::: "memory")
; #define PG8_BAR __builtin_amdgcn_s_barrier()
; template <class Epi, class Sched, bool ALIGN_EPI = false, bool SP2 = false>
; __device__ __forceinline__ void gemm_phase(PG8_LAS unsigned char* lds, const Gemm g, const Sched& S, const Epi& E) {
;     ...
;         const bool has_next = S.next(ui + 1, nxt);
;         const char* nA = has_next ? (const char*)g.A + (size_t)nxt.pm * tstep + (size_t)nxt.kt0 * kstep : cA; const char* nB = has_next ? (const char*)g.Bt + (size_t)nxt.pn * tstep + (size_t)nxt.kt0 * kstep : cB;
;         const int nt = cur.nkt, rot = cur.krot;
;         const char* nAr = has_next ? nA + (size_t)nxt.krot * kstep : PG8_KP(cA, 0, rot, nt); const char* nBr = has_next ? nB + (size_t)nxt.krot * kstep : PG8_KP(cB, 0, rot, nt);
;         for (int t = 0; t < nt; t += 2) {
;             const bool last = (t == nt - 2);
;             const char* a1 = PG8_KP(cA, t + 1, rot, nt);
;             const char* a2 = last ? nAr : PG8_KP(cA, t + 2, rot, nt); const char* b2 = last ? nBr : PG8_KP(cB, t + 2, rot, nt);
;             const char* a3 = a2 + kstep; const char* b3 = b2 + kstep;
;             if (last && has_next) S.a_ready(nxt);
;             if constexpr (SP2) {
;             PG8_LDB(B0, 0, 0); PG8_LDB(B1, 0, 1); PG8_SCHED; PG8_LDA(At, 0, 0); PG8_STAGE(PG8_SA(1, 1), a1 + hstep, voffA);
;             PG8_WAIT_V(8); PG8_WAIT_L(0); PG8_BAR; PG8_MMA(0, 0, At, B0); PG8_MMA(0, 1, At, B1); PG8_BAR; PG8_SCHED;
;             PG8_LDA(At, 0, 1); PG8_STAGEB(PG8_SB(0, 0), b2, voffB); PG8_STAGEB(PG8_SB(0, 1), b2 + hstep, voffB); PG8_STAGE(PG8_SA(0, 0), a2, voffA);
;             PG8_WAIT_V(8); PG8_WAIT_L(0); PG8_BAR; PG8_MMA(1, 0, At, B0); PG8_MMA(1, 1, At, B1); PG8_BAR; PG8_SCHED;
;     ...
;         if constexpr (ALIGN_EPI) { if (wr == 1) PG8_BAR; }
.LBB0_269:
	s_ashr_i32 s29, s28, 31
	s_lshl_b64 s[0:1], s[28:29], 20
	s_add_u32 s52, s88, s0
	s_addc_u32 s53, s8, s1
	s_ashr_i32 s35, s34, 31
	s_lshl_b64 s[0:1], s[34:35], 20
	s_add_u32 s54, s24, s0
	s_addc_u32 s55, s25, s1
	s_and_b64 s[0:1], s[26:27], exec
	s_cselect_b32 s49, s53, s41
	s_cselect_b32 s51, s52, s40
	s_cselect_b32 vcc_lo, s55, s39
	s_cselect_b32 vcc_hi, s54, s38
	s_add_u32 s0, s40, 0x80080
	s_addc_u32 s1, s41, 0
	s_waitcnt vmcnt(0)
	v_lshl_add_u64 v[132:133], s[0:1], 0, v[188:189]
	v_lshl_add_u64 v[134:135], s[0:1], 0, v[190:191]
	s_mov_b32 s29, 0
	s_waitcnt lgkmcnt(0)
	s_cmp_lg_u64 s[10:11], 0
	s_cbranch_scc1 .Lrp_270
	s_barrier
.Lrp_270:
.Lpk_270:
	s_add_i32 s81, s29, 2
	s_cmp_lt_u32 s29, 30
	s_cselect_b32 s0, 0, 0xffffffe0
	s_add_i32 s0, s81, s0
	s_ashr_i32 s1, s0, 31
	s_lshl_b64 s[0:1], s[0:1], 7
	s_add_u32 s42, s40, s0
	s_addc_u32 s43, s41, s1
	s_add_u32 s0, s38, s0
	s_addc_u32 s1, s39, s1
	s_cmp_eq_u32 s29, 30
	s_cselect_b32 s59, s49, s43
	s_cselect_b32 s58, s51, s42
	s_cselect_b32 s61, vcc_lo, s1
	s_cselect_b32 s60, vcc_hi, s0
	s_add_i32 s43, 0, 0x10000
	s_add_i32 s97, s43, s70
	s_add_i32 s46, 0, 0x14000
	s_add_i32 m0, s96, 0xc000
	s_add_i32 s69, s96, 0xe000
	s_add_i32 s84, s97, 0x2000
	s_add_u32 s62, s60, 0x80000
	s_addc_u32 s63, s61, 0
	s_add_i32 s4, s46, s70
	v_add_u32_e32 v148, s43, v221
	v_add_u32_e32 v164, s46, v221
	s_add_i32 s5, s4, 0x2000
	s_add_i32 s1, 0, 0x18000
	s_add_i32 s47, 0, 0x1c000
	ds_read_b128 v[136:139], v148
	ds_read_b128 v[140:143], v148 offset:1024
	ds_read_b128 v[144:147], v148 offset:2048
	ds_read_b128 v[148:151], v148 offset:3072
	ds_read_b128 v[152:155], v164
	ds_read_b128 v[156:159], v164 offset:1024
	ds_read_b128 v[160:163], v164 offset:2048
	ds_read_b128 v[164:167], v164 offset:3072
	s_add_u32 s56, s58, 0x80000
	s_addc_u32 s57, s59, 0
	s_add_i32 s0, s1, s70
	s_add_i32 s89, s0, 0x2000
	s_add_u32 s42, s60, 0x80080
	s_addc_u32 s43, s61, 0
	s_add_i32 s46, s47, s70
	s_add_i32 s92, s46, 0x2000
	s_cmp_gt_u32 s29, 29
	ds_read_b128 v[192:195], v222
	ds_read_b128 v[196:199], v222 offset:1024
	ds_read_b128 v[200:203], v222 offset:2048
	ds_read_b128 v[224:227], v222 offset:3072
	ds_read_b128 v[228:231], v222 offset:4096
	ds_read_b128 v[232:235], v222 offset:5120
	ds_read_b128 v[236:239], v222 offset:6144
	ds_read_b128 v[240:243], v222 offset:7168
	global_load_lds_dwordx4 v[134:135], off
	s_mov_b32 m0, s69
	s_nop 0
	global_load_lds_dwordx4 v[132:133], off
	s_waitcnt vmcnt(8)
	s_waitcnt lgkmcnt(0)
	s_setprio 1
	s_barrier
	v_mfma_f32_16x16x32_bf16 v[128:131], v[136:139], v[192:195], 0
	v_mfma_f32_16x16x32_bf16 v[128:131], v[140:143], v[196:199], v[128:131]
	v_mfma_f32_16x16x32_bf16 v[124:127], v[144:147], v[192:195], 0
	v_mfma_f32_16x16x32_bf16 v[124:127], v[148:151], v[196:199], v[124:127]
	v_mfma_f32_16x16x32_bf16 v[112:115], v[136:139], v[200:203], 0
	v_mfma_f32_16x16x32_bf16 v[112:115], v[140:143], v[224:227], v[112:115]
	v_mfma_f32_16x16x32_bf16 v[108:111], v[144:147], v[200:203], 0
	v_mfma_f32_16x16x32_bf16 v[108:111], v[148:151], v[224:227], v[108:111]
	v_mfma_f32_16x16x32_bf16 v[94:97], v[136:139], v[228:231], 0
	v_mfma_f32_16x16x32_bf16 v[94:97], v[140:143], v[232:235], v[94:97]
	v_mfma_f32_16x16x32_bf16 v[90:93], v[144:147], v[228:231], 0
	v_mfma_f32_16x16x32_bf16 v[90:93], v[148:151], v[232:235], v[90:93]
	v_mfma_f32_16x16x32_bf16 v[78:81], v[136:139], v[236:239], 0
	v_mfma_f32_16x16x32_bf16 v[78:81], v[140:143], v[240:243], v[78:81]
	v_mfma_f32_16x16x32_bf16 v[74:77], v[144:147], v[236:239], 0
	v_mfma_f32_16x16x32_bf16 v[74:77], v[148:151], v[240:243], v[74:77]
	s_setprio 0
	s_setprio 1
	v_mfma_f32_16x16x32_bf16 v[120:123], v[152:155], v[192:195], 0
	v_mfma_f32_16x16x32_bf16 v[120:123], v[156:159], v[196:199], v[120:123]
	v_mfma_f32_16x16x32_bf16 v[116:119], v[160:163], v[192:195], 0
	v_mfma_f32_16x16x32_bf16 v[116:119], v[164:167], v[196:199], v[116:119]
	v_mfma_f32_16x16x32_bf16 v[104:107], v[152:155], v[200:203], 0
	v_mfma_f32_16x16x32_bf16 v[104:107], v[156:159], v[224:227], v[104:107]
	v_mfma_f32_16x16x32_bf16 v[100:103], v[160:163], v[200:203], 0
	v_mfma_f32_16x16x32_bf16 v[100:103], v[164:167], v[224:227], v[100:103]
	v_mfma_f32_16x16x32_bf16 v[86:89], v[152:155], v[228:231], 0
	v_mfma_f32_16x16x32_bf16 v[86:89], v[156:159], v[232:235], v[86:89]
	v_mfma_f32_16x16x32_bf16 v[82:85], v[160:163], v[228:231], 0
	v_mfma_f32_16x16x32_bf16 v[82:85], v[164:167], v[232:235], v[82:85]
	v_mfma_f32_16x16x32_bf16 v[70:73], v[152:155], v[236:239], 0
	v_mfma_f32_16x16x32_bf16 v[70:73], v[156:159], v[240:243], v[70:73]
	s_setprio 2
	s_barrier
	v_mfma_f32_16x16x32_bf16 v[66:69], v[160:163], v[236:239], 0
	v_mfma_f32_16x16x32_bf16 v[66:69], v[164:167], v[240:243], v[66:69]
	s_setprio 0
	s_mov_b32 m0, s97
	v_lshl_add_u64 v[244:245], s[60:61], 0, v[184:185]
	ds_read_b128 v[192:195], v222 offset:16384
	ds_read_b128 v[196:199], v222 offset:17408
	ds_read_b128 v[200:203], v222 offset:18432
	ds_read_b128 v[224:227], v222 offset:19456
	ds_read_b128 v[228:231], v222 offset:20480
	ds_read_b128 v[232:235], v222 offset:21504
	ds_read_b128 v[236:239], v222 offset:22528
	ds_read_b128 v[240:243], v222 offset:23552
	global_load_lds_dwordx4 v[244:245], off
	v_lshl_add_u64 v[246:247], s[60:61], 0, v[180:181]
	s_mov_b32 m0, s84
	v_lshl_add_u64 v[212:213], s[62:63], 0, v[184:185]
	global_load_lds_dwordx4 v[246:247], off
	s_mov_b32 m0, s4
	v_lshl_add_u64 v[172:173], s[58:59], 0, v[182:183]
	global_load_lds_dwordx4 v[212:213], off
	v_lshl_add_u64 v[212:213], s[62:63], 0, v[180:181]
	s_mov_b32 m0, s5
	s_nop 0
	global_load_lds_dwordx4 v[212:213], off
	v_lshl_add_u64 v[212:213], s[58:59], 0, v[186:187]
	s_mov_b32 m0, s96
	s_nop 0
	global_load_lds_dwordx4 v[212:213], off
	s_mov_b32 m0, s71
	s_nop 0
	global_load_lds_dwordx4 v[172:173], off
	s_waitcnt vmcnt(8)
	s_waitcnt lgkmcnt(0)
	s_setprio 1
	s_barrier
; #define PG8_STAGE(bufoff, gbase, voff) do { _Pragma("unroll") for (int _i = 0; _i < 2; ++_i) \
;         __builtin_amdgcn_global_load_lds((const unsigned*)((const char*)(gbase) + (voff)[_i]), (PG8_LAS unsigned*)(lds + (bufoff) + ldsw + _i * 8192), 16, 0, AUX_A); } while (0)
; #define PG8_LDA(dst, b, h) do { _Pragma("unroll") for (int m = 0; m < 4; ++m) _Pragma("unroll") for (int k = 0; k < 2; ++k) dst[m][k] = *(const PG8_LAS bf16x8*)(lds + PG8_SA(b, h) + aoff + m * 2048 + k * 1024); } while (0)
; #define PG8_LDB(dst, b, h) do { _Pragma("unroll") for (int n = 0; n < 2; ++n) _Pragma("unroll") for (int k = 0; k < 2; ++k) dst[n][k] = *(const PG8_LAS bf16x8*)(lds + PG8_SB(b, h) + boff + n * 2048 + k * 1024); } while (0)
; #define PG8_MMA(ai, bj, At, Bt) do { __builtin_amdgcn_s_setprio(1); _Pragma("unroll") for (int m = 0; m < 4; ++m) _Pragma("unroll") for (int n = 0; n < 2; ++n) _Pragma("unroll") for (int k = 0; k < 2; ++k) \
;         acc[ai][bj][m][n] = __builtin_amdgcn_mfma_f32_16x16x32_bf16(Bt[n][k], At[m][k], acc[ai][bj][m][n], 0, 0, 0); __builtin_amdgcn_s_setprio(0); } while (0)
; #define PG8_WAIT_V(n) asm volatile("s_waitcnt vmcnt(" #n ")" ::: "memory")
; #define PG8_WAIT_L(n) asm volatile("s_waitcnt lgkmcnt(" #n ")" ::: "memory")
; #define PG8_BAR __builtin_amdgcn_s_barrier()
; #define PG8_SCHED __builtin_amdgcn_sched_barrier(0)
; template <class Epi, class Sched, bool ALIGN_EPI = false, bool SP2 = false>
; __device__ __forceinline__ void gemm_phase(PG8_LAS unsigned char* lds, const Gemm g, const Sched& S, const Epi& E) {
;     ...
;             PG8_WAIT_V(8); PG8_WAIT_L(0); PG8_BAR; PG8_MMA(1, 0, At, B0); PG8_MMA(1, 1, At, B1); PG8_BAR; PG8_SCHED;
;             PG8_LDB(B0, 1, 0); PG8_LDB(B1, 1, 1); PG8_SCHED; PG8_LDA(At, 1, 0); PG8_STAGE(PG8_SA(0, 1), a2 + hstep, voffA);
;             PG8_WAIT_V(8); PG8_WAIT_L(0); PG8_BAR; PG8_MMA(0, 0, At, B0); PG8_MMA(0, 1, At, B1); PG8_BAR; PG8_SCHED;
	v_mfma_f32_16x16x32_bf16 v[62:65], v[136:139], v[192:195], 0
	v_mfma_f32_16x16x32_bf16 v[62:65], v[140:143], v[196:199], v[62:65]
	v_mfma_f32_16x16x32_bf16 v[58:61], v[144:147], v[192:195], 0
	v_mfma_f32_16x16x32_bf16 v[58:61], v[148:151], v[196:199], v[58:61]
	v_mfma_f32_16x16x32_bf16 v[46:49], v[136:139], v[200:203], 0
	v_mfma_f32_16x16x32_bf16 v[46:49], v[140:143], v[224:227], v[46:49]
	v_mfma_f32_16x16x32_bf16 v[42:45], v[144:147], v[200:203], 0
	v_mfma_f32_16x16x32_bf16 v[42:45], v[148:151], v[224:227], v[42:45]
	v_mfma_f32_16x16x32_bf16 v[30:33], v[136:139], v[228:231], 0
	v_mfma_f32_16x16x32_bf16 v[30:33], v[140:143], v[232:235], v[30:33]
	v_mfma_f32_16x16x32_bf16 v[26:29], v[144:147], v[228:231], 0
	v_mfma_f32_16x16x32_bf16 v[26:29], v[148:151], v[232:235], v[26:29]
	v_mfma_f32_16x16x32_bf16 v[14:17], v[136:139], v[236:239], 0
	v_mfma_f32_16x16x32_bf16 v[14:17], v[140:143], v[240:243], v[14:17]
	v_mfma_f32_16x16x32_bf16 v[10:13], v[144:147], v[236:239], 0
	v_mfma_f32_16x16x32_bf16 v[10:13], v[148:151], v[240:243], v[10:13]
	s_setprio 0
	s_setprio 1
	v_mfma_f32_16x16x32_bf16 v[54:57], v[152:155], v[192:195], 0
	v_mfma_f32_16x16x32_bf16 v[54:57], v[156:159], v[196:199], v[54:57]
	v_mfma_f32_16x16x32_bf16 v[50:53], v[160:163], v[192:195], 0
	v_mfma_f32_16x16x32_bf16 v[50:53], v[164:167], v[196:199], v[50:53]
	v_mfma_f32_16x16x32_bf16 v[38:41], v[152:155], v[200:203], 0
	v_mfma_f32_16x16x32_bf16 v[38:41], v[156:159], v[224:227], v[38:41]
	v_mfma_f32_16x16x32_bf16 v[34:37], v[160:163], v[200:203], 0
	v_mfma_f32_16x16x32_bf16 v[34:37], v[164:167], v[224:227], v[34:37]
	v_mfma_f32_16x16x32_bf16 v[22:25], v[152:155], v[228:231], 0
	v_mfma_f32_16x16x32_bf16 v[22:25], v[156:159], v[232:235], v[22:25]
	v_mfma_f32_16x16x32_bf16 v[18:21], v[160:163], v[228:231], 0
	v_mfma_f32_16x16x32_bf16 v[18:21], v[164:167], v[232:235], v[18:21]
	v_mfma_f32_16x16x32_bf16 v[6:9], v[152:155], v[236:239], 0
	v_mfma_f32_16x16x32_bf16 v[6:9], v[156:159], v[240:243], v[6:9]
	s_setprio 2
	s_barrier
	v_mfma_f32_16x16x32_bf16 v[2:5], v[160:163], v[236:239], 0
	v_mfma_f32_16x16x32_bf16 v[2:5], v[164:167], v[240:243], v[2:5]
	s_setprio 0
	v_add_u32_e32 v148, s1, v221
	v_add_u32_e32 v164, s47, v221
	ds_read_b128 v[136:139], v148
	ds_read_b128 v[140:143], v148 offset:1024
	ds_read_b128 v[144:147], v148 offset:2048
	ds_read_b128 v[148:151], v148 offset:3072
	ds_read_b128 v[152:155], v164
	ds_read_b128 v[156:159], v164 offset:1024
	ds_read_b128 v[160:163], v164 offset:2048
	ds_read_b128 v[164:167], v164 offset:3072
	s_mov_b32 m0, s33
	v_lshl_add_u64 v[168:169], s[56:57], 0, v[186:187]
	ds_read_b128 v[192:195], v222 offset:32768
	ds_read_b128 v[196:199], v222 offset:33792
	ds_read_b128 v[200:203], v222 offset:34816
	ds_read_b128 v[224:227], v222 offset:35840
	ds_read_b128 v[228:231], v222 offset:36864
	ds_read_b128 v[232:235], v222 offset:37888
	ds_read_b128 v[236:239], v222 offset:38912
	ds_read_b128 v[240:243], v222 offset:39936
	global_load_lds_dwordx4 v[168:169], off
	v_lshl_add_u64 v[168:169], s[56:57], 0, v[182:183]
	s_mov_b32 m0, s30
	s_nop 0
	global_load_lds_dwordx4 v[168:169], off
	s_waitcnt vmcnt(8)
	s_waitcnt lgkmcnt(0)
	s_setprio 1
	s_barrier
	v_mfma_f32_16x16x32_bf16 v[128:131], v[136:139], v[192:195], v[128:131]
	v_mfma_f32_16x16x32_bf16 v[128:131], v[140:143], v[196:199], v[128:131]
	v_mfma_f32_16x16x32_bf16 v[124:127], v[144:147], v[192:195], v[124:127]
	v_mfma_f32_16x16x32_bf16 v[124:127], v[148:151], v[196:199], v[124:127]
	v_mfma_f32_16x16x32_bf16 v[112:115], v[136:139], v[200:203], v[112:115]
	v_mfma_f32_16x16x32_bf16 v[112:115], v[140:143], v[224:227], v[112:115]
	v_mfma_f32_16x16x32_bf16 v[108:111], v[144:147], v[200:203], v[108:111]
	v_mfma_f32_16x16x32_bf16 v[108:111], v[148:151], v[224:227], v[108:111]
	v_mfma_f32_16x16x32_bf16 v[94:97], v[136:139], v[228:231], v[94:97]
	v_mfma_f32_16x16x32_bf16 v[94:97], v[140:143], v[232:235], v[94:97]
	v_mfma_f32_16x16x32_bf16 v[90:93], v[144:147], v[228:231], v[90:93]
	v_mfma_f32_16x16x32_bf16 v[90:93], v[148:151], v[232:235], v[90:93]
	v_mfma_f32_16x16x32_bf16 v[78:81], v[136:139], v[236:239], v[78:81]
	v_mfma_f32_16x16x32_bf16 v[78:81], v[140:143], v[240:243], v[78:81]
	v_mfma_f32_16x16x32_bf16 v[74:77], v[144:147], v[236:239], v[74:77]
	v_mfma_f32_16x16x32_bf16 v[74:77], v[148:151], v[240:243], v[74:77]
	s_setprio 0
	s_setprio 1
	v_mfma_f32_16x16x32_bf16 v[120:123], v[152:155], v[192:195], v[120:123]
	v_mfma_f32_16x16x32_bf16 v[120:123], v[156:159], v[196:199], v[120:123]
	v_mfma_f32_16x16x32_bf16 v[116:119], v[160:163], v[192:195], v[116:119]
	v_mfma_f32_16x16x32_bf16 v[116:119], v[164:167], v[196:199], v[116:119]
	v_mfma_f32_16x16x32_bf16 v[104:107], v[152:155], v[200:203], v[104:107]
	v_mfma_f32_16x16x32_bf16 v[104:107], v[156:159], v[224:227], v[104:107]
	v_mfma_f32_16x16x32_bf16 v[100:103], v[160:163], v[200:203], v[100:103]
	v_mfma_f32_16x16x32_bf16 v[100:103], v[164:167], v[224:227], v[100:103]
	v_mfma_f32_16x16x32_bf16 v[86:89], v[152:155], v[228:231], v[86:89]
	v_mfma_f32_16x16x32_bf16 v[86:89], v[156:159], v[232:235], v[86:89]
	v_mfma_f32_16x16x32_bf16 v[82:85], v[160:163], v[228:231], v[82:85]
	v_mfma_f32_16x16x32_bf16 v[82:85], v[164:167], v[232:235], v[82:85]
	v_mfma_f32_16x16x32_bf16 v[70:73], v[152:155], v[236:239], v[70:73]
	v_mfma_f32_16x16x32_bf16 v[70:73], v[156:159], v[240:243], v[70:73]
	s_setprio 2
	s_barrier
; #define PG8_STAGE(bufoff, gbase, voff) do { _Pragma("unroll") for (int _i = 0; _i < 2; ++_i) \
;         __builtin_amdgcn_global_load_lds((const unsigned*)((const char*)(gbase) + (voff)[_i]), (PG8_LAS unsigned*)(lds + (bufoff) + ldsw + _i * 8192), 16, 0, AUX_A); } while (0)
; #define PG8_STAGEB(bufoff, gbase, voff) do { _Pragma("unroll") for (int _i = 0; _i < 2; ++_i) \
;         __builtin_amdgcn_global_load_lds((const unsigned*)((const char*)(gbase) + (voff)[_i]), (PG8_LAS unsigned*)(lds + (bufoff) + ldsw + _i * 8192), 16, 0, AUX_B); } while (0)
; #define PG8_LDA(dst, b, h) do { _Pragma("unroll") for (int m = 0; m < 4; ++m) _Pragma("unroll") for (int k = 0; k < 2; ++k) dst[m][k] = *(const PG8_LAS bf16x8*)(lds + PG8_SA(b, h) + aoff + m * 2048 + k * 1024); } while (0)
; #define PG8_MMA(ai, bj, At, Bt) do { __builtin_amdgcn_s_setprio(1); _Pragma("unroll") for (int m = 0; m < 4; ++m) _Pragma("unroll") for (int n = 0; n < 2; ++n) _Pragma("unroll") for (int k = 0; k < 2; ++k) \
;         acc[ai][bj][m][n] = __builtin_amdgcn_mfma_f32_16x16x32_bf16(Bt[n][k], At[m][k], acc[ai][bj][m][n], 0, 0, 0); __builtin_amdgcn_s_setprio(0); } while (0)
; #define PG8_WAIT_V(n) asm volatile("s_waitcnt vmcnt(" #n ")" ::: "memory")
; #define PG8_WAIT_L(n) asm volatile("s_waitcnt lgkmcnt(" #n ")" ::: "memory")
; #define PG8_BAR __builtin_amdgcn_s_barrier()
; #define PG8_SCHED __builtin_amdgcn_sched_barrier(0)
; template <class Epi, class Sched, bool ALIGN_EPI = false, bool SP2 = false>
; __device__ __forceinline__ void gemm_phase(PG8_LAS unsigned char* lds, const Gemm g, const Sched& S, const Epi& E) {
;     ...
;             PG8_LDA(At, 1, 1); PG8_STAGEB(PG8_SB(1, 0), b3, voffB); PG8_STAGEB(PG8_SB(1, 1), b3 + hstep, voffB); PG8_STAGE(PG8_SA(1, 0), a3, voffA);
;             PG8_WAIT_V(8); PG8_WAIT_L(0); PG8_BAR; PG8_MMA(1, 0, At, B0); PG8_MMA(1, 1, At, B1); PG8_BAR; PG8_SCHED;
	v_mfma_f32_16x16x32_bf16 v[66:69], v[160:163], v[236:239], v[66:69]
	v_mfma_f32_16x16x32_bf16 v[66:69], v[164:167], v[240:243], v[66:69]
	s_setprio 0
	s_mov_b32 m0, s0
	v_lshl_add_u64 v[168:169], v[244:245], 0, s[76:77]
	ds_read_b128 v[192:195], v222 offset:49152
	ds_read_b128 v[196:199], v222 offset:50176
	ds_read_b128 v[200:203], v222 offset:51200
	ds_read_b128 v[224:227], v222 offset:52224
	ds_read_b128 v[228:231], v222 offset:53248
	ds_read_b128 v[232:235], v222 offset:54272
	ds_read_b128 v[236:239], v222 offset:55296
	ds_read_b128 v[240:243], v222 offset:56320
	global_load_lds_dwordx4 v[168:169], off
	v_lshl_add_u64 v[168:169], v[246:247], 0, s[76:77]
	s_mov_b32 m0, s89
	s_nop 0
	global_load_lds_dwordx4 v[168:169], off
	v_lshl_add_u64 v[168:169], s[42:43], 0, v[184:185]
	s_mov_b32 m0, s46
	s_nop 0
	global_load_lds_dwordx4 v[168:169], off
	v_lshl_add_u64 v[168:169], s[42:43], 0, v[180:181]
	s_mov_b32 m0, s92
	s_nop 0
	global_load_lds_dwordx4 v[168:169], off
	v_lshl_add_u64 v[168:169], v[212:213], 0, s[76:77]
	s_mov_b32 m0, s90
	s_nop 0
	global_load_lds_dwordx4 v[168:169], off
	v_lshl_add_u64 v[168:169], v[172:173], 0, s[76:77]
	s_mov_b32 m0, s91
	s_nop 0
	global_load_lds_dwordx4 v[168:169], off
	s_waitcnt vmcnt(8)
	s_waitcnt lgkmcnt(0)
	s_setprio 1
	s_barrier
	v_mfma_f32_16x16x32_bf16 v[62:65], v[136:139], v[192:195], v[62:65]
	v_mfma_f32_16x16x32_bf16 v[62:65], v[140:143], v[196:199], v[62:65]
	v_mfma_f32_16x16x32_bf16 v[58:61], v[144:147], v[192:195], v[58:61]
	v_mfma_f32_16x16x32_bf16 v[58:61], v[148:151], v[196:199], v[58:61]
	v_mfma_f32_16x16x32_bf16 v[46:49], v[136:139], v[200:203], v[46:49]
	v_mfma_f32_16x16x32_bf16 v[46:49], v[140:143], v[224:227], v[46:49]
	v_mfma_f32_16x16x32_bf16 v[42:45], v[144:147], v[200:203], v[42:45]
	v_mfma_f32_16x16x32_bf16 v[42:45], v[148:151], v[224:227], v[42:45]
	v_mfma_f32_16x16x32_bf16 v[30:33], v[136:139], v[228:231], v[30:33]
	v_mfma_f32_16x16x32_bf16 v[30:33], v[140:143], v[232:235], v[30:33]
	v_mfma_f32_16x16x32_bf16 v[26:29], v[144:147], v[228:231], v[26:29]
	v_mfma_f32_16x16x32_bf16 v[26:29], v[148:151], v[232:235], v[26:29]
	v_mfma_f32_16x16x32_bf16 v[14:17], v[136:139], v[236:239], v[14:17]
	v_mfma_f32_16x16x32_bf16 v[14:17], v[140:143], v[240:243], v[14:17]
	v_mfma_f32_16x16x32_bf16 v[10:13], v[144:147], v[236:239], v[10:13]
	v_mfma_f32_16x16x32_bf16 v[10:13], v[148:151], v[240:243], v[10:13]
	s_setprio 0
	s_setprio 1
	v_mfma_f32_16x16x32_bf16 v[54:57], v[152:155], v[192:195], v[54:57]
	v_mfma_f32_16x16x32_bf16 v[54:57], v[156:159], v[196:199], v[54:57]
	v_mfma_f32_16x16x32_bf16 v[50:53], v[160:163], v[192:195], v[50:53]
	v_mfma_f32_16x16x32_bf16 v[50:53], v[164:167], v[196:199], v[50:53]
	v_mfma_f32_16x16x32_bf16 v[38:41], v[152:155], v[200:203], v[38:41]
	v_mfma_f32_16x16x32_bf16 v[38:41], v[156:159], v[224:227], v[38:41]
	v_mfma_f32_16x16x32_bf16 v[34:37], v[160:163], v[200:203], v[34:37]
	v_mfma_f32_16x16x32_bf16 v[34:37], v[164:167], v[224:227], v[34:37]
	v_mfma_f32_16x16x32_bf16 v[22:25], v[152:155], v[228:231], v[22:25]
	v_mfma_f32_16x16x32_bf16 v[22:25], v[156:159], v[232:235], v[22:25]
	v_mfma_f32_16x16x32_bf16 v[18:21], v[160:163], v[228:231], v[18:21]
	v_mfma_f32_16x16x32_bf16 v[18:21], v[164:167], v[232:235], v[18:21]
	v_mfma_f32_16x16x32_bf16 v[6:9], v[152:155], v[236:239], v[6:9]
	v_mfma_f32_16x16x32_bf16 v[6:9], v[156:159], v[240:243], v[6:9]
	s_setprio 2
	s_barrier
	v_mfma_f32_16x16x32_bf16 v[2:5], v[160:163], v[236:239], v[2:5]
	v_mfma_f32_16x16x32_bf16 v[2:5], v[164:167], v[240:243], v[2:5]
	s_setprio 0
	v_lshl_add_u64 v[132:133], v[132:133], 0, s[86:87]
	v_lshl_add_u64 v[134:135], v[134:135], 0, s[86:87]
	s_mov_b32 s29, s81
	s_cbranch_scc1 .Lpx_270

; #define PG8_STAGE(bufoff, gbase, voff) do { _Pragma("unroll") for (int _i = 0; _i < 2; ++_i) \
;         __builtin_amdgcn_global_load_lds((const unsigned*)((const char*)(gbase) + (voff)[_i]), (PG8_LAS unsigned*)(lds + (bufoff) + ldsw + _i * 8192), 16, 0, AUX_A); } while (0)
; #define PG8_WAIT_V(n) asm volatile("s_waitcnt vmcnt(" #n ")" ::: "memory")
; template <class Epi, class Sched, bool ALIGN_EPI = false, bool SP2 = false>
; __device__ __forceinline__ void gemm_phase(PG8_LAS unsigned char* lds, const Gemm g, const Sched& S, const Epi& E) {
;     ...
;     const int tid = tid_l, wid = __builtin_amdgcn_readfirstlane(tid >> 6), lane = tid & 63, wr = wid >> 2, wc = wid & 3, fr = lane & 15, fq = lane >> 4;
;     const int K = g.K;
;     unsigned voffA[2], voffB[2];
; #pragma unroll
;     for (int i = 0; i < 2; ++i) { int R, C; stage_rc(tid * 16 + i * 8192, R, C); const int Rb = Epi::PERM ? ((R & ~31) + perm32(R & 31)) : R;
;         voffA[i] = (unsigned)(R * K + C) * 2u; voffB[i] = (unsigned)(Rb * K + C) * 2u; }
;     const size_t kstep = (size_t)(BK * 2);
;     const size_t hstep = (size_t)HALF * K * 2;
;     const size_t tstep = 2 * hstep;
;     const unsigned ldsw = (unsigned)wid * 1024u;
;     const int aoff = lds_byte(wr * 64 + fr, fq * 8), boff = lds_byte(wc * 32 + fr, fq * 8);
;     ...
;     { const int rot0 = cur.krot, nt0 = cur.nkt; const char* sA0 = PG8_KP(cA, 0, rot0, nt0); const char* sA1 = PG8_KP(cA, 1, rot0, nt0); const char* sB0 = PG8_KP(cB, 0, rot0, nt0); const char* sB1 = PG8_KP(cB, 1, rot0, nt0);
;     if constexpr (SP2) {
;         PG8_STAGEB(PG8_SB(0, 0), sB0, voffB); PG8_STAGEB(PG8_SB(0, 1), sB0 + hstep, voffB); PG8_STAGE(PG8_SA(0, 0), sA0, voffA); PG8_STAGE(PG8_SA(0, 1), sA0 + hstep, voffA);
;         if (wr == 1) PG8_BAR;
;         PG8_WAIT_V(2); PG8_BAR;
;         PG8_STAGEB(PG8_SB(1, 0), sB1, voffB); PG8_STAGE(PG8_SA(1, 0), sA1, voffA); PG8_STAGEB(PG8_SB(1, 1), sB1 + hstep, voffB);
;         PG8_WAIT_V(6); PG8_BAR;
;     } else {
;         PG8_STAGEB(PG8_SB(0, 0), sB0, voffB); PG8_STAGE(PG8_SA(0, 0), sA0, voffA); PG8_STAGEB(PG8_SB(0, 1), sB0 + hstep, voffB); PG8_STAGE(PG8_SA(0, 1), sA0 + hstep, voffA);
;         if (wr == 1) PG8_BAR;
;         PG8_WAIT_V(4); PG8_BAR;
;         PG8_STAGEB(PG8_SB(1, 0), sB1, voffB); PG8_STAGE(PG8_SA(1, 0), sA1, voffA); PG8_STAGEB(PG8_SB(1, 1), sB1 + hstep, voffB);
;         PG8_WAIT_V(6); PG8_BAR;
;     }
.LBB0_918:
	v_readlane_b32 s0, v254, 53
	v_readlane_b32 s1, v254, 54
	s_mov_b32 s1, s79
	v_writelane_b32 v254, s0, 53
	s_andn2_b64 vcc, exec, s[4:5]
	s_nop 0
	v_writelane_b32 v254, s1, 54
	s_cbranch_vccnz .LBB0_943
	v_ashrrev_i32_e32 v2, 31, v13
	v_lshrrev_b32_e32 v2, 26, v2
	v_add_u32_e32 v2, v13, v2
	v_ashrrev_i32_e32 v10, 6, v2
	v_bfe_i32 v2, v13, 27, 1
	v_lshlrev_b32_e32 v1, 4, v13
	v_lshrrev_b32_e32 v2, 22, v2
	v_add_u32_e32 v2, v1, v2
	v_and_b32_e32 v2, 0xfffffc00, v2
	v_sub_u32_e32 v2, v1, v2
	v_readlane_b32 s2, v254, 53
	v_lshrrev_b32_e32 v3, 4, v2
	v_readlane_b32 s3, v254, 54
	v_bitop3_b32 v2, v3, v2, 32 bitop3:0x6c
	s_lshl_b64 s[0:1], s[2:3], 21
	v_ashrrev_i32_e32 v4, 31, v2
	s_add_u32 s4, s34, 0x27780000
	v_lshrrev_b32_e32 v4, 26, v4
	s_addc_u32 s5, s35, 0
	v_add_u32_e32 v4, v2, v4
	s_add_u32 s0, s34, s0
	v_lshlrev_b32_e32 v3, 3, v10
	v_ashrrev_i32_e32 v11, 6, v4
	v_and_b32_e32 v4, 0xc0, v4
	s_addc_u32 s1, s35, s1
	v_and_b32_e32 v3, -16, v3
	v_sub_u32_e32 v2, v2, v4
	s_add_u32 s30, s0, 0x7800000
	v_add_u32_e32 v3, v11, v3
	v_ashrrev_i16_sdwa v2, v207, sext(v2) dst_sel:DWORD dst_unused:UNUSED_PAD src0_sel:DWORD src1_sel:BYTE_0
	s_addc_u32 s31, s1, 0
	v_lshlrev_b32_e32 v5, 5, v10
	v_bfe_i32 v12, v2, 0, 16
	v_lshlrev_b32_e32 v2, 1, v3
	v_lshrrev_b32_e32 v4, 2, v3
	v_and_b32_e32 v6, 3, v11
	s_mov_b32 s1, 0x1fffe0
	v_and_b32_e32 v5, 32, v5
	v_and_b32_e32 v2, 24, v2
	v_and_b32_e32 v4, 4, v4
	v_and_or_b32 v6, v3, s1, v6
	v_or3_b32 v2, v6, v4, v2
	v_add_lshl_u32 v4, v5, v12, 1
	v_add_u32_e32 v1, 0x2000, v1
	v_lshl_add_u32 v150, v2, 11, v4
	v_ashrrev_i32_e32 v2, 31, v1
	v_lshrrev_b32_e32 v2, 22, v2
	v_add_u32_e32 v2, v1, v2
	v_ashrrev_i32_e32 v14, 10, v2
	v_mul_i32_i24_e32 v2, 0x400, v14
	v_sub_u32_e32 v1, v1, v2
	v_lshrrev_b32_e32 v2, 4, v1
	v_bitop3_b32 v1, v2, v1, 32 bitop3:0x6c
	v_lshl_add_u32 v148, v3, 11, v4
	v_ashrrev_i32_e32 v3, 31, v1
	v_lshrrev_b32_e32 v3, 26, v3
	v_lshlrev_b32_e32 v2, 3, v14
	v_add_u32_e32 v3, v1, v3
	v_and_b32_e32 v2, -16, v2
	v_ashrrev_i32_e32 v15, 6, v3
	v_add_u32_e32 v2, v15, v2
	v_and_b32_e32 v5, 3, v15
	v_and_or_b32 v5, v2, s1, v5
	s_ashr_i32 s1, s12, 6
	s_ashr_i32 s43, s42, 31
	s_ashr_i32 s25, s24, 31
	s_ashr_i32 s0, s12, 8
	s_lshl_b32 s33, s1, 10
	s_lshl_b64 s[6:7], s[42:43], 19
	s_lshl_b64 s[8:9], s[24:25], 19
	v_and_b32_e32 v3, 0xc0, v3
	s_add_u32 s26, s30, s8
	v_sub_u32_e32 v1, v1, v3
	s_addc_u32 s27, s31, s9
	s_add_i32 s25, s33, 0
	v_ashrrev_i16_sdwa v1, v207, sext(v1) dst_sel:DWORD dst_unused:UNUSED_PAD src0_sel:DWORD src1_sel:BYTE_0
	s_add_i32 m0, s25, 0x10000
	v_lshlrev_b32_e32 v4, 5, v14
	v_bfe_i32 v16, v1, 0, 16
	v_lshlrev_b32_e32 v1, 1, v2
	v_lshrrev_b32_e32 v3, 2, v2
	global_load_lds_dwordx4 v150, s[26:27]
	s_add_i32 m0, s25, 0x12000
	v_and_b32_e32 v4, 32, v4
	v_and_b32_e32 v1, 24, v1
	v_and_b32_e32 v3, 4, v3
	s_add_u32 s64, s4, s6
	v_or3_b32 v1, v5, v3, v1
	v_add_lshl_u32 v3, v4, v16, 1
	s_addc_u32 s65, s5, s7
	v_lshl_add_u32 v154, v1, 11, v3
	s_add_u32 s6, s26, 0x40000
	global_load_lds_dwordx4 v154, s[26:27]
	s_addc_u32 s7, s27, 0
	s_add_i32 m0, s25, 0x14000
	s_add_i32 s62, s25, 0x2000
	global_load_lds_dwordx4 v150, s[6:7]
	s_add_i32 m0, s25, 0x16000
	v_lshl_add_u32 v152, v2, 11, v3
	global_load_lds_dwordx4 v154, s[6:7]
	s_mov_b32 m0, s25
	s_add_u32 s6, s64, 0x40000
	global_load_lds_dwordx4 v148, s[64:65]
	s_mov_b32 m0, s62
	s_addc_u32 s7, s65, 0
	s_add_i32 s63, s25, 0x4000
	global_load_lds_dwordx4 v152, s[64:65]
	s_mov_b32 m0, s63
	s_add_i32 s69, s25, 0x6000
	global_load_lds_dwordx4 v148, s[6:7]
	s_mov_b32 m0, s69
	v_mov_b32_e32 v151, v98
	global_load_lds_dwordx4 v152, s[6:7]
	v_mov_b32_e32 v155, v98
	v_mov_b32_e32 v149, v98
	v_mov_b32_e32 v153, v98
	s_cmp_eq_u32 s0, 1
	v_lshl_add_u64 v[8:9], s[26:27], 0, v[150:151]
	v_lshl_add_u64 v[6:7], s[26:27], 0, v[154:155]
	v_lshl_add_u64 v[2:3], s[64:65], 0, v[148:149]
	s_cselect_b64 s[6:7], -1, 0
	s_cmp_lg_u32 s0, 1
	v_lshl_add_u64 v[4:5], s[64:65], 0, v[152:153]
	s_cbranch_scc1 .LBB0_921
.LBB0_921:
	v_readlane_b32 s44, v249, 34
	s_lshl_b64 s[8:9], s[2:3], 12
	v_readlane_b32 s56, v249, 46
	v_readlane_b32 s57, v249, 47
	s_add_u32 s8, s56, s8
	v_lshrrev_b32_e32 v18, 1, v13
	s_addc_u32 s9, s57, s9
	v_and_b32_e32 v18, 24, v18
	s_add_u32 s10, s34, 0x28980000
	v_and_b32_e32 v17, 15, v13
	v_lshlrev_b32_e32 v19, 1, v18
	v_lshlrev_b32_e32 v13, 2, v13
	s_addc_u32 s11, s35, 0
	v_lshl_or_b32 v1, s0, 6, v17
	v_lshl_or_b32 v17, v17, 6, v19
	s_lshl_b32 s0, s0, 13
	v_and_b32_e32 v13, 32, v13
	v_bitop3_b32 v19, v17, s0, v13 bitop3:0xde
	s_lshl_b32 s0, s1, 5
	s_and_b32 s2, s0, 0x60
	s_add_i32 m0, s25, 0x18000
	v_lshl_add_u64 v[8:9], v[8:9], 0, s[76:77]
	s_lshl_b32 s0, s2, 7
	global_load_lds_dwordx4 v[8:9], off
	v_lshl_add_u64 v[6:7], v[6:7], 0, s[76:77]
	s_add_i32 m0, s25, 0x1a000
	s_add_i32 s70, s25, 0x8000
	s_add_i32 s71, s25, 0xa000
	v_bitop3_b32 v99, v17, s0, v13 bitop3:0xde
	global_load_lds_dwordx4 v[6:7], off
	v_lshl_add_u64 v[2:3], v[2:3], 0, s[76:77]
	s_mov_b32 m0, s70
	s_add_u32 s0, s26, 0x40080
	global_load_lds_dwordx4 v[2:3], off
	v_lshl_add_u64 v[2:3], v[4:5], 0, s[76:77]
	s_mov_b32 m0, s71
	s_addc_u32 s1, s27, 0
	global_load_lds_dwordx4 v[2:3], off
	s_add_i32 m0, s25, 0x1c000
	v_lshl_add_u64 v[2:3], s[0:1], 0, v[150:151]
	global_load_lds_dwordx4 v[2:3], off
	v_lshl_add_u64 v[2:3], s[0:1], 0, v[154:155]
	s_add_i32 m0, s25, 0x1e000
	v_readlane_b32 s45, v249, 35
	global_load_lds_dwordx4 v[2:3], off
	s_waitcnt vmcnt(8)
	s_barrier
	v_lshlrev_b32_e32 v2, 14, v14
	v_and_b32_e32 v2, 0xffff8000, v2
	v_lshl_add_u32 v2, v15, 11, v2
	v_and_b32_e32 v3, 1, v14
	v_lshl_or_b32 v2, v3, 6, v2
	v_lshl_add_u32 v156, v16, 1, v2
	v_lshlrev_b32_e32 v2, 14, v10
	v_and_b32_e32 v2, 0xffff8000, v2
	s_waitcnt vmcnt(6)
	v_lshl_add_u32 v2, v11, 11, v2
	v_and_b32_e32 v3, 1, v10
	v_readlane_b32 s48, v249, 38
	v_readlane_b32 s49, v249, 39
	v_readlane_b32 s50, v249, 40
	v_readlane_b32 s51, v249, 41
	s_cmpk_lt_u32 s12, 0x100
	v_lshl_or_b32 v2, v3, 6, v2
	s_cselect_b64 s[12:13], -1, 0
	v_or_b32_e32 v164, s2, v18
	v_mov_b32_e32 v157, v98
	v_lshl_add_u32 v158, v12, 1, v2
	v_mov_b32_e32 v159, v98
	s_mov_b32 s75, 0
	v_add_u32_e32 v165, 0, v19
	v_readlane_b32 s3, v252, 31
	v_readlane_b32 s44, v252, 33
	v_readlane_b32 s45, v252, 11
	v_readlane_b32 s48, v252, 12
	s_mov_b32 s49, 0x40000
	s_mov_b32 s50, 0x48000
	s_mov_b32 s51, 0x50000
	s_mov_b32 s66, 0x58000
	v_readlane_b32 s46, v249, 36
	v_readlane_b32 s47, v249, 37
	v_readlane_b32 s52, v249, 42
	v_readlane_b32 s53, v249, 43
	v_readlane_b32 s54, v249, 44
	v_readlane_b32 s55, v249, 45
	v_readlane_b32 s58, v249, 48
	v_readlane_b32 s59, v249, 49
	s_barrier
	s_branch .LBB0_924

; #define PG8_STAGE(bufoff, gbase, voff) do { _Pragma("unroll") for (int _i = 0; _i < 2; ++_i) \
;         __builtin_amdgcn_global_load_lds((const unsigned*)((const char*)(gbase) + (voff)[_i]), (PG8_LAS unsigned*)(lds + (bufoff) + ldsw + _i * 8192), 16, 0, AUX_A); } while (0)
; #define PG8_STAGEB(bufoff, gbase, voff) do { _Pragma("unroll") for (int _i = 0; _i < 2; ++_i) \
;         __builtin_amdgcn_global_load_lds((const unsigned*)((const char*)(gbase) + (voff)[_i]), (PG8_LAS unsigned*)(lds + (bufoff) + ldsw + _i * 8192), 16, 0, AUX_B); } while (0)
; #define PG8_WAIT_V(n) asm volatile("s_waitcnt vmcnt(" #n ")" ::: "memory")
; #define PG8_BAR __builtin_amdgcn_s_barrier()
; template <class Epi, class Sched, bool ALIGN_EPI = false, bool SP2 = false>
; __device__ __forceinline__ void gemm_phase(PG8_LAS unsigned char* lds, const Gemm g, const Sched& S, const Epi& E) {
;     ...
;         const bool has_next = S.next(ui + 1, nxt);
;         const char* nA = has_next ? (const char*)g.A + (size_t)nxt.pm * tstep + (size_t)nxt.kt0 * kstep : cA; const char* nB = has_next ? (const char*)g.Bt + (size_t)nxt.pn * tstep + (size_t)nxt.kt0 * kstep : cB;
;         const int nt = cur.nkt, rot = cur.krot;
;         const char* nAr = has_next ? nA + (size_t)nxt.krot * kstep : PG8_KP(cA, 0, rot, nt); const char* nBr = has_next ? nB + (size_t)nxt.krot * kstep : PG8_KP(cB, 0, rot, nt);
;         for (int t = 0; t < nt; t += 2) {
;             const bool last = (t == nt - 2);
;             const char* a1 = PG8_KP(cA, t + 1, rot, nt);
;             const char* a2 = last ? nAr : PG8_KP(cA, t + 2, rot, nt); const char* b2 = last ? nBr : PG8_KP(cB, t + 2, rot, nt);
;             const char* a3 = a2 + kstep; const char* b3 = b2 + kstep;
;             if (last && has_next) S.a_ready(nxt);
;             if constexpr (SP2) {
;             PG8_LDB(B0, 0, 0); PG8_LDB(B1, 0, 1); PG8_SCHED; PG8_LDA(At, 0, 0); PG8_STAGE(PG8_SA(1, 1), a1 + hstep, voffA);
;             PG8_WAIT_V(8); PG8_WAIT_L(0); PG8_BAR; PG8_MMA(0, 0, At, B0); PG8_MMA(0, 1, At, B1); PG8_BAR; PG8_SCHED;
;             PG8_LDA(At, 0, 1); PG8_STAGEB(PG8_SB(0, 0), b2, voffB); PG8_STAGEB(PG8_SB(0, 1), b2 + hstep, voffB); PG8_STAGE(PG8_SA(0, 0), a2, voffA);
;             PG8_WAIT_V(8); PG8_WAIT_L(0); PG8_BAR; PG8_MMA(1, 0, At, B0); PG8_MMA(1, 1, At, B1); PG8_BAR; PG8_SCHED;
;     ...
;         if constexpr (ALIGN_EPI) { if (wr == 1) PG8_BAR; }
.LBB0_935:
	s_mov_b32 s14, s1
	s_ashr_i32 s15, s1, 31
	s_mov_b32 s16, s0
	s_lshl_b64 s[0:1], s[14:15], 19
	s_add_u32 s38, s4, s0
	s_addc_u32 s39, s5, s1
	s_ashr_i32 s17, s16, 31
	s_lshl_b64 s[0:1], s[16:17], 19
	s_add_u32 s40, s30, s0
	s_addc_u32 s41, s31, s1
	s_and_b64 s[0:1], s[18:19], exec
	s_cselect_b32 s15, s39, s65
	s_cselect_b32 s17, s38, s64
	s_cselect_b32 s43, s41, s27
	s_cselect_b32 s78, s40, s26
	s_add_u32 s0, s64, 0x40080
	s_addc_u32 s1, s65, 0
	v_lshl_add_u64 v[14:15], s[0:1], 0, v[156:157]
	v_lshl_add_u64 v[16:17], s[0:1], 0, v[158:159]
	s_mov_b32 s29, 0
	s_waitcnt vmcnt(0)
	s_waitcnt lgkmcnt(0)
	s_waitcnt vmcnt(0)
	s_cmp_lg_u64 s[12:13], 0
	s_cbranch_scc1 .Lrp_936
	s_barrier
.Lrp_936:
.Lpk_936:
	s_add_i32 s81, s29, 2
	s_cmp_lt_u32 s29, 14
	s_cselect_b32 s0, 0, -16
	s_add_i32 s0, s81, s0
	s_ashr_i32 s1, s0, 31
	s_lshl_b64 s[0:1], s[0:1], 7
	s_add_u32 s2, s64, s0
	s_addc_u32 s46, s65, s1
	s_add_u32 s0, s26, s0
	s_addc_u32 s1, s27, s1
	s_cmp_eq_u32 s29, 14
	s_cselect_b32 s57, s15, s46
	s_cselect_b32 s56, s17, s2
	s_cselect_b32 s59, s43, s1
	s_cselect_b32 s58, s78, s0
	s_add_i32 s2, 0, 0x10000
	s_add_i32 s83, s2, s33
	s_add_i32 s46, 0, 0x14000
	s_add_i32 m0, s25, 0xc000
	s_add_i32 s82, s25, 0xe000
	s_add_i32 s84, s83, 0x2000
	s_add_u32 s60, s58, 0x40000
	s_addc_u32 s61, s59, 0
	s_add_i32 s88, s46, s33
	v_add_u32_e32 v160, s2, v99
	v_add_u32_e32 v166, s46, v99
	s_add_i32 s89, s88, 0x2000
	s_add_i32 s90, 0, 0x18000
	s_add_i32 s91, 0, 0x1c000
	ds_read_b128 v[22:25], v160
	ds_read_b128 v[34:37], v160 offset:1024
	ds_read_b128 v[38:41], v160 offset:2048
	ds_read_b128 v[160:163], v160 offset:3072
	ds_read_b128 v[180:183], v166
	ds_read_b128 v[184:187], v166 offset:1024
	ds_read_b128 v[188:191], v166 offset:2048
	ds_read_b128 v[192:195], v166 offset:3072
	s_add_u32 s54, s56, 0x40000
	s_addc_u32 s55, s57, 0
	s_add_i32 s1, s90, s33
	s_add_i32 s0, s1, 0x2000
	s_add_u32 s52, s58, 0x40080
	s_addc_u32 s53, s59, 0
	s_add_i32 s47, s91, s33
	s_add_i32 s46, s47, 0x2000
	s_cmp_gt_u32 s29, 13
	ds_read_b128 v[196:199], v165
	ds_read_b128 v[200:203], v165 offset:1024
	ds_read_b128 v[222:225], v165 offset:2048
	ds_read_b128 v[226:229], v165 offset:3072
	ds_read_b128 v[230:233], v165 offset:4096
	ds_read_b128 v[234:237], v165 offset:5120
	ds_read_b128 v[238:241], v165 offset:6144
	ds_read_b128 v[242:245], v165 offset:7168
	global_load_lds_dwordx4 v[16:17], off
	s_mov_b32 m0, s82
	s_nop 0
	global_load_lds_dwordx4 v[14:15], off
	s_waitcnt vmcnt(8)
	s_waitcnt lgkmcnt(0)
	s_setprio 1
	s_barrier
	v_mfma_f32_16x16x32_bf16 v[144:147], v[22:25], v[196:199], 0
	v_mfma_f32_16x16x32_bf16 v[144:147], v[34:37], v[200:203], v[144:147]
	v_mfma_f32_16x16x32_bf16 v[140:143], v[38:41], v[196:199], 0
	v_mfma_f32_16x16x32_bf16 v[140:143], v[160:163], v[200:203], v[140:143]
	v_mfma_f32_16x16x32_bf16 v[128:131], v[22:25], v[222:225], 0
	v_mfma_f32_16x16x32_bf16 v[128:131], v[34:37], v[226:229], v[128:131]
	v_mfma_f32_16x16x32_bf16 v[124:127], v[38:41], v[222:225], 0
	v_mfma_f32_16x16x32_bf16 v[124:127], v[160:163], v[226:229], v[124:127]
	v_mfma_f32_16x16x32_bf16 v[112:115], v[22:25], v[230:233], 0
	v_mfma_f32_16x16x32_bf16 v[112:115], v[34:37], v[234:237], v[112:115]
	v_mfma_f32_16x16x32_bf16 v[108:111], v[38:41], v[230:233], 0
	v_mfma_f32_16x16x32_bf16 v[108:111], v[160:163], v[234:237], v[108:111]
	v_mfma_f32_16x16x32_bf16 v[94:97], v[22:25], v[238:241], 0
	v_mfma_f32_16x16x32_bf16 v[94:97], v[34:37], v[242:245], v[94:97]
	v_mfma_f32_16x16x32_bf16 v[90:93], v[38:41], v[238:241], 0
	v_mfma_f32_16x16x32_bf16 v[90:93], v[160:163], v[242:245], v[90:93]
	s_setprio 0
	s_setprio 1
	v_mfma_f32_16x16x32_bf16 v[136:139], v[180:183], v[196:199], 0
	v_mfma_f32_16x16x32_bf16 v[136:139], v[184:187], v[200:203], v[136:139]
	v_mfma_f32_16x16x32_bf16 v[132:135], v[188:191], v[196:199], 0
	v_mfma_f32_16x16x32_bf16 v[132:135], v[192:195], v[200:203], v[132:135]
	v_mfma_f32_16x16x32_bf16 v[120:123], v[180:183], v[222:225], 0
	v_mfma_f32_16x16x32_bf16 v[120:123], v[184:187], v[226:229], v[120:123]
	v_mfma_f32_16x16x32_bf16 v[116:119], v[188:191], v[222:225], 0
	v_mfma_f32_16x16x32_bf16 v[116:119], v[192:195], v[226:229], v[116:119]
	v_mfma_f32_16x16x32_bf16 v[104:107], v[180:183], v[230:233], 0
	v_mfma_f32_16x16x32_bf16 v[104:107], v[184:187], v[234:237], v[104:107]
	v_mfma_f32_16x16x32_bf16 v[100:103], v[188:191], v[230:233], 0
	v_mfma_f32_16x16x32_bf16 v[100:103], v[192:195], v[234:237], v[100:103]
	v_mfma_f32_16x16x32_bf16 v[86:89], v[180:183], v[238:241], 0
	v_mfma_f32_16x16x32_bf16 v[86:89], v[184:187], v[242:245], v[86:89]
	s_setprio 2
	s_barrier
	v_mfma_f32_16x16x32_bf16 v[82:85], v[188:191], v[238:241], 0
	v_mfma_f32_16x16x32_bf16 v[82:85], v[192:195], v[242:245], v[82:85]
	s_setprio 0
	s_mov_b32 m0, s83
	v_lshl_add_u64 v[166:167], s[58:59], 0, v[150:151]
	ds_read_b128 v[196:199], v165 offset:16384
	ds_read_b128 v[200:203], v165 offset:17408
	ds_read_b128 v[222:225], v165 offset:18432
	ds_read_b128 v[226:229], v165 offset:19456
	ds_read_b128 v[230:233], v165 offset:20480
	ds_read_b128 v[234:237], v165 offset:21504
	ds_read_b128 v[238:241], v165 offset:22528
	ds_read_b128 v[242:245], v165 offset:23552
	global_load_lds_dwordx4 v[166:167], off
	v_lshl_add_u64 v[168:169], s[58:59], 0, v[154:155]
	s_mov_b32 m0, s84
	v_lshl_add_u64 v[172:173], s[60:61], 0, v[150:151]
	global_load_lds_dwordx4 v[168:169], off
	s_mov_b32 m0, s88
	v_lshl_add_u64 v[212:213], s[56:57], 0, v[152:153]
	global_load_lds_dwordx4 v[172:173], off
	v_lshl_add_u64 v[172:173], s[60:61], 0, v[154:155]
	s_mov_b32 m0, s89
	s_nop 0
	global_load_lds_dwordx4 v[172:173], off
	v_lshl_add_u64 v[172:173], s[56:57], 0, v[148:149]
	s_mov_b32 m0, s25
	s_nop 0
	global_load_lds_dwordx4 v[172:173], off
	s_mov_b32 m0, s62
	s_nop 0
	global_load_lds_dwordx4 v[212:213], off
	s_waitcnt vmcnt(8)
	s_waitcnt lgkmcnt(0)
	s_setprio 1
	s_barrier
; #define PG8_STAGE(bufoff, gbase, voff) do { _Pragma("unroll") for (int _i = 0; _i < 2; ++_i) \
;         __builtin_amdgcn_global_load_lds((const unsigned*)((const char*)(gbase) + (voff)[_i]), (PG8_LAS unsigned*)(lds + (bufoff) + ldsw + _i * 8192), 16, 0, AUX_A); } while (0)
; #define PG8_LDA(dst, b, h) do { _Pragma("unroll") for (int m = 0; m < 4; ++m) _Pragma("unroll") for (int k = 0; k < 2; ++k) dst[m][k] = *(const PG8_LAS bf16x8*)(lds + PG8_SA(b, h) + aoff + m * 2048 + k * 1024); } while (0)
; #define PG8_LDB(dst, b, h) do { _Pragma("unroll") for (int n = 0; n < 2; ++n) _Pragma("unroll") for (int k = 0; k < 2; ++k) dst[n][k] = *(const PG8_LAS bf16x8*)(lds + PG8_SB(b, h) + boff + n * 2048 + k * 1024); } while (0)
; #define PG8_MMA(ai, bj, At, Bt) do { __builtin_amdgcn_s_setprio(1); _Pragma("unroll") for (int m = 0; m < 4; ++m) _Pragma("unroll") for (int n = 0; n < 2; ++n) _Pragma("unroll") for (int k = 0; k < 2; ++k) \
;         acc[ai][bj][m][n] = __builtin_amdgcn_mfma_f32_16x16x32_bf16(Bt[n][k], At[m][k], acc[ai][bj][m][n], 0, 0, 0); __builtin_amdgcn_s_setprio(0); } while (0)
; #define PG8_WAIT_V(n) asm volatile("s_waitcnt vmcnt(" #n ")" ::: "memory")
; #define PG8_WAIT_L(n) asm volatile("s_waitcnt lgkmcnt(" #n ")" ::: "memory")
; #define PG8_BAR __builtin_amdgcn_s_barrier()
; #define PG8_SCHED __builtin_amdgcn_sched_barrier(0)
; template <class Epi, class Sched, bool ALIGN_EPI = false, bool SP2 = false>
; __device__ __forceinline__ void gemm_phase(PG8_LAS unsigned char* lds, const Gemm g, const Sched& S, const Epi& E) {
;     ...
;             PG8_WAIT_V(8); PG8_WAIT_L(0); PG8_BAR; PG8_MMA(1, 0, At, B0); PG8_MMA(1, 1, At, B1); PG8_BAR; PG8_SCHED;
;             PG8_LDB(B0, 1, 0); PG8_LDB(B1, 1, 1); PG8_SCHED; PG8_LDA(At, 1, 0); PG8_STAGE(PG8_SA(0, 1), a2 + hstep, voffA);
;             PG8_WAIT_V(8); PG8_WAIT_L(0); PG8_BAR; PG8_MMA(0, 0, At, B0); PG8_MMA(0, 1, At, B1); PG8_BAR; PG8_SCHED;
	v_mfma_f32_16x16x32_bf16 v[78:81], v[22:25], v[196:199], 0
	v_mfma_f32_16x16x32_bf16 v[78:81], v[34:37], v[200:203], v[78:81]
	v_mfma_f32_16x16x32_bf16 v[74:77], v[38:41], v[196:199], 0
	v_mfma_f32_16x16x32_bf16 v[74:77], v[160:163], v[200:203], v[74:77]
	v_mfma_f32_16x16x32_bf16 v[62:65], v[22:25], v[222:225], 0
	v_mfma_f32_16x16x32_bf16 v[62:65], v[34:37], v[226:229], v[62:65]
	v_mfma_f32_16x16x32_bf16 v[58:61], v[38:41], v[222:225], 0
	v_mfma_f32_16x16x32_bf16 v[58:61], v[160:163], v[226:229], v[58:61]
	v_mfma_f32_16x16x32_bf16 v[46:49], v[22:25], v[230:233], 0
	v_mfma_f32_16x16x32_bf16 v[46:49], v[34:37], v[234:237], v[46:49]
	v_mfma_f32_16x16x32_bf16 v[42:45], v[38:41], v[230:233], 0
	v_mfma_f32_16x16x32_bf16 v[42:45], v[160:163], v[234:237], v[42:45]
	v_mfma_f32_16x16x32_bf16 v[18:21], v[22:25], v[238:241], 0
	v_mfma_f32_16x16x32_bf16 v[18:21], v[34:37], v[242:245], v[18:21]
	v_mfma_f32_16x16x32_bf16 v[10:13], v[38:41], v[238:241], 0
	v_mfma_f32_16x16x32_bf16 v[10:13], v[160:163], v[242:245], v[10:13]
	s_setprio 0
	s_setprio 1
	v_mfma_f32_16x16x32_bf16 v[50:53], v[188:191], v[222:225], 0
	v_mfma_f32_16x16x32_bf16 v[30:33], v[180:183], v[230:233], 0
	v_mfma_f32_16x16x32_bf16 v[26:29], v[188:191], v[230:233], 0
	v_mfma_f32_16x16x32_bf16 v[6:9], v[180:183], v[238:241], 0
	v_mfma_f32_16x16x32_bf16 v[2:5], v[188:191], v[238:241], 0
	v_mfma_f32_16x16x32_bf16 v[22:25], v[180:183], v[196:199], 0
	v_mfma_f32_16x16x32_bf16 v[34:37], v[188:191], v[196:199], 0
	v_mfma_f32_16x16x32_bf16 v[38:41], v[180:183], v[222:225], 0
	v_mfma_f32_16x16x32_bf16 v[50:53], v[192:195], v[226:229], v[50:53]
	v_mfma_f32_16x16x32_bf16 v[30:33], v[184:187], v[234:237], v[30:33]
	v_mfma_f32_16x16x32_bf16 v[26:29], v[192:195], v[234:237], v[26:29]
	v_mfma_f32_16x16x32_bf16 v[6:9], v[184:187], v[242:245], v[6:9]
	v_mfma_f32_16x16x32_bf16 v[2:5], v[192:195], v[242:245], v[2:5]
	v_mfma_f32_16x16x32_bf16 v[22:25], v[184:187], v[200:203], v[22:25]
	s_setprio 2
	s_barrier
	v_mfma_f32_16x16x32_bf16 v[34:37], v[192:195], v[200:203], v[34:37]
	v_mfma_f32_16x16x32_bf16 v[38:41], v[184:187], v[226:229], v[38:41]
	s_setprio 0
	v_add_u32_e32 v160, s90, v99
	v_add_u32_e32 v192, s91, v99
	ds_read_b128 v[54:57], v160
	ds_read_b128 v[66:69], v160 offset:1024
	ds_read_b128 v[70:73], v160 offset:2048
	ds_read_b128 v[160:163], v160 offset:3072
	ds_read_b128 v[180:183], v192
	ds_read_b128 v[184:187], v192 offset:1024
	ds_read_b128 v[188:191], v192 offset:2048
	ds_read_b128 v[192:195], v192 offset:3072
	s_mov_b32 m0, s63
	v_lshl_add_u64 v[246:247], s[54:55], 0, v[148:149]
	ds_read_b128 v[196:199], v165 offset:32768
	ds_read_b128 v[200:203], v165 offset:33792
	ds_read_b128 v[222:225], v165 offset:34816
	ds_read_b128 v[226:229], v165 offset:35840
	ds_read_b128 v[230:233], v165 offset:36864
	ds_read_b128 v[234:237], v165 offset:37888
	ds_read_b128 v[238:241], v165 offset:38912
	ds_read_b128 v[242:245], v165 offset:39936
	global_load_lds_dwordx4 v[246:247], off
	v_lshl_add_u64 v[246:247], s[54:55], 0, v[152:153]
	s_mov_b32 m0, s69
	s_nop 0
	global_load_lds_dwordx4 v[246:247], off
	s_waitcnt vmcnt(8)
	s_waitcnt lgkmcnt(0)
	s_setprio 1
	s_barrier
	v_mfma_f32_16x16x32_bf16 v[144:147], v[54:57], v[196:199], v[144:147]
	v_mfma_f32_16x16x32_bf16 v[144:147], v[66:69], v[200:203], v[144:147]
	v_mfma_f32_16x16x32_bf16 v[140:143], v[70:73], v[196:199], v[140:143]
	v_mfma_f32_16x16x32_bf16 v[140:143], v[160:163], v[200:203], v[140:143]
	v_mfma_f32_16x16x32_bf16 v[128:131], v[54:57], v[222:225], v[128:131]
	v_mfma_f32_16x16x32_bf16 v[128:131], v[66:69], v[226:229], v[128:131]
	v_mfma_f32_16x16x32_bf16 v[124:127], v[70:73], v[222:225], v[124:127]
	v_mfma_f32_16x16x32_bf16 v[124:127], v[160:163], v[226:229], v[124:127]
	v_mfma_f32_16x16x32_bf16 v[112:115], v[54:57], v[230:233], v[112:115]
	v_mfma_f32_16x16x32_bf16 v[112:115], v[66:69], v[234:237], v[112:115]
	v_mfma_f32_16x16x32_bf16 v[108:111], v[70:73], v[230:233], v[108:111]
	v_mfma_f32_16x16x32_bf16 v[108:111], v[160:163], v[234:237], v[108:111]
	v_mfma_f32_16x16x32_bf16 v[94:97], v[54:57], v[238:241], v[94:97]
	v_mfma_f32_16x16x32_bf16 v[94:97], v[66:69], v[242:245], v[94:97]
	v_mfma_f32_16x16x32_bf16 v[90:93], v[70:73], v[238:241], v[90:93]
	v_mfma_f32_16x16x32_bf16 v[90:93], v[160:163], v[242:245], v[90:93]
	s_setprio 0
	s_setprio 1
	v_mfma_f32_16x16x32_bf16 v[136:139], v[180:183], v[196:199], v[136:139]
	v_mfma_f32_16x16x32_bf16 v[136:139], v[184:187], v[200:203], v[136:139]
	v_mfma_f32_16x16x32_bf16 v[132:135], v[188:191], v[196:199], v[132:135]
	v_mfma_f32_16x16x32_bf16 v[132:135], v[192:195], v[200:203], v[132:135]
	v_mfma_f32_16x16x32_bf16 v[120:123], v[180:183], v[222:225], v[120:123]
	v_mfma_f32_16x16x32_bf16 v[120:123], v[184:187], v[226:229], v[120:123]
	v_mfma_f32_16x16x32_bf16 v[116:119], v[188:191], v[222:225], v[116:119]
	v_mfma_f32_16x16x32_bf16 v[116:119], v[192:195], v[226:229], v[116:119]
	v_mfma_f32_16x16x32_bf16 v[104:107], v[180:183], v[230:233], v[104:107]
	v_mfma_f32_16x16x32_bf16 v[104:107], v[184:187], v[234:237], v[104:107]
	v_mfma_f32_16x16x32_bf16 v[100:103], v[188:191], v[230:233], v[100:103]
	v_mfma_f32_16x16x32_bf16 v[100:103], v[192:195], v[234:237], v[100:103]
	v_mfma_f32_16x16x32_bf16 v[86:89], v[180:183], v[238:241], v[86:89]
	v_mfma_f32_16x16x32_bf16 v[86:89], v[184:187], v[242:245], v[86:89]
	s_setprio 2
	s_barrier
; #define PG8_STAGE(bufoff, gbase, voff) do { _Pragma("unroll") for (int _i = 0; _i < 2; ++_i) \
;         __builtin_amdgcn_global_load_lds((const unsigned*)((const char*)(gbase) + (voff)[_i]), (PG8_LAS unsigned*)(lds + (bufoff) + ldsw + _i * 8192), 16, 0, AUX_A); } while (0)
; #define PG8_STAGEB(bufoff, gbase, voff) do { _Pragma("unroll") for (int _i = 0; _i < 2; ++_i) \
;         __builtin_amdgcn_global_load_lds((const unsigned*)((const char*)(gbase) + (voff)[_i]), (PG8_LAS unsigned*)(lds + (bufoff) + ldsw + _i * 8192), 16, 0, AUX_B); } while (0)
; #define PG8_LDA(dst, b, h) do { _Pragma("unroll") for (int m = 0; m < 4; ++m) _Pragma("unroll") for (int k = 0; k < 2; ++k) dst[m][k] = *(const PG8_LAS bf16x8*)(lds + PG8_SA(b, h) + aoff + m * 2048 + k * 1024); } while (0)
; #define PG8_MMA(ai, bj, At, Bt) do { __builtin_amdgcn_s_setprio(1); _Pragma("unroll") for (int m = 0; m < 4; ++m) _Pragma("unroll") for (int n = 0; n < 2; ++n) _Pragma("unroll") for (int k = 0; k < 2; ++k) \
;         acc[ai][bj][m][n] = __builtin_amdgcn_mfma_f32_16x16x32_bf16(Bt[n][k], At[m][k], acc[ai][bj][m][n], 0, 0, 0); __builtin_amdgcn_s_setprio(0); } while (0)
; #define PG8_WAIT_V(n) asm volatile("s_waitcnt vmcnt(" #n ")" ::: "memory")
; #define PG8_WAIT_L(n) asm volatile("s_waitcnt lgkmcnt(" #n ")" ::: "memory")
; #define PG8_BAR __builtin_amdgcn_s_barrier()
; #define PG8_SCHED __builtin_amdgcn_sched_barrier(0)
; template <class Epi, class Sched, bool ALIGN_EPI = false, bool SP2 = false>
; __device__ __forceinline__ void gemm_phase(PG8_LAS unsigned char* lds, const Gemm g, const Sched& S, const Epi& E) {
;     ...
;             PG8_LDA(At, 1, 1); PG8_STAGEB(PG8_SB(1, 0), b3, voffB); PG8_STAGEB(PG8_SB(1, 1), b3 + hstep, voffB); PG8_STAGE(PG8_SA(1, 0), a3, voffA);
;             PG8_WAIT_V(8); PG8_WAIT_L(0); PG8_BAR; PG8_MMA(1, 0, At, B0); PG8_MMA(1, 1, At, B1); PG8_BAR; PG8_SCHED;
	v_mfma_f32_16x16x32_bf16 v[82:85], v[188:191], v[238:241], v[82:85]
	v_mfma_f32_16x16x32_bf16 v[82:85], v[192:195], v[242:245], v[82:85]
	s_setprio 0
	s_mov_b32 m0, s1
	v_lshl_add_u64 v[166:167], v[166:167], 0, s[76:77]
	ds_read_b128 v[196:199], v165 offset:49152
	ds_read_b128 v[200:203], v165 offset:50176
	ds_read_b128 v[222:225], v165 offset:51200
	ds_read_b128 v[226:229], v165 offset:52224
	ds_read_b128 v[230:233], v165 offset:53248
	ds_read_b128 v[234:237], v165 offset:54272
	ds_read_b128 v[238:241], v165 offset:55296
	ds_read_b128 v[242:245], v165 offset:56320
	global_load_lds_dwordx4 v[166:167], off
	v_lshl_add_u64 v[166:167], v[168:169], 0, s[76:77]
	s_mov_b32 m0, s0
	s_nop 0
	global_load_lds_dwordx4 v[166:167], off
	v_lshl_add_u64 v[166:167], s[52:53], 0, v[150:151]
	s_mov_b32 m0, s47
	s_nop 0
	global_load_lds_dwordx4 v[166:167], off
	v_lshl_add_u64 v[166:167], s[52:53], 0, v[154:155]
	s_mov_b32 m0, s46
	s_nop 0
	global_load_lds_dwordx4 v[166:167], off
	v_lshl_add_u64 v[166:167], v[172:173], 0, s[76:77]
	s_mov_b32 m0, s70
	s_nop 0
	global_load_lds_dwordx4 v[166:167], off
	v_lshl_add_u64 v[166:167], v[212:213], 0, s[76:77]
	s_mov_b32 m0, s71
	s_nop 0
	global_load_lds_dwordx4 v[166:167], off
	s_waitcnt vmcnt(8)
	s_waitcnt lgkmcnt(0)
	s_setprio 1
	s_barrier
	v_mfma_f32_16x16x32_bf16 v[78:81], v[54:57], v[196:199], v[78:81]
	v_mfma_f32_16x16x32_bf16 v[78:81], v[66:69], v[200:203], v[78:81]
	v_mfma_f32_16x16x32_bf16 v[74:77], v[70:73], v[196:199], v[74:77]
	v_mfma_f32_16x16x32_bf16 v[74:77], v[160:163], v[200:203], v[74:77]
	v_mfma_f32_16x16x32_bf16 v[62:65], v[54:57], v[222:225], v[62:65]
	v_mfma_f32_16x16x32_bf16 v[62:65], v[66:69], v[226:229], v[62:65]
	v_mfma_f32_16x16x32_bf16 v[58:61], v[70:73], v[222:225], v[58:61]
	v_mfma_f32_16x16x32_bf16 v[58:61], v[160:163], v[226:229], v[58:61]
	v_mfma_f32_16x16x32_bf16 v[46:49], v[54:57], v[230:233], v[46:49]
	v_mfma_f32_16x16x32_bf16 v[46:49], v[66:69], v[234:237], v[46:49]
	v_mfma_f32_16x16x32_bf16 v[42:45], v[70:73], v[230:233], v[42:45]
	v_mfma_f32_16x16x32_bf16 v[42:45], v[160:163], v[234:237], v[42:45]
	v_mfma_f32_16x16x32_bf16 v[18:21], v[54:57], v[238:241], v[18:21]
	v_mfma_f32_16x16x32_bf16 v[18:21], v[66:69], v[242:245], v[18:21]
	v_mfma_f32_16x16x32_bf16 v[10:13], v[70:73], v[238:241], v[10:13]
	v_mfma_f32_16x16x32_bf16 v[10:13], v[160:163], v[242:245], v[10:13]
	s_setprio 0
	s_setprio 1
	v_mfma_f32_16x16x32_bf16 v[22:25], v[180:183], v[196:199], v[22:25]
	v_mfma_f32_16x16x32_bf16 v[70:73], v[184:187], v[200:203], v[22:25]
	v_mfma_f32_16x16x32_bf16 v[22:25], v[188:191], v[196:199], v[34:37]
	v_mfma_f32_16x16x32_bf16 v[66:69], v[192:195], v[200:203], v[22:25]
	v_mfma_f32_16x16x32_bf16 v[22:25], v[180:183], v[222:225], v[38:41]
	v_mfma_f32_16x16x32_bf16 v[54:57], v[184:187], v[226:229], v[22:25]
	v_mfma_f32_16x16x32_bf16 v[22:25], v[188:191], v[222:225], v[50:53]
	v_mfma_f32_16x16x32_bf16 v[50:53], v[192:195], v[226:229], v[22:25]
	v_mfma_f32_16x16x32_bf16 v[22:25], v[180:183], v[230:233], v[30:33]
	v_mfma_f32_16x16x32_bf16 v[30:33], v[184:187], v[234:237], v[22:25]
	v_mfma_f32_16x16x32_bf16 v[22:25], v[188:191], v[230:233], v[26:29]
	v_mfma_f32_16x16x32_bf16 v[6:9], v[180:183], v[238:241], v[6:9]
	v_mfma_f32_16x16x32_bf16 v[2:5], v[188:191], v[238:241], v[2:5]
	v_mfma_f32_16x16x32_bf16 v[26:29], v[192:195], v[234:237], v[22:25]
	s_setprio 2
	s_barrier
	v_mfma_f32_16x16x32_bf16 v[6:9], v[184:187], v[242:245], v[6:9]
	v_mfma_f32_16x16x32_bf16 v[2:5], v[192:195], v[242:245], v[2:5]
	s_setprio 0
	v_lshl_add_u64 v[14:15], v[14:15], 0, s[86:87]
	v_lshl_add_u64 v[16:17], v[16:17], 0, s[86:87]
	s_mov_b32 s29, s81
	s_cbranch_scc1 .Lpx_936

; #define GAS __attribute__((address_space(1)))
; __device__ __forceinline__ u32x4 pack8(f32x4 v0, f32x4 v1) { u32x4 w; w.x = cvt_pk_bf16(v0[0], v0[1]); w.y = cvt_pk_bf16(v0[2], v0[3]); w.z = cvt_pk_bf16(v1[0], v1[1]); w.w = cvt_pk_bf16(v1[2], v1[3]); return w; }
; __device__ __forceinline__ void unpack8(u32x4 w, f32x4& v0, f32x4& v1) { v0 = (f32x4){bflo(w.x), bfhi(w.x), bflo(w.y), bfhi(w.y)}; v1 = (f32x4){bflo(w.z), bfhi(w.z), bflo(w.w), bfhi(w.w)}; }
; #define GAS __attribute__((address_space(1)))
; __device__ __forceinline__ f32x4 sigmoid4(f32x4 v) {
;     const f32x2 t0 = (f32x2){v[0], v[1]} * -1.4426950408889634f, t1 = (f32x2){v[2], v[3]} * -1.4426950408889634f;
;     const f32x2 d0 = (f32x2){__builtin_amdgcn_exp2f(t0.x), __builtin_amdgcn_exp2f(t0.y)} + 1.0f, d1 = (f32x2){__builtin_amdgcn_exp2f(t1.x), __builtin_amdgcn_exp2f(t1.y)} + 1.0f;
;     return (f32x4){__builtin_amdgcn_rcpf(d0.x), __builtin_amdgcn_rcpf(d0.y), __builtin_amdgcn_rcpf(d1.x), __builtin_amdgcn_rcpf(d1.y)}; }
;     __device__ __forceinline__ void operator()(const f32x4 (&acc)[2][2][4][2], const Unit& u, int wr, int wc, int fr, int fq) const {
;         const int row0 = u.pm * BM + wr * 64 + fr, col0 = u.pn * BM + wc * 32 + 8 * fq;
;         f32x4 bv[2][2];
; #pragma unroll
;         for (int bj = 0; bj < 2; ++bj)
; #pragma unroll
;             for (int n = 0; n < 2; ++n) bv[bj][n] = *(const f32x4*)(bglu + col0 + bj * HALF + 4 * n);
;         const bf16_t* const zb = Z + (size_t)row0 * 1024 + col0; bf16_t* const sob = SO + (size_t)row0 * 1024 + col0;
; #pragma unroll
;         for (int ai = 0; ai < 2; ++ai)
; #pragma unroll
;             for (int m = 0; m < 4; ++m) { const size_t off = (size_t)(ai * HALF + m * 16) * 1024;
; #pragma unroll
;                 for (int bj = 0; bj < 2; ++bj) { f32x4 z0, z1; unpack8(*(const GAS u32x4*)(zb + off + bj * HALF), z0, z1);
;                     const f32x4 v0 = z0 * sigmoid4(acc[ai][bj][m][0] + bv[bj][0]), v1 = z1 * sigmoid4(acc[ai][bj][m][1] + bv[bj][1]);
;                     *(GAS u32x4*)(sob + off + bj * HALF) = pack8(v0, v1); } }
;     }
.LBB0_939:
	v_lshl_or_b32 v160, s24, 8, v164
	v_ashrrev_i32_e32 v161, 31, v160
	v_lshl_add_u64 v[22:23], v[160:161], 2, s[8:9]
	global_load_dwordx4 v[34:37], v[22:23], off offset:16
	global_load_dwordx4 v[38:41], v[22:23], off
	global_load_dwordx4 v[14:17], v[22:23], off offset:528
	s_nop 0
	global_load_dwordx4 v[22:25], v[22:23], off offset:512
	v_lshl_add_u32 v162, s42, 8, v1
	v_ashrrev_i32_e32 v163, 31, v162
	v_lshlrev_b64 v[166:167], 11, v[162:163]
	v_lshl_add_u64 v[162:163], s[4:5], 0, v[166:167]
	v_lshlrev_b64 v[160:161], 1, v[160:161]
	v_lshl_add_u64 v[162:163], v[162:163], 0, v[160:161]
	global_load_dwordx4 v[184:187], v[162:163], off
	global_load_dwordx4 v[188:191], v[162:163], off offset:256
	v_add_co_u32_e32 v242, vcc, s94, v162
	v_addc_co_u32_e32 v243, vcc, 0, v163, vcc
	global_load_dwordx4 v[192:195], v[242:243], off
	global_load_dwordx4 v[196:199], v[242:243], off offset:256
	v_add_co_u32_e32 v242, vcc, s73, v162
	v_addc_co_u32_e32 v243, vcc, 0, v163, vcc
	global_load_dwordx4 v[200:203], v[242:243], off
	global_load_dwordx4 v[222:225], v[242:243], off offset:256
	v_add_co_u32_e32 v242, vcc, s93, v162
	v_addc_co_u32_e32 v243, vcc, 0, v163, vcc
	global_load_dwordx4 v[226:229], v[242:243], off
	global_load_dwordx4 v[230:233], v[242:243], off offset:256
	v_add_co_u32_e32 v242, vcc, s49, v162
	v_addc_co_u32_e32 v243, vcc, 0, v163, vcc
	global_load_dwordx4 v[234:237], v[242:243], off
	global_load_dwordx4 v[238:241], v[242:243], off offset:256
	v_lshl_add_u64 v[166:167], s[10:11], 0, v[166:167]
	v_lshl_add_u64 v[160:161], v[166:167], 0, v[160:161]
	v_readlane_b32 s90, v254, 50
	s_mov_b64 s[42:43], -1
	v_readlane_b32 s91, v254, 51
	s_waitcnt vmcnt(9)
	v_mov_b32_e32 v180, v184
	v_mov_b32_e32 v181, v185
	v_mov_b32_e32 v182, v186
	v_mov_b32_e32 v183, v187
	v_add_co_u32_e32 v242, vcc, s50, v162
	v_addc_co_u32_e32 v243, vcc, 0, v163, vcc
	global_load_dwordx4 v[184:187], v[242:243], off
	v_pk_add_f32 v[142:143], v[142:143], v[36:37]
	v_pk_add_f32 v[146:147], v[146:147], v[40:41]
	v_pk_add_f32 v[144:145], v[144:145], v[38:39]
	v_pk_add_f32 v[140:141], v[140:141], v[34:35]
	v_pk_mul_f32 v[144:145], v[144:145], s[74:75] op_sel_hi:[1,0]
	v_pk_mul_f32 v[146:147], v[146:147], s[74:75] op_sel_hi:[1,0]
	v_pk_mul_f32 v[140:141], v[140:141], s[74:75] op_sel_hi:[1,0]
	v_pk_mul_f32 v[142:143], v[142:143], s[74:75] op_sel_hi:[1,0]
	v_exp_f32_e32 v144, v144
	v_exp_f32_e32 v145, v145
	v_exp_f32_e32 v146, v146
	v_exp_f32_e32 v147, v147
	v_exp_f32_e32 v140, v140
	v_exp_f32_e32 v141, v141
	v_exp_f32_e32 v142, v142
	v_exp_f32_e32 v143, v143
	v_pk_add_f32 v[144:145], v[144:145], 1.0 op_sel_hi:[1,0]
	v_pk_add_f32 v[146:147], v[146:147], 1.0 op_sel_hi:[1,0]
	v_pk_add_f32 v[140:141], v[140:141], 1.0 op_sel_hi:[1,0]
	v_pk_add_f32 v[142:143], v[142:143], 1.0 op_sel_hi:[1,0]
	v_rcp_f32_e32 v144, v144
	v_rcp_f32_e32 v145, v145
	v_rcp_f32_e32 v146, v146
	v_rcp_f32_e32 v147, v147
	v_rcp_f32_e32 v140, v140
	v_rcp_f32_e32 v141, v141
	v_rcp_f32_e32 v142, v142
	v_rcp_f32_e32 v143, v143
	v_lshlrev_b32_e32 v166, 16, v180
	v_and_b32_e32 v167, 0xffff0000, v180
	v_lshlrev_b32_e32 v168, 16, v181
	v_and_b32_e32 v169, 0xffff0000, v181
	v_lshlrev_b32_e32 v172, 16, v182
	v_and_b32_e32 v173, 0xffff0000, v182
	v_lshlrev_b32_e32 v180, 16, v183
	v_and_b32_e32 v181, 0xffff0000, v183
	v_pk_mul_f32 v[146:147], v[146:147], v[168:169]
	v_pk_mul_f32 v[144:145], v[144:145], v[166:167]
	v_pk_mul_f32 v[166:167], v[142:143], v[180:181]
	v_pk_mul_f32 v[142:143], v[140:141], v[172:173]
	v_cvt_pk_bf16_f32 v140, v144, v145
	v_cvt_pk_bf16_f32 v141, v146, v147
	v_cvt_pk_bf16_f32 v142, v142, v143
	v_cvt_pk_bf16_f32 v143, v166, v167
	global_store_dwordx4 v[160:161], v[140:143], off
	v_pk_add_f32 v[138:139], v[138:139], v[24:25]
	v_pk_add_f32 v[136:137], v[136:137], v[22:23]
	v_pk_add_f32 v[134:135], v[134:135], v[16:17]
	v_pk_add_f32 v[132:133], v[132:133], v[14:15]
	v_pk_mul_f32 v[136:137], v[136:137], s[74:75] op_sel_hi:[1,0]
	v_pk_mul_f32 v[138:139], v[138:139], s[74:75] op_sel_hi:[1,0]
	v_pk_mul_f32 v[132:133], v[132:133], s[74:75] op_sel_hi:[1,0]
	v_pk_mul_f32 v[134:135], v[134:135], s[74:75] op_sel_hi:[1,0]
	v_exp_f32_e32 v136, v136
	v_exp_f32_e32 v137, v137
	v_exp_f32_e32 v138, v138
	v_exp_f32_e32 v139, v139
	v_exp_f32_e32 v132, v132
	v_exp_f32_e32 v133, v133
	v_exp_f32_e32 v134, v134
	v_exp_f32_e32 v135, v135
	v_pk_add_f32 v[136:137], v[136:137], 1.0 op_sel_hi:[1,0]
	v_pk_add_f32 v[138:139], v[138:139], 1.0 op_sel_hi:[1,0]
	v_pk_add_f32 v[132:133], v[132:133], 1.0 op_sel_hi:[1,0]
	v_pk_add_f32 v[134:135], v[134:135], 1.0 op_sel_hi:[1,0]
	v_rcp_f32_e32 v136, v136
	v_rcp_f32_e32 v137, v137
	v_rcp_f32_e32 v138, v138
	v_rcp_f32_e32 v139, v139
	v_rcp_f32_e32 v132, v132
	v_rcp_f32_e32 v133, v133
	v_rcp_f32_e32 v134, v134
	v_rcp_f32_e32 v135, v135
	v_pk_add_f32 v[128:129], v[128:129], v[38:39]
	v_pk_add_f32 v[124:125], v[124:125], v[34:35]
	v_pk_add_f32 v[130:131], v[130:131], v[40:41]
	v_pk_mul_f32 v[128:129], v[128:129], s[74:75] op_sel_hi:[1,0]
	v_pk_add_f32 v[126:127], v[126:127], v[36:37]
	v_pk_mul_f32 v[124:125], v[124:125], s[74:75] op_sel_hi:[1,0]
	v_pk_mul_f32 v[130:131], v[130:131], s[74:75] op_sel_hi:[1,0]
	v_exp_f32_e32 v128, v128
	v_exp_f32_e32 v129, v129
	v_pk_mul_f32 v[126:127], v[126:127], s[74:75] op_sel_hi:[1,0]
	v_exp_f32_e32 v124, v124
	v_exp_f32_e32 v125, v125
	v_exp_f32_e32 v130, v130
	v_exp_f32_e32 v131, v131
	v_exp_f32_e32 v126, v126
	v_exp_f32_e32 v127, v127
	v_pk_add_f32 v[128:129], v[128:129], 1.0 op_sel_hi:[1,0]
	v_pk_add_f32 v[124:125], v[124:125], 1.0 op_sel_hi:[1,0]
	v_pk_add_f32 v[130:131], v[130:131], 1.0 op_sel_hi:[1,0]
	v_rcp_f32_e32 v128, v128
	v_rcp_f32_e32 v129, v129
	v_pk_add_f32 v[126:127], v[126:127], 1.0 op_sel_hi:[1,0]
	v_rcp_f32_e32 v124, v124
	v_rcp_f32_e32 v125, v125
	v_rcp_f32_e32 v130, v130
	v_rcp_f32_e32 v131, v131
	v_rcp_f32_e32 v126, v126
	v_rcp_f32_e32 v127, v127
	v_pk_add_f32 v[122:123], v[122:123], v[24:25]
	v_pk_add_f32 v[120:121], v[120:121], v[22:23]
	v_pk_add_f32 v[118:119], v[118:119], v[16:17]
	v_pk_add_f32 v[116:117], v[116:117], v[14:15]
	v_pk_mul_f32 v[120:121], v[120:121], s[74:75] op_sel_hi:[1,0]
	v_pk_mul_f32 v[122:123], v[122:123], s[74:75] op_sel_hi:[1,0]
	v_pk_mul_f32 v[116:117], v[116:117], s[74:75] op_sel_hi:[1,0]
	v_pk_mul_f32 v[118:119], v[118:119], s[74:75] op_sel_hi:[1,0]
	v_exp_f32_e32 v120, v120
	v_exp_f32_e32 v121, v121
	v_exp_f32_e32 v122, v122
	v_exp_f32_e32 v123, v123
	v_exp_f32_e32 v116, v116
	v_exp_f32_e32 v117, v117
	v_exp_f32_e32 v118, v118
	v_exp_f32_e32 v119, v119
	v_pk_add_f32 v[120:121], v[120:121], 1.0 op_sel_hi:[1,0]
	v_pk_add_f32 v[122:123], v[122:123], 1.0 op_sel_hi:[1,0]
	v_pk_add_f32 v[116:117], v[116:117], 1.0 op_sel_hi:[1,0]
	v_pk_add_f32 v[118:119], v[118:119], 1.0 op_sel_hi:[1,0]
	v_rcp_f32_e32 v120, v120
	v_rcp_f32_e32 v121, v121
	v_rcp_f32_e32 v122, v122
	s_waitcnt vmcnt(10)
; #define GAS __attribute__((address_space(1)))
; __device__ __forceinline__ u32x4 pack8(f32x4 v0, f32x4 v1) { u32x4 w; w.x = cvt_pk_bf16(v0[0], v0[1]); w.y = cvt_pk_bf16(v0[2], v0[3]); w.z = cvt_pk_bf16(v1[0], v1[1]); w.w = cvt_pk_bf16(v1[2], v1[3]); return w; }
; __device__ __forceinline__ void unpack8(u32x4 w, f32x4& v0, f32x4& v1) { v0 = (f32x4){bflo(w.x), bfhi(w.x), bflo(w.y), bfhi(w.y)}; v1 = (f32x4){bflo(w.z), bfhi(w.z), bflo(w.w), bfhi(w.w)}; }
; #define GAS __attribute__((address_space(1)))
;     __device__ __forceinline__ void operator()(const f32x4 (&acc)[2][2][4][2], const Unit& u, int wr, int wc, int fr, int fq) const {
;     ...
;             for (int m = 0; m < 4; ++m) { const size_t off = (size_t)(ai * HALF + m * 16) * 1024;
; #pragma unroll
;                 for (int bj = 0; bj < 2; ++bj) { f32x4 z0, z1; unpack8(*(const GAS u32x4*)(zb + off + bj * HALF), z0, z1);
;                     const f32x4 v0 = z0 * sigmoid4(acc[ai][bj][m][0] + bv[bj][0]), v1 = z1 * sigmoid4(acc[ai][bj][m][1] + bv[bj][1]);
;                     *(GAS u32x4*)(sob + off + bj * HALF) = pack8(v0, v1); } }
	v_mov_b32_e32 v140, v188
	v_mov_b32_e32 v141, v189
	v_mov_b32_e32 v142, v190
	v_mov_b32_e32 v143, v191
	global_load_dwordx4 v[188:191], v[242:243], off offset:256
	v_lshlrev_b32_e32 v144, 16, v140
	v_and_b32_e32 v145, 0xffff0000, v140
	v_lshlrev_b32_e32 v140, 16, v141
	v_and_b32_e32 v141, 0xffff0000, v141
	v_lshlrev_b32_e32 v146, 16, v142
	v_and_b32_e32 v147, 0xffff0000, v142
	v_lshlrev_b32_e32 v142, 16, v143
	v_and_b32_e32 v143, 0xffff0000, v143
	v_pk_mul_f32 v[138:139], v[138:139], v[140:141]
	v_pk_mul_f32 v[136:137], v[136:137], v[144:145]
	v_pk_mul_f32 v[140:141], v[134:135], v[142:143]
	v_pk_mul_f32 v[134:135], v[132:133], v[146:147]
	v_cvt_pk_bf16_f32 v132, v136, v137
	v_cvt_pk_bf16_f32 v133, v138, v139
	v_cvt_pk_bf16_f32 v134, v134, v135
	v_cvt_pk_bf16_f32 v135, v140, v141
	global_store_dwordx4 v[160:161], v[132:135], off offset:256
	v_rcp_f32_e32 v123, v123
	v_rcp_f32_e32 v116, v116
	v_add_co_u32_e32 v132, vcc, s94, v162
	v_rcp_f32_e32 v117, v117
	s_nop 0
	v_addc_co_u32_e32 v133, vcc, 0, v163, vcc
	v_rcp_f32_e32 v118, v118
	v_rcp_f32_e32 v119, v119
	v_pk_add_f32 v[112:113], v[112:113], v[38:39]
	v_pk_add_f32 v[108:109], v[108:109], v[34:35]
	v_pk_add_f32 v[114:115], v[114:115], v[40:41]
	v_pk_mul_f32 v[112:113], v[112:113], s[74:75] op_sel_hi:[1,0]
	v_pk_add_f32 v[110:111], v[110:111], v[36:37]
	v_pk_mul_f32 v[108:109], v[108:109], s[74:75] op_sel_hi:[1,0]
	v_pk_mul_f32 v[114:115], v[114:115], s[74:75] op_sel_hi:[1,0]
	v_exp_f32_e32 v112, v112
	v_exp_f32_e32 v113, v113
	v_pk_mul_f32 v[110:111], v[110:111], s[74:75] op_sel_hi:[1,0]
	v_exp_f32_e32 v108, v108
	v_exp_f32_e32 v109, v109
	v_exp_f32_e32 v114, v114
	v_exp_f32_e32 v115, v115
	v_exp_f32_e32 v110, v110
	v_exp_f32_e32 v111, v111
	v_pk_add_f32 v[112:113], v[112:113], 1.0 op_sel_hi:[1,0]
	v_pk_add_f32 v[108:109], v[108:109], 1.0 op_sel_hi:[1,0]
	v_pk_add_f32 v[114:115], v[114:115], 1.0 op_sel_hi:[1,0]
	v_rcp_f32_e32 v112, v112
	v_rcp_f32_e32 v113, v113
	v_pk_add_f32 v[110:111], v[110:111], 1.0 op_sel_hi:[1,0]
	v_rcp_f32_e32 v108, v108
	v_rcp_f32_e32 v109, v109
	v_rcp_f32_e32 v114, v114
	v_rcp_f32_e32 v115, v115
	v_rcp_f32_e32 v110, v110
	v_rcp_f32_e32 v111, v111
	v_pk_add_f32 v[106:107], v[106:107], v[24:25]
	v_pk_add_f32 v[104:105], v[104:105], v[22:23]
	v_pk_add_f32 v[102:103], v[102:103], v[16:17]
	v_pk_add_f32 v[100:101], v[100:101], v[14:15]
	v_pk_mul_f32 v[104:105], v[104:105], s[74:75] op_sel_hi:[1,0]
	v_pk_mul_f32 v[106:107], v[106:107], s[74:75] op_sel_hi:[1,0]
	v_pk_mul_f32 v[100:101], v[100:101], s[74:75] op_sel_hi:[1,0]
	v_pk_mul_f32 v[102:103], v[102:103], s[74:75] op_sel_hi:[1,0]
	v_exp_f32_e32 v104, v104
	v_exp_f32_e32 v105, v105
	v_exp_f32_e32 v106, v106
	v_exp_f32_e32 v107, v107
	v_exp_f32_e32 v100, v100
	v_exp_f32_e32 v101, v101
	v_exp_f32_e32 v102, v102
	v_exp_f32_e32 v103, v103
	v_pk_add_f32 v[104:105], v[104:105], 1.0 op_sel_hi:[1,0]
	v_pk_add_f32 v[106:107], v[106:107], 1.0 op_sel_hi:[1,0]
	v_pk_add_f32 v[100:101], v[100:101], 1.0 op_sel_hi:[1,0]
	v_pk_add_f32 v[102:103], v[102:103], 1.0 op_sel_hi:[1,0]
	v_rcp_f32_e32 v104, v104
	v_rcp_f32_e32 v105, v105
	v_rcp_f32_e32 v106, v106
	v_rcp_f32_e32 v107, v107
	v_rcp_f32_e32 v100, v100
	v_rcp_f32_e32 v101, v101
	v_rcp_f32_e32 v102, v102
	v_rcp_f32_e32 v103, v103
	v_pk_add_f32 v[94:95], v[94:95], v[38:39]
	v_pk_add_f32 v[90:91], v[90:91], v[34:35]
	v_pk_add_f32 v[96:97], v[96:97], v[40:41]
	v_pk_mul_f32 v[94:95], v[94:95], s[74:75] op_sel_hi:[1,0]
	v_pk_add_f32 v[92:93], v[92:93], v[36:37]
	v_pk_mul_f32 v[90:91], v[90:91], s[74:75] op_sel_hi:[1,0]
	v_pk_mul_f32 v[96:97], v[96:97], s[74:75] op_sel_hi:[1,0]
	v_exp_f32_e32 v94, v94
	v_exp_f32_e32 v95, v95
	v_pk_mul_f32 v[92:93], v[92:93], s[74:75] op_sel_hi:[1,0]
	v_exp_f32_e32 v90, v90
	v_exp_f32_e32 v91, v91
	v_exp_f32_e32 v96, v96
	v_exp_f32_e32 v97, v97
	v_exp_f32_e32 v92, v92
	v_exp_f32_e32 v93, v93
	v_pk_add_f32 v[94:95], v[94:95], 1.0 op_sel_hi:[1,0]
	v_pk_add_f32 v[90:91], v[90:91], 1.0 op_sel_hi:[1,0]
	v_pk_add_f32 v[96:97], v[96:97], 1.0 op_sel_hi:[1,0]
	v_rcp_f32_e32 v94, v94
	v_rcp_f32_e32 v95, v95
	s_waitcnt vmcnt(11)
	v_mov_b32_e32 v134, v192
	v_mov_b32_e32 v135, v193
	v_mov_b32_e32 v136, v194
	v_mov_b32_e32 v137, v195
	v_add_co_u32_e32 v242, vcc, s51, v162
	v_addc_co_u32_e32 v243, vcc, 0, v163, vcc
	global_load_dwordx4 v[192:195], v[242:243], off
	v_lshlrev_b32_e32 v138, 16, v134
	v_and_b32_e32 v139, 0xffff0000, v134
	v_lshlrev_b32_e32 v140, 16, v136
	v_and_b32_e32 v141, 0xffff0000, v136
	v_lshlrev_b32_e32 v134, 16, v135
	v_and_b32_e32 v135, 0xffff0000, v135
	v_lshlrev_b32_e32 v136, 16, v137
	v_and_b32_e32 v137, 0xffff0000, v137
	v_pk_mul_f32 v[128:129], v[128:129], v[138:139]
	v_pk_mul_f32 v[124:125], v[124:125], v[140:141]
	v_pk_mul_f32 v[130:131], v[130:131], v[134:135]
	v_pk_mul_f32 v[134:135], v[126:127], v[136:137]
	v_cvt_pk_bf16_f32 v126, v128, v129
	v_cvt_pk_bf16_f32 v128, v124, v125
	v_add_co_u32_e32 v124, vcc, s94, v160
	v_cvt_pk_bf16_f32 v127, v130, v131
	v_cvt_pk_bf16_f32 v129, v134, v135
	v_addc_co_u32_e32 v125, vcc, 0, v161, vcc
	global_store_dwordx4 v[124:125], v[126:129], off
	v_pk_add_f32 v[92:93], v[92:93], 1.0 op_sel_hi:[1,0]
	v_rcp_f32_e32 v90, v90
	v_rcp_f32_e32 v91, v91
	v_rcp_f32_e32 v96, v96
	v_rcp_f32_e32 v97, v97
	v_rcp_f32_e32 v92, v92
	v_rcp_f32_e32 v93, v93
	v_pk_add_f32 v[88:89], v[88:89], v[24:25]
	v_pk_add_f32 v[86:87], v[86:87], v[22:23]
	v_pk_add_f32 v[84:85], v[84:85], v[16:17]
	v_pk_add_f32 v[82:83], v[82:83], v[14:15]
	v_pk_mul_f32 v[86:87], v[86:87], s[74:75] op_sel_hi:[1,0]
	v_pk_mul_f32 v[88:89], v[88:89], s[74:75] op_sel_hi:[1,0]
	v_pk_mul_f32 v[82:83], v[82:83], s[74:75] op_sel_hi:[1,0]
; #define GAS __attribute__((address_space(1)))
; __device__ __forceinline__ u32x4 pack8(f32x4 v0, f32x4 v1) { u32x4 w; w.x = cvt_pk_bf16(v0[0], v0[1]); w.y = cvt_pk_bf16(v0[2], v0[3]); w.z = cvt_pk_bf16(v1[0], v1[1]); w.w = cvt_pk_bf16(v1[2], v1[3]); return w; }
; __device__ __forceinline__ void unpack8(u32x4 w, f32x4& v0, f32x4& v1) { v0 = (f32x4){bflo(w.x), bfhi(w.x), bflo(w.y), bfhi(w.y)}; v1 = (f32x4){bflo(w.z), bfhi(w.z), bflo(w.w), bfhi(w.w)}; }
; #define GAS __attribute__((address_space(1)))
;     __device__ __forceinline__ void operator()(const f32x4 (&acc)[2][2][4][2], const Unit& u, int wr, int wc, int fr, int fq) const {
;     ...
;             for (int m = 0; m < 4; ++m) { const size_t off = (size_t)(ai * HALF + m * 16) * 1024;
; #pragma unroll
;                 for (int bj = 0; bj < 2; ++bj) { f32x4 z0, z1; unpack8(*(const GAS u32x4*)(zb + off + bj * HALF), z0, z1);
;                     const f32x4 v0 = z0 * sigmoid4(acc[ai][bj][m][0] + bv[bj][0]), v1 = z1 * sigmoid4(acc[ai][bj][m][1] + bv[bj][1]);
;                     *(GAS u32x4*)(sob + off + bj * HALF) = pack8(v0, v1); } }
	v_pk_mul_f32 v[84:85], v[84:85], s[74:75] op_sel_hi:[1,0]
	v_exp_f32_e32 v86, v86
	v_exp_f32_e32 v87, v87
	v_exp_f32_e32 v88, v88
	v_exp_f32_e32 v89, v89
	v_exp_f32_e32 v82, v82
	v_exp_f32_e32 v83, v83
	v_exp_f32_e32 v84, v84
	v_exp_f32_e32 v85, v85
	v_pk_add_f32 v[86:87], v[86:87], 1.0 op_sel_hi:[1,0]
	v_pk_add_f32 v[88:89], v[88:89], 1.0 op_sel_hi:[1,0]
	v_pk_add_f32 v[82:83], v[82:83], 1.0 op_sel_hi:[1,0]
	v_pk_add_f32 v[84:85], v[84:85], 1.0 op_sel_hi:[1,0]
	v_rcp_f32_e32 v86, v86
	v_rcp_f32_e32 v87, v87
	v_rcp_f32_e32 v88, v88
	v_rcp_f32_e32 v89, v89
	v_rcp_f32_e32 v82, v82
	v_rcp_f32_e32 v83, v83
	v_rcp_f32_e32 v84, v84
	v_rcp_f32_e32 v85, v85
	v_pk_add_f32 v[78:79], v[78:79], v[38:39]
	v_pk_add_f32 v[74:75], v[74:75], v[34:35]
	v_pk_add_f32 v[80:81], v[80:81], v[40:41]
	v_pk_mul_f32 v[78:79], v[78:79], s[74:75] op_sel_hi:[1,0]
	v_pk_add_f32 v[76:77], v[76:77], v[36:37]
	v_pk_mul_f32 v[74:75], v[74:75], s[74:75] op_sel_hi:[1,0]
	v_pk_mul_f32 v[80:81], v[80:81], s[74:75] op_sel_hi:[1,0]
	v_exp_f32_e32 v78, v78
	v_exp_f32_e32 v79, v79
	v_pk_mul_f32 v[76:77], v[76:77], s[74:75] op_sel_hi:[1,0]
	v_exp_f32_e32 v74, v74
	v_exp_f32_e32 v75, v75
	v_exp_f32_e32 v80, v80
	v_exp_f32_e32 v81, v81
	v_exp_f32_e32 v76, v76
	v_exp_f32_e32 v77, v77
	v_pk_add_f32 v[78:79], v[78:79], 1.0 op_sel_hi:[1,0]
	v_pk_add_f32 v[74:75], v[74:75], 1.0 op_sel_hi:[1,0]
	v_pk_add_f32 v[80:81], v[80:81], 1.0 op_sel_hi:[1,0]
	v_rcp_f32_e32 v78, v78
	v_rcp_f32_e32 v79, v79
	v_pk_add_f32 v[76:77], v[76:77], 1.0 op_sel_hi:[1,0]
	v_rcp_f32_e32 v74, v74
	v_rcp_f32_e32 v75, v75
	v_rcp_f32_e32 v80, v80
	v_rcp_f32_e32 v81, v81
	v_rcp_f32_e32 v76, v76
	v_rcp_f32_e32 v77, v77
	v_pk_add_f32 v[72:73], v[72:73], v[24:25]
	v_pk_add_f32 v[70:71], v[70:71], v[22:23]
	v_pk_add_f32 v[68:69], v[68:69], v[16:17]
	v_pk_add_f32 v[66:67], v[66:67], v[14:15]
	v_pk_mul_f32 v[70:71], v[70:71], s[74:75] op_sel_hi:[1,0]
	v_pk_mul_f32 v[72:73], v[72:73], s[74:75] op_sel_hi:[1,0]
	v_pk_mul_f32 v[66:67], v[66:67], s[74:75] op_sel_hi:[1,0]
	v_pk_mul_f32 v[68:69], v[68:69], s[74:75] op_sel_hi:[1,0]
	v_exp_f32_e32 v70, v70
	v_exp_f32_e32 v71, v71
	v_exp_f32_e32 v72, v72
	v_exp_f32_e32 v73, v73
	v_exp_f32_e32 v66, v66
	v_exp_f32_e32 v67, v67
	v_exp_f32_e32 v68, v68
	v_exp_f32_e32 v69, v69
	s_waitcnt vmcnt(12)
	v_mov_b32_e32 v126, v196
	v_mov_b32_e32 v127, v197
	v_mov_b32_e32 v128, v198
	v_mov_b32_e32 v129, v199
	global_load_dwordx4 v[196:199], v[242:243], off offset:256
	v_lshlrev_b32_e32 v130, 16, v126
	v_and_b32_e32 v131, 0xffff0000, v126
	v_lshlrev_b32_e32 v126, 16, v127
	v_and_b32_e32 v127, 0xffff0000, v127
	v_lshlrev_b32_e32 v132, 16, v128
	v_and_b32_e32 v133, 0xffff0000, v128
	v_lshlrev_b32_e32 v128, 16, v129
	v_and_b32_e32 v129, 0xffff0000, v129
	v_pk_mul_f32 v[122:123], v[122:123], v[126:127]
	v_pk_mul_f32 v[120:121], v[120:121], v[130:131]
	v_pk_mul_f32 v[126:127], v[118:119], v[128:129]
	v_pk_mul_f32 v[118:119], v[116:117], v[132:133]
	v_cvt_pk_bf16_f32 v116, v120, v121
	v_cvt_pk_bf16_f32 v117, v122, v123
	v_cvt_pk_bf16_f32 v118, v118, v119
	v_cvt_pk_bf16_f32 v119, v126, v127
	global_store_dwordx4 v[124:125], v[116:119], off offset:256
	v_pk_add_f32 v[70:71], v[70:71], 1.0 op_sel_hi:[1,0]
	v_pk_add_f32 v[72:73], v[72:73], 1.0 op_sel_hi:[1,0]
	v_add_co_u32_e32 v116, vcc, s73, v162
	v_pk_add_f32 v[66:67], v[66:67], 1.0 op_sel_hi:[1,0]
	s_nop 0
	v_addc_co_u32_e32 v117, vcc, 0, v163, vcc
	v_pk_add_f32 v[68:69], v[68:69], 1.0 op_sel_hi:[1,0]
	v_rcp_f32_e32 v70, v70
	v_rcp_f32_e32 v71, v71
	v_rcp_f32_e32 v72, v72
	v_rcp_f32_e32 v73, v73
	v_rcp_f32_e32 v66, v66
	v_rcp_f32_e32 v67, v67
	v_rcp_f32_e32 v68, v68
	v_rcp_f32_e32 v69, v69
	v_pk_add_f32 v[62:63], v[62:63], v[38:39]
	v_pk_add_f32 v[58:59], v[58:59], v[34:35]
	v_pk_add_f32 v[64:65], v[64:65], v[40:41]
	v_pk_mul_f32 v[62:63], v[62:63], s[74:75] op_sel_hi:[1,0]
	v_pk_add_f32 v[60:61], v[60:61], v[36:37]
	v_pk_mul_f32 v[58:59], v[58:59], s[74:75] op_sel_hi:[1,0]
	v_pk_mul_f32 v[64:65], v[64:65], s[74:75] op_sel_hi:[1,0]
	v_exp_f32_e32 v62, v62
	v_exp_f32_e32 v63, v63
	v_pk_mul_f32 v[60:61], v[60:61], s[74:75] op_sel_hi:[1,0]
	v_exp_f32_e32 v58, v58
	v_exp_f32_e32 v59, v59
	v_exp_f32_e32 v64, v64
	v_exp_f32_e32 v65, v65
	v_exp_f32_e32 v60, v60
	v_exp_f32_e32 v61, v61
	v_pk_add_f32 v[62:63], v[62:63], 1.0 op_sel_hi:[1,0]
	v_pk_add_f32 v[58:59], v[58:59], 1.0 op_sel_hi:[1,0]
	v_pk_add_f32 v[64:65], v[64:65], 1.0 op_sel_hi:[1,0]
	v_rcp_f32_e32 v62, v62
	v_rcp_f32_e32 v63, v63
	v_pk_add_f32 v[60:61], v[60:61], 1.0 op_sel_hi:[1,0]
	v_rcp_f32_e32 v58, v58
	v_rcp_f32_e32 v59, v59
	v_rcp_f32_e32 v64, v64
	v_rcp_f32_e32 v65, v65
	v_rcp_f32_e32 v60, v60
	v_rcp_f32_e32 v61, v61
	v_pk_add_f32 v[56:57], v[56:57], v[24:25]
	v_pk_add_f32 v[54:55], v[54:55], v[22:23]
	v_pk_add_f32 v[52:53], v[52:53], v[16:17]
	v_pk_add_f32 v[50:51], v[50:51], v[14:15]
	v_pk_mul_f32 v[54:55], v[54:55], s[74:75] op_sel_hi:[1,0]
	v_pk_mul_f32 v[56:57], v[56:57], s[74:75] op_sel_hi:[1,0]
	v_pk_mul_f32 v[50:51], v[50:51], s[74:75] op_sel_hi:[1,0]
	v_pk_mul_f32 v[52:53], v[52:53], s[74:75] op_sel_hi:[1,0]
	v_exp_f32_e32 v54, v54
	v_exp_f32_e32 v55, v55
	v_exp_f32_e32 v56, v56
	v_exp_f32_e32 v57, v57
	v_exp_f32_e32 v50, v50
	v_exp_f32_e32 v51, v51
	v_exp_f32_e32 v52, v52
	v_exp_f32_e32 v53, v53
	v_pk_add_f32 v[54:55], v[54:55], 1.0 op_sel_hi:[1,0]
	v_pk_add_f32 v[56:57], v[56:57], 1.0 op_sel_hi:[1,0]
	v_pk_add_f32 v[50:51], v[50:51], 1.0 op_sel_hi:[1,0]
	v_pk_add_f32 v[52:53], v[52:53], 1.0 op_sel_hi:[1,0]
	v_rcp_f32_e32 v54, v54
	v_rcp_f32_e32 v55, v55
	v_rcp_f32_e32 v56, v56
	v_rcp_f32_e32 v57, v57
	v_rcp_f32_e32 v50, v50
	v_rcp_f32_e32 v51, v51
	v_rcp_f32_e32 v52, v52
	v_rcp_f32_e32 v53, v53
	v_pk_add_f32 v[46:47], v[46:47], v[38:39]
	v_pk_add_f32 v[42:43], v[42:43], v[34:35]
	v_pk_add_f32 v[48:49], v[48:49], v[40:41]
	v_pk_mul_f32 v[46:47], v[46:47], s[74:75] op_sel_hi:[1,0]
	v_pk_add_f32 v[44:45], v[44:45], v[36:37]
	v_pk_mul_f32 v[42:43], v[42:43], s[74:75] op_sel_hi:[1,0]
	v_pk_mul_f32 v[48:49], v[48:49], s[74:75] op_sel_hi:[1,0]
	v_exp_f32_e32 v46, v46
	v_exp_f32_e32 v47, v47
	v_pk_mul_f32 v[44:45], v[44:45], s[74:75] op_sel_hi:[1,0]
	v_exp_f32_e32 v42, v42
	v_exp_f32_e32 v43, v43
	v_exp_f32_e32 v48, v48
	v_exp_f32_e32 v49, v49
	s_waitcnt vmcnt(13)
; #define GAS __attribute__((address_space(1)))
; __device__ __forceinline__ u32x4 pack8(f32x4 v0, f32x4 v1) { u32x4 w; w.x = cvt_pk_bf16(v0[0], v0[1]); w.y = cvt_pk_bf16(v0[2], v0[3]); w.z = cvt_pk_bf16(v1[0], v1[1]); w.w = cvt_pk_bf16(v1[2], v1[3]); return w; }
; __device__ __forceinline__ void unpack8(u32x4 w, f32x4& v0, f32x4& v1) { v0 = (f32x4){bflo(w.x), bfhi(w.x), bflo(w.y), bfhi(w.y)}; v1 = (f32x4){bflo(w.z), bfhi(w.z), bflo(w.w), bfhi(w.w)}; }
; #define GAS __attribute__((address_space(1)))
; __device__ __forceinline__ f32x4 sigmoid4(f32x4 v) {
;     const f32x2 t0 = (f32x2){v[0], v[1]} * -1.4426950408889634f, t1 = (f32x2){v[2], v[3]} * -1.4426950408889634f;
;     const f32x2 d0 = (f32x2){__builtin_amdgcn_exp2f(t0.x), __builtin_amdgcn_exp2f(t0.y)} + 1.0f, d1 = (f32x2){__builtin_amdgcn_exp2f(t1.x), __builtin_amdgcn_exp2f(t1.y)} + 1.0f;
;     return (f32x4){__builtin_amdgcn_rcpf(d0.x), __builtin_amdgcn_rcpf(d0.y), __builtin_amdgcn_rcpf(d1.x), __builtin_amdgcn_rcpf(d1.y)}; }
;     __device__ __forceinline__ void operator()(const f32x4 (&acc)[2][2][4][2], const Unit& u, int wr, int wc, int fr, int fq) const {
;     ...
;         const bf16_t* const zb = Z + (size_t)row0 * 1024 + col0; bf16_t* const sob = SO + (size_t)row0 * 1024 + col0;
; #pragma unroll
;         for (int ai = 0; ai < 2; ++ai)
; #pragma unroll
;             for (int m = 0; m < 4; ++m) { const size_t off = (size_t)(ai * HALF + m * 16) * 1024;
; #pragma unroll
;                 for (int bj = 0; bj < 2; ++bj) { f32x4 z0, z1; unpack8(*(const GAS u32x4*)(zb + off + bj * HALF), z0, z1);
;                     const f32x4 v0 = z0 * sigmoid4(acc[ai][bj][m][0] + bv[bj][0]), v1 = z1 * sigmoid4(acc[ai][bj][m][1] + bv[bj][1]);
;                     *(GAS u32x4*)(sob + off + bj * HALF) = pack8(v0, v1); } }
	v_mov_b32_e32 v118, v200
	v_mov_b32_e32 v119, v201
	v_mov_b32_e32 v120, v202
	v_mov_b32_e32 v121, v203
	v_add_co_u32_e32 v242, vcc, s66, v162
	v_addc_co_u32_e32 v243, vcc, 0, v163, vcc
	global_load_dwordx4 v[200:203], v[242:243], off
	v_lshlrev_b32_e32 v122, 16, v118
	v_and_b32_e32 v123, 0xffff0000, v118
	v_lshlrev_b32_e32 v124, 16, v120
	v_and_b32_e32 v125, 0xffff0000, v120
	v_lshlrev_b32_e32 v118, 16, v119
	v_and_b32_e32 v119, 0xffff0000, v119
	v_lshlrev_b32_e32 v120, 16, v121
	v_and_b32_e32 v121, 0xffff0000, v121
	v_pk_mul_f32 v[112:113], v[112:113], v[122:123]
	v_pk_mul_f32 v[108:109], v[108:109], v[124:125]
	v_pk_mul_f32 v[114:115], v[114:115], v[118:119]
	v_pk_mul_f32 v[118:119], v[110:111], v[120:121]
	v_cvt_pk_bf16_f32 v110, v112, v113
	v_cvt_pk_bf16_f32 v112, v108, v109
	v_add_co_u32_e32 v108, vcc, s73, v160
	v_cvt_pk_bf16_f32 v111, v114, v115
	v_cvt_pk_bf16_f32 v113, v118, v119
	v_addc_co_u32_e32 v109, vcc, 0, v161, vcc
	global_store_dwordx4 v[108:109], v[110:113], off
	v_exp_f32_e32 v44, v44
	v_exp_f32_e32 v45, v45
	v_pk_add_f32 v[46:47], v[46:47], 1.0 op_sel_hi:[1,0]
	v_pk_add_f32 v[42:43], v[42:43], 1.0 op_sel_hi:[1,0]
	v_pk_add_f32 v[48:49], v[48:49], 1.0 op_sel_hi:[1,0]
	v_rcp_f32_e32 v46, v46
	v_rcp_f32_e32 v47, v47
	v_pk_add_f32 v[44:45], v[44:45], 1.0 op_sel_hi:[1,0]
	v_rcp_f32_e32 v42, v42
	v_rcp_f32_e32 v43, v43
	v_rcp_f32_e32 v48, v48
	v_rcp_f32_e32 v49, v49
	v_rcp_f32_e32 v44, v44
	v_rcp_f32_e32 v45, v45
	v_pk_add_f32 v[32:33], v[32:33], v[24:25]
	v_pk_add_f32 v[30:31], v[30:31], v[22:23]
	v_pk_add_f32 v[28:29], v[28:29], v[16:17]
	v_pk_add_f32 v[26:27], v[26:27], v[14:15]
	v_pk_mul_f32 v[30:31], v[30:31], s[74:75] op_sel_hi:[1,0]
	v_pk_mul_f32 v[32:33], v[32:33], s[74:75] op_sel_hi:[1,0]
	v_pk_mul_f32 v[26:27], v[26:27], s[74:75] op_sel_hi:[1,0]
	v_pk_mul_f32 v[28:29], v[28:29], s[74:75] op_sel_hi:[1,0]
	v_exp_f32_e32 v30, v30
	v_exp_f32_e32 v31, v31
	v_exp_f32_e32 v32, v32
	v_exp_f32_e32 v33, v33
	v_exp_f32_e32 v26, v26
	v_exp_f32_e32 v27, v27
	v_exp_f32_e32 v28, v28
	v_exp_f32_e32 v29, v29
	v_pk_add_f32 v[30:31], v[30:31], 1.0 op_sel_hi:[1,0]
	v_pk_add_f32 v[32:33], v[32:33], 1.0 op_sel_hi:[1,0]
	v_pk_add_f32 v[26:27], v[26:27], 1.0 op_sel_hi:[1,0]
	v_pk_add_f32 v[28:29], v[28:29], 1.0 op_sel_hi:[1,0]
	v_rcp_f32_e32 v30, v30
	v_rcp_f32_e32 v31, v31
	v_rcp_f32_e32 v32, v32
	v_rcp_f32_e32 v33, v33
	v_rcp_f32_e32 v26, v26
	v_rcp_f32_e32 v27, v27
	v_rcp_f32_e32 v28, v28
	v_rcp_f32_e32 v29, v29
	v_pk_add_f32 v[18:19], v[18:19], v[38:39]
	v_pk_add_f32 v[20:21], v[20:21], v[40:41]
	v_pk_mul_f32 v[18:19], v[18:19], s[74:75] op_sel_hi:[1,0]
	v_pk_add_f32 v[12:13], v[12:13], v[36:37]
	v_pk_add_f32 v[10:11], v[10:11], v[34:35]
	v_pk_mul_f32 v[20:21], v[20:21], s[74:75] op_sel_hi:[1,0]
	v_exp_f32_e32 v18, v18
	v_exp_f32_e32 v19, v19
	v_pk_mul_f32 v[10:11], v[10:11], s[74:75] op_sel_hi:[1,0]
	v_pk_mul_f32 v[12:13], v[12:13], s[74:75] op_sel_hi:[1,0]
	v_exp_f32_e32 v20, v20
	v_exp_f32_e32 v21, v21
	v_exp_f32_e32 v10, v10
	v_exp_f32_e32 v11, v11
	v_exp_f32_e32 v12, v12
	v_exp_f32_e32 v13, v13
	v_pk_add_f32 v[18:19], v[18:19], 1.0 op_sel_hi:[1,0]
	v_pk_add_f32 v[20:21], v[20:21], 1.0 op_sel_hi:[1,0]
	v_rcp_f32_e32 v18, v18
	v_rcp_f32_e32 v19, v19
	v_pk_add_f32 v[10:11], v[10:11], 1.0 op_sel_hi:[1,0]
	v_pk_add_f32 v[12:13], v[12:13], 1.0 op_sel_hi:[1,0]
	v_rcp_f32_e32 v20, v20
	v_rcp_f32_e32 v21, v21
	v_rcp_f32_e32 v10, v10
	v_rcp_f32_e32 v11, v11
	v_rcp_f32_e32 v12, v12
	v_rcp_f32_e32 v13, v13
	v_pk_add_f32 v[8:9], v[8:9], v[24:25]
	v_pk_add_f32 v[6:7], v[6:7], v[22:23]
	v_pk_add_f32 v[4:5], v[4:5], v[16:17]
	v_pk_add_f32 v[2:3], v[2:3], v[14:15]
	v_pk_mul_f32 v[6:7], v[6:7], s[74:75] op_sel_hi:[1,0]
	v_pk_mul_f32 v[8:9], v[8:9], s[74:75] op_sel_hi:[1,0]
	v_pk_mul_f32 v[2:3], v[2:3], s[74:75] op_sel_hi:[1,0]
	v_pk_mul_f32 v[4:5], v[4:5], s[74:75] op_sel_hi:[1,0]
	v_exp_f32_e32 v6, v6
	s_waitcnt vmcnt(14)
	v_mov_b32_e32 v110, v222
	v_mov_b32_e32 v111, v223
	v_mov_b32_e32 v112, v224
	v_mov_b32_e32 v113, v225
	global_load_dwordx4 v[222:225], v[242:243], off offset:256
	v_lshlrev_b32_e32 v114, 16, v110
	v_and_b32_e32 v115, 0xffff0000, v110
	v_lshlrev_b32_e32 v110, 16, v111
	v_and_b32_e32 v111, 0xffff0000, v111
	v_lshlrev_b32_e32 v116, 16, v112
	v_and_b32_e32 v117, 0xffff0000, v112
	v_lshlrev_b32_e32 v112, 16, v113
	v_and_b32_e32 v113, 0xffff0000, v113
	v_pk_mul_f32 v[106:107], v[106:107], v[110:111]
	v_pk_mul_f32 v[104:105], v[104:105], v[114:115]
	v_pk_mul_f32 v[110:111], v[102:103], v[112:113]
	v_pk_mul_f32 v[102:103], v[100:101], v[116:117]
	v_cvt_pk_bf16_f32 v100, v104, v105
	v_cvt_pk_bf16_f32 v101, v106, v107
	v_cvt_pk_bf16_f32 v102, v102, v103
	v_cvt_pk_bf16_f32 v103, v110, v111
	global_store_dwordx4 v[108:109], v[100:103], off offset:256
	v_exp_f32_e32 v7, v7
	v_exp_f32_e32 v8, v8
	v_add_co_u32_e32 v100, vcc, s93, v162
	v_exp_f32_e32 v9, v9
	s_nop 0
	v_addc_co_u32_e32 v101, vcc, 0, v163, vcc
	v_exp_f32_e32 v2, v2
	v_exp_f32_e32 v3, v3
	v_exp_f32_e32 v4, v4
	v_exp_f32_e32 v5, v5
	v_pk_add_f32 v[6:7], v[6:7], 1.0 op_sel_hi:[1,0]
	v_pk_add_f32 v[8:9], v[8:9], 1.0 op_sel_hi:[1,0]
	v_pk_add_f32 v[2:3], v[2:3], 1.0 op_sel_hi:[1,0]
	v_pk_add_f32 v[4:5], v[4:5], 1.0 op_sel_hi:[1,0]
	v_rcp_f32_e32 v6, v6
	v_rcp_f32_e32 v7, v7
	v_rcp_f32_e32 v8, v8
	v_rcp_f32_e32 v9, v9
	v_rcp_f32_e32 v2, v2
	v_rcp_f32_e32 v3, v3
	v_rcp_f32_e32 v4, v4
	v_rcp_f32_e32 v5, v5
	s_waitcnt vmcnt(15)
; #define GAS __attribute__((address_space(1)))
; __device__ __forceinline__ u32x4 pack8(f32x4 v0, f32x4 v1) { u32x4 w; w.x = cvt_pk_bf16(v0[0], v0[1]); w.y = cvt_pk_bf16(v0[2], v0[3]); w.z = cvt_pk_bf16(v1[0], v1[1]); w.w = cvt_pk_bf16(v1[2], v1[3]); return w; }
; __device__ __forceinline__ void unpack8(u32x4 w, f32x4& v0, f32x4& v1) { v0 = (f32x4){bflo(w.x), bfhi(w.x), bflo(w.y), bfhi(w.y)}; v1 = (f32x4){bflo(w.z), bfhi(w.z), bflo(w.w), bfhi(w.w)}; }
; #define GAS __attribute__((address_space(1)))
;     __device__ __forceinline__ void operator()(const f32x4 (&acc)[2][2][4][2], const Unit& u, int wr, int wc, int fr, int fq) const {
;     ...
;             for (int m = 0; m < 4; ++m) { const size_t off = (size_t)(ai * HALF + m * 16) * 1024;
; #pragma unroll
;                 for (int bj = 0; bj < 2; ++bj) { f32x4 z0, z1; unpack8(*(const GAS u32x4*)(zb + off + bj * HALF), z0, z1);
;                     const f32x4 v0 = z0 * sigmoid4(acc[ai][bj][m][0] + bv[bj][0]), v1 = z1 * sigmoid4(acc[ai][bj][m][1] + bv[bj][1]);
;                     *(GAS u32x4*)(sob + off + bj * HALF) = pack8(v0, v1); } }
	v_mov_b32_e32 v102, v226
	v_mov_b32_e32 v103, v227
	v_mov_b32_e32 v104, v228
	v_mov_b32_e32 v105, v229
	v_lshlrev_b32_e32 v106, 16, v102
	v_and_b32_e32 v107, 0xffff0000, v102
	v_lshlrev_b32_e32 v108, 16, v104
	v_and_b32_e32 v109, 0xffff0000, v104
	v_lshlrev_b32_e32 v102, 16, v103
	v_and_b32_e32 v103, 0xffff0000, v103
	v_lshlrev_b32_e32 v104, 16, v105
	v_and_b32_e32 v105, 0xffff0000, v105
	v_pk_mul_f32 v[94:95], v[94:95], v[106:107]
	v_pk_mul_f32 v[90:91], v[90:91], v[108:109]
	v_pk_mul_f32 v[96:97], v[96:97], v[102:103]
	v_pk_mul_f32 v[102:103], v[92:93], v[104:105]
	v_cvt_pk_bf16_f32 v92, v94, v95
	v_cvt_pk_bf16_f32 v94, v90, v91
	v_add_co_u32_e32 v90, vcc, s93, v160
	v_cvt_pk_bf16_f32 v93, v96, v97
	v_cvt_pk_bf16_f32 v95, v102, v103
	v_addc_co_u32_e32 v91, vcc, 0, v161, vcc
	global_store_dwordx4 v[90:91], v[92:95], off
	s_waitcnt vmcnt(15)
	v_mov_b32_e32 v92, v230
	v_mov_b32_e32 v93, v231
	v_mov_b32_e32 v94, v232
	v_mov_b32_e32 v95, v233
	v_lshlrev_b32_e32 v96, 16, v92
	v_and_b32_e32 v97, 0xffff0000, v92
	v_lshlrev_b32_e32 v92, 16, v93
	v_and_b32_e32 v93, 0xffff0000, v93
	v_lshlrev_b32_e32 v100, 16, v94
	v_and_b32_e32 v101, 0xffff0000, v94
	v_lshlrev_b32_e32 v94, 16, v95
	v_and_b32_e32 v95, 0xffff0000, v95
	v_pk_mul_f32 v[88:89], v[88:89], v[92:93]
	v_pk_mul_f32 v[86:87], v[86:87], v[96:97]
	v_pk_mul_f32 v[92:93], v[84:85], v[94:95]
	v_pk_mul_f32 v[84:85], v[82:83], v[100:101]
	v_cvt_pk_bf16_f32 v82, v86, v87
	v_cvt_pk_bf16_f32 v83, v88, v89
	v_cvt_pk_bf16_f32 v84, v84, v85
	v_cvt_pk_bf16_f32 v85, v92, v93
	global_store_dwordx4 v[90:91], v[82:85], off offset:256
	s_nop 1
	v_add_co_u32_e32 v82, vcc, s49, v162
	s_nop 1
	v_addc_co_u32_e32 v83, vcc, 0, v163, vcc
	s_waitcnt vmcnt(15)
	v_mov_b32_e32 v84, v234
	v_mov_b32_e32 v85, v235
	v_mov_b32_e32 v86, v236
	v_mov_b32_e32 v87, v237
	v_lshlrev_b32_e32 v88, 16, v84
	v_and_b32_e32 v89, 0xffff0000, v84
	v_lshlrev_b32_e32 v90, 16, v86
	v_and_b32_e32 v91, 0xffff0000, v86
	v_lshlrev_b32_e32 v84, 16, v85
	v_and_b32_e32 v85, 0xffff0000, v85
	v_lshlrev_b32_e32 v86, 16, v87
	v_and_b32_e32 v87, 0xffff0000, v87
	v_pk_mul_f32 v[78:79], v[78:79], v[88:89]
	v_pk_mul_f32 v[74:75], v[74:75], v[90:91]
	v_pk_mul_f32 v[80:81], v[80:81], v[84:85]
	v_pk_mul_f32 v[84:85], v[76:77], v[86:87]
	v_cvt_pk_bf16_f32 v76, v78, v79
	v_cvt_pk_bf16_f32 v78, v74, v75
	v_add_co_u32_e32 v74, vcc, s49, v160
	v_cvt_pk_bf16_f32 v77, v80, v81
	v_cvt_pk_bf16_f32 v79, v84, v85
	v_addc_co_u32_e32 v75, vcc, 0, v161, vcc
	global_store_dwordx4 v[74:75], v[76:79], off
	s_waitcnt vmcnt(15)
	v_mov_b32_e32 v76, v238
	v_mov_b32_e32 v77, v239
	v_mov_b32_e32 v78, v240
	v_mov_b32_e32 v79, v241
	v_lshlrev_b32_e32 v80, 16, v76
	v_and_b32_e32 v81, 0xffff0000, v76
	v_lshlrev_b32_e32 v76, 16, v77
	v_and_b32_e32 v77, 0xffff0000, v77
	v_lshlrev_b32_e32 v82, 16, v78
	v_and_b32_e32 v83, 0xffff0000, v78
	v_lshlrev_b32_e32 v78, 16, v79
	v_and_b32_e32 v79, 0xffff0000, v79
	v_pk_mul_f32 v[72:73], v[72:73], v[76:77]
	v_pk_mul_f32 v[70:71], v[70:71], v[80:81]
	v_pk_mul_f32 v[76:77], v[68:69], v[78:79]
	v_pk_mul_f32 v[68:69], v[66:67], v[82:83]
	v_cvt_pk_bf16_f32 v66, v70, v71
	v_cvt_pk_bf16_f32 v67, v72, v73
	v_cvt_pk_bf16_f32 v68, v68, v69
	v_cvt_pk_bf16_f32 v69, v76, v77
	global_store_dwordx4 v[74:75], v[66:69], off offset:256
	s_nop 1
	v_add_co_u32_e32 v66, vcc, s50, v162
	s_nop 1
	v_addc_co_u32_e32 v67, vcc, 0, v163, vcc
	s_waitcnt vmcnt(15)
	v_mov_b32_e32 v68, v184
	v_mov_b32_e32 v69, v185
	v_mov_b32_e32 v70, v186
	v_mov_b32_e32 v71, v187
	v_lshlrev_b32_e32 v72, 16, v68
	v_and_b32_e32 v73, 0xffff0000, v68
	v_lshlrev_b32_e32 v74, 16, v70
	v_and_b32_e32 v75, 0xffff0000, v70
	v_lshlrev_b32_e32 v68, 16, v69
	v_and_b32_e32 v69, 0xffff0000, v69
	v_lshlrev_b32_e32 v70, 16, v71
	v_and_b32_e32 v71, 0xffff0000, v71
	v_pk_mul_f32 v[62:63], v[62:63], v[72:73]
	v_pk_mul_f32 v[58:59], v[58:59], v[74:75]
	v_pk_mul_f32 v[64:65], v[64:65], v[68:69]
	v_pk_mul_f32 v[68:69], v[60:61], v[70:71]
	v_cvt_pk_bf16_f32 v60, v62, v63
	v_cvt_pk_bf16_f32 v62, v58, v59
	v_add_co_u32_e32 v58, vcc, s50, v160
	v_cvt_pk_bf16_f32 v61, v64, v65
	v_cvt_pk_bf16_f32 v63, v68, v69
	v_addc_co_u32_e32 v59, vcc, 0, v161, vcc
	global_store_dwordx4 v[58:59], v[60:63], off
	s_waitcnt vmcnt(14)
; #define GAS __attribute__((address_space(1)))
; __device__ __forceinline__ u32x4 pack8(f32x4 v0, f32x4 v1) { u32x4 w; w.x = cvt_pk_bf16(v0[0], v0[1]); w.y = cvt_pk_bf16(v0[2], v0[3]); w.z = cvt_pk_bf16(v1[0], v1[1]); w.w = cvt_pk_bf16(v1[2], v1[3]); return w; }
; __device__ __forceinline__ void unpack8(u32x4 w, f32x4& v0, f32x4& v1) { v0 = (f32x4){bflo(w.x), bfhi(w.x), bflo(w.y), bfhi(w.y)}; v1 = (f32x4){bflo(w.z), bfhi(w.z), bflo(w.w), bfhi(w.w)}; }
; #define PG8_BAR __builtin_amdgcn_s_barrier()
; #define GAS __attribute__((address_space(1)))
;     __device__ __forceinline__ void operator()(const f32x4 (&acc)[2][2][4][2], const Unit& u, int wr, int wc, int fr, int fq) const {
;     ...
;         const bf16_t* const zb = Z + (size_t)row0 * 1024 + col0; bf16_t* const sob = SO + (size_t)row0 * 1024 + col0;
; #pragma unroll
;         for (int ai = 0; ai < 2; ++ai)
; #pragma unroll
;             for (int m = 0; m < 4; ++m) { const size_t off = (size_t)(ai * HALF + m * 16) * 1024;
; #pragma unroll
;                 for (int bj = 0; bj < 2; ++bj) { f32x4 z0, z1; unpack8(*(const GAS u32x4*)(zb + off + bj * HALF), z0, z1);
;                     const f32x4 v0 = z0 * sigmoid4(acc[ai][bj][m][0] + bv[bj][0]), v1 = z1 * sigmoid4(acc[ai][bj][m][1] + bv[bj][1]);
;                     *(GAS u32x4*)(sob + off + bj * HALF) = pack8(v0, v1); } }
; template <class Epi, class Sched, bool ALIGN_EPI = false, bool SP2 = false>
; __device__ __forceinline__ void gemm_phase(PG8_LAS unsigned char* lds, const Gemm g, const Sched& S, const Epi& E) {
;     ...
;         if (!has_next) break;
; #pragma unroll
;         for (int a = 0; a < 2; ++a)
; #pragma unroll
;             for (int b = 0; b < 2; ++b)
; #pragma unroll
;                 for (int m = 0; m < 4; ++m)
; #pragma unroll
;                     for (int n = 0; n < 2; ++n) acc[a][b][m][n] = (f32x4){0.f, 0.f, 0.f, 0.f};
;         cur = nxt; cA = nA; cB = nB; ++ui;
;         if constexpr (ALIGN_EPI) { if (wr == 1) PG8_BAR; }
	v_mov_b32_e32 v60, v188
	v_mov_b32_e32 v61, v189
	v_mov_b32_e32 v62, v190
	v_mov_b32_e32 v63, v191
	v_lshlrev_b32_e32 v64, 16, v60
	v_and_b32_e32 v65, 0xffff0000, v60
	v_lshlrev_b32_e32 v60, 16, v61
	v_and_b32_e32 v61, 0xffff0000, v61
	v_lshlrev_b32_e32 v66, 16, v62
	v_and_b32_e32 v67, 0xffff0000, v62
	v_lshlrev_b32_e32 v62, 16, v63
	v_and_b32_e32 v63, 0xffff0000, v63
	v_pk_mul_f32 v[56:57], v[56:57], v[60:61]
	v_pk_mul_f32 v[54:55], v[54:55], v[64:65]
	v_pk_mul_f32 v[60:61], v[52:53], v[62:63]
	v_pk_mul_f32 v[52:53], v[50:51], v[66:67]
	v_cvt_pk_bf16_f32 v50, v54, v55
	v_cvt_pk_bf16_f32 v51, v56, v57
	v_cvt_pk_bf16_f32 v52, v52, v53
	v_cvt_pk_bf16_f32 v53, v60, v61
	global_store_dwordx4 v[58:59], v[50:53], off offset:256
	s_nop 1
	v_add_co_u32_e32 v50, vcc, s51, v162
	s_nop 1
	v_addc_co_u32_e32 v51, vcc, 0, v163, vcc
	s_waitcnt vmcnt(13)
	v_mov_b32_e32 v52, v192
	v_mov_b32_e32 v53, v193
	v_mov_b32_e32 v54, v194
	v_mov_b32_e32 v55, v195
	v_lshlrev_b32_e32 v56, 16, v52
	v_and_b32_e32 v57, 0xffff0000, v52
	v_lshlrev_b32_e32 v58, 16, v54
	v_and_b32_e32 v59, 0xffff0000, v54
	v_lshlrev_b32_e32 v52, 16, v53
	v_and_b32_e32 v53, 0xffff0000, v53
	v_lshlrev_b32_e32 v54, 16, v55
	v_and_b32_e32 v55, 0xffff0000, v55
	v_pk_mul_f32 v[46:47], v[46:47], v[56:57]
	v_pk_mul_f32 v[42:43], v[42:43], v[58:59]
	v_pk_mul_f32 v[48:49], v[48:49], v[52:53]
	v_pk_mul_f32 v[52:53], v[44:45], v[54:55]
	v_cvt_pk_bf16_f32 v44, v46, v47
	v_cvt_pk_bf16_f32 v46, v42, v43
	v_add_co_u32_e32 v42, vcc, s51, v160
	v_cvt_pk_bf16_f32 v45, v48, v49
	v_cvt_pk_bf16_f32 v47, v52, v53
	v_addc_co_u32_e32 v43, vcc, 0, v161, vcc
	global_store_dwordx4 v[42:43], v[44:47], off
	s_waitcnt vmcnt(12)
	v_mov_b32_e32 v44, v196
	v_mov_b32_e32 v45, v197
	v_mov_b32_e32 v46, v198
	v_mov_b32_e32 v47, v199
	v_lshlrev_b32_e32 v48, 16, v44
	v_and_b32_e32 v49, 0xffff0000, v44
	v_lshlrev_b32_e32 v44, 16, v45
	v_and_b32_e32 v45, 0xffff0000, v45
	v_lshlrev_b32_e32 v50, 16, v46
	v_and_b32_e32 v51, 0xffff0000, v46
	v_lshlrev_b32_e32 v46, 16, v47
	v_and_b32_e32 v47, 0xffff0000, v47
	v_pk_mul_f32 v[32:33], v[32:33], v[44:45]
	v_pk_mul_f32 v[30:31], v[30:31], v[48:49]
	v_pk_mul_f32 v[44:45], v[28:29], v[46:47]
	v_pk_mul_f32 v[28:29], v[26:27], v[50:51]
	v_cvt_pk_bf16_f32 v26, v30, v31
	v_cvt_pk_bf16_f32 v27, v32, v33
	v_cvt_pk_bf16_f32 v28, v28, v29
	v_cvt_pk_bf16_f32 v29, v44, v45
	global_store_dwordx4 v[42:43], v[26:29], off offset:256
	s_nop 1
	v_add_co_u32_e32 v26, vcc, s66, v162
	s_nop 1
	v_addc_co_u32_e32 v27, vcc, 0, v163, vcc
	s_waitcnt vmcnt(11)
	v_mov_b32_e32 v28, v200
	v_mov_b32_e32 v29, v201
	v_mov_b32_e32 v30, v202
	v_mov_b32_e32 v31, v203
	v_lshlrev_b32_e32 v32, 16, v28
	v_and_b32_e32 v33, 0xffff0000, v28
	v_lshlrev_b32_e32 v28, 16, v29
	v_and_b32_e32 v29, 0xffff0000, v29
	v_lshlrev_b32_e32 v42, 16, v30
	v_and_b32_e32 v43, 0xffff0000, v30
	v_lshlrev_b32_e32 v30, 16, v31
	v_and_b32_e32 v31, 0xffff0000, v31
	v_pk_mul_f32 v[18:19], v[18:19], v[32:33]
	v_pk_mul_f32 v[20:21], v[20:21], v[28:29]
	v_pk_mul_f32 v[28:29], v[12:13], v[30:31]
	v_pk_mul_f32 v[12:13], v[10:11], v[42:43]
	v_cvt_pk_bf16_f32 v10, v18, v19
	v_add_co_u32_e32 v18, vcc, s66, v160
	v_cvt_pk_bf16_f32 v11, v20, v21
	v_cvt_pk_bf16_f32 v12, v12, v13
	v_cvt_pk_bf16_f32 v13, v28, v29
	v_addc_co_u32_e32 v19, vcc, 0, v161, vcc
	global_store_dwordx4 v[18:19], v[10:13], off
	s_andn2_b64 vcc, exec, s[18:19]
	s_waitcnt vmcnt(10)
	v_mov_b32_e32 v10, v222
	v_mov_b32_e32 v11, v223
	v_mov_b32_e32 v12, v224
	v_mov_b32_e32 v13, v225
	v_lshlrev_b32_e32 v20, 16, v10
	v_and_b32_e32 v21, 0xffff0000, v10
	v_lshlrev_b32_e32 v10, 16, v11
	v_and_b32_e32 v11, 0xffff0000, v11
	v_lshlrev_b32_e32 v26, 16, v12
	v_and_b32_e32 v27, 0xffff0000, v12
	v_lshlrev_b32_e32 v12, 16, v13
	v_and_b32_e32 v13, 0xffff0000, v13
	v_pk_mul_f32 v[8:9], v[8:9], v[10:11]
	v_pk_mul_f32 v[6:7], v[6:7], v[20:21]
	v_pk_mul_f32 v[10:11], v[4:5], v[12:13]
	v_pk_mul_f32 v[4:5], v[2:3], v[26:27]
	v_cvt_pk_bf16_f32 v2, v6, v7
	v_cvt_pk_bf16_f32 v3, v8, v9
	v_cvt_pk_bf16_f32 v4, v4, v5
	v_cvt_pk_bf16_f32 v5, v10, v11
	global_store_dwordx4 v[18:19], v[2:5], off offset:256
	s_cbranch_vccnz .LBB0_923
	s_andn2_b64 vcc, exec, s[6:7]
	s_cbranch_vccnz .LBB0_922
	s_branch .LBB0_922

; #define PG8_STAGE(bufoff, gbase, voff) do { _Pragma("unroll") for (int _i = 0; _i < 2; ++_i) \
;         __builtin_amdgcn_global_load_lds((const unsigned*)((const char*)(gbase) + (voff)[_i]), (PG8_LAS unsigned*)(lds + (bufoff) + ldsw + _i * 8192), 16, 0, AUX_A); } while (0)
; #define PG8_WAIT_V(n) asm volatile("s_waitcnt vmcnt(" #n ")" ::: "memory")
; template <class Epi, class Sched, bool ALIGN_EPI = false, bool SP2 = false>
; __device__ __forceinline__ void gemm_phase(PG8_LAS unsigned char* lds, const Gemm g, const Sched& S, const Epi& E) {
;     ...
;     const int tid = tid_l, wid = __builtin_amdgcn_readfirstlane(tid >> 6), lane = tid & 63, wr = wid >> 2, wc = wid & 3, fr = lane & 15, fq = lane >> 4;
;     const int K = g.K;
;     unsigned voffA[2], voffB[2];
; #pragma unroll
;     for (int i = 0; i < 2; ++i) { int R, C; stage_rc(tid * 16 + i * 8192, R, C); const int Rb = Epi::PERM ? ((R & ~31) + perm32(R & 31)) : R;
;         voffA[i] = (unsigned)(R * K + C) * 2u; voffB[i] = (unsigned)(Rb * K + C) * 2u; }
;     const size_t kstep = (size_t)(BK * 2);
;     const size_t hstep = (size_t)HALF * K * 2;
;     const size_t tstep = 2 * hstep;
;     const unsigned ldsw = (unsigned)wid * 1024u;
;     const int aoff = lds_byte(wr * 64 + fr, fq * 8), boff = lds_byte(wc * 32 + fr, fq * 8);
;     ...
;     { const int rot0 = cur.krot, nt0 = cur.nkt; const char* sA0 = PG8_KP(cA, 0, rot0, nt0); const char* sA1 = PG8_KP(cA, 1, rot0, nt0); const char* sB0 = PG8_KP(cB, 0, rot0, nt0); const char* sB1 = PG8_KP(cB, 1, rot0, nt0);
;     if constexpr (SP2) {
;         PG8_STAGEB(PG8_SB(0, 0), sB0, voffB); PG8_STAGEB(PG8_SB(0, 1), sB0 + hstep, voffB); PG8_STAGE(PG8_SA(0, 0), sA0, voffA); PG8_STAGE(PG8_SA(0, 1), sA0 + hstep, voffA);
;         if (wr == 1) PG8_BAR;
;         PG8_WAIT_V(2); PG8_BAR;
;         PG8_STAGEB(PG8_SB(1, 0), sB1, voffB); PG8_STAGE(PG8_SA(1, 0), sA1, voffA); PG8_STAGEB(PG8_SB(1, 1), sB1 + hstep, voffB);
;         PG8_WAIT_V(6); PG8_BAR;
;     } else {
;         PG8_STAGEB(PG8_SB(0, 0), sB0, voffB); PG8_STAGE(PG8_SA(0, 0), sA0, voffA); PG8_STAGEB(PG8_SB(0, 1), sB0 + hstep, voffB); PG8_STAGE(PG8_SA(0, 1), sA0 + hstep, voffA);
;         if (wr == 1) PG8_BAR;
;         PG8_WAIT_V(4); PG8_BAR;
;         PG8_STAGEB(PG8_SB(1, 0), sB1, voffB); PG8_STAGE(PG8_SA(1, 0), sA1, voffA); PG8_STAGEB(PG8_SB(1, 1), sB1 + hstep, voffB);
;         PG8_WAIT_V(6); PG8_BAR;
;     }
.LBB0_1052:
	s_andn2_b64 vcc, exec, s[4:5]
	s_cbranch_vccnz .LBB0_1288
	v_readlane_b32 s0, v254, 53
	v_readlane_b32 s1, v254, 54
	s_mov_b32 s1, s79
	s_lshl_b64 s[44:45], s[0:1], 22
	v_writelane_b32 v254, s0, 53
	s_mov_b64 s[4:5], s[66:67]
	v_mov_b32_e32 v16, v0
	v_writelane_b32 v254, s1, 54
	s_lshl_b64 s[0:1], s[0:1], 13
	s_add_u32 s2, s4, s44
	s_addc_u32 s6, s5, s45
	s_add_u32 s34, s2, 0x8000000
	s_addc_u32 s35, s6, 0
	s_add_u32 s8, s4, 0x1ec00000
	s_addc_u32 s9, s5, 0
	s_add_u32 s10, s4, 0x2ad80000
	s_addc_u32 s11, s5, 0
	s_add_u32 s0, s4, s0
	s_addc_u32 s1, s5, s1
	s_add_u32 s30, s0, 0x8000
	s_addc_u32 s31, s1, 0
	v_readlane_b32 s0, v252, 55
	v_readlane_b32 s1, v252, 56
	s_andn2_b64 vcc, exec, s[0:1]
	v_readfirstlane_b32 s12, v16
	v_cndmask_b32_e64 v1, 0, 1, s[0:1]
	v_cmp_ne_u32_e64 s[38:39], 1, v1
	s_cbranch_vccnz .LBB0_1143
	v_lshlrev_b32_e32 v1, 4, v16
	v_add_u32_e32 v2, 0x2000, v1
	v_ashrrev_i32_e32 v3, 31, v2
	v_lshrrev_b32_e32 v3, 22, v3
	v_add_u32_e32 v3, v2, v3
	v_ashrrev_i32_e32 v10, 10, v3
	v_mul_i32_i24_e32 v3, 0x400, v10
	v_sub_u32_e32 v2, v2, v3
	v_lshrrev_b32_e32 v3, 4, v2
	v_bitop3_b32 v2, v3, v2, 32 bitop3:0x6c
	v_ashrrev_i32_e32 v3, 31, v2
	v_lshrrev_b32_e32 v3, 26, v3
	v_add_u32_e32 v3, v2, v3
	v_lshlrev_b32_e32 v4, 3, v10
	v_ashrrev_i32_e32 v11, 6, v3
	v_and_b32_e32 v4, -16, v4
	v_add_u32_e32 v4, v11, v4
	v_and_b32_e32 v5, 3, v11
	s_mov_b32 s2, 0x1fffe0
	v_lshrrev_b32_e32 v6, 2, v4
	v_lshlrev_b32_e32 v7, 1, v4
	v_and_b32_e32 v3, 0xc0, v3
	v_and_or_b32 v5, v4, s2, v5
	v_and_b32_e32 v6, 4, v6
	v_and_b32_e32 v7, 24, v7
	v_sub_u32_e32 v2, v2, v3
	v_or3_b32 v5, v5, v6, v7
	v_lshlrev_b32_e32 v6, 5, v10
	v_ashrrev_i16_sdwa v2, v207, sext(v2) dst_sel:DWORD dst_unused:UNUSED_PAD src0_sel:DWORD src1_sel:BYTE_0
	v_and_b32_e32 v6, 32, v6
	v_bfe_i32 v12, v2, 0, 16
	v_add_lshl_u32 v2, v6, v12, 1
	s_waitcnt vmcnt(0)
	v_lshl_add_u32 v132, v5, 11, v2
	v_lshl_add_u32 v134, v4, 11, v2
	v_bfe_i32 v2, v16, 27, 1
	v_lshrrev_b32_e32 v2, 22, v2
	v_add_u32_e32 v2, v1, v2
	v_and_b32_e32 v2, 0xfffffc00, v2
	v_sub_u32_e32 v1, v1, v2
	v_lshrrev_b32_e32 v2, 4, v1
	v_ashrrev_i32_e32 v3, 31, v16
	v_bitop3_b32 v1, v2, v1, 32 bitop3:0x6c
	v_lshrrev_b32_e32 v3, 26, v3
	v_ashrrev_i32_e32 v2, 31, v1
	v_add_u32_e32 v3, v16, v3
	v_lshrrev_b32_e32 v2, 26, v2
	v_ashrrev_i32_e32 v14, 6, v3
	v_add_u32_e32 v2, v1, v2
	v_lshlrev_b32_e32 v3, 3, v14
	v_ashrrev_i32_e32 v13, 6, v2
	v_and_b32_e32 v3, -16, v3
	v_add_u32_e32 v3, v13, v3
	s_add_u32 s33, s4, 0x28980000
	v_and_b32_e32 v4, 3, v13
	v_lshrrev_b32_e32 v5, 2, v3
	v_lshlrev_b32_e32 v6, 1, v3
	v_and_b32_e32 v2, 0xc0, v2
	s_addc_u32 s69, s5, 0
	s_ashr_i32 s0, s12, 6
	v_and_or_b32 v4, v3, s2, v4
	v_and_b32_e32 v5, 4, v5
	v_and_b32_e32 v6, 24, v6
	v_sub_u32_e32 v1, v1, v2
	s_ashr_i32 s1, s12, 8
	s_lshl_b32 s70, s0, 10
	v_or3_b32 v4, v4, v5, v6
	v_lshlrev_b32_e32 v5, 5, v14
	v_ashrrev_i16_sdwa v1, v207, sext(v1) dst_sel:DWORD dst_unused:UNUSED_PAD src0_sel:DWORD src1_sel:BYTE_0
	v_readlane_b32 s2, v253, 3
	v_and_b32_e32 v5, 32, v5
	v_bfe_i32 v15, v1, 0, 16
	v_readlane_b32 s3, v253, 4
	s_add_u32 s42, s34, s2
	v_add_lshl_u32 v1, v5, v15, 1
	s_addc_u32 s43, s35, s3
	s_add_i32 s71, s70, 0
	v_lshl_add_u32 v136, v4, 11, v1
	s_add_i32 m0, s71, 0x10000
	v_readlane_b32 s2, v252, 63
	global_load_lds_dwordx4 v136, s[42:43]
	s_add_i32 m0, s71, 0x12000
	v_readlane_b32 s3, v253, 0
	s_add_u32 s52, s33, s2
	s_addc_u32 s53, s69, s3
	s_add_u32 s6, s42, 0x40000
	global_load_lds_dwordx4 v132, s[42:43]
	s_addc_u32 s7, s43, 0
	s_add_i32 m0, s71, 0x14000
	s_add_i32 s75, s71, 0x2000
	global_load_lds_dwordx4 v136, s[6:7]
	s_add_i32 m0, s71, 0x16000
	v_lshl_add_u32 v138, v3, 11, v1
	global_load_lds_dwordx4 v132, s[6:7]
	s_mov_b32 m0, s71
	s_add_u32 s6, s52, 0x40000
	global_load_lds_dwordx4 v138, s[52:53]
	s_mov_b32 m0, s75
	s_addc_u32 s7, s53, 0
	s_add_i32 s78, s71, 0x4000
	global_load_lds_dwordx4 v134, s[52:53]
	s_mov_b32 m0, s78
	s_add_i32 s82, s71, 0x6000
	global_load_lds_dwordx4 v138, s[6:7]
	s_mov_b32 m0, s82
	v_mov_b32_e32 v137, v98
	global_load_lds_dwordx4 v134, s[6:7]
	v_mov_b32_e32 v133, v98
	v_mov_b32_e32 v139, v98
	v_mov_b32_e32 v135, v98
	s_cmp_eq_u32 s1, 1
	v_lshl_add_u64 v[8:9], s[42:43], 0, v[136:137]
	v_lshl_add_u64 v[6:7], s[42:43], 0, v[132:133]
	v_lshl_add_u64 v[2:3], s[52:53], 0, v[138:139]
	s_cselect_b64 s[6:7], -1, 0
	s_cmp_lg_u32 s1, 1
	v_lshl_add_u64 v[4:5], s[52:53], 0, v[134:135]
	s_cbranch_scc1 .LBB0_1056
.LBB0_1056:
	v_bfe_u32 v18, v16, 4, 2
	s_lshl_b32 s0, s0, 5
	v_and_b32_e32 v17, 15, v16
	v_lshlrev_b32_e32 v19, 4, v18
	v_lshlrev_b32_e32 v16, 2, v16
	s_and_b32 s2, s0, 0x60
	s_add_i32 m0, s71, 0x18000
	v_lshl_add_u64 v[8:9], v[8:9], 0, s[76:77]
	v_lshl_or_b32 v1, s1, 6, v17
	v_lshl_or_b32 v19, v17, 6, v19
	s_lshl_b32 s1, s1, 13
	v_and_b32_e32 v16, 32, v16
	s_lshl_b32 s0, s2, 7
	global_load_lds_dwordx4 v[8:9], off
	v_lshl_add_u64 v[6:7], v[6:7], 0, s[76:77]
	s_add_i32 m0, s71, 0x1a000
	s_add_i32 s83, s71, 0x8000
	s_add_i32 s88, s71, 0xa000
	v_bitop3_b32 v99, v19, s0, v16 bitop3:0xde
	global_load_lds_dwordx4 v[6:7], off
	v_lshl_add_u64 v[2:3], v[2:3], 0, s[76:77]
	s_mov_b32 m0, s83
	s_add_u32 s0, s42, 0x40080
	v_bitop3_b32 v20, v19, s1, v16 bitop3:0xde
	global_load_lds_dwordx4 v[2:3], off
	v_lshl_add_u64 v[2:3], v[4:5], 0, s[76:77]
	s_mov_b32 m0, s88
	s_addc_u32 s1, s43, 0
	global_load_lds_dwordx4 v[2:3], off
	s_add_i32 m0, s71, 0x1c000
	v_lshl_add_u64 v[2:3], s[0:1], 0, v[136:137]
	global_load_lds_dwordx4 v[2:3], off
	v_lshl_add_u64 v[2:3], s[0:1], 0, v[132:133]
	s_add_i32 m0, s71, 0x1e000
	v_lshl_or_b32 v150, v18, 3, s2
	global_load_lds_dwordx4 v[2:3], off
	s_waitcnt vmcnt(8)
	s_barrier
	v_or_b32_e32 v2, v18, v17
	v_cmp_eq_u32_e64 s[40:41], 0, v2
	v_lshlrev_b32_e32 v2, 14, v10
	v_and_b32_e32 v2, 0xffff8000, v2
	v_lshl_add_u32 v2, v11, 11, v2
	v_and_b32_e32 v3, 1, v10
	v_lshl_or_b32 v2, v3, 6, v2
	v_lshl_add_u32 v140, v12, 1, v2
	v_lshlrev_b32_e32 v2, 14, v14
	v_and_b32_e32 v2, 0xffff8000, v2
	v_readlane_b32 s2, v253, 1
	s_waitcnt vmcnt(6)
	v_lshl_add_u32 v2, v13, 11, v2
	v_and_b32_e32 v3, 1, v14
	v_readlane_b32 s3, v253, 2
	s_cmpk_lt_u32 s12, 0x100
	v_lshl_or_b32 v2, v3, 6, v2
	s_mov_b32 s91, s2
	v_readlane_b32 s2, v252, 61
	s_cselect_b64 s[12:13], -1, 0
	s_mov_b32 s0, 0
	v_mov_b32_e32 v141, v98
	v_lshl_add_u32 v142, v15, 1, v2
	v_mov_b32_e32 v143, v98
	v_add_u32_e32 v151, 0, v20
	s_mov_b32 s90, s2
	s_barrier
	v_readlane_b32 s3, v252, 62
	s_branch .LBB0_1059

; #define PG8_STAGE(bufoff, gbase, voff) do { _Pragma("unroll") for (int _i = 0; _i < 2; ++_i) \
;         __builtin_amdgcn_global_load_lds((const unsigned*)((const char*)(gbase) + (voff)[_i]), (PG8_LAS unsigned*)(lds + (bufoff) + ldsw + _i * 8192), 16, 0, AUX_A); } while (0)
; #define PG8_STAGEB(bufoff, gbase, voff) do { _Pragma("unroll") for (int _i = 0; _i < 2; ++_i) \
;         __builtin_amdgcn_global_load_lds((const unsigned*)((const char*)(gbase) + (voff)[_i]), (PG8_LAS unsigned*)(lds + (bufoff) + ldsw + _i * 8192), 16, 0, AUX_B); } while (0)
; #define PG8_WAIT_V(n) asm volatile("s_waitcnt vmcnt(" #n ")" ::: "memory")
; #define PG8_WAIT_L(n) asm volatile("s_waitcnt lgkmcnt(" #n ")" ::: "memory")
; template <class Epi, class Sched, bool ALIGN_EPI = false, bool SP2 = false>
; __device__ __forceinline__ void gemm_phase(PG8_LAS unsigned char* lds, const Gemm g, const Sched& S, const Epi& E) {
;     ...
;         const bool has_next = S.next(ui + 1, nxt);
;         const char* nA = has_next ? (const char*)g.A + (size_t)nxt.pm * tstep + (size_t)nxt.kt0 * kstep : cA; const char* nB = has_next ? (const char*)g.Bt + (size_t)nxt.pn * tstep + (size_t)nxt.kt0 * kstep : cB;
;         const int nt = cur.nkt, rot = cur.krot;
;         const char* nAr = has_next ? nA + (size_t)nxt.krot * kstep : PG8_KP(cA, 0, rot, nt); const char* nBr = has_next ? nB + (size_t)nxt.krot * kstep : PG8_KP(cB, 0, rot, nt);
;         for (int t = 0; t < nt; t += 2) {
;             const bool last = (t == nt - 2);
;             const char* a1 = PG8_KP(cA, t + 1, rot, nt);
;             const char* a2 = last ? nAr : PG8_KP(cA, t + 2, rot, nt); const char* b2 = last ? nBr : PG8_KP(cB, t + 2, rot, nt);
;             const char* a3 = a2 + kstep; const char* b3 = b2 + kstep;
;             if (last && has_next) S.a_ready(nxt);
;             if constexpr (SP2) {
;             PG8_LDB(B0, 0, 0); PG8_LDB(B1, 0, 1); PG8_SCHED; PG8_LDA(At, 0, 0); PG8_STAGE(PG8_SA(1, 1), a1 + hstep, voffA);
;             PG8_WAIT_V(8); PG8_WAIT_L(0); PG8_BAR; PG8_MMA(0, 0, At, B0); PG8_MMA(0, 1, At, B1); PG8_BAR; PG8_SCHED;
;             PG8_LDA(At, 0, 1); PG8_STAGEB(PG8_SB(0, 0), b2, voffB); PG8_STAGEB(PG8_SB(0, 1), b2 + hstep, voffB); PG8_STAGE(PG8_SA(0, 0), a2, voffA);
;             PG8_WAIT_V(8); PG8_WAIT_L(0); PG8_BAR; PG8_MMA(1, 0, At, B0); PG8_MMA(1, 1, At, B1); PG8_BAR; PG8_SCHED;
.LBB0_1066:
	s_mov_b32 s14, s15
	s_ashr_i32 s15, s15, 31
	s_mov_b32 s16, s1
	s_lshl_b64 s[0:1], s[14:15], 19
	s_add_u32 s48, s33, s0
	s_addc_u32 s49, s69, s1
	s_ashr_i32 s17, s16, 31
	s_lshl_b64 s[0:1], s[16:17], 19
	s_add_u32 s50, s34, s0
	s_addc_u32 s51, s35, s1
	s_and_b64 s[0:1], s[18:19], exec
	s_cselect_b32 s15, s49, s53
	s_cselect_b32 s17, s48, s52
	s_cselect_b32 s92, s51, s43
	s_cselect_b32 s93, s50, s42
	s_add_u32 s0, s52, 0x40080
	s_addc_u32 s1, s53, 0
	v_lshl_add_u64 v[144:145], s[0:1], 0, v[140:141]
	v_lshl_add_u64 v[146:147], s[0:1], 0, v[142:143]
	s_mov_b32 s29, 0
	s_waitcnt vmcnt(0)
	s_waitcnt lgkmcnt(0)
	s_cmp_lg_u64 s[12:13], 0
	s_cbranch_scc1 .Lrp_1067
	s_barrier
.Lrp_1067:
.Lpk_1067:
	s_add_i32 s81, s29, 2
	s_cmp_lt_u32 s29, 14
	s_cselect_b32 s0, 0, -16
	s_add_i32 s0, s81, s0
	s_ashr_i32 s1, s0, 31
	s_lshl_b64 s[0:1], s[0:1], 7
	s_add_u32 s2, s52, s0
	s_addc_u32 s46, s53, s1
	s_add_u32 s0, s42, s0
	s_addc_u32 s1, s43, s1
	s_cmp_eq_u32 s29, 14
	s_cselect_b32 s59, s15, s46
	s_cselect_b32 s58, s17, s2
	s_cselect_b32 s61, s92, s1
	s_cselect_b32 s60, s93, s0
	s_add_i32 s2, 0, 0x10000
	s_add_i32 s94, s2, s70
	s_add_i32 s46, 0, 0x14000
	s_add_i32 m0, s71, 0xc000
	s_add_i32 s84, s71, 0xe000
	s_add_i32 s95, s94, 0x2000
	s_add_u32 s62, s60, 0x40000
	v_add_u32_e32 v148, s2, v99
	s_addc_u32 s63, s61, 0
	s_add_i32 s96, s46, s70
	ds_read_b128 v[152:155], v148
	ds_read_b128 v[156:159], v148 offset:1024
	ds_read_b128 v[160:163], v148 offset:2048
	ds_read_b128 v[164:167], v148 offset:3072
	v_add_u32_e32 v148, s46, v99
	s_add_i32 s97, s96, 0x2000
	s_add_i32 vcc_lo, 0, 0x18000
	s_add_i32 vcc_hi, 0, 0x1c000
	ds_read_b128 v[180:183], v148
	ds_read_b128 v[184:187], v148 offset:1024
	ds_read_b128 v[188:191], v148 offset:2048
	ds_read_b128 v[192:195], v148 offset:3072
	s_add_u32 s56, s58, 0x40000
	s_addc_u32 s57, s59, 0
	s_add_i32 s1, vcc_lo, s70
	s_add_i32 s0, s1, 0x2000
	s_add_u32 s54, s60, 0x40080
	s_addc_u32 s55, s61, 0
	s_add_i32 s47, vcc_hi, s70
	s_add_i32 s46, s47, 0x2000
	s_cmp_gt_u32 s29, 13
	ds_read_b128 v[196:199], v151
	ds_read_b128 v[200:203], v151 offset:1024
	ds_read_b128 v[222:225], v151 offset:2048
	ds_read_b128 v[226:229], v151 offset:3072
	ds_read_b128 v[230:233], v151 offset:4096
	ds_read_b128 v[234:237], v151 offset:5120
	ds_read_b128 v[238:241], v151 offset:6144
	ds_read_b128 v[242:245], v151 offset:7168
	global_load_lds_dwordx4 v[146:147], off
	s_mov_b32 m0, s84
	s_nop 0
	global_load_lds_dwordx4 v[144:145], off
	s_waitcnt vmcnt(8)
	s_waitcnt lgkmcnt(0)
	s_setprio 1
	s_barrier
	v_mfma_f32_16x16x32_bf16 v[128:131], v[152:155], v[196:199], 0
	v_mfma_f32_16x16x32_bf16 v[128:131], v[156:159], v[200:203], v[128:131]
	v_mfma_f32_16x16x32_bf16 v[124:127], v[160:163], v[196:199], 0
	v_mfma_f32_16x16x32_bf16 v[124:127], v[164:167], v[200:203], v[124:127]
	v_mfma_f32_16x16x32_bf16 v[112:115], v[152:155], v[222:225], 0
	v_mfma_f32_16x16x32_bf16 v[112:115], v[156:159], v[226:229], v[112:115]
	v_mfma_f32_16x16x32_bf16 v[108:111], v[160:163], v[222:225], 0
	v_mfma_f32_16x16x32_bf16 v[108:111], v[164:167], v[226:229], v[108:111]
	v_mfma_f32_16x16x32_bf16 v[94:97], v[152:155], v[230:233], 0
	v_mfma_f32_16x16x32_bf16 v[94:97], v[156:159], v[234:237], v[94:97]
	v_mfma_f32_16x16x32_bf16 v[90:93], v[160:163], v[230:233], 0
	v_mfma_f32_16x16x32_bf16 v[90:93], v[164:167], v[234:237], v[90:93]
	v_mfma_f32_16x16x32_bf16 v[78:81], v[152:155], v[238:241], 0
	v_mfma_f32_16x16x32_bf16 v[78:81], v[156:159], v[242:245], v[78:81]
	v_mfma_f32_16x16x32_bf16 v[74:77], v[160:163], v[238:241], 0
	v_mfma_f32_16x16x32_bf16 v[74:77], v[164:167], v[242:245], v[74:77]
	s_setprio 0
	s_setprio 1
	v_mfma_f32_16x16x32_bf16 v[120:123], v[180:183], v[196:199], 0
	v_mfma_f32_16x16x32_bf16 v[120:123], v[184:187], v[200:203], v[120:123]
	v_mfma_f32_16x16x32_bf16 v[116:119], v[188:191], v[196:199], 0
	v_mfma_f32_16x16x32_bf16 v[116:119], v[192:195], v[200:203], v[116:119]
	v_mfma_f32_16x16x32_bf16 v[104:107], v[180:183], v[222:225], 0
	v_mfma_f32_16x16x32_bf16 v[104:107], v[184:187], v[226:229], v[104:107]
	v_mfma_f32_16x16x32_bf16 v[100:103], v[188:191], v[222:225], 0
	v_mfma_f32_16x16x32_bf16 v[100:103], v[192:195], v[226:229], v[100:103]
	v_mfma_f32_16x16x32_bf16 v[86:89], v[180:183], v[230:233], 0
	v_mfma_f32_16x16x32_bf16 v[86:89], v[184:187], v[234:237], v[86:89]
	v_mfma_f32_16x16x32_bf16 v[82:85], v[188:191], v[230:233], 0
	v_mfma_f32_16x16x32_bf16 v[82:85], v[192:195], v[234:237], v[82:85]
	v_mfma_f32_16x16x32_bf16 v[70:73], v[180:183], v[238:241], 0
	v_mfma_f32_16x16x32_bf16 v[70:73], v[184:187], v[242:245], v[70:73]
	s_setprio 2
	s_barrier
	v_mfma_f32_16x16x32_bf16 v[66:69], v[188:191], v[238:241], 0
	v_mfma_f32_16x16x32_bf16 v[66:69], v[192:195], v[242:245], v[66:69]
	s_setprio 0
	s_mov_b32 m0, s94
	v_lshl_add_u64 v[148:149], s[60:61], 0, v[136:137]
	ds_read_b128 v[196:199], v151 offset:16384
	ds_read_b128 v[200:203], v151 offset:17408
	ds_read_b128 v[222:225], v151 offset:18432
	ds_read_b128 v[226:229], v151 offset:19456
	ds_read_b128 v[230:233], v151 offset:20480
	ds_read_b128 v[234:237], v151 offset:21504
	ds_read_b128 v[238:241], v151 offset:22528
	ds_read_b128 v[242:245], v151 offset:23552
	global_load_lds_dwordx4 v[148:149], off
	v_lshl_add_u64 v[168:169], s[60:61], 0, v[132:133]
	s_mov_b32 m0, s95
	v_lshl_add_u64 v[172:173], s[62:63], 0, v[136:137]
	global_load_lds_dwordx4 v[168:169], off
	s_mov_b32 m0, s96
	v_lshl_add_u64 v[212:213], s[58:59], 0, v[134:135]
	global_load_lds_dwordx4 v[172:173], off
	v_lshl_add_u64 v[172:173], s[62:63], 0, v[132:133]
	s_mov_b32 m0, s97
	s_nop 0
	global_load_lds_dwordx4 v[172:173], off
	v_lshl_add_u64 v[172:173], s[58:59], 0, v[138:139]
	s_mov_b32 m0, s71
	s_nop 0
	global_load_lds_dwordx4 v[172:173], off
	s_mov_b32 m0, s75
	s_nop 0
	global_load_lds_dwordx4 v[212:213], off
	s_waitcnt vmcnt(8)
	s_waitcnt lgkmcnt(0)
	s_setprio 1
	s_barrier
; #define PG8_STAGE(bufoff, gbase, voff) do { _Pragma("unroll") for (int _i = 0; _i < 2; ++_i) \
;         __builtin_amdgcn_global_load_lds((const unsigned*)((const char*)(gbase) + (voff)[_i]), (PG8_LAS unsigned*)(lds + (bufoff) + ldsw + _i * 8192), 16, 0, AUX_A); } while (0)
; #define PG8_STAGEB(bufoff, gbase, voff) do { _Pragma("unroll") for (int _i = 0; _i < 2; ++_i) \
;         __builtin_amdgcn_global_load_lds((const unsigned*)((const char*)(gbase) + (voff)[_i]), (PG8_LAS unsigned*)(lds + (bufoff) + ldsw + _i * 8192), 16, 0, AUX_B); } while (0)
; #define PG8_LDA(dst, b, h) do { _Pragma("unroll") for (int m = 0; m < 4; ++m) _Pragma("unroll") for (int k = 0; k < 2; ++k) dst[m][k] = *(const PG8_LAS bf16x8*)(lds + PG8_SA(b, h) + aoff + m * 2048 + k * 1024); } while (0)
; #define PG8_LDB(dst, b, h) do { _Pragma("unroll") for (int n = 0; n < 2; ++n) _Pragma("unroll") for (int k = 0; k < 2; ++k) dst[n][k] = *(const PG8_LAS bf16x8*)(lds + PG8_SB(b, h) + boff + n * 2048 + k * 1024); } while (0)
; #define PG8_MMA(ai, bj, At, Bt) do { __builtin_amdgcn_s_setprio(1); _Pragma("unroll") for (int m = 0; m < 4; ++m) _Pragma("unroll") for (int n = 0; n < 2; ++n) _Pragma("unroll") for (int k = 0; k < 2; ++k) \
;         acc[ai][bj][m][n] = __builtin_amdgcn_mfma_f32_16x16x32_bf16(Bt[n][k], At[m][k], acc[ai][bj][m][n], 0, 0, 0); __builtin_amdgcn_s_setprio(0); } while (0)
; #define PG8_WAIT_V(n) asm volatile("s_waitcnt vmcnt(" #n ")" ::: "memory")
; #define PG8_WAIT_L(n) asm volatile("s_waitcnt lgkmcnt(" #n ")" ::: "memory")
; template <class Epi, class Sched, bool ALIGN_EPI = false, bool SP2 = false>
; __device__ __forceinline__ void gemm_phase(PG8_LAS unsigned char* lds, const Gemm g, const Sched& S, const Epi& E) {
;     ...
;             PG8_WAIT_V(8); PG8_WAIT_L(0); PG8_BAR; PG8_MMA(0, 0, At, B0); PG8_MMA(0, 1, At, B1); PG8_BAR; PG8_SCHED;
;             PG8_LDA(At, 0, 1); PG8_STAGEB(PG8_SB(0, 0), b2, voffB); PG8_STAGEB(PG8_SB(0, 1), b2 + hstep, voffB); PG8_STAGE(PG8_SA(0, 0), a2, voffA);
;             PG8_WAIT_V(8); PG8_WAIT_L(0); PG8_BAR; PG8_MMA(1, 0, At, B0); PG8_MMA(1, 1, At, B1); PG8_BAR; PG8_SCHED;
;             PG8_LDB(B0, 1, 0); PG8_LDB(B1, 1, 1); PG8_SCHED; PG8_LDA(At, 1, 0); PG8_STAGE(PG8_SA(0, 1), a2 + hstep, voffA);
;             PG8_WAIT_V(8); PG8_WAIT_L(0); PG8_BAR; PG8_MMA(0, 0, At, B0); PG8_MMA(0, 1, At, B1); PG8_BAR; PG8_SCHED;
	v_mfma_f32_16x16x32_bf16 v[62:65], v[152:155], v[196:199], 0
	v_mfma_f32_16x16x32_bf16 v[62:65], v[156:159], v[200:203], v[62:65]
	v_mfma_f32_16x16x32_bf16 v[58:61], v[160:163], v[196:199], 0
	v_mfma_f32_16x16x32_bf16 v[58:61], v[164:167], v[200:203], v[58:61]
	v_mfma_f32_16x16x32_bf16 v[46:49], v[152:155], v[222:225], 0
	v_mfma_f32_16x16x32_bf16 v[46:49], v[156:159], v[226:229], v[46:49]
	v_mfma_f32_16x16x32_bf16 v[42:45], v[160:163], v[222:225], 0
	v_mfma_f32_16x16x32_bf16 v[42:45], v[164:167], v[226:229], v[42:45]
	v_mfma_f32_16x16x32_bf16 v[30:33], v[152:155], v[230:233], 0
	v_mfma_f32_16x16x32_bf16 v[30:33], v[156:159], v[234:237], v[30:33]
	v_mfma_f32_16x16x32_bf16 v[26:29], v[160:163], v[230:233], 0
	v_mfma_f32_16x16x32_bf16 v[26:29], v[164:167], v[234:237], v[26:29]
	v_mfma_f32_16x16x32_bf16 v[14:17], v[152:155], v[238:241], 0
	v_mfma_f32_16x16x32_bf16 v[14:17], v[156:159], v[242:245], v[14:17]
	v_mfma_f32_16x16x32_bf16 v[10:13], v[160:163], v[238:241], 0
	v_mfma_f32_16x16x32_bf16 v[10:13], v[164:167], v[242:245], v[10:13]
	s_setprio 0
	s_setprio 1
	v_mfma_f32_16x16x32_bf16 v[54:57], v[180:183], v[196:199], 0
	v_mfma_f32_16x16x32_bf16 v[54:57], v[184:187], v[200:203], v[54:57]
	v_mfma_f32_16x16x32_bf16 v[50:53], v[188:191], v[196:199], 0
	v_mfma_f32_16x16x32_bf16 v[50:53], v[192:195], v[200:203], v[50:53]
	v_mfma_f32_16x16x32_bf16 v[38:41], v[180:183], v[222:225], 0
	v_mfma_f32_16x16x32_bf16 v[38:41], v[184:187], v[226:229], v[38:41]
	v_mfma_f32_16x16x32_bf16 v[34:37], v[188:191], v[222:225], 0
	v_mfma_f32_16x16x32_bf16 v[34:37], v[192:195], v[226:229], v[34:37]
	v_mfma_f32_16x16x32_bf16 v[22:25], v[180:183], v[230:233], 0
	v_mfma_f32_16x16x32_bf16 v[22:25], v[184:187], v[234:237], v[22:25]
	v_mfma_f32_16x16x32_bf16 v[18:21], v[188:191], v[230:233], 0
	v_mfma_f32_16x16x32_bf16 v[18:21], v[192:195], v[234:237], v[18:21]
	v_mfma_f32_16x16x32_bf16 v[6:9], v[180:183], v[238:241], 0
	v_mfma_f32_16x16x32_bf16 v[6:9], v[184:187], v[242:245], v[6:9]
	s_setprio 2
	s_barrier
	v_mfma_f32_16x16x32_bf16 v[2:5], v[188:191], v[238:241], 0
	v_mfma_f32_16x16x32_bf16 v[2:5], v[192:195], v[242:245], v[2:5]
	s_setprio 0
	v_add_u32_e32 v164, vcc_lo, v99
	v_add_u32_e32 v192, vcc_hi, v99
	ds_read_b128 v[152:155], v164
	ds_read_b128 v[156:159], v164 offset:1024
	ds_read_b128 v[160:163], v164 offset:2048
	ds_read_b128 v[164:167], v164 offset:3072
	ds_read_b128 v[180:183], v192
	ds_read_b128 v[184:187], v192 offset:1024
	ds_read_b128 v[188:191], v192 offset:2048
	ds_read_b128 v[192:195], v192 offset:3072
	s_mov_b32 m0, s78
	v_lshl_add_u64 v[246:247], s[56:57], 0, v[138:139]
	ds_read_b128 v[196:199], v151 offset:32768
	ds_read_b128 v[200:203], v151 offset:33792
	ds_read_b128 v[222:225], v151 offset:34816
	ds_read_b128 v[226:229], v151 offset:35840
	ds_read_b128 v[230:233], v151 offset:36864
	ds_read_b128 v[234:237], v151 offset:37888
	ds_read_b128 v[238:241], v151 offset:38912
	ds_read_b128 v[242:245], v151 offset:39936
	global_load_lds_dwordx4 v[246:247], off
	v_lshl_add_u64 v[246:247], s[56:57], 0, v[134:135]
	s_mov_b32 m0, s82
	s_nop 0
	global_load_lds_dwordx4 v[246:247], off
	s_waitcnt vmcnt(8)
	s_waitcnt lgkmcnt(0)
	s_setprio 1
	s_barrier
	v_mfma_f32_16x16x32_bf16 v[128:131], v[152:155], v[196:199], v[128:131]
	v_mfma_f32_16x16x32_bf16 v[128:131], v[156:159], v[200:203], v[128:131]
	v_mfma_f32_16x16x32_bf16 v[124:127], v[160:163], v[196:199], v[124:127]
	v_mfma_f32_16x16x32_bf16 v[124:127], v[164:167], v[200:203], v[124:127]
	v_mfma_f32_16x16x32_bf16 v[112:115], v[152:155], v[222:225], v[112:115]
	v_mfma_f32_16x16x32_bf16 v[112:115], v[156:159], v[226:229], v[112:115]
	v_mfma_f32_16x16x32_bf16 v[108:111], v[160:163], v[222:225], v[108:111]
	v_mfma_f32_16x16x32_bf16 v[108:111], v[164:167], v[226:229], v[108:111]
	v_mfma_f32_16x16x32_bf16 v[94:97], v[152:155], v[230:233], v[94:97]
	v_mfma_f32_16x16x32_bf16 v[94:97], v[156:159], v[234:237], v[94:97]
	v_mfma_f32_16x16x32_bf16 v[90:93], v[160:163], v[230:233], v[90:93]
	v_mfma_f32_16x16x32_bf16 v[90:93], v[164:167], v[234:237], v[90:93]
	v_mfma_f32_16x16x32_bf16 v[78:81], v[152:155], v[238:241], v[78:81]
	v_mfma_f32_16x16x32_bf16 v[78:81], v[156:159], v[242:245], v[78:81]
	v_mfma_f32_16x16x32_bf16 v[74:77], v[160:163], v[238:241], v[74:77]
	v_mfma_f32_16x16x32_bf16 v[74:77], v[164:167], v[242:245], v[74:77]
	s_setprio 0
	s_setprio 1
	v_mfma_f32_16x16x32_bf16 v[120:123], v[180:183], v[196:199], v[120:123]
	v_mfma_f32_16x16x32_bf16 v[120:123], v[184:187], v[200:203], v[120:123]
	v_mfma_f32_16x16x32_bf16 v[116:119], v[188:191], v[196:199], v[116:119]
	v_mfma_f32_16x16x32_bf16 v[116:119], v[192:195], v[200:203], v[116:119]
	v_mfma_f32_16x16x32_bf16 v[104:107], v[180:183], v[222:225], v[104:107]
	v_mfma_f32_16x16x32_bf16 v[104:107], v[184:187], v[226:229], v[104:107]
	v_mfma_f32_16x16x32_bf16 v[100:103], v[188:191], v[222:225], v[100:103]
	v_mfma_f32_16x16x32_bf16 v[100:103], v[192:195], v[226:229], v[100:103]
	v_mfma_f32_16x16x32_bf16 v[86:89], v[180:183], v[230:233], v[86:89]
	v_mfma_f32_16x16x32_bf16 v[86:89], v[184:187], v[234:237], v[86:89]
	v_mfma_f32_16x16x32_bf16 v[82:85], v[188:191], v[230:233], v[82:85]
	v_mfma_f32_16x16x32_bf16 v[82:85], v[192:195], v[234:237], v[82:85]
	v_mfma_f32_16x16x32_bf16 v[70:73], v[180:183], v[238:241], v[70:73]
	v_mfma_f32_16x16x32_bf16 v[70:73], v[184:187], v[242:245], v[70:73]
	s_setprio 2
	s_barrier
; #define PG8_STAGE(bufoff, gbase, voff) do { _Pragma("unroll") for (int _i = 0; _i < 2; ++_i) \
;         __builtin_amdgcn_global_load_lds((const unsigned*)((const char*)(gbase) + (voff)[_i]), (PG8_LAS unsigned*)(lds + (bufoff) + ldsw + _i * 8192), 16, 0, AUX_A); } while (0)
; #define PG8_STAGEB(bufoff, gbase, voff) do { _Pragma("unroll") for (int _i = 0; _i < 2; ++_i) \
;         __builtin_amdgcn_global_load_lds((const unsigned*)((const char*)(gbase) + (voff)[_i]), (PG8_LAS unsigned*)(lds + (bufoff) + ldsw + _i * 8192), 16, 0, AUX_B); } while (0)
; #define PG8_LDA(dst, b, h) do { _Pragma("unroll") for (int m = 0; m < 4; ++m) _Pragma("unroll") for (int k = 0; k < 2; ++k) dst[m][k] = *(const PG8_LAS bf16x8*)(lds + PG8_SA(b, h) + aoff + m * 2048 + k * 1024); } while (0)
; #define PG8_LDB(dst, b, h) do { _Pragma("unroll") for (int n = 0; n < 2; ++n) _Pragma("unroll") for (int k = 0; k < 2; ++k) dst[n][k] = *(const PG8_LAS bf16x8*)(lds + PG8_SB(b, h) + boff + n * 2048 + k * 1024); } while (0)
; #define PG8_MMA(ai, bj, At, Bt) do { __builtin_amdgcn_s_setprio(1); _Pragma("unroll") for (int m = 0; m < 4; ++m) _Pragma("unroll") for (int n = 0; n < 2; ++n) _Pragma("unroll") for (int k = 0; k < 2; ++k) \
;         acc[ai][bj][m][n] = __builtin_amdgcn_mfma_f32_16x16x32_bf16(Bt[n][k], At[m][k], acc[ai][bj][m][n], 0, 0, 0); __builtin_amdgcn_s_setprio(0); } while (0)
; #define PG8_WAIT_V(n) asm volatile("s_waitcnt vmcnt(" #n ")" ::: "memory")
; #define PG8_WAIT_L(n) asm volatile("s_waitcnt lgkmcnt(" #n ")" ::: "memory")
; #define PG8_BAR __builtin_amdgcn_s_barrier()
; #define PG8_SCHED __builtin_amdgcn_sched_barrier(0)
; template <class Epi, class Sched, bool ALIGN_EPI = false, bool SP2 = false>
; __device__ __forceinline__ void gemm_phase(PG8_LAS unsigned char* lds, const Gemm g, const Sched& S, const Epi& E) {
;     ...
;             PG8_LDB(B0, 1, 0); PG8_LDB(B1, 1, 1); PG8_SCHED; PG8_LDA(At, 1, 0); PG8_STAGE(PG8_SA(0, 1), a2 + hstep, voffA);
;             PG8_WAIT_V(8); PG8_WAIT_L(0); PG8_BAR; PG8_MMA(0, 0, At, B0); PG8_MMA(0, 1, At, B1); PG8_BAR; PG8_SCHED;
;             PG8_LDA(At, 1, 1); PG8_STAGEB(PG8_SB(1, 0), b3, voffB); PG8_STAGEB(PG8_SB(1, 1), b3 + hstep, voffB); PG8_STAGE(PG8_SA(1, 0), a3, voffA);
;             PG8_WAIT_V(8); PG8_WAIT_L(0); PG8_BAR; PG8_MMA(1, 0, At, B0); PG8_MMA(1, 1, At, B1); PG8_BAR; PG8_SCHED;
	v_mfma_f32_16x16x32_bf16 v[66:69], v[188:191], v[238:241], v[66:69]
	v_mfma_f32_16x16x32_bf16 v[66:69], v[192:195], v[242:245], v[66:69]
	s_setprio 0
	s_mov_b32 m0, s1
	v_lshl_add_u64 v[148:149], v[148:149], 0, s[76:77]
	ds_read_b128 v[196:199], v151 offset:49152
	ds_read_b128 v[200:203], v151 offset:50176
	ds_read_b128 v[222:225], v151 offset:51200
	ds_read_b128 v[226:229], v151 offset:52224
	ds_read_b128 v[230:233], v151 offset:53248
	ds_read_b128 v[234:237], v151 offset:54272
	ds_read_b128 v[238:241], v151 offset:55296
	ds_read_b128 v[242:245], v151 offset:56320
	global_load_lds_dwordx4 v[148:149], off
	v_lshl_add_u64 v[148:149], v[168:169], 0, s[76:77]
	s_mov_b32 m0, s0
	s_nop 0
	global_load_lds_dwordx4 v[148:149], off
	v_lshl_add_u64 v[148:149], s[54:55], 0, v[136:137]
	s_mov_b32 m0, s47
	s_nop 0
	global_load_lds_dwordx4 v[148:149], off
	v_lshl_add_u64 v[148:149], s[54:55], 0, v[132:133]
	s_mov_b32 m0, s46
	s_nop 0
	global_load_lds_dwordx4 v[148:149], off
	v_lshl_add_u64 v[148:149], v[172:173], 0, s[76:77]
	s_mov_b32 m0, s83
	s_nop 0
	global_load_lds_dwordx4 v[148:149], off
	v_lshl_add_u64 v[148:149], v[212:213], 0, s[76:77]
	s_mov_b32 m0, s88
	s_nop 0
	global_load_lds_dwordx4 v[148:149], off
	s_waitcnt vmcnt(8)
	s_waitcnt lgkmcnt(0)
	s_setprio 1
	s_barrier
	v_mfma_f32_16x16x32_bf16 v[62:65], v[152:155], v[196:199], v[62:65]
	v_mfma_f32_16x16x32_bf16 v[62:65], v[156:159], v[200:203], v[62:65]
	v_mfma_f32_16x16x32_bf16 v[58:61], v[160:163], v[196:199], v[58:61]
	v_mfma_f32_16x16x32_bf16 v[58:61], v[164:167], v[200:203], v[58:61]
	v_mfma_f32_16x16x32_bf16 v[46:49], v[152:155], v[222:225], v[46:49]
	v_mfma_f32_16x16x32_bf16 v[46:49], v[156:159], v[226:229], v[46:49]
	v_mfma_f32_16x16x32_bf16 v[42:45], v[160:163], v[222:225], v[42:45]
	v_mfma_f32_16x16x32_bf16 v[42:45], v[164:167], v[226:229], v[42:45]
	v_mfma_f32_16x16x32_bf16 v[30:33], v[152:155], v[230:233], v[30:33]
	v_mfma_f32_16x16x32_bf16 v[30:33], v[156:159], v[234:237], v[30:33]
	v_mfma_f32_16x16x32_bf16 v[26:29], v[160:163], v[230:233], v[26:29]
	v_mfma_f32_16x16x32_bf16 v[26:29], v[164:167], v[234:237], v[26:29]
	v_mfma_f32_16x16x32_bf16 v[14:17], v[152:155], v[238:241], v[14:17]
	v_mfma_f32_16x16x32_bf16 v[14:17], v[156:159], v[242:245], v[14:17]
	v_mfma_f32_16x16x32_bf16 v[10:13], v[160:163], v[238:241], v[10:13]
	v_mfma_f32_16x16x32_bf16 v[10:13], v[164:167], v[242:245], v[10:13]
	s_setprio 0
	s_setprio 1
	v_mfma_f32_16x16x32_bf16 v[54:57], v[180:183], v[196:199], v[54:57]
	v_mfma_f32_16x16x32_bf16 v[54:57], v[184:187], v[200:203], v[54:57]
	v_mfma_f32_16x16x32_bf16 v[50:53], v[188:191], v[196:199], v[50:53]
	v_mfma_f32_16x16x32_bf16 v[50:53], v[192:195], v[200:203], v[50:53]
	v_mfma_f32_16x16x32_bf16 v[38:41], v[180:183], v[222:225], v[38:41]
	v_mfma_f32_16x16x32_bf16 v[38:41], v[184:187], v[226:229], v[38:41]
	v_mfma_f32_16x16x32_bf16 v[34:37], v[188:191], v[222:225], v[34:37]
	v_mfma_f32_16x16x32_bf16 v[34:37], v[192:195], v[226:229], v[34:37]
	v_mfma_f32_16x16x32_bf16 v[22:25], v[180:183], v[230:233], v[22:25]
	v_mfma_f32_16x16x32_bf16 v[22:25], v[184:187], v[234:237], v[22:25]
	v_mfma_f32_16x16x32_bf16 v[18:21], v[188:191], v[230:233], v[18:21]
	v_mfma_f32_16x16x32_bf16 v[18:21], v[192:195], v[234:237], v[18:21]
	v_mfma_f32_16x16x32_bf16 v[6:9], v[180:183], v[238:241], v[6:9]
	v_mfma_f32_16x16x32_bf16 v[6:9], v[184:187], v[242:245], v[6:9]
	s_setprio 2
	s_barrier
	v_mfma_f32_16x16x32_bf16 v[2:5], v[188:191], v[238:241], v[2:5]
	v_mfma_f32_16x16x32_bf16 v[2:5], v[192:195], v[242:245], v[2:5]
	s_setprio 0
	v_lshl_add_u64 v[144:145], v[144:145], 0, s[86:87]
	v_lshl_add_u64 v[146:147], v[146:147], 0, s[86:87]
	s_mov_b32 s29, s81
	s_cbranch_scc1 .Lpx_1067

; #define PG8_STAGE(bufoff, gbase, voff) do { _Pragma("unroll") for (int _i = 0; _i < 2; ++_i) \
;         __builtin_amdgcn_global_load_lds((const unsigned*)((const char*)(gbase) + (voff)[_i]), (PG8_LAS unsigned*)(lds + (bufoff) + ldsw + _i * 8192), 16, 0, AUX_A); } while (0)
; #define PG8_WAIT_V(n) asm volatile("s_waitcnt vmcnt(" #n ")" ::: "memory")
; template <class Epi, class Sched, bool ALIGN_EPI = false, bool SP2 = false>
; __device__ __forceinline__ void gemm_phase(PG8_LAS unsigned char* lds, const Gemm g, const Sched& S, const Epi& E) {
;     ...
;     const int tid = tid_l, wid = __builtin_amdgcn_readfirstlane(tid >> 6), lane = tid & 63, wr = wid >> 2, wc = wid & 3, fr = lane & 15, fq = lane >> 4;
;     const int K = g.K;
;     unsigned voffA[2], voffB[2];
; #pragma unroll
;     for (int i = 0; i < 2; ++i) { int R, C; stage_rc(tid * 16 + i * 8192, R, C); const int Rb = Epi::PERM ? ((R & ~31) + perm32(R & 31)) : R;
;         voffA[i] = (unsigned)(R * K + C) * 2u; voffB[i] = (unsigned)(Rb * K + C) * 2u; }
;     const size_t kstep = (size_t)(BK * 2);
;     const size_t hstep = (size_t)HALF * K * 2;
;     const size_t tstep = 2 * hstep;
;     const unsigned ldsw = (unsigned)wid * 1024u;
;     const int aoff = lds_byte(wr * 64 + fr, fq * 8), boff = lds_byte(wc * 32 + fr, fq * 8);
;     ...
;     { const int rot0 = cur.krot, nt0 = cur.nkt; const char* sA0 = PG8_KP(cA, 0, rot0, nt0); const char* sA1 = PG8_KP(cA, 1, rot0, nt0); const char* sB0 = PG8_KP(cB, 0, rot0, nt0); const char* sB1 = PG8_KP(cB, 1, rot0, nt0);
;     if constexpr (SP2) {
;         PG8_STAGEB(PG8_SB(0, 0), sB0, voffB); PG8_STAGEB(PG8_SB(0, 1), sB0 + hstep, voffB); PG8_STAGE(PG8_SA(0, 0), sA0, voffA); PG8_STAGE(PG8_SA(0, 1), sA0 + hstep, voffA);
;         if (wr == 1) PG8_BAR;
;         PG8_WAIT_V(2); PG8_BAR;
;         PG8_STAGEB(PG8_SB(1, 0), sB1, voffB); PG8_STAGE(PG8_SA(1, 0), sA1, voffA); PG8_STAGEB(PG8_SB(1, 1), sB1 + hstep, voffB);
;         PG8_WAIT_V(6); PG8_BAR;
;     } else {
;         PG8_STAGEB(PG8_SB(0, 0), sB0, voffB); PG8_STAGE(PG8_SA(0, 0), sA0, voffA); PG8_STAGEB(PG8_SB(0, 1), sB0 + hstep, voffB); PG8_STAGE(PG8_SA(0, 1), sA0 + hstep, voffA);
;         if (wr == 1) PG8_BAR;
;         PG8_WAIT_V(4); PG8_BAR;
;         PG8_STAGEB(PG8_SB(1, 0), sB1, voffB); PG8_STAGE(PG8_SA(1, 0), sA1, voffA); PG8_STAGEB(PG8_SB(1, 1), sB1 + hstep, voffB);
;         PG8_WAIT_V(6); PG8_BAR;
;     }
.LBB0_1143:
	s_add_u32 s0, s4, s44
	s_waitcnt vmcnt(0)
	s_addc_u32 s1, s5, s45
	s_add_u32 s6, s0, 0x9000000
	v_mov_b32_e32 v16, v0
	s_waitcnt vmcnt(0) lgkmcnt(0)
	s_barrier
	s_addc_u32 s7, s1, 0
	s_and_b64 vcc, exec, s[38:39]
	v_readfirstlane_b32 s16, v16
	s_cbranch_vccnz .LBB0_1182
	v_lshlrev_b32_e32 v1, 4, v16
	v_add_u32_e32 v2, 0x2000, v1
	v_ashrrev_i32_e32 v3, 31, v2
	v_lshrrev_b32_e32 v3, 22, v3
	v_add_u32_e32 v3, v2, v3
	v_ashrrev_i32_e32 v10, 10, v3
	v_mul_i32_i24_e32 v3, 0x400, v10
	v_sub_u32_e32 v2, v2, v3
	v_lshrrev_b32_e32 v3, 4, v2
	v_bitop3_b32 v2, v3, v2, 32 bitop3:0x6c
	v_ashrrev_i32_e32 v3, 31, v2
	v_lshrrev_b32_e32 v3, 26, v3
	v_add_u32_e32 v3, v2, v3
	v_lshlrev_b32_e32 v4, 3, v10
	v_ashrrev_i32_e32 v11, 6, v3
	v_and_b32_e32 v4, -16, v4
	v_add_u32_e32 v4, v11, v4
	v_and_b32_e32 v5, 3, v11
	s_mov_b32 s2, 0x1fffe0
	v_lshrrev_b32_e32 v6, 2, v4
	v_lshlrev_b32_e32 v7, 1, v4
	v_and_b32_e32 v3, 0xc0, v3
	v_and_or_b32 v5, v4, s2, v5
	v_and_b32_e32 v6, 4, v6
	v_and_b32_e32 v7, 24, v7
	v_sub_u32_e32 v2, v2, v3
	v_or3_b32 v5, v5, v6, v7
	v_lshlrev_b32_e32 v6, 5, v10
	v_ashrrev_i16_sdwa v2, v207, sext(v2) dst_sel:DWORD dst_unused:UNUSED_PAD src0_sel:DWORD src1_sel:BYTE_0
	v_and_b32_e32 v6, 32, v6
	v_bfe_i32 v12, v2, 0, 16
	v_add_lshl_u32 v2, v6, v12, 1
	v_lshl_add_u32 v132, v5, 11, v2
	v_lshl_add_u32 v134, v4, 11, v2
	v_bfe_i32 v2, v16, 27, 1
	v_lshrrev_b32_e32 v2, 22, v2
	v_add_u32_e32 v2, v1, v2
	v_and_b32_e32 v2, 0xfffffc00, v2
	v_sub_u32_e32 v1, v1, v2
	v_lshrrev_b32_e32 v2, 4, v1
	v_ashrrev_i32_e32 v3, 31, v16
	v_bitop3_b32 v1, v2, v1, 32 bitop3:0x6c
	v_lshrrev_b32_e32 v3, 26, v3
	v_ashrrev_i32_e32 v2, 31, v1
	v_add_u32_e32 v3, v16, v3
	v_lshrrev_b32_e32 v2, 26, v2
	v_ashrrev_i32_e32 v14, 6, v3
	v_add_u32_e32 v2, v1, v2
	v_lshlrev_b32_e32 v3, 3, v14
	v_ashrrev_i32_e32 v13, 6, v2
	v_and_b32_e32 v3, -16, v3
	v_add_u32_e32 v3, v13, v3
	s_add_u32 s33, s4, 0x29b80000
	v_and_b32_e32 v4, 3, v13
	v_lshrrev_b32_e32 v5, 2, v3
	v_lshlrev_b32_e32 v6, 1, v3
	v_and_b32_e32 v2, 0xc0, v2
	s_addc_u32 s69, s5, 0
	s_ashr_i32 s0, s16, 6
	v_and_or_b32 v4, v3, s2, v4
	v_and_b32_e32 v5, 4, v5
	v_and_b32_e32 v6, 24, v6
	v_sub_u32_e32 v1, v1, v2
	s_ashr_i32 s1, s16, 8
	s_lshl_b32 s70, s0, 10
	v_or3_b32 v4, v4, v5, v6
	v_lshlrev_b32_e32 v5, 5, v14
	v_ashrrev_i16_sdwa v1, v207, sext(v1) dst_sel:DWORD dst_unused:UNUSED_PAD src0_sel:DWORD src1_sel:BYTE_0
	v_readlane_b32 s2, v253, 3
	v_and_b32_e32 v5, 32, v5
	v_bfe_i32 v15, v1, 0, 16
	v_readlane_b32 s3, v253, 4
	s_add_u32 s50, s6, s2
	v_add_lshl_u32 v1, v5, v15, 1
	s_addc_u32 s51, s7, s3
	s_add_i32 s71, s70, 0
	v_lshl_add_u32 v136, v4, 11, v1
	s_add_i32 m0, s71, 0x10000
	v_readlane_b32 s2, v252, 63
	global_load_lds_dwordx4 v136, s[50:51]
	s_add_i32 m0, s71, 0x12000
	v_readlane_b32 s3, v253, 0
	s_add_u32 s52, s33, s2
	s_addc_u32 s53, s69, s3
	s_add_u32 s12, s50, 0x40000
	global_load_lds_dwordx4 v132, s[50:51]
	s_addc_u32 s13, s51, 0
	s_add_i32 m0, s71, 0x14000
	s_add_i32 s75, s71, 0x2000
	global_load_lds_dwordx4 v136, s[12:13]
	s_add_i32 m0, s71, 0x16000
	v_lshl_add_u32 v138, v3, 11, v1
	global_load_lds_dwordx4 v132, s[12:13]
	s_mov_b32 m0, s71
	s_add_u32 s12, s52, 0x40000
	global_load_lds_dwordx4 v138, s[52:53]
	s_mov_b32 m0, s75
	s_addc_u32 s13, s53, 0
	s_add_i32 s78, s71, 0x4000
	global_load_lds_dwordx4 v134, s[52:53]
	s_mov_b32 m0, s78
	s_add_i32 s82, s71, 0x6000
	global_load_lds_dwordx4 v138, s[12:13]
	s_mov_b32 m0, s82
	v_mov_b32_e32 v137, v98
	global_load_lds_dwordx4 v134, s[12:13]
	v_mov_b32_e32 v133, v98
	v_mov_b32_e32 v139, v98
	v_mov_b32_e32 v135, v98
	s_cmp_eq_u32 s1, 1
	v_lshl_add_u64 v[8:9], s[50:51], 0, v[136:137]
	v_lshl_add_u64 v[6:7], s[50:51], 0, v[132:133]
	v_lshl_add_u64 v[2:3], s[52:53], 0, v[138:139]
	s_cselect_b64 s[12:13], -1, 0
	s_cmp_lg_u32 s1, 1
	v_lshl_add_u64 v[4:5], s[52:53], 0, v[134:135]
	s_cbranch_scc1 .LBB0_1146
.LBB0_1146:
	s_add_u32 s14, s4, 0x2d180000
	v_lshrrev_b32_e32 v18, 1, v16
	s_addc_u32 s15, s5, 0
	v_and_b32_e32 v18, 24, v18
	s_lshl_b32 s0, s0, 5
	v_and_b32_e32 v17, 15, v16
	v_lshlrev_b32_e32 v19, 1, v18
	v_lshlrev_b32_e32 v16, 2, v16
	s_and_b32 s2, s0, 0x60
	s_add_i32 m0, s71, 0x18000
	v_lshl_add_u64 v[8:9], v[8:9], 0, s[76:77]
	v_lshl_or_b32 v1, s1, 6, v17
	v_lshl_or_b32 v17, v17, 6, v19
	s_lshl_b32 s1, s1, 13
	v_and_b32_e32 v16, 32, v16
	s_lshl_b32 s0, s2, 7
	global_load_lds_dwordx4 v[8:9], off
	v_lshl_add_u64 v[6:7], v[6:7], 0, s[76:77]
	s_add_i32 m0, s71, 0x1a000
	s_add_i32 s83, s71, 0x8000
	s_add_i32 s88, s71, 0xa000
	v_bitop3_b32 v99, v17, s0, v16 bitop3:0xde
	global_load_lds_dwordx4 v[6:7], off
	v_lshl_add_u64 v[2:3], v[2:3], 0, s[76:77]
	s_mov_b32 m0, s83
	s_add_u32 s0, s50, 0x40080
	v_bitop3_b32 v19, v17, s1, v16 bitop3:0xde
	global_load_lds_dwordx4 v[2:3], off
	v_lshl_add_u64 v[2:3], v[4:5], 0, s[76:77]
	s_mov_b32 m0, s88
	s_addc_u32 s1, s51, 0
	global_load_lds_dwordx4 v[2:3], off
	s_add_i32 m0, s71, 0x1c000
	v_lshl_add_u64 v[2:3], s[0:1], 0, v[136:137]
	global_load_lds_dwordx4 v[2:3], off
	v_lshl_add_u64 v[2:3], s[0:1], 0, v[132:133]
	s_add_i32 m0, s71, 0x1e000
	v_or_b32_e32 v152, s2, v18
	global_load_lds_dwordx4 v[2:3], off
	s_waitcnt vmcnt(8)
	s_barrier
	v_lshlrev_b32_e32 v2, 14, v10
	v_and_b32_e32 v2, 0xffff8000, v2
	v_lshl_add_u32 v2, v11, 11, v2
	v_and_b32_e32 v3, 1, v10
	v_lshl_or_b32 v2, v3, 6, v2
	v_lshl_add_u32 v140, v12, 1, v2
	v_lshlrev_b32_e32 v2, 14, v14
	v_and_b32_e32 v2, 0xffff8000, v2
	v_readlane_b32 s2, v253, 1
	s_waitcnt vmcnt(6)
	v_lshl_add_u32 v2, v13, 11, v2
	v_and_b32_e32 v3, 1, v14
	v_readlane_b32 s3, v253, 2
	s_cmpk_lt_u32 s16, 0x100
	v_lshl_or_b32 v2, v3, 6, v2
	s_mov_b32 s91, s2
	v_readlane_b32 s2, v252, 61
	s_cselect_b64 s[16:17], -1, 0
	v_mov_b32_e32 v141, v98
	v_lshl_add_u32 v142, v15, 1, v2
	v_mov_b32_e32 v143, v98
	s_mov_b32 s0, 0
	v_add_u32_e32 v153, 0, v19
	s_mov_b32 s90, s2
	s_barrier
	v_readlane_b32 s3, v252, 62
	s_branch .LBB0_1149

; #define PG8_STAGE(bufoff, gbase, voff) do { _Pragma("unroll") for (int _i = 0; _i < 2; ++_i) \
;         __builtin_amdgcn_global_load_lds((const unsigned*)((const char*)(gbase) + (voff)[_i]), (PG8_LAS unsigned*)(lds + (bufoff) + ldsw + _i * 8192), 16, 0, AUX_A); } while (0)
; #define PG8_STAGEB(bufoff, gbase, voff) do { _Pragma("unroll") for (int _i = 0; _i < 2; ++_i) \
;         __builtin_amdgcn_global_load_lds((const unsigned*)((const char*)(gbase) + (voff)[_i]), (PG8_LAS unsigned*)(lds + (bufoff) + ldsw + _i * 8192), 16, 0, AUX_B); } while (0)
; #define PG8_WAIT_V(n) asm volatile("s_waitcnt vmcnt(" #n ")" ::: "memory")
; #define PG8_WAIT_L(n) asm volatile("s_waitcnt lgkmcnt(" #n ")" ::: "memory")
; template <class Epi, class Sched, bool ALIGN_EPI = false, bool SP2 = false>
; __device__ __forceinline__ void gemm_phase(PG8_LAS unsigned char* lds, const Gemm g, const Sched& S, const Epi& E) {
;     ...
;         const bool has_next = S.next(ui + 1, nxt);
;         const char* nA = has_next ? (const char*)g.A + (size_t)nxt.pm * tstep + (size_t)nxt.kt0 * kstep : cA; const char* nB = has_next ? (const char*)g.Bt + (size_t)nxt.pn * tstep + (size_t)nxt.kt0 * kstep : cB;
;         const int nt = cur.nkt, rot = cur.krot;
;         const char* nAr = has_next ? nA + (size_t)nxt.krot * kstep : PG8_KP(cA, 0, rot, nt); const char* nBr = has_next ? nB + (size_t)nxt.krot * kstep : PG8_KP(cB, 0, rot, nt);
;         for (int t = 0; t < nt; t += 2) {
;             const bool last = (t == nt - 2);
;             const char* a1 = PG8_KP(cA, t + 1, rot, nt);
;             const char* a2 = last ? nAr : PG8_KP(cA, t + 2, rot, nt); const char* b2 = last ? nBr : PG8_KP(cB, t + 2, rot, nt);
;             const char* a3 = a2 + kstep; const char* b3 = b2 + kstep;
;             if (last && has_next) S.a_ready(nxt);
;             if constexpr (SP2) {
;             PG8_LDB(B0, 0, 0); PG8_LDB(B1, 0, 1); PG8_SCHED; PG8_LDA(At, 0, 0); PG8_STAGE(PG8_SA(1, 1), a1 + hstep, voffA);
;             PG8_WAIT_V(8); PG8_WAIT_L(0); PG8_BAR; PG8_MMA(0, 0, At, B0); PG8_MMA(0, 1, At, B1); PG8_BAR; PG8_SCHED;
;             PG8_LDA(At, 0, 1); PG8_STAGEB(PG8_SB(0, 0), b2, voffB); PG8_STAGEB(PG8_SB(0, 1), b2 + hstep, voffB); PG8_STAGE(PG8_SA(0, 0), a2, voffA);
;             PG8_WAIT_V(8); PG8_WAIT_L(0); PG8_BAR; PG8_MMA(1, 0, At, B0); PG8_MMA(1, 1, At, B1); PG8_BAR; PG8_SCHED;
.LBB0_1156:
	s_mov_b32 s18, s19
	s_ashr_i32 s19, s19, 31
	s_mov_b32 s38, s1
	s_lshl_b64 s[0:1], s[18:19], 19
	s_add_u32 s40, s33, s0
	s_addc_u32 s41, s69, s1
	s_ashr_i32 s39, s38, 31
	s_lshl_b64 s[0:1], s[38:39], 19
	s_add_u32 s48, s6, s0
	s_addc_u32 s49, s7, s1
	s_and_b64 s[0:1], s[42:43], exec
	s_cselect_b32 s19, s41, s53
	s_cselect_b32 s39, s40, s52
	s_cselect_b32 s92, s49, s51
	s_cselect_b32 s93, s48, s50
	s_add_u32 s0, s52, 0x40080
	s_addc_u32 s1, s53, 0
	v_lshl_add_u64 v[144:145], s[0:1], 0, v[140:141]
	v_lshl_add_u64 v[146:147], s[0:1], 0, v[142:143]
	s_mov_b32 s29, 0
	s_cmp_lg_u64 s[16:17], 0
	s_cbranch_scc1 .Lrp_1157
	s_barrier
.Lrp_1157:
.Lpk_1157:
	s_add_i32 s81, s29, 2
	s_cmp_lt_u32 s29, 14
	s_cselect_b32 s0, 0, -16
	s_add_i32 s0, s81, s0
	s_ashr_i32 s1, s0, 31
	s_lshl_b64 s[0:1], s[0:1], 7
	s_add_u32 s2, s52, s0
	s_addc_u32 s46, s53, s1
	s_add_u32 s0, s50, s0
	s_addc_u32 s1, s51, s1
	s_cmp_eq_u32 s29, 14
	s_cselect_b32 s59, s19, s46
	s_cselect_b32 s58, s39, s2
	s_cselect_b32 s61, s92, s1
	s_cselect_b32 s60, s93, s0
	s_add_i32 s2, 0, 0x10000
	s_add_i32 s94, s2, s70
	s_add_i32 s46, 0, 0x14000
	s_add_i32 m0, s71, 0xc000
	s_add_i32 s84, s71, 0xe000
	s_add_i32 s95, s94, 0x2000
	s_add_u32 s62, s60, 0x40000
	s_addc_u32 s63, s61, 0
	s_add_i32 s96, s46, s70
	v_add_u32_e32 v162, s2, v99
	v_add_u32_e32 v166, s46, v99
	s_add_i32 s97, s96, 0x2000
	s_add_i32 vcc_lo, 0, 0x18000
	s_add_i32 vcc_hi, 0, 0x1c000
	ds_read_b128 v[148:151], v162
	ds_read_b128 v[154:157], v162 offset:1024
	ds_read_b128 v[158:161], v162 offset:2048
	ds_read_b128 v[162:165], v162 offset:3072
	ds_read_b128 v[180:183], v166
	ds_read_b128 v[184:187], v166 offset:1024
	ds_read_b128 v[188:191], v166 offset:2048
	ds_read_b128 v[192:195], v166 offset:3072
	s_add_u32 s56, s58, 0x40000
	s_addc_u32 s57, s59, 0
	s_add_i32 s1, vcc_lo, s70
	s_add_i32 s0, s1, 0x2000
	s_add_u32 s54, s60, 0x40080
	s_addc_u32 s55, s61, 0
	s_add_i32 s47, vcc_hi, s70
	s_add_i32 s46, s47, 0x2000
	s_cmp_gt_u32 s29, 13
	ds_read_b128 v[196:199], v153
	ds_read_b128 v[200:203], v153 offset:1024
	ds_read_b128 v[222:225], v153 offset:2048
	ds_read_b128 v[226:229], v153 offset:3072
	ds_read_b128 v[230:233], v153 offset:4096
	ds_read_b128 v[234:237], v153 offset:5120
	ds_read_b128 v[238:241], v153 offset:6144
	ds_read_b128 v[242:245], v153 offset:7168
	global_load_lds_dwordx4 v[146:147], off
	s_mov_b32 m0, s84
	s_nop 0
	global_load_lds_dwordx4 v[144:145], off
	s_waitcnt vmcnt(8)
	s_waitcnt lgkmcnt(0)
	s_setprio 1
	s_barrier
	v_mfma_f32_16x16x32_bf16 v[128:131], v[148:151], v[196:199], 0
	v_mfma_f32_16x16x32_bf16 v[128:131], v[154:157], v[200:203], v[128:131]
	v_mfma_f32_16x16x32_bf16 v[124:127], v[158:161], v[196:199], 0
	v_mfma_f32_16x16x32_bf16 v[124:127], v[162:165], v[200:203], v[124:127]
	v_mfma_f32_16x16x32_bf16 v[112:115], v[148:151], v[222:225], 0
	v_mfma_f32_16x16x32_bf16 v[112:115], v[154:157], v[226:229], v[112:115]
	v_mfma_f32_16x16x32_bf16 v[108:111], v[158:161], v[222:225], 0
	v_mfma_f32_16x16x32_bf16 v[108:111], v[162:165], v[226:229], v[108:111]
	v_mfma_f32_16x16x32_bf16 v[94:97], v[148:151], v[230:233], 0
	v_mfma_f32_16x16x32_bf16 v[94:97], v[154:157], v[234:237], v[94:97]
	v_mfma_f32_16x16x32_bf16 v[90:93], v[158:161], v[230:233], 0
	v_mfma_f32_16x16x32_bf16 v[90:93], v[162:165], v[234:237], v[90:93]
	v_mfma_f32_16x16x32_bf16 v[78:81], v[148:151], v[238:241], 0
	v_mfma_f32_16x16x32_bf16 v[78:81], v[154:157], v[242:245], v[78:81]
	v_mfma_f32_16x16x32_bf16 v[74:77], v[158:161], v[238:241], 0
	v_mfma_f32_16x16x32_bf16 v[74:77], v[162:165], v[242:245], v[74:77]
	s_setprio 0
	s_setprio 1
	v_mfma_f32_16x16x32_bf16 v[120:123], v[180:183], v[196:199], 0
	v_mfma_f32_16x16x32_bf16 v[120:123], v[184:187], v[200:203], v[120:123]
	v_mfma_f32_16x16x32_bf16 v[116:119], v[188:191], v[196:199], 0
	v_mfma_f32_16x16x32_bf16 v[116:119], v[192:195], v[200:203], v[116:119]
	v_mfma_f32_16x16x32_bf16 v[104:107], v[180:183], v[222:225], 0
	v_mfma_f32_16x16x32_bf16 v[104:107], v[184:187], v[226:229], v[104:107]
	v_mfma_f32_16x16x32_bf16 v[100:103], v[188:191], v[222:225], 0
	v_mfma_f32_16x16x32_bf16 v[100:103], v[192:195], v[226:229], v[100:103]
	v_mfma_f32_16x16x32_bf16 v[86:89], v[180:183], v[230:233], 0
	v_mfma_f32_16x16x32_bf16 v[86:89], v[184:187], v[234:237], v[86:89]
	v_mfma_f32_16x16x32_bf16 v[82:85], v[188:191], v[230:233], 0
	v_mfma_f32_16x16x32_bf16 v[82:85], v[192:195], v[234:237], v[82:85]
	v_mfma_f32_16x16x32_bf16 v[70:73], v[180:183], v[238:241], 0
	v_mfma_f32_16x16x32_bf16 v[70:73], v[184:187], v[242:245], v[70:73]
	s_setprio 2
	s_barrier
	v_mfma_f32_16x16x32_bf16 v[66:69], v[188:191], v[238:241], 0
	v_mfma_f32_16x16x32_bf16 v[66:69], v[192:195], v[242:245], v[66:69]
	s_setprio 0
	s_mov_b32 m0, s94
	v_lshl_add_u64 v[166:167], s[60:61], 0, v[136:137]
	ds_read_b128 v[196:199], v153 offset:16384
	ds_read_b128 v[200:203], v153 offset:17408
	ds_read_b128 v[222:225], v153 offset:18432
	ds_read_b128 v[226:229], v153 offset:19456
	ds_read_b128 v[230:233], v153 offset:20480
	ds_read_b128 v[234:237], v153 offset:21504
	ds_read_b128 v[238:241], v153 offset:22528
	ds_read_b128 v[242:245], v153 offset:23552
	global_load_lds_dwordx4 v[166:167], off
	v_lshl_add_u64 v[168:169], s[60:61], 0, v[132:133]
	s_mov_b32 m0, s95
	v_lshl_add_u64 v[172:173], s[62:63], 0, v[136:137]
	global_load_lds_dwordx4 v[168:169], off
	s_mov_b32 m0, s96
	v_lshl_add_u64 v[212:213], s[58:59], 0, v[134:135]
	global_load_lds_dwordx4 v[172:173], off
	v_lshl_add_u64 v[172:173], s[62:63], 0, v[132:133]
	s_mov_b32 m0, s97
	s_nop 0
	global_load_lds_dwordx4 v[172:173], off
	v_lshl_add_u64 v[172:173], s[58:59], 0, v[138:139]
	s_mov_b32 m0, s71
	s_nop 0
	global_load_lds_dwordx4 v[172:173], off
	s_mov_b32 m0, s75
	s_nop 0
	global_load_lds_dwordx4 v[212:213], off
	s_waitcnt vmcnt(8)
	s_waitcnt lgkmcnt(0)
	s_setprio 1
	s_barrier
; #define PG8_STAGE(bufoff, gbase, voff) do { _Pragma("unroll") for (int _i = 0; _i < 2; ++_i) \
;         __builtin_amdgcn_global_load_lds((const unsigned*)((const char*)(gbase) + (voff)[_i]), (PG8_LAS unsigned*)(lds + (bufoff) + ldsw + _i * 8192), 16, 0, AUX_A); } while (0)
; #define PG8_STAGEB(bufoff, gbase, voff) do { _Pragma("unroll") for (int _i = 0; _i < 2; ++_i) \
;         __builtin_amdgcn_global_load_lds((const unsigned*)((const char*)(gbase) + (voff)[_i]), (PG8_LAS unsigned*)(lds + (bufoff) + ldsw + _i * 8192), 16, 0, AUX_B); } while (0)
; #define PG8_LDA(dst, b, h) do { _Pragma("unroll") for (int m = 0; m < 4; ++m) _Pragma("unroll") for (int k = 0; k < 2; ++k) dst[m][k] = *(const PG8_LAS bf16x8*)(lds + PG8_SA(b, h) + aoff + m * 2048 + k * 1024); } while (0)
; #define PG8_LDB(dst, b, h) do { _Pragma("unroll") for (int n = 0; n < 2; ++n) _Pragma("unroll") for (int k = 0; k < 2; ++k) dst[n][k] = *(const PG8_LAS bf16x8*)(lds + PG8_SB(b, h) + boff + n * 2048 + k * 1024); } while (0)
; #define PG8_MMA(ai, bj, At, Bt) do { __builtin_amdgcn_s_setprio(1); _Pragma("unroll") for (int m = 0; m < 4; ++m) _Pragma("unroll") for (int n = 0; n < 2; ++n) _Pragma("unroll") for (int k = 0; k < 2; ++k) \
;         acc[ai][bj][m][n] = __builtin_amdgcn_mfma_f32_16x16x32_bf16(Bt[n][k], At[m][k], acc[ai][bj][m][n], 0, 0, 0); __builtin_amdgcn_s_setprio(0); } while (0)
; #define PG8_WAIT_V(n) asm volatile("s_waitcnt vmcnt(" #n ")" ::: "memory")
; #define PG8_WAIT_L(n) asm volatile("s_waitcnt lgkmcnt(" #n ")" ::: "memory")
; template <class Epi, class Sched, bool ALIGN_EPI = false, bool SP2 = false>
; __device__ __forceinline__ void gemm_phase(PG8_LAS unsigned char* lds, const Gemm g, const Sched& S, const Epi& E) {
;     ...
;             PG8_WAIT_V(8); PG8_WAIT_L(0); PG8_BAR; PG8_MMA(0, 0, At, B0); PG8_MMA(0, 1, At, B1); PG8_BAR; PG8_SCHED;
;             PG8_LDA(At, 0, 1); PG8_STAGEB(PG8_SB(0, 0), b2, voffB); PG8_STAGEB(PG8_SB(0, 1), b2 + hstep, voffB); PG8_STAGE(PG8_SA(0, 0), a2, voffA);
;             PG8_WAIT_V(8); PG8_WAIT_L(0); PG8_BAR; PG8_MMA(1, 0, At, B0); PG8_MMA(1, 1, At, B1); PG8_BAR; PG8_SCHED;
;             PG8_LDB(B0, 1, 0); PG8_LDB(B1, 1, 1); PG8_SCHED; PG8_LDA(At, 1, 0); PG8_STAGE(PG8_SA(0, 1), a2 + hstep, voffA);
;             PG8_WAIT_V(8); PG8_WAIT_L(0); PG8_BAR; PG8_MMA(0, 0, At, B0); PG8_MMA(0, 1, At, B1); PG8_BAR; PG8_SCHED;
	v_mfma_f32_16x16x32_bf16 v[62:65], v[148:151], v[196:199], 0
	v_mfma_f32_16x16x32_bf16 v[62:65], v[154:157], v[200:203], v[62:65]
	v_mfma_f32_16x16x32_bf16 v[58:61], v[158:161], v[196:199], 0
	v_mfma_f32_16x16x32_bf16 v[58:61], v[162:165], v[200:203], v[58:61]
	v_mfma_f32_16x16x32_bf16 v[46:49], v[148:151], v[222:225], 0
	v_mfma_f32_16x16x32_bf16 v[46:49], v[154:157], v[226:229], v[46:49]
	v_mfma_f32_16x16x32_bf16 v[42:45], v[158:161], v[222:225], 0
	v_mfma_f32_16x16x32_bf16 v[42:45], v[162:165], v[226:229], v[42:45]
	v_mfma_f32_16x16x32_bf16 v[30:33], v[148:151], v[230:233], 0
	v_mfma_f32_16x16x32_bf16 v[30:33], v[154:157], v[234:237], v[30:33]
	v_mfma_f32_16x16x32_bf16 v[26:29], v[158:161], v[230:233], 0
	v_mfma_f32_16x16x32_bf16 v[26:29], v[162:165], v[234:237], v[26:29]
	v_mfma_f32_16x16x32_bf16 v[14:17], v[148:151], v[238:241], 0
	v_mfma_f32_16x16x32_bf16 v[14:17], v[154:157], v[242:245], v[14:17]
	v_mfma_f32_16x16x32_bf16 v[10:13], v[158:161], v[238:241], 0
	v_mfma_f32_16x16x32_bf16 v[10:13], v[162:165], v[242:245], v[10:13]
	s_setprio 0
	s_setprio 1
	v_mfma_f32_16x16x32_bf16 v[54:57], v[180:183], v[196:199], 0
	v_mfma_f32_16x16x32_bf16 v[54:57], v[184:187], v[200:203], v[54:57]
	v_mfma_f32_16x16x32_bf16 v[50:53], v[188:191], v[196:199], 0
	v_mfma_f32_16x16x32_bf16 v[50:53], v[192:195], v[200:203], v[50:53]
	v_mfma_f32_16x16x32_bf16 v[38:41], v[180:183], v[222:225], 0
	v_mfma_f32_16x16x32_bf16 v[38:41], v[184:187], v[226:229], v[38:41]
	v_mfma_f32_16x16x32_bf16 v[34:37], v[188:191], v[222:225], 0
	v_mfma_f32_16x16x32_bf16 v[34:37], v[192:195], v[226:229], v[34:37]
	v_mfma_f32_16x16x32_bf16 v[22:25], v[180:183], v[230:233], 0
	v_mfma_f32_16x16x32_bf16 v[22:25], v[184:187], v[234:237], v[22:25]
	v_mfma_f32_16x16x32_bf16 v[18:21], v[188:191], v[230:233], 0
	v_mfma_f32_16x16x32_bf16 v[18:21], v[192:195], v[234:237], v[18:21]
	v_mfma_f32_16x16x32_bf16 v[6:9], v[180:183], v[238:241], 0
	v_mfma_f32_16x16x32_bf16 v[6:9], v[184:187], v[242:245], v[6:9]
	s_setprio 2
	s_barrier
	v_mfma_f32_16x16x32_bf16 v[2:5], v[188:191], v[238:241], 0
	v_mfma_f32_16x16x32_bf16 v[2:5], v[192:195], v[242:245], v[2:5]
	s_setprio 0
	v_add_u32_e32 v162, vcc_lo, v99
	v_add_u32_e32 v192, vcc_hi, v99
	ds_read_b128 v[148:151], v162
	ds_read_b128 v[154:157], v162 offset:1024
	ds_read_b128 v[158:161], v162 offset:2048
	ds_read_b128 v[162:165], v162 offset:3072
	ds_read_b128 v[180:183], v192
	ds_read_b128 v[184:187], v192 offset:1024
	ds_read_b128 v[188:191], v192 offset:2048
	ds_read_b128 v[192:195], v192 offset:3072
	s_mov_b32 m0, s78
	v_lshl_add_u64 v[246:247], s[56:57], 0, v[138:139]
	ds_read_b128 v[196:199], v153 offset:32768
	ds_read_b128 v[200:203], v153 offset:33792
	ds_read_b128 v[222:225], v153 offset:34816
	ds_read_b128 v[226:229], v153 offset:35840
	ds_read_b128 v[230:233], v153 offset:36864
	ds_read_b128 v[234:237], v153 offset:37888
	ds_read_b128 v[238:241], v153 offset:38912
	ds_read_b128 v[242:245], v153 offset:39936
	global_load_lds_dwordx4 v[246:247], off
	v_lshl_add_u64 v[246:247], s[56:57], 0, v[134:135]
	s_mov_b32 m0, s82
	s_nop 0
	global_load_lds_dwordx4 v[246:247], off
	s_waitcnt vmcnt(8)
	s_waitcnt lgkmcnt(0)
	s_setprio 1
	s_barrier
	v_mfma_f32_16x16x32_bf16 v[128:131], v[148:151], v[196:199], v[128:131]
	v_mfma_f32_16x16x32_bf16 v[128:131], v[154:157], v[200:203], v[128:131]
	v_mfma_f32_16x16x32_bf16 v[124:127], v[158:161], v[196:199], v[124:127]
	v_mfma_f32_16x16x32_bf16 v[124:127], v[162:165], v[200:203], v[124:127]
	v_mfma_f32_16x16x32_bf16 v[112:115], v[148:151], v[222:225], v[112:115]
	v_mfma_f32_16x16x32_bf16 v[112:115], v[154:157], v[226:229], v[112:115]
	v_mfma_f32_16x16x32_bf16 v[108:111], v[158:161], v[222:225], v[108:111]
	v_mfma_f32_16x16x32_bf16 v[108:111], v[162:165], v[226:229], v[108:111]
	v_mfma_f32_16x16x32_bf16 v[94:97], v[148:151], v[230:233], v[94:97]
	v_mfma_f32_16x16x32_bf16 v[94:97], v[154:157], v[234:237], v[94:97]
	v_mfma_f32_16x16x32_bf16 v[90:93], v[158:161], v[230:233], v[90:93]
	v_mfma_f32_16x16x32_bf16 v[90:93], v[162:165], v[234:237], v[90:93]
	v_mfma_f32_16x16x32_bf16 v[78:81], v[148:151], v[238:241], v[78:81]
	v_mfma_f32_16x16x32_bf16 v[78:81], v[154:157], v[242:245], v[78:81]
	v_mfma_f32_16x16x32_bf16 v[74:77], v[158:161], v[238:241], v[74:77]
	v_mfma_f32_16x16x32_bf16 v[74:77], v[162:165], v[242:245], v[74:77]
	s_setprio 0
	s_setprio 1
	v_mfma_f32_16x16x32_bf16 v[120:123], v[180:183], v[196:199], v[120:123]
	v_mfma_f32_16x16x32_bf16 v[120:123], v[184:187], v[200:203], v[120:123]
	v_mfma_f32_16x16x32_bf16 v[116:119], v[188:191], v[196:199], v[116:119]
	v_mfma_f32_16x16x32_bf16 v[116:119], v[192:195], v[200:203], v[116:119]
	v_mfma_f32_16x16x32_bf16 v[104:107], v[180:183], v[222:225], v[104:107]
	v_mfma_f32_16x16x32_bf16 v[104:107], v[184:187], v[226:229], v[104:107]
	v_mfma_f32_16x16x32_bf16 v[100:103], v[188:191], v[222:225], v[100:103]
	v_mfma_f32_16x16x32_bf16 v[100:103], v[192:195], v[226:229], v[100:103]
	v_mfma_f32_16x16x32_bf16 v[86:89], v[180:183], v[230:233], v[86:89]
	v_mfma_f32_16x16x32_bf16 v[86:89], v[184:187], v[234:237], v[86:89]
	v_mfma_f32_16x16x32_bf16 v[82:85], v[188:191], v[230:233], v[82:85]
	v_mfma_f32_16x16x32_bf16 v[82:85], v[192:195], v[234:237], v[82:85]
	v_mfma_f32_16x16x32_bf16 v[70:73], v[180:183], v[238:241], v[70:73]
	v_mfma_f32_16x16x32_bf16 v[70:73], v[184:187], v[242:245], v[70:73]
	s_setprio 2
	s_barrier
; #define PG8_STAGE(bufoff, gbase, voff) do { _Pragma("unroll") for (int _i = 0; _i < 2; ++_i) \
;         __builtin_amdgcn_global_load_lds((const unsigned*)((const char*)(gbase) + (voff)[_i]), (PG8_LAS unsigned*)(lds + (bufoff) + ldsw + _i * 8192), 16, 0, AUX_A); } while (0)
; #define PG8_STAGEB(bufoff, gbase, voff) do { _Pragma("unroll") for (int _i = 0; _i < 2; ++_i) \
;         __builtin_amdgcn_global_load_lds((const unsigned*)((const char*)(gbase) + (voff)[_i]), (PG8_LAS unsigned*)(lds + (bufoff) + ldsw + _i * 8192), 16, 0, AUX_B); } while (0)
; #define PG8_LDA(dst, b, h) do { _Pragma("unroll") for (int m = 0; m < 4; ++m) _Pragma("unroll") for (int k = 0; k < 2; ++k) dst[m][k] = *(const PG8_LAS bf16x8*)(lds + PG8_SA(b, h) + aoff + m * 2048 + k * 1024); } while (0)
; #define PG8_LDB(dst, b, h) do { _Pragma("unroll") for (int n = 0; n < 2; ++n) _Pragma("unroll") for (int k = 0; k < 2; ++k) dst[n][k] = *(const PG8_LAS bf16x8*)(lds + PG8_SB(b, h) + boff + n * 2048 + k * 1024); } while (0)
; #define PG8_MMA(ai, bj, At, Bt) do { __builtin_amdgcn_s_setprio(1); _Pragma("unroll") for (int m = 0; m < 4; ++m) _Pragma("unroll") for (int n = 0; n < 2; ++n) _Pragma("unroll") for (int k = 0; k < 2; ++k) \
;         acc[ai][bj][m][n] = __builtin_amdgcn_mfma_f32_16x16x32_bf16(Bt[n][k], At[m][k], acc[ai][bj][m][n], 0, 0, 0); __builtin_amdgcn_s_setprio(0); } while (0)
; #define PG8_WAIT_V(n) asm volatile("s_waitcnt vmcnt(" #n ")" ::: "memory")
; #define PG8_WAIT_L(n) asm volatile("s_waitcnt lgkmcnt(" #n ")" ::: "memory")
; #define PG8_BAR __builtin_amdgcn_s_barrier()
; #define PG8_SCHED __builtin_amdgcn_sched_barrier(0)
; template <class Epi, class Sched, bool ALIGN_EPI = false, bool SP2 = false>
; __device__ __forceinline__ void gemm_phase(PG8_LAS unsigned char* lds, const Gemm g, const Sched& S, const Epi& E) {
;     ...
;             PG8_LDB(B0, 1, 0); PG8_LDB(B1, 1, 1); PG8_SCHED; PG8_LDA(At, 1, 0); PG8_STAGE(PG8_SA(0, 1), a2 + hstep, voffA);
;             PG8_WAIT_V(8); PG8_WAIT_L(0); PG8_BAR; PG8_MMA(0, 0, At, B0); PG8_MMA(0, 1, At, B1); PG8_BAR; PG8_SCHED;
;             PG8_LDA(At, 1, 1); PG8_STAGEB(PG8_SB(1, 0), b3, voffB); PG8_STAGEB(PG8_SB(1, 1), b3 + hstep, voffB); PG8_STAGE(PG8_SA(1, 0), a3, voffA);
;             PG8_WAIT_V(8); PG8_WAIT_L(0); PG8_BAR; PG8_MMA(1, 0, At, B0); PG8_MMA(1, 1, At, B1); PG8_BAR; PG8_SCHED;
	v_mfma_f32_16x16x32_bf16 v[66:69], v[188:191], v[238:241], v[66:69]
	v_mfma_f32_16x16x32_bf16 v[66:69], v[192:195], v[242:245], v[66:69]
	s_setprio 0
	s_mov_b32 m0, s1
	v_lshl_add_u64 v[166:167], v[166:167], 0, s[76:77]
	ds_read_b128 v[196:199], v153 offset:49152
	ds_read_b128 v[200:203], v153 offset:50176
	ds_read_b128 v[222:225], v153 offset:51200
	ds_read_b128 v[226:229], v153 offset:52224
	ds_read_b128 v[230:233], v153 offset:53248
	ds_read_b128 v[234:237], v153 offset:54272
	ds_read_b128 v[238:241], v153 offset:55296
	ds_read_b128 v[242:245], v153 offset:56320
	global_load_lds_dwordx4 v[166:167], off
	v_lshl_add_u64 v[166:167], v[168:169], 0, s[76:77]
	s_mov_b32 m0, s0
	s_nop 0
	global_load_lds_dwordx4 v[166:167], off
	v_lshl_add_u64 v[166:167], s[54:55], 0, v[136:137]
	s_mov_b32 m0, s47
	s_nop 0
	global_load_lds_dwordx4 v[166:167], off
	v_lshl_add_u64 v[166:167], s[54:55], 0, v[132:133]
	s_mov_b32 m0, s46
	s_nop 0
	global_load_lds_dwordx4 v[166:167], off
	v_lshl_add_u64 v[166:167], v[172:173], 0, s[76:77]
	s_mov_b32 m0, s83
	s_nop 0
	global_load_lds_dwordx4 v[166:167], off
	v_lshl_add_u64 v[166:167], v[212:213], 0, s[76:77]
	s_mov_b32 m0, s88
	s_nop 0
	global_load_lds_dwordx4 v[166:167], off
	s_waitcnt vmcnt(8)
	s_waitcnt lgkmcnt(0)
	s_setprio 1
	s_barrier
	v_mfma_f32_16x16x32_bf16 v[62:65], v[148:151], v[196:199], v[62:65]
	v_mfma_f32_16x16x32_bf16 v[62:65], v[154:157], v[200:203], v[62:65]
	v_mfma_f32_16x16x32_bf16 v[58:61], v[158:161], v[196:199], v[58:61]
	v_mfma_f32_16x16x32_bf16 v[58:61], v[162:165], v[200:203], v[58:61]
	v_mfma_f32_16x16x32_bf16 v[46:49], v[148:151], v[222:225], v[46:49]
	v_mfma_f32_16x16x32_bf16 v[46:49], v[154:157], v[226:229], v[46:49]
	v_mfma_f32_16x16x32_bf16 v[42:45], v[158:161], v[222:225], v[42:45]
	v_mfma_f32_16x16x32_bf16 v[42:45], v[162:165], v[226:229], v[42:45]
	v_mfma_f32_16x16x32_bf16 v[30:33], v[148:151], v[230:233], v[30:33]
	v_mfma_f32_16x16x32_bf16 v[30:33], v[154:157], v[234:237], v[30:33]
	v_mfma_f32_16x16x32_bf16 v[26:29], v[158:161], v[230:233], v[26:29]
	v_mfma_f32_16x16x32_bf16 v[26:29], v[162:165], v[234:237], v[26:29]
	v_mfma_f32_16x16x32_bf16 v[14:17], v[148:151], v[238:241], v[14:17]
	v_mfma_f32_16x16x32_bf16 v[14:17], v[154:157], v[242:245], v[14:17]
	v_mfma_f32_16x16x32_bf16 v[10:13], v[158:161], v[238:241], v[10:13]
	v_mfma_f32_16x16x32_bf16 v[10:13], v[162:165], v[242:245], v[10:13]
	s_setprio 0
	s_setprio 1
	v_mfma_f32_16x16x32_bf16 v[54:57], v[180:183], v[196:199], v[54:57]
	v_mfma_f32_16x16x32_bf16 v[54:57], v[184:187], v[200:203], v[54:57]
	v_mfma_f32_16x16x32_bf16 v[50:53], v[188:191], v[196:199], v[50:53]
	v_mfma_f32_16x16x32_bf16 v[50:53], v[192:195], v[200:203], v[50:53]
	v_mfma_f32_16x16x32_bf16 v[38:41], v[180:183], v[222:225], v[38:41]
	v_mfma_f32_16x16x32_bf16 v[38:41], v[184:187], v[226:229], v[38:41]
	v_mfma_f32_16x16x32_bf16 v[34:37], v[188:191], v[222:225], v[34:37]
	v_mfma_f32_16x16x32_bf16 v[34:37], v[192:195], v[226:229], v[34:37]
	v_mfma_f32_16x16x32_bf16 v[22:25], v[180:183], v[230:233], v[22:25]
	v_mfma_f32_16x16x32_bf16 v[22:25], v[184:187], v[234:237], v[22:25]
	v_mfma_f32_16x16x32_bf16 v[18:21], v[188:191], v[230:233], v[18:21]
	v_mfma_f32_16x16x32_bf16 v[18:21], v[192:195], v[234:237], v[18:21]
	v_mfma_f32_16x16x32_bf16 v[6:9], v[180:183], v[238:241], v[6:9]
	v_mfma_f32_16x16x32_bf16 v[6:9], v[184:187], v[242:245], v[6:9]
	s_setprio 2
	s_barrier
	v_mfma_f32_16x16x32_bf16 v[2:5], v[188:191], v[238:241], v[2:5]
	v_mfma_f32_16x16x32_bf16 v[2:5], v[192:195], v[242:245], v[2:5]
	s_setprio 0
	v_lshl_add_u64 v[144:145], v[144:145], 0, s[86:87]
	v_lshl_add_u64 v[146:147], v[146:147], 0, s[86:87]
	s_mov_b32 s29, s81
	s_cbranch_scc1 .Lpx_1157

; #define GAS __attribute__((address_space(1)))
; __device__ __forceinline__ u32x4 pack8(f32x4 v0, f32x4 v1) { u32x4 w; w.x = cvt_pk_bf16(v0[0], v0[1]); w.y = cvt_pk_bf16(v0[2], v0[3]); w.z = cvt_pk_bf16(v1[0], v1[1]); w.w = cvt_pk_bf16(v1[2], v1[3]); return w; }
; __device__ __forceinline__ void unpack8(u32x4 w, f32x4& v0, f32x4& v1) { v0 = (f32x4){bflo(w.x), bfhi(w.x), bflo(w.y), bfhi(w.y)}; v1 = (f32x4){bflo(w.z), bfhi(w.z), bflo(w.w), bfhi(w.w)}; }
; #define GAS __attribute__((address_space(1)))
;     __device__ __forceinline__ void operator()(const f32x4 (&acc)[2][2][4][2], const Unit& u, int wr, int wc, int fr, int fq) const {
;     ...
;             for (int m = 0; m < 4; ++m) { const size_t r = (size_t)(row0 + ai * HALF + m * 16); const size_t off = r * 2048 + col0; const bf16_t* gp = P + r * NPJ + 2560 + MODE * 2048 + col0;
; #pragma unroll
;                 for (int bj = 0; bj < 2; ++bj) { f32x4 g0, g1; unpack8(*(const GAS u32x4*)(gp + bj * HALF), g0, g1);
;                     f32x4 v0 = g0 * acc[ai][bj][m][0], v1 = g1 * acc[ai][bj][m][1];
;                     if (MODE == 1) { f32x4 t0, t1; unpack8(*(const GAS u32x4*)(T1 + off + bj * HALF), t0, t1); v0 += t0; v1 += t1; }
;                     const u32x4 w = pack8(v0, v1);
;                     if (MODE == 0 && samp) asm volatile("global_store_dwordx4 %0, %1, off sc1\n\ts_nop 1" :: "v"(O + off + bj * HALF), "v"(w) : "memory");
;                     else *(GAS u32x4*)(O + off + bj * HALF) = w; } }
.LBB0_1178:
	v_or_b32_e32 v144, s19, v152
	v_lshl_add_u32 v146, s90, 8, v1
	v_ashrrev_i32_e32 v145, 31, v144
	v_mov_b64_e32 v[148:149], s[8:9]
	v_ashrrev_i32_e32 v147, 31, v146
	v_mad_i64_i32 v[154:155], s[0:1], v146, s95, v[148:149]
	v_lshlrev_b64 v[150:151], 1, v[144:145]
	v_lshlrev_b64 v[158:159], 11, v[146:147]
	v_lshl_add_u64 v[162:163], v[154:155], 0, v[150:151]
	v_lshl_add_u64 v[158:159], v[158:159], 0, v[144:145]
	v_add_co_u32_e32 v154, vcc, 0x2000, v162
	v_lshlrev_b64 v[164:165], 1, v[158:159]
	s_nop 0
	v_addc_co_u32_e32 v155, vcc, 0, v163, vcc
	v_lshl_add_u64 v[166:167], s[10:11], 0, v[164:165]
	global_load_dwordx4 v[222:225], v[154:155], off offset:1024
	global_load_dwordx4 v[226:229], v[166:167], off
	global_load_dwordx4 v[230:233], v[154:155], off offset:1280
	global_load_dwordx4 v[234:237], v[166:167], off offset:256
	v_add_co_u32_e32 v192, vcc, 0x34000, v154
	s_nop 1
	v_addc_co_u32_e32 v193, vcc, 0, v155, vcc
	global_load_dwordx4 v[238:241], v[192:193], off offset:1024
	v_add_co_u32_e32 v194, vcc, 0x10000, v166
	s_nop 1
	v_addc_co_u32_e32 v195, vcc, 0, v167, vcc
	global_load_dwordx4 v[242:245], v[194:195], off
	global_load_dwordx4 v[184:187], v[192:193], off offset:1280
	global_load_dwordx4 v[188:191], v[194:195], off offset:256
	s_mov_b64 s[2:3], 0x2400
	v_lshl_add_u64 v[164:165], s[14:15], 0, v[164:165]
	v_lshl_add_u64 v[162:163], v[162:163], 0, s[2:3]
	s_movk_i32 s19, 0x2000
	s_waitcnt vmcnt(6)
	s_nop 1
	v_mov_b32_e32 v154, v222
	v_mov_b32_e32 v155, v223
	v_mov_b32_e32 v156, v224
	v_mov_b32_e32 v157, v225
	v_mov_b32_e32 v158, v226
	v_mov_b32_e32 v159, v227
	v_mov_b32_e32 v160, v228
	v_mov_b32_e32 v161, v229
	v_lshlrev_b32_e32 v168, 16, v154
	v_and_b32_e32 v169, 0xffff0000, v154
	v_lshlrev_b32_e32 v154, 16, v155
	v_and_b32_e32 v155, 0xffff0000, v155
	v_lshlrev_b32_e32 v172, 16, v156
	v_and_b32_e32 v173, 0xffff0000, v156
	v_lshlrev_b32_e32 v156, 16, v157
	v_and_b32_e32 v157, 0xffff0000, v157
	v_lshlrev_b32_e32 v180, 16, v158
	v_and_b32_e32 v181, 0xffff0000, v158
	v_lshlrev_b32_e32 v158, 16, v159
	v_and_b32_e32 v159, 0xffff0000, v159
	v_lshlrev_b32_e32 v182, 16, v160
	v_and_b32_e32 v183, 0xffff0000, v160
	v_lshlrev_b32_e32 v160, 16, v161
	v_and_b32_e32 v161, 0xffff0000, v161
	v_pk_fma_f32 v[130:131], v[130:131], v[154:155], v[158:159]
	v_pk_fma_f32 v[128:129], v[128:129], v[168:169], v[180:181]
	v_pk_fma_f32 v[154:155], v[126:127], v[156:157], v[160:161]
	v_pk_fma_f32 v[126:127], v[124:125], v[172:173], v[182:183]
	v_cvt_pk_bf16_f32 v124, v128, v129
	v_cvt_pk_bf16_f32 v125, v130, v131
	v_cvt_pk_bf16_f32 v126, v126, v127
	v_cvt_pk_bf16_f32 v127, v154, v155
	global_store_dwordx4 v[164:165], v[124:127], off
	s_nop 0
	v_or_b32_e32 v154, 16, v146
	v_ashrrev_i32_e32 v155, 31, v154
	v_mad_i64_i32 v[156:157], s[0:1], v154, s95, v[148:149]
	v_lshl_add_u64 v[156:157], v[156:157], 0, v[150:151]
	v_add_co_u32_e32 v158, vcc, s19, v156
	s_waitcnt vmcnt(6)
	s_nop 1
	v_mov_b32_e32 v124, v230
	v_mov_b32_e32 v125, v231
	v_mov_b32_e32 v126, v232
	v_mov_b32_e32 v127, v233
	v_lshlrev_b32_e32 v160, 16, v124
	v_and_b32_e32 v161, 0xffff0000, v124
	s_waitcnt vmcnt(5)
	s_nop 1
	v_mov_b32_e32 v128, v234
	v_mov_b32_e32 v129, v235
	v_mov_b32_e32 v130, v236
	v_mov_b32_e32 v131, v237
	v_lshlrev_b32_e32 v166, 16, v128
	v_and_b32_e32 v167, 0xffff0000, v128
	v_lshlrev_b32_e32 v124, 16, v125
	v_and_b32_e32 v125, 0xffff0000, v125
	v_lshlrev_b32_e32 v162, 16, v126
	v_and_b32_e32 v163, 0xffff0000, v126
	v_lshlrev_b32_e32 v126, 16, v127
	v_and_b32_e32 v127, 0xffff0000, v127
	v_lshlrev_b32_e32 v128, 16, v129
	v_and_b32_e32 v129, 0xffff0000, v129
	v_lshlrev_b32_e32 v168, 16, v130
	v_and_b32_e32 v169, 0xffff0000, v130
	v_lshlrev_b32_e32 v130, 16, v131
	v_and_b32_e32 v131, 0xffff0000, v131
	v_pk_fma_f32 v[120:121], v[120:121], v[160:161], v[166:167]
	v_pk_fma_f32 v[122:123], v[122:123], v[124:125], v[128:129]
	v_pk_fma_f32 v[124:125], v[118:119], v[126:127], v[130:131]
	v_pk_fma_f32 v[118:119], v[116:117], v[162:163], v[168:169]
	v_cvt_pk_bf16_f32 v116, v120, v121
	v_lshlrev_b64 v[120:121], 11, v[154:155]
	v_lshl_add_u64 v[120:121], v[120:121], 0, v[144:145]
	v_cvt_pk_bf16_f32 v117, v122, v123
	v_cvt_pk_bf16_f32 v118, v118, v119
	v_cvt_pk_bf16_f32 v119, v124, v125
	v_lshlrev_b64 v[124:125], 1, v[120:121]
	v_addc_co_u32_e32 v159, vcc, 0, v157, vcc
	global_store_dwordx4 v[164:165], v[116:119], off offset:256
	v_lshl_add_u64 v[126:127], s[10:11], 0, v[124:125]
	v_lshl_add_u64 v[128:129], v[156:157], 0, s[2:3]
	v_lshl_add_u64 v[124:125], s[14:15], 0, v[124:125]
	s_waitcnt vmcnt(5)
	s_nop 1
	v_mov_b32_e32 v116, v238
	v_mov_b32_e32 v117, v239
	v_mov_b32_e32 v118, v240
	v_mov_b32_e32 v119, v241
	v_lshlrev_b32_e32 v130, 16, v116
	v_and_b32_e32 v131, 0xffff0000, v116
	v_lshlrev_b32_e32 v116, 16, v117
	v_and_b32_e32 v117, 0xffff0000, v117
	v_lshlrev_b32_e32 v154, 16, v118
	v_and_b32_e32 v155, 0xffff0000, v118
	v_lshlrev_b32_e32 v118, 16, v119
	v_and_b32_e32 v119, 0xffff0000, v119
	s_waitcnt vmcnt(4)
	s_nop 1
	v_mov_b32_e32 v120, v242
	v_mov_b32_e32 v121, v243
	v_mov_b32_e32 v122, v244
	v_mov_b32_e32 v123, v245
	v_lshlrev_b32_e32 v156, 16, v120
	v_and_b32_e32 v157, 0xffff0000, v120
	v_lshlrev_b32_e32 v120, 16, v121
	v_and_b32_e32 v121, 0xffff0000, v121
	v_lshlrev_b32_e32 v158, 16, v122
	v_and_b32_e32 v159, 0xffff0000, v122
	v_lshlrev_b32_e32 v122, 16, v123
	v_and_b32_e32 v123, 0xffff0000, v123
	v_pk_fma_f32 v[114:115], v[114:115], v[116:117], v[120:121]
	v_pk_fma_f32 v[112:113], v[112:113], v[130:131], v[156:157]
	v_pk_fma_f32 v[116:117], v[110:111], v[118:119], v[122:123]
	v_pk_fma_f32 v[110:111], v[108:109], v[154:155], v[158:159]
	v_cvt_pk_bf16_f32 v108, v112, v113
	v_cvt_pk_bf16_f32 v109, v114, v115
	v_cvt_pk_bf16_f32 v110, v110, v111
	v_cvt_pk_bf16_f32 v111, v116, v117
	global_store_dwordx4 v[124:125], v[108:111], off
	s_nop 0
	v_or_b32_e32 v116, 32, v146
	v_ashrrev_i32_e32 v117, 31, v116
	v_mad_i64_i32 v[118:119], s[0:1], v116, s95, v[148:149]
	v_lshl_add_u64 v[118:119], v[118:119], 0, v[150:151]
	v_add_co_u32_e32 v120, vcc, s19, v118
	s_waitcnt vmcnt(4)
; #define GAS __attribute__((address_space(1)))
; __device__ __forceinline__ u32x4 pack8(f32x4 v0, f32x4 v1) { u32x4 w; w.x = cvt_pk_bf16(v0[0], v0[1]); w.y = cvt_pk_bf16(v0[2], v0[3]); w.z = cvt_pk_bf16(v1[0], v1[1]); w.w = cvt_pk_bf16(v1[2], v1[3]); return w; }
; __device__ __forceinline__ void unpack8(u32x4 w, f32x4& v0, f32x4& v1) { v0 = (f32x4){bflo(w.x), bfhi(w.x), bflo(w.y), bfhi(w.y)}; v1 = (f32x4){bflo(w.z), bfhi(w.z), bflo(w.w), bfhi(w.w)}; }
; #define GAS __attribute__((address_space(1)))
;     __device__ __forceinline__ void operator()(const f32x4 (&acc)[2][2][4][2], const Unit& u, int wr, int wc, int fr, int fq) const {
;     ...
;             for (int m = 0; m < 4; ++m) { const size_t r = (size_t)(row0 + ai * HALF + m * 16); const size_t off = r * 2048 + col0; const bf16_t* gp = P + r * NPJ + 2560 + MODE * 2048 + col0;
; #pragma unroll
;                 for (int bj = 0; bj < 2; ++bj) { f32x4 g0, g1; unpack8(*(const GAS u32x4*)(gp + bj * HALF), g0, g1);
;                     f32x4 v0 = g0 * acc[ai][bj][m][0], v1 = g1 * acc[ai][bj][m][1];
;                     if (MODE == 1) { f32x4 t0, t1; unpack8(*(const GAS u32x4*)(T1 + off + bj * HALF), t0, t1); v0 += t0; v1 += t1; }
;                     const u32x4 w = pack8(v0, v1);
;                     if (MODE == 0 && samp) asm volatile("global_store_dwordx4 %0, %1, off sc1\n\ts_nop 1" :: "v"(O + off + bj * HALF), "v"(w) : "memory");
;                     else *(GAS u32x4*)(O + off + bj * HALF) = w; } }
	s_nop 1
	v_mov_b32_e32 v108, v184
	v_mov_b32_e32 v109, v185
	v_mov_b32_e32 v110, v186
	v_mov_b32_e32 v111, v187
	v_lshlrev_b32_e32 v122, 16, v108
	v_and_b32_e32 v123, 0xffff0000, v108
	s_waitcnt vmcnt(3)
	s_nop 1
	v_mov_b32_e32 v112, v188
	v_mov_b32_e32 v113, v189
	v_mov_b32_e32 v114, v190
	v_mov_b32_e32 v115, v191
	v_lshlrev_b32_e32 v128, 16, v112
	v_and_b32_e32 v129, 0xffff0000, v112
	v_lshlrev_b32_e32 v108, 16, v109
	v_and_b32_e32 v109, 0xffff0000, v109
	v_lshlrev_b32_e32 v126, 16, v110
	v_and_b32_e32 v127, 0xffff0000, v110
	v_lshlrev_b32_e32 v110, 16, v111
	v_and_b32_e32 v111, 0xffff0000, v111
	v_lshlrev_b32_e32 v112, 16, v113
	v_and_b32_e32 v113, 0xffff0000, v113
	v_lshlrev_b32_e32 v130, 16, v114
	v_and_b32_e32 v131, 0xffff0000, v114
	v_lshlrev_b32_e32 v114, 16, v115
	v_and_b32_e32 v115, 0xffff0000, v115
	v_pk_fma_f32 v[104:105], v[104:105], v[122:123], v[128:129]
	v_pk_fma_f32 v[106:107], v[106:107], v[108:109], v[112:113]
	v_pk_fma_f32 v[108:109], v[102:103], v[110:111], v[114:115]
	v_pk_fma_f32 v[102:103], v[100:101], v[126:127], v[130:131]
	v_cvt_pk_bf16_f32 v100, v104, v105
	v_lshlrev_b64 v[104:105], 11, v[116:117]
	v_lshl_add_u64 v[104:105], v[104:105], 0, v[144:145]
	v_cvt_pk_bf16_f32 v101, v106, v107
	v_cvt_pk_bf16_f32 v102, v102, v103
	v_cvt_pk_bf16_f32 v103, v108, v109
	v_lshlrev_b64 v[108:109], 1, v[104:105]
	v_addc_co_u32_e32 v121, vcc, 0, v119, vcc
	global_store_dwordx4 v[124:125], v[100:103], off offset:256
	v_lshl_add_u64 v[110:111], s[10:11], 0, v[108:109]
	global_load_dwordx4 v[222:225], v[120:121], off offset:1024
	global_load_dwordx4 v[226:229], v[110:111], off
	global_load_dwordx4 v[230:233], v[120:121], off offset:1280
	global_load_dwordx4 v[234:237], v[110:111], off offset:256
	v_add_co_u32_e32 v192, vcc, 0x34000, v120
	s_nop 1
	v_addc_co_u32_e32 v193, vcc, 0, v121, vcc
	global_load_dwordx4 v[238:241], v[192:193], off offset:1024
	v_add_co_u32_e32 v194, vcc, 0x10000, v110
	s_nop 1
	v_addc_co_u32_e32 v195, vcc, 0, v111, vcc
	global_load_dwordx4 v[242:245], v[194:195], off
	global_load_dwordx4 v[184:187], v[192:193], off offset:1280
	global_load_dwordx4 v[188:191], v[194:195], off offset:256
	v_lshl_add_u64 v[112:113], v[118:119], 0, s[2:3]
	v_lshl_add_u64 v[108:109], s[14:15], 0, v[108:109]
	s_waitcnt vmcnt(7)
	s_nop 1
	v_mov_b32_e32 v100, v222
	v_mov_b32_e32 v101, v223
	v_mov_b32_e32 v102, v224
	v_mov_b32_e32 v103, v225
	v_lshlrev_b32_e32 v114, 16, v100
	v_and_b32_e32 v115, 0xffff0000, v100
	v_lshlrev_b32_e32 v100, 16, v101
	v_and_b32_e32 v101, 0xffff0000, v101
	v_lshlrev_b32_e32 v116, 16, v102
	v_and_b32_e32 v117, 0xffff0000, v102
	v_lshlrev_b32_e32 v102, 16, v103
	v_and_b32_e32 v103, 0xffff0000, v103
	s_waitcnt vmcnt(6)
	s_nop 1
	v_mov_b32_e32 v104, v226
	v_mov_b32_e32 v105, v227
	v_mov_b32_e32 v106, v228
	v_mov_b32_e32 v107, v229
	v_lshlrev_b32_e32 v118, 16, v104
	v_and_b32_e32 v119, 0xffff0000, v104
	v_lshlrev_b32_e32 v104, 16, v105
	v_and_b32_e32 v105, 0xffff0000, v105
	v_lshlrev_b32_e32 v120, 16, v106
	v_and_b32_e32 v121, 0xffff0000, v106
	v_lshlrev_b32_e32 v106, 16, v107
	v_and_b32_e32 v107, 0xffff0000, v107
	v_pk_fma_f32 v[96:97], v[96:97], v[100:101], v[104:105]
	v_pk_fma_f32 v[94:95], v[94:95], v[114:115], v[118:119]
	v_pk_fma_f32 v[100:101], v[92:93], v[102:103], v[106:107]
	v_pk_fma_f32 v[92:93], v[90:91], v[116:117], v[120:121]
	v_cvt_pk_bf16_f32 v90, v94, v95
	v_cvt_pk_bf16_f32 v91, v96, v97
	v_cvt_pk_bf16_f32 v92, v92, v93
	v_cvt_pk_bf16_f32 v93, v100, v101
	global_store_dwordx4 v[108:109], v[90:93], off
	s_nop 0
	v_or_b32_e32 v100, 48, v146
	v_ashrrev_i32_e32 v101, 31, v100
	v_mad_i64_i32 v[102:103], s[0:1], v100, s95, v[148:149]
	v_lshl_add_u64 v[102:103], v[102:103], 0, v[150:151]
	v_add_co_u32_e32 v104, vcc, s19, v102
	s_waitcnt vmcnt(6)
	s_nop 1
	v_mov_b32_e32 v90, v230
	v_mov_b32_e32 v91, v231
	v_mov_b32_e32 v92, v232
	v_mov_b32_e32 v93, v233
	v_lshlrev_b32_e32 v106, 16, v90
	v_and_b32_e32 v107, 0xffff0000, v90
	s_waitcnt vmcnt(5)
	s_nop 1
	v_mov_b32_e32 v94, v234
	v_mov_b32_e32 v95, v235
	v_mov_b32_e32 v96, v236
	v_mov_b32_e32 v97, v237
	v_lshlrev_b32_e32 v112, 16, v94
	v_and_b32_e32 v113, 0xffff0000, v94
	v_lshlrev_b32_e32 v90, 16, v91
	v_and_b32_e32 v91, 0xffff0000, v91
	v_lshlrev_b32_e32 v110, 16, v92
	v_and_b32_e32 v111, 0xffff0000, v92
	v_lshlrev_b32_e32 v92, 16, v93
	v_and_b32_e32 v93, 0xffff0000, v93
	v_lshlrev_b32_e32 v94, 16, v95
	v_and_b32_e32 v95, 0xffff0000, v95
	v_lshlrev_b32_e32 v114, 16, v96
	v_and_b32_e32 v115, 0xffff0000, v96
	v_lshlrev_b32_e32 v96, 16, v97
	v_and_b32_e32 v97, 0xffff0000, v97
	v_pk_fma_f32 v[86:87], v[86:87], v[106:107], v[112:113]
	v_pk_fma_f32 v[88:89], v[88:89], v[90:91], v[94:95]
	v_pk_fma_f32 v[90:91], v[84:85], v[92:93], v[96:97]
	v_pk_fma_f32 v[84:85], v[82:83], v[110:111], v[114:115]
	v_cvt_pk_bf16_f32 v82, v86, v87
	v_lshlrev_b64 v[86:87], 11, v[100:101]
	v_lshl_add_u64 v[86:87], v[86:87], 0, v[144:145]
	v_cvt_pk_bf16_f32 v83, v88, v89
	v_cvt_pk_bf16_f32 v84, v84, v85
	v_cvt_pk_bf16_f32 v85, v90, v91
	v_lshlrev_b64 v[90:91], 1, v[86:87]
	v_addc_co_u32_e32 v105, vcc, 0, v103, vcc
	global_store_dwordx4 v[108:109], v[82:85], off offset:256
	v_lshl_add_u64 v[92:93], s[10:11], 0, v[90:91]
	v_lshl_add_u64 v[94:95], v[102:103], 0, s[2:3]
	v_lshl_add_u64 v[90:91], s[14:15], 0, v[90:91]
	s_waitcnt vmcnt(5)
	s_nop 1
	v_mov_b32_e32 v82, v238
	v_mov_b32_e32 v83, v239
	v_mov_b32_e32 v84, v240
	v_mov_b32_e32 v85, v241
	v_lshlrev_b32_e32 v96, 16, v82
	v_and_b32_e32 v97, 0xffff0000, v82
	v_lshlrev_b32_e32 v82, 16, v83
	v_and_b32_e32 v83, 0xffff0000, v83
	v_lshlrev_b32_e32 v100, 16, v84
	v_and_b32_e32 v101, 0xffff0000, v84
	v_lshlrev_b32_e32 v84, 16, v85
	v_and_b32_e32 v85, 0xffff0000, v85
	s_waitcnt vmcnt(4)
; #define GAS __attribute__((address_space(1)))
; __device__ __forceinline__ u32x4 pack8(f32x4 v0, f32x4 v1) { u32x4 w; w.x = cvt_pk_bf16(v0[0], v0[1]); w.y = cvt_pk_bf16(v0[2], v0[3]); w.z = cvt_pk_bf16(v1[0], v1[1]); w.w = cvt_pk_bf16(v1[2], v1[3]); return w; }
; __device__ __forceinline__ void unpack8(u32x4 w, f32x4& v0, f32x4& v1) { v0 = (f32x4){bflo(w.x), bfhi(w.x), bflo(w.y), bfhi(w.y)}; v1 = (f32x4){bflo(w.z), bfhi(w.z), bflo(w.w), bfhi(w.w)}; }
; #define GAS __attribute__((address_space(1)))
;     __device__ __forceinline__ void operator()(const f32x4 (&acc)[2][2][4][2], const Unit& u, int wr, int wc, int fr, int fq) const {
;     ...
;             for (int m = 0; m < 4; ++m) { const size_t r = (size_t)(row0 + ai * HALF + m * 16); const size_t off = r * 2048 + col0; const bf16_t* gp = P + r * NPJ + 2560 + MODE * 2048 + col0;
; #pragma unroll
;                 for (int bj = 0; bj < 2; ++bj) { f32x4 g0, g1; unpack8(*(const GAS u32x4*)(gp + bj * HALF), g0, g1);
;                     f32x4 v0 = g0 * acc[ai][bj][m][0], v1 = g1 * acc[ai][bj][m][1];
;                     if (MODE == 1) { f32x4 t0, t1; unpack8(*(const GAS u32x4*)(T1 + off + bj * HALF), t0, t1); v0 += t0; v1 += t1; }
;                     const u32x4 w = pack8(v0, v1);
;                     if (MODE == 0 && samp) asm volatile("global_store_dwordx4 %0, %1, off sc1\n\ts_nop 1" :: "v"(O + off + bj * HALF), "v"(w) : "memory");
;                     else *(GAS u32x4*)(O + off + bj * HALF) = w; } }
	s_nop 1
	v_mov_b32_e32 v86, v242
	v_mov_b32_e32 v87, v243
	v_mov_b32_e32 v88, v244
	v_mov_b32_e32 v89, v245
	v_lshlrev_b32_e32 v102, 16, v86
	v_and_b32_e32 v103, 0xffff0000, v86
	v_lshlrev_b32_e32 v86, 16, v87
	v_and_b32_e32 v87, 0xffff0000, v87
	v_lshlrev_b32_e32 v104, 16, v88
	v_and_b32_e32 v105, 0xffff0000, v88
	v_lshlrev_b32_e32 v88, 16, v89
	v_and_b32_e32 v89, 0xffff0000, v89
	v_pk_fma_f32 v[80:81], v[80:81], v[82:83], v[86:87]
	v_pk_fma_f32 v[78:79], v[78:79], v[96:97], v[102:103]
	v_pk_fma_f32 v[82:83], v[76:77], v[84:85], v[88:89]
	v_pk_fma_f32 v[76:77], v[74:75], v[100:101], v[104:105]
	v_cvt_pk_bf16_f32 v74, v78, v79
	v_cvt_pk_bf16_f32 v75, v80, v81
	v_cvt_pk_bf16_f32 v76, v76, v77
	v_cvt_pk_bf16_f32 v77, v82, v83
	global_store_dwordx4 v[90:91], v[74:77], off
	s_nop 0
	v_add_u32_e32 v82, 0x80, v146
	v_ashrrev_i32_e32 v83, 31, v82
	v_mad_i64_i32 v[84:85], s[0:1], v82, s95, v[148:149]
	v_lshl_add_u64 v[84:85], v[84:85], 0, v[150:151]
	v_add_co_u32_e32 v86, vcc, s19, v84
	s_waitcnt vmcnt(4)
	s_nop 1
	v_mov_b32_e32 v74, v184
	v_mov_b32_e32 v75, v185
	v_mov_b32_e32 v76, v186
	v_mov_b32_e32 v77, v187
	v_lshlrev_b32_e32 v88, 16, v74
	v_and_b32_e32 v89, 0xffff0000, v74
	s_waitcnt vmcnt(3)
	s_nop 1
	v_mov_b32_e32 v78, v188
	v_mov_b32_e32 v79, v189
	v_mov_b32_e32 v80, v190
	v_mov_b32_e32 v81, v191
	v_lshlrev_b32_e32 v94, 16, v78
	v_and_b32_e32 v95, 0xffff0000, v78
	v_lshlrev_b32_e32 v74, 16, v75
	v_and_b32_e32 v75, 0xffff0000, v75
	v_lshlrev_b32_e32 v92, 16, v76
	v_and_b32_e32 v93, 0xffff0000, v76
	v_lshlrev_b32_e32 v76, 16, v77
	v_and_b32_e32 v77, 0xffff0000, v77
	v_lshlrev_b32_e32 v78, 16, v79
	v_and_b32_e32 v79, 0xffff0000, v79
	v_lshlrev_b32_e32 v96, 16, v80
	v_and_b32_e32 v97, 0xffff0000, v80
	v_lshlrev_b32_e32 v80, 16, v81
	v_and_b32_e32 v81, 0xffff0000, v81
	v_pk_fma_f32 v[70:71], v[70:71], v[88:89], v[94:95]
	v_pk_fma_f32 v[72:73], v[72:73], v[74:75], v[78:79]
	v_pk_fma_f32 v[74:75], v[68:69], v[76:77], v[80:81]
	v_pk_fma_f32 v[68:69], v[66:67], v[92:93], v[96:97]
	v_cvt_pk_bf16_f32 v66, v70, v71
	v_lshlrev_b64 v[70:71], 11, v[82:83]
	v_lshl_add_u64 v[70:71], v[70:71], 0, v[144:145]
	v_cvt_pk_bf16_f32 v67, v72, v73
	v_cvt_pk_bf16_f32 v68, v68, v69
	v_cvt_pk_bf16_f32 v69, v74, v75
	v_lshlrev_b64 v[74:75], 1, v[70:71]
	v_addc_co_u32_e32 v87, vcc, 0, v85, vcc
	global_store_dwordx4 v[90:91], v[66:69], off offset:256
	v_lshl_add_u64 v[76:77], s[10:11], 0, v[74:75]
	global_load_dwordx4 v[222:225], v[86:87], off offset:1024
	global_load_dwordx4 v[226:229], v[76:77], off
	global_load_dwordx4 v[230:233], v[86:87], off offset:1280
	global_load_dwordx4 v[234:237], v[76:77], off offset:256
	v_add_co_u32_e32 v192, vcc, 0x34000, v86
	s_nop 1
	v_addc_co_u32_e32 v193, vcc, 0, v87, vcc
	global_load_dwordx4 v[238:241], v[192:193], off offset:1024
	v_add_co_u32_e32 v194, vcc, 0x10000, v76
	s_nop 1
	v_addc_co_u32_e32 v195, vcc, 0, v77, vcc
	global_load_dwordx4 v[242:245], v[194:195], off
	global_load_dwordx4 v[184:187], v[192:193], off offset:1280
	global_load_dwordx4 v[188:191], v[194:195], off offset:256
	v_lshl_add_u64 v[78:79], v[84:85], 0, s[2:3]
	v_lshl_add_u64 v[74:75], s[14:15], 0, v[74:75]
	s_waitcnt vmcnt(7)
	s_nop 1
	v_mov_b32_e32 v66, v222
	v_mov_b32_e32 v67, v223
	v_mov_b32_e32 v68, v224
	v_mov_b32_e32 v69, v225
	v_lshlrev_b32_e32 v80, 16, v66
	v_and_b32_e32 v81, 0xffff0000, v66
	v_lshlrev_b32_e32 v66, 16, v67
	v_and_b32_e32 v67, 0xffff0000, v67
	v_lshlrev_b32_e32 v82, 16, v68
	v_and_b32_e32 v83, 0xffff0000, v68
	v_lshlrev_b32_e32 v68, 16, v69
	v_and_b32_e32 v69, 0xffff0000, v69
	s_waitcnt vmcnt(6)
	s_nop 1
	v_mov_b32_e32 v70, v226
	v_mov_b32_e32 v71, v227
	v_mov_b32_e32 v72, v228
	v_mov_b32_e32 v73, v229
	v_lshlrev_b32_e32 v84, 16, v70
	v_and_b32_e32 v85, 0xffff0000, v70
	v_lshlrev_b32_e32 v70, 16, v71
	v_and_b32_e32 v71, 0xffff0000, v71
	v_lshlrev_b32_e32 v86, 16, v72
	v_and_b32_e32 v87, 0xffff0000, v72
	v_lshlrev_b32_e32 v72, 16, v73
	v_and_b32_e32 v73, 0xffff0000, v73
	v_pk_fma_f32 v[64:65], v[64:65], v[66:67], v[70:71]
	v_pk_fma_f32 v[62:63], v[62:63], v[80:81], v[84:85]
	v_pk_fma_f32 v[66:67], v[60:61], v[68:69], v[72:73]
	v_pk_fma_f32 v[60:61], v[58:59], v[82:83], v[86:87]
	v_cvt_pk_bf16_f32 v58, v62, v63
	v_cvt_pk_bf16_f32 v59, v64, v65
	v_cvt_pk_bf16_f32 v60, v60, v61
	v_cvt_pk_bf16_f32 v61, v66, v67
	global_store_dwordx4 v[74:75], v[58:61], off
	s_nop 0
	v_add_u32_e32 v66, 0x90, v146
	v_ashrrev_i32_e32 v67, 31, v66
	v_mad_i64_i32 v[68:69], s[0:1], v66, s95, v[148:149]
	v_lshl_add_u64 v[68:69], v[68:69], 0, v[150:151]
	v_add_co_u32_e32 v70, vcc, s19, v68
	s_waitcnt vmcnt(6)
	s_nop 1
	v_mov_b32_e32 v58, v230
	v_mov_b32_e32 v59, v231
	v_mov_b32_e32 v60, v232
	v_mov_b32_e32 v61, v233
	v_lshlrev_b32_e32 v72, 16, v58
	v_and_b32_e32 v73, 0xffff0000, v58
	s_waitcnt vmcnt(5)
	s_nop 1
	v_mov_b32_e32 v62, v234
	v_mov_b32_e32 v63, v235
	v_mov_b32_e32 v64, v236
	v_mov_b32_e32 v65, v237
	v_lshlrev_b32_e32 v78, 16, v62
	v_and_b32_e32 v79, 0xffff0000, v62
	v_lshlrev_b32_e32 v58, 16, v59
	v_and_b32_e32 v59, 0xffff0000, v59
	v_lshlrev_b32_e32 v76, 16, v60
	v_and_b32_e32 v77, 0xffff0000, v60
	v_lshlrev_b32_e32 v60, 16, v61
	v_and_b32_e32 v61, 0xffff0000, v61
	v_lshlrev_b32_e32 v62, 16, v63
	v_and_b32_e32 v63, 0xffff0000, v63
	v_lshlrev_b32_e32 v80, 16, v64
	v_and_b32_e32 v81, 0xffff0000, v64
	v_lshlrev_b32_e32 v64, 16, v65
	v_and_b32_e32 v65, 0xffff0000, v65
	v_pk_fma_f32 v[54:55], v[54:55], v[72:73], v[78:79]
	v_pk_fma_f32 v[56:57], v[56:57], v[58:59], v[62:63]
	v_pk_fma_f32 v[58:59], v[52:53], v[60:61], v[64:65]
	v_pk_fma_f32 v[52:53], v[50:51], v[76:77], v[80:81]
	v_cvt_pk_bf16_f32 v50, v54, v55
	v_lshlrev_b64 v[54:55], 11, v[66:67]
	v_lshl_add_u64 v[54:55], v[54:55], 0, v[144:145]
	v_cvt_pk_bf16_f32 v51, v56, v57
	v_cvt_pk_bf16_f32 v52, v52, v53
	v_cvt_pk_bf16_f32 v53, v58, v59
	v_lshlrev_b64 v[58:59], 1, v[54:55]
	v_addc_co_u32_e32 v71, vcc, 0, v69, vcc
	global_store_dwordx4 v[74:75], v[50:53], off offset:256
	v_lshl_add_u64 v[60:61], s[10:11], 0, v[58:59]
	v_lshl_add_u64 v[62:63], v[68:69], 0, s[2:3]
	v_lshl_add_u64 v[58:59], s[14:15], 0, v[58:59]
	s_waitcnt vmcnt(5)
; #define GAS __attribute__((address_space(1)))
; __device__ __forceinline__ u32x4 pack8(f32x4 v0, f32x4 v1) { u32x4 w; w.x = cvt_pk_bf16(v0[0], v0[1]); w.y = cvt_pk_bf16(v0[2], v0[3]); w.z = cvt_pk_bf16(v1[0], v1[1]); w.w = cvt_pk_bf16(v1[2], v1[3]); return w; }
; __device__ __forceinline__ void unpack8(u32x4 w, f32x4& v0, f32x4& v1) { v0 = (f32x4){bflo(w.x), bfhi(w.x), bflo(w.y), bfhi(w.y)}; v1 = (f32x4){bflo(w.z), bfhi(w.z), bflo(w.w), bfhi(w.w)}; }
; #define GAS __attribute__((address_space(1)))
;     __device__ __forceinline__ void operator()(const f32x4 (&acc)[2][2][4][2], const Unit& u, int wr, int wc, int fr, int fq) const {
;     ...
;             for (int m = 0; m < 4; ++m) { const size_t r = (size_t)(row0 + ai * HALF + m * 16); const size_t off = r * 2048 + col0; const bf16_t* gp = P + r * NPJ + 2560 + MODE * 2048 + col0;
; #pragma unroll
;                 for (int bj = 0; bj < 2; ++bj) { f32x4 g0, g1; unpack8(*(const GAS u32x4*)(gp + bj * HALF), g0, g1);
;                     f32x4 v0 = g0 * acc[ai][bj][m][0], v1 = g1 * acc[ai][bj][m][1];
;                     if (MODE == 1) { f32x4 t0, t1; unpack8(*(const GAS u32x4*)(T1 + off + bj * HALF), t0, t1); v0 += t0; v1 += t1; }
;                     const u32x4 w = pack8(v0, v1);
;                     if (MODE == 0 && samp) asm volatile("global_store_dwordx4 %0, %1, off sc1\n\ts_nop 1" :: "v"(O + off + bj * HALF), "v"(w) : "memory");
;                     else *(GAS u32x4*)(O + off + bj * HALF) = w; } }
	s_nop 1
	v_mov_b32_e32 v50, v238
	v_mov_b32_e32 v51, v239
	v_mov_b32_e32 v52, v240
	v_mov_b32_e32 v53, v241
	v_lshlrev_b32_e32 v64, 16, v50
	v_and_b32_e32 v65, 0xffff0000, v50
	v_lshlrev_b32_e32 v50, 16, v51
	v_and_b32_e32 v51, 0xffff0000, v51
	v_lshlrev_b32_e32 v66, 16, v52
	v_and_b32_e32 v67, 0xffff0000, v52
	v_lshlrev_b32_e32 v52, 16, v53
	v_and_b32_e32 v53, 0xffff0000, v53
	s_waitcnt vmcnt(4)
	s_nop 1
	v_mov_b32_e32 v54, v242
	v_mov_b32_e32 v55, v243
	v_mov_b32_e32 v56, v244
	v_mov_b32_e32 v57, v245
	v_lshlrev_b32_e32 v68, 16, v54
	v_and_b32_e32 v69, 0xffff0000, v54
	v_lshlrev_b32_e32 v54, 16, v55
	v_and_b32_e32 v55, 0xffff0000, v55
	v_lshlrev_b32_e32 v70, 16, v56
	v_and_b32_e32 v71, 0xffff0000, v56
	v_lshlrev_b32_e32 v56, 16, v57
	v_and_b32_e32 v57, 0xffff0000, v57
	v_pk_fma_f32 v[48:49], v[48:49], v[50:51], v[54:55]
	v_pk_fma_f32 v[46:47], v[46:47], v[64:65], v[68:69]
	v_pk_fma_f32 v[50:51], v[44:45], v[52:53], v[56:57]
	v_pk_fma_f32 v[44:45], v[42:43], v[66:67], v[70:71]
	v_cvt_pk_bf16_f32 v42, v46, v47
	v_cvt_pk_bf16_f32 v43, v48, v49
	v_cvt_pk_bf16_f32 v44, v44, v45
	v_cvt_pk_bf16_f32 v45, v50, v51
	global_store_dwordx4 v[58:59], v[42:45], off
	s_nop 0
	v_add_u32_e32 v50, 0xa0, v146
	v_ashrrev_i32_e32 v51, 31, v50
	v_mad_i64_i32 v[52:53], s[0:1], v50, s95, v[148:149]
	v_lshl_add_u64 v[52:53], v[52:53], 0, v[150:151]
	v_add_co_u32_e32 v54, vcc, s19, v52
	s_waitcnt vmcnt(4)
	s_nop 1
	v_mov_b32_e32 v42, v184
	v_mov_b32_e32 v43, v185
	v_mov_b32_e32 v44, v186
	v_mov_b32_e32 v45, v187
	v_lshlrev_b32_e32 v56, 16, v42
	v_and_b32_e32 v57, 0xffff0000, v42
	s_waitcnt vmcnt(3)
	s_nop 1
	v_mov_b32_e32 v46, v188
	v_mov_b32_e32 v47, v189
	v_mov_b32_e32 v48, v190
	v_mov_b32_e32 v49, v191
	v_lshlrev_b32_e32 v62, 16, v46
	v_and_b32_e32 v63, 0xffff0000, v46
	v_lshlrev_b32_e32 v42, 16, v43
	v_and_b32_e32 v43, 0xffff0000, v43
	v_lshlrev_b32_e32 v60, 16, v44
	v_and_b32_e32 v61, 0xffff0000, v44
	v_lshlrev_b32_e32 v44, 16, v45
	v_and_b32_e32 v45, 0xffff0000, v45
	v_lshlrev_b32_e32 v46, 16, v47
	v_and_b32_e32 v47, 0xffff0000, v47
	v_lshlrev_b32_e32 v64, 16, v48
	v_and_b32_e32 v65, 0xffff0000, v48
	v_lshlrev_b32_e32 v48, 16, v49
	v_and_b32_e32 v49, 0xffff0000, v49
	v_pk_fma_f32 v[38:39], v[38:39], v[56:57], v[62:63]
	v_pk_fma_f32 v[40:41], v[40:41], v[42:43], v[46:47]
	v_pk_fma_f32 v[42:43], v[36:37], v[44:45], v[48:49]
	v_pk_fma_f32 v[36:37], v[34:35], v[60:61], v[64:65]
	v_cvt_pk_bf16_f32 v34, v38, v39
	v_lshlrev_b64 v[38:39], 11, v[50:51]
	v_lshl_add_u64 v[38:39], v[38:39], 0, v[144:145]
	v_cvt_pk_bf16_f32 v35, v40, v41
	v_cvt_pk_bf16_f32 v36, v36, v37
	v_cvt_pk_bf16_f32 v37, v42, v43
	v_lshlrev_b64 v[42:43], 1, v[38:39]
	v_addc_co_u32_e32 v55, vcc, 0, v53, vcc
	global_store_dwordx4 v[58:59], v[34:37], off offset:256
	v_lshl_add_u64 v[44:45], s[10:11], 0, v[42:43]
	global_load_dwordx4 v[222:225], v[54:55], off offset:1024
	global_load_dwordx4 v[226:229], v[44:45], off
	global_load_dwordx4 v[230:233], v[54:55], off offset:1280
	global_load_dwordx4 v[234:237], v[44:45], off offset:256
	v_add_co_u32_e32 v192, vcc, 0x34000, v54
	s_nop 1
	v_addc_co_u32_e32 v193, vcc, 0, v55, vcc
	global_load_dwordx4 v[238:241], v[192:193], off offset:1024
	v_add_co_u32_e32 v194, vcc, 0x10000, v44
	s_nop 1
	v_addc_co_u32_e32 v195, vcc, 0, v45, vcc
	global_load_dwordx4 v[242:245], v[194:195], off
	global_load_dwordx4 v[184:187], v[192:193], off offset:1280
	global_load_dwordx4 v[188:191], v[194:195], off offset:256
	v_lshl_add_u64 v[46:47], v[52:53], 0, s[2:3]
	v_lshl_add_u64 v[42:43], s[14:15], 0, v[42:43]
	s_waitcnt vmcnt(7)
	s_nop 1
	v_mov_b32_e32 v34, v222
	v_mov_b32_e32 v35, v223
	v_mov_b32_e32 v36, v224
	v_mov_b32_e32 v37, v225
	v_lshlrev_b32_e32 v48, 16, v34
	v_and_b32_e32 v49, 0xffff0000, v34
	v_lshlrev_b32_e32 v34, 16, v35
	v_and_b32_e32 v35, 0xffff0000, v35
	v_lshlrev_b32_e32 v50, 16, v36
	v_and_b32_e32 v51, 0xffff0000, v36
	v_lshlrev_b32_e32 v36, 16, v37
	v_and_b32_e32 v37, 0xffff0000, v37
	s_waitcnt vmcnt(6)
	s_nop 1
	v_mov_b32_e32 v38, v226
	v_mov_b32_e32 v39, v227
	v_mov_b32_e32 v40, v228
	v_mov_b32_e32 v41, v229
	v_lshlrev_b32_e32 v52, 16, v38
	v_and_b32_e32 v53, 0xffff0000, v38
	v_lshlrev_b32_e32 v38, 16, v39
	v_and_b32_e32 v39, 0xffff0000, v39
	v_lshlrev_b32_e32 v54, 16, v40
	v_and_b32_e32 v55, 0xffff0000, v40
	v_lshlrev_b32_e32 v40, 16, v41
	v_and_b32_e32 v41, 0xffff0000, v41
	v_pk_fma_f32 v[32:33], v[32:33], v[34:35], v[38:39]
	v_pk_fma_f32 v[30:31], v[30:31], v[48:49], v[52:53]
	v_pk_fma_f32 v[34:35], v[28:29], v[36:37], v[40:41]
	v_pk_fma_f32 v[28:29], v[26:27], v[50:51], v[54:55]
	v_cvt_pk_bf16_f32 v26, v30, v31
	v_cvt_pk_bf16_f32 v27, v32, v33
	v_cvt_pk_bf16_f32 v28, v28, v29
	v_cvt_pk_bf16_f32 v29, v34, v35
	global_store_dwordx4 v[42:43], v[26:29], off
	s_nop 0
	v_add_u32_e32 v34, 0xb0, v146
	v_ashrrev_i32_e32 v35, 31, v34
	v_mad_i64_i32 v[36:37], s[0:1], v34, s95, v[148:149]
	v_lshl_add_u64 v[36:37], v[36:37], 0, v[150:151]
	v_add_co_u32_e32 v38, vcc, s19, v36
	s_waitcnt vmcnt(6)
; #define GAS __attribute__((address_space(1)))
; __device__ __forceinline__ u32x4 pack8(f32x4 v0, f32x4 v1) { u32x4 w; w.x = cvt_pk_bf16(v0[0], v0[1]); w.y = cvt_pk_bf16(v0[2], v0[3]); w.z = cvt_pk_bf16(v1[0], v1[1]); w.w = cvt_pk_bf16(v1[2], v1[3]); return w; }
; __device__ __forceinline__ void unpack8(u32x4 w, f32x4& v0, f32x4& v1) { v0 = (f32x4){bflo(w.x), bfhi(w.x), bflo(w.y), bfhi(w.y)}; v1 = (f32x4){bflo(w.z), bfhi(w.z), bflo(w.w), bfhi(w.w)}; }
; #define PG8_BAR __builtin_amdgcn_s_barrier()
; #define GAS __attribute__((address_space(1)))
;     __device__ __forceinline__ void operator()(const f32x4 (&acc)[2][2][4][2], const Unit& u, int wr, int wc, int fr, int fq) const {
;     ...
;             for (int m = 0; m < 4; ++m) { const size_t r = (size_t)(row0 + ai * HALF + m * 16); const size_t off = r * 2048 + col0; const bf16_t* gp = P + r * NPJ + 2560 + MODE * 2048 + col0;
; #pragma unroll
;                 for (int bj = 0; bj < 2; ++bj) { f32x4 g0, g1; unpack8(*(const GAS u32x4*)(gp + bj * HALF), g0, g1);
;                     f32x4 v0 = g0 * acc[ai][bj][m][0], v1 = g1 * acc[ai][bj][m][1];
;                     if (MODE == 1) { f32x4 t0, t1; unpack8(*(const GAS u32x4*)(T1 + off + bj * HALF), t0, t1); v0 += t0; v1 += t1; }
;                     const u32x4 w = pack8(v0, v1);
;                     if (MODE == 0 && samp) asm volatile("global_store_dwordx4 %0, %1, off sc1\n\ts_nop 1" :: "v"(O + off + bj * HALF), "v"(w) : "memory");
;                     else *(GAS u32x4*)(O + off + bj * HALF) = w; } }
; template <class Epi, class Sched, bool ALIGN_EPI = false, bool SP2 = false>
; __device__ __forceinline__ void gemm_phase(PG8_LAS unsigned char* lds, const Gemm g, const Sched& S, const Epi& E) {
;     ...
;         if (!has_next) break;
; #pragma unroll
;         for (int a = 0; a < 2; ++a)
; #pragma unroll
;             for (int b = 0; b < 2; ++b)
; #pragma unroll
;                 for (int m = 0; m < 4; ++m)
; #pragma unroll
;                     for (int n = 0; n < 2; ++n) acc[a][b][m][n] = (f32x4){0.f, 0.f, 0.f, 0.f};
;         cur = nxt; cA = nA; cB = nB; ++ui;
;         if constexpr (ALIGN_EPI) { if (wr == 1) PG8_BAR; }
	s_nop 1
	v_mov_b32_e32 v26, v230
	v_mov_b32_e32 v27, v231
	v_mov_b32_e32 v28, v232
	v_mov_b32_e32 v29, v233
	v_lshlrev_b32_e32 v40, 16, v26
	v_and_b32_e32 v41, 0xffff0000, v26
	s_waitcnt vmcnt(5)
	s_nop 1
	v_mov_b32_e32 v30, v234
	v_mov_b32_e32 v31, v235
	v_mov_b32_e32 v32, v236
	v_mov_b32_e32 v33, v237
	v_lshlrev_b32_e32 v46, 16, v30
	v_and_b32_e32 v47, 0xffff0000, v30
	v_lshlrev_b32_e32 v26, 16, v27
	v_and_b32_e32 v27, 0xffff0000, v27
	v_lshlrev_b32_e32 v44, 16, v28
	v_and_b32_e32 v45, 0xffff0000, v28
	v_lshlrev_b32_e32 v28, 16, v29
	v_and_b32_e32 v29, 0xffff0000, v29
	v_lshlrev_b32_e32 v30, 16, v31
	v_and_b32_e32 v31, 0xffff0000, v31
	v_lshlrev_b32_e32 v48, 16, v32
	v_and_b32_e32 v49, 0xffff0000, v32
	v_lshlrev_b32_e32 v32, 16, v33
	v_and_b32_e32 v33, 0xffff0000, v33
	v_pk_fma_f32 v[22:23], v[22:23], v[40:41], v[46:47]
	v_pk_fma_f32 v[24:25], v[24:25], v[26:27], v[30:31]
	v_pk_fma_f32 v[26:27], v[20:21], v[28:29], v[32:33]
	v_pk_fma_f32 v[20:21], v[18:19], v[44:45], v[48:49]
	v_cvt_pk_bf16_f32 v18, v22, v23
	v_lshlrev_b64 v[22:23], 11, v[34:35]
	v_lshl_add_u64 v[22:23], v[22:23], 0, v[144:145]
	v_cvt_pk_bf16_f32 v19, v24, v25
	v_cvt_pk_bf16_f32 v20, v20, v21
	v_cvt_pk_bf16_f32 v21, v26, v27
	v_lshlrev_b64 v[26:27], 1, v[22:23]
	v_addc_co_u32_e32 v39, vcc, 0, v37, vcc
	global_store_dwordx4 v[42:43], v[18:21], off offset:256
	v_lshl_add_u64 v[28:29], s[10:11], 0, v[26:27]
	v_lshl_add_u64 v[30:31], v[36:37], 0, s[2:3]
	v_lshl_add_u64 v[26:27], s[14:15], 0, v[26:27]
	s_andn2_b64 vcc, exec, s[42:43]
	s_mov_b64 s[42:43], -1
	s_waitcnt vmcnt(5)
	s_nop 1
	v_mov_b32_e32 v18, v238
	v_mov_b32_e32 v19, v239
	v_mov_b32_e32 v20, v240
	v_mov_b32_e32 v21, v241
	v_lshlrev_b32_e32 v32, 16, v18
	v_and_b32_e32 v33, 0xffff0000, v18
	v_lshlrev_b32_e32 v18, 16, v19
	v_and_b32_e32 v19, 0xffff0000, v19
	v_lshlrev_b32_e32 v34, 16, v20
	v_and_b32_e32 v35, 0xffff0000, v20
	v_lshlrev_b32_e32 v20, 16, v21
	v_and_b32_e32 v21, 0xffff0000, v21
	s_waitcnt vmcnt(4)
	s_nop 1
	v_mov_b32_e32 v22, v242
	v_mov_b32_e32 v23, v243
	v_mov_b32_e32 v24, v244
	v_mov_b32_e32 v25, v245
	v_lshlrev_b32_e32 v36, 16, v22
	v_and_b32_e32 v37, 0xffff0000, v22
	v_lshlrev_b32_e32 v22, 16, v23
	v_and_b32_e32 v23, 0xffff0000, v23
	v_lshlrev_b32_e32 v38, 16, v24
	v_and_b32_e32 v39, 0xffff0000, v24
	v_lshlrev_b32_e32 v24, 16, v25
	v_and_b32_e32 v25, 0xffff0000, v25
	v_pk_fma_f32 v[16:17], v[16:17], v[18:19], v[22:23]
	v_pk_fma_f32 v[14:15], v[14:15], v[32:33], v[36:37]
	v_pk_fma_f32 v[18:19], v[12:13], v[20:21], v[24:25]
	v_pk_fma_f32 v[12:13], v[10:11], v[34:35], v[38:39]
	v_cvt_pk_bf16_f32 v10, v14, v15
	v_cvt_pk_bf16_f32 v11, v16, v17
	v_cvt_pk_bf16_f32 v12, v12, v13
	v_cvt_pk_bf16_f32 v13, v18, v19
	global_store_dwordx4 v[26:27], v[10:13], off
	s_nop 0
	s_waitcnt vmcnt(4)
	s_nop 1
	v_mov_b32_e32 v10, v184
	v_mov_b32_e32 v11, v185
	v_mov_b32_e32 v12, v186
	v_mov_b32_e32 v13, v187
	v_lshlrev_b32_e32 v18, 16, v10
	v_and_b32_e32 v19, 0xffff0000, v10
	v_lshlrev_b32_e32 v10, 16, v11
	v_and_b32_e32 v11, 0xffff0000, v11
	v_lshlrev_b32_e32 v20, 16, v12
	v_and_b32_e32 v21, 0xffff0000, v12
	v_lshlrev_b32_e32 v12, 16, v13
	v_and_b32_e32 v13, 0xffff0000, v13
	s_waitcnt vmcnt(3)
	s_nop 1
	v_mov_b32_e32 v14, v188
	v_mov_b32_e32 v15, v189
	v_mov_b32_e32 v16, v190
	v_mov_b32_e32 v17, v191
	v_lshlrev_b32_e32 v22, 16, v14
	v_and_b32_e32 v23, 0xffff0000, v14
	v_lshlrev_b32_e32 v14, 16, v15
	v_and_b32_e32 v15, 0xffff0000, v15
	v_lshlrev_b32_e32 v24, 16, v16
	v_and_b32_e32 v25, 0xffff0000, v16
	v_lshlrev_b32_e32 v16, 16, v17
	v_and_b32_e32 v17, 0xffff0000, v17
	v_pk_fma_f32 v[8:9], v[8:9], v[10:11], v[14:15]
	v_pk_fma_f32 v[6:7], v[6:7], v[18:19], v[22:23]
	v_pk_fma_f32 v[10:11], v[4:5], v[12:13], v[16:17]
	v_pk_fma_f32 v[4:5], v[2:3], v[20:21], v[24:25]
	v_cvt_pk_bf16_f32 v2, v6, v7
	v_cvt_pk_bf16_f32 v3, v8, v9
	v_cvt_pk_bf16_f32 v4, v4, v5
	v_cvt_pk_bf16_f32 v5, v10, v11
	global_store_dwordx4 v[26:27], v[2:5], off offset:256
	s_cbranch_vccnz .LBB0_1148
	s_andn2_b64 vcc, exec, s[12:13]
	s_cbranch_vccnz .LBB0_1147
	s_branch .LBB0_1147

; #define PG8_STAGE(bufoff, gbase, voff) do { _Pragma("unroll") for (int _i = 0; _i < 2; ++_i) \
;         __builtin_amdgcn_global_load_lds((const unsigned*)((const char*)(gbase) + (voff)[_i]), (PG8_LAS unsigned*)(lds + (bufoff) + ldsw + _i * 8192), 16, 0, AUX_A); } while (0)
; #define PG8_WAIT_V(n) asm volatile("s_waitcnt vmcnt(" #n ")" ::: "memory")
; template <class Epi, class Sched, bool ALIGN_EPI = false, bool SP2 = false>
; __device__ __forceinline__ void gemm_phase(PG8_LAS unsigned char* lds, const Gemm g, const Sched& S, const Epi& E) {
;     ...
;     const int tid = tid_l, wid = __builtin_amdgcn_readfirstlane(tid >> 6), lane = tid & 63, wr = wid >> 2, wc = wid & 3, fr = lane & 15, fq = lane >> 4;
;     const int K = g.K;
;     unsigned voffA[2], voffB[2];
; #pragma unroll
;     for (int i = 0; i < 2; ++i) { int R, C; stage_rc(tid * 16 + i * 8192, R, C); const int Rb = Epi::PERM ? ((R & ~31) + perm32(R & 31)) : R;
;         voffA[i] = (unsigned)(R * K + C) * 2u; voffB[i] = (unsigned)(Rb * K + C) * 2u; }
;     const size_t kstep = (size_t)(BK * 2);
;     const size_t hstep = (size_t)HALF * K * 2;
;     const size_t tstep = 2 * hstep;
;     const unsigned ldsw = (unsigned)wid * 1024u;
;     const int aoff = lds_byte(wr * 64 + fr, fq * 8), boff = lds_byte(wc * 32 + fr, fq * 8);
;     ...
;     { const int rot0 = cur.krot, nt0 = cur.nkt; const char* sA0 = PG8_KP(cA, 0, rot0, nt0); const char* sA1 = PG8_KP(cA, 1, rot0, nt0); const char* sB0 = PG8_KP(cB, 0, rot0, nt0); const char* sB1 = PG8_KP(cB, 1, rot0, nt0);
;     if constexpr (SP2) {
;         PG8_STAGEB(PG8_SB(0, 0), sB0, voffB); PG8_STAGEB(PG8_SB(0, 1), sB0 + hstep, voffB); PG8_STAGE(PG8_SA(0, 0), sA0, voffA); PG8_STAGE(PG8_SA(0, 1), sA0 + hstep, voffA);
;         if (wr == 1) PG8_BAR;
;         PG8_WAIT_V(2); PG8_BAR;
;         PG8_STAGEB(PG8_SB(1, 0), sB1, voffB); PG8_STAGE(PG8_SA(1, 0), sA1, voffA); PG8_STAGEB(PG8_SB(1, 1), sB1 + hstep, voffB);
;         PG8_WAIT_V(6); PG8_BAR;
;     } else {
;         PG8_STAGEB(PG8_SB(0, 0), sB0, voffB); PG8_STAGE(PG8_SA(0, 0), sA0, voffA); PG8_STAGEB(PG8_SB(0, 1), sB0 + hstep, voffB); PG8_STAGE(PG8_SA(0, 1), sA0 + hstep, voffA);
;         if (wr == 1) PG8_BAR;
;         PG8_WAIT_V(4); PG8_BAR;
;         PG8_STAGEB(PG8_SB(1, 0), sB1, voffB); PG8_STAGE(PG8_SA(1, 0), sA1, voffA); PG8_STAGEB(PG8_SB(1, 1), sB1 + hstep, voffB);
;         PG8_WAIT_V(6); PG8_BAR;
;     }
.LBB0_1290:
	v_readlane_b32 s0, v252, 26
	v_readlane_b32 s1, v252, 27
	s_andn2_b64 vcc, exec, s[4:5]
	s_nop 0
	v_cndmask_b32_e64 v1, 0, 1, s[0:1]
	v_cmp_ne_u32_e64 s[0:1], 1, v1
	s_nop 1
	v_writelane_b32 v254, s0, 58
	s_nop 1
	v_writelane_b32 v254, s1, 59
	s_cbranch_vccnz .LBB0_1377
	v_readlane_b32 s0, v254, 58
	s_mov_b64 s[8:9], s[66:67]
	v_mov_b32_e32 v16, v0
	v_readlane_b32 s1, v254, 59
	s_and_b64 vcc, exec, s[0:1]
	v_readfirstlane_b32 s10, v16
	s_cbranch_vccnz .LBB0_1323
	v_lshlrev_b32_e32 v1, 4, v16
	v_add_u32_e32 v2, 0x2000, v1
	v_ashrrev_i32_e32 v3, 31, v2
	v_lshrrev_b32_e32 v3, 22, v3
	v_add_u32_e32 v3, v2, v3
	v_ashrrev_i32_e32 v10, 10, v3
	v_mul_i32_i24_e32 v3, 0x400, v10
	v_sub_u32_e32 v2, v2, v3
	v_lshrrev_b32_e32 v3, 4, v2
	v_bitop3_b32 v2, v3, v2, 32 bitop3:0x6c
	v_ashrrev_i32_e32 v3, 31, v2
	v_lshrrev_b32_e32 v3, 26, v3
	v_add_u32_e32 v3, v2, v3
	v_lshlrev_b32_e32 v4, 3, v10
	v_ashrrev_i32_e32 v11, 6, v3
	v_and_b32_e32 v4, -16, v4
	v_add_u32_e32 v4, v11, v4
	v_and_b32_e32 v5, 3, v11
	s_mov_b32 s2, 0xfffe0
	v_lshrrev_b32_e32 v6, 2, v4
	v_lshlrev_b32_e32 v7, 1, v4
	v_and_b32_e32 v3, 0xc0, v3
	v_and_or_b32 v5, v4, s2, v5
	v_and_b32_e32 v6, 4, v6
	v_and_b32_e32 v7, 24, v7
	v_sub_u32_e32 v2, v2, v3
	v_or3_b32 v5, v5, v6, v7
	v_lshlrev_b32_e32 v6, 5, v10
	v_ashrrev_i16_sdwa v2, v207, sext(v2) dst_sel:DWORD dst_unused:UNUSED_PAD src0_sel:DWORD src1_sel:BYTE_0
	v_and_b32_e32 v6, 32, v6
	v_bfe_i32 v12, v2, 0, 16
	v_add_lshl_u32 v2, v6, v12, 1
	v_lshl_add_u32 v152, v5, 12, v2
	v_lshl_add_u32 v154, v4, 12, v2
	v_bfe_i32 v2, v16, 27, 1
	v_lshrrev_b32_e32 v2, 22, v2
	v_readlane_b32 s64, v254, 53
	v_add_u32_e32 v2, v1, v2
	v_readlane_b32 s65, v254, 54
	v_and_b32_e32 v2, 0xfffffc00, v2
	s_mov_b32 s65, s79
	v_sub_u32_e32 v1, v1, v2
	s_lshl_b64 s[0:1], s[64:65], 23
	v_lshrrev_b32_e32 v2, 4, v1
	v_ashrrev_i32_e32 v3, 31, v16
	s_add_u32 s30, s8, 0x2d180000
	v_bitop3_b32 v1, v2, v1, 32 bitop3:0x6c
	v_lshrrev_b32_e32 v3, 26, v3
	s_addc_u32 s31, s9, 0
	v_ashrrev_i32_e32 v2, 31, v1
	v_add_u32_e32 v3, v16, v3
	s_add_u32 s0, s8, s0
	v_lshrrev_b32_e32 v2, 26, v2
	v_ashrrev_i32_e32 v14, 6, v3
	s_addc_u32 s1, s9, s1
	v_add_u32_e32 v2, v1, v2
	v_lshlrev_b32_e32 v3, 3, v14
	s_add_u32 s33, s0, 0xa000000
	v_ashrrev_i32_e32 v13, 6, v2
	v_and_b32_e32 v3, -16, v3
	s_addc_u32 s48, s1, 0
	s_ashr_i32 s0, s10, 6
	v_add_u32_e32 v3, v13, v3
	v_and_b32_e32 v4, 3, v13
	s_ashr_i32 s1, s10, 8
	s_lshl_b32 s49, s0, 10
	v_and_or_b32 v4, v3, s2, v4
	v_readlane_b32 s2, v252, 58
	s_add_u32 s2, s30, s2
	v_lshrrev_b32_e32 v5, 2, v3
	v_lshlrev_b32_e32 v6, 1, v3
	v_and_b32_e32 v2, 0xc0, v2
	s_addc_u32 s4, s31, 0
	v_readlane_b32 s3, v252, 60
	v_and_b32_e32 v5, 4, v5
	v_and_b32_e32 v6, 24, v6
	v_sub_u32_e32 v1, v1, v2
	s_add_u32 s5, s33, s3
	v_or3_b32 v4, v4, v5, v6
	v_lshlrev_b32_e32 v5, 5, v14
	v_ashrrev_i16_sdwa v1, v207, sext(v1) dst_sel:DWORD dst_unused:UNUSED_PAD src0_sel:DWORD src1_sel:BYTE_0
	s_addc_u32 s6, s48, 0
	v_readlane_b32 s3, v252, 41
	v_and_b32_e32 v5, 32, v5
	v_bfe_i32 v15, v1, 0, 16
	s_add_u32 s34, s5, s3
	v_add_lshl_u32 v1, v5, v15, 1
	s_addc_u32 s35, s6, 0
	s_add_i32 s50, s49, 0
	v_lshl_add_u32 v156, v4, 12, v1
	s_add_i32 m0, s50, 0x10000
	v_lshl_add_u32 v158, v3, 12, v1
	global_load_lds_dwordx4 v156, s[34:35]
	s_add_i32 m0, s50, 0x12000
	s_add_u32 s40, s2, s3
	s_addc_u32 s41, s4, 0
	s_add_u32 s4, s34, 0x80000
	global_load_lds_dwordx4 v152, s[34:35]
	s_addc_u32 s5, s35, 0
	s_add_i32 m0, s50, 0x14000
	s_add_i32 s51, s50, 0x2000
	global_load_lds_dwordx4 v156, s[4:5]
	s_add_i32 m0, s50, 0x16000
	v_mov_b32_e32 v157, v98
	global_load_lds_dwordx4 v152, s[4:5]
	s_mov_b32 m0, s50
	s_add_u32 s4, s40, 0x80000
	global_load_lds_dwordx4 v158, s[40:41]
	s_mov_b32 m0, s51
	s_addc_u32 s5, s41, 0
	s_add_i32 s52, s50, 0x4000
	global_load_lds_dwordx4 v154, s[40:41]
	s_mov_b32 m0, s52
	s_add_i32 s53, s50, 0x6000
	global_load_lds_dwordx4 v158, s[4:5]
	s_mov_b32 m0, s53
	v_mov_b32_e32 v153, v98
	global_load_lds_dwordx4 v154, s[4:5]
	v_mov_b32_e32 v159, v98
	v_mov_b32_e32 v155, v98
	s_cmp_eq_u32 s1, 1
	v_lshl_add_u64 v[8:9], s[34:35], 0, v[156:157]
	v_lshl_add_u64 v[6:7], s[34:35], 0, v[152:153]
	v_lshl_add_u64 v[2:3], s[40:41], 0, v[158:159]
	s_cselect_b64 s[4:5], -1, 0
	s_cmp_lg_u32 s1, 1
	v_lshl_add_u64 v[4:5], s[40:41], 0, v[154:155]
	s_cbranch_scc1 .LBB0_1294
.LBB0_1294:
	s_add_u32 s6, s8, 0x39880000
	s_mul_i32 s11, s64, 0xf0000
	s_addc_u32 s7, s9, 0
	s_mul_hi_u32 s2, s64, 0xf0000
	s_add_u32 s11, s8, s11
	s_addc_u32 s2, s9, s2
	s_add_u32 s54, s11, 0x104000
	s_addc_u32 s55, s2, 0
	s_add_u32 s56, s8, 0x35880000
	v_lshrrev_b32_e32 v17, 1, v16
	s_addc_u32 s57, s9, 0
	v_and_b32_e32 v17, 24, v17
	s_lshl_b32 s0, s0, 5
	v_and_b32_e32 v1, 15, v16
	v_lshlrev_b32_e32 v18, 1, v17
	v_lshlrev_b32_e32 v16, 2, v16
	s_and_b32 s2, s0, 0x60
	s_add_i32 m0, s50, 0x18000
	v_lshl_add_u64 v[8:9], v[8:9], 0, s[76:77]
	s_lshl_b32 s58, s1, 6
	v_lshl_or_b32 v18, v1, 6, v18
	s_lshl_b32 s1, s1, 13
	v_and_b32_e32 v16, 32, v16
	s_lshl_b32 s0, s2, 7
	global_load_lds_dwordx4 v[8:9], off
	v_lshl_add_u64 v[6:7], v[6:7], 0, s[76:77]
	s_add_i32 m0, s50, 0x1a000
	s_add_i32 s59, s50, 0x8000
	s_add_i32 s60, s50, 0xa000
	v_bitop3_b32 v99, v18, s0, v16 bitop3:0xde
	global_load_lds_dwordx4 v[6:7], off
	v_lshl_add_u64 v[2:3], v[2:3], 0, s[76:77]
	s_mov_b32 m0, s59
	s_add_u32 s0, s34, 0x80080
	v_bitop3_b32 v19, v18, s1, v16 bitop3:0xde
	global_load_lds_dwordx4 v[2:3], off
	v_lshl_add_u64 v[2:3], v[4:5], 0, s[76:77]
	s_mov_b32 m0, s60
	s_addc_u32 s1, s35, 0
	global_load_lds_dwordx4 v[2:3], off
	s_add_i32 m0, s50, 0x1c000
	v_lshl_add_u64 v[2:3], s[0:1], 0, v[156:157]
	global_load_lds_dwordx4 v[2:3], off
	v_lshl_add_u64 v[2:3], s[0:1], 0, v[152:153]
	s_add_i32 m0, s50, 0x1e000
	s_cmpk_lt_u32 s10, 0x100
	global_load_lds_dwordx4 v[2:3], off
	s_waitcnt vmcnt(8)
	s_barrier
	v_lshlrev_b32_e32 v2, 15, v10
	v_and_b32_e32 v2, 0xffff0000, v2
	v_lshl_add_u32 v2, v11, 12, v2
	v_and_b32_e32 v3, 1, v10
	v_lshl_or_b32 v2, v3, 6, v2
	v_lshl_add_u32 v160, v12, 1, v2
	v_lshlrev_b32_e32 v2, 15, v14
	v_and_b32_e32 v2, 0xffff0000, v2
	s_waitcnt vmcnt(6)
	v_lshl_add_u32 v2, v13, 12, v2
	v_and_b32_e32 v3, 1, v14
	v_lshl_or_b32 v2, v3, 6, v2
	v_readlane_b32 s0, v252, 45
	s_cselect_b64 s[8:9], -1, 0
	v_or_b32_e32 v180, s2, v17
	v_mov_b32_e32 v161, v98
	v_lshl_add_u32 v162, v15, 1, v2
	v_mov_b32_e32 v163, v98
	s_mov_b32 s61, 0
	v_add_u32_e32 v181, 0, v19
	s_mov_b32 s78, s0
	v_readlane_b32 s71, v252, 46
	v_readlane_b32 s70, v252, 59
	v_readlane_b32 s69, v252, 57
	s_mov_b32 s3, 0x20000
	s_mov_b32 s46, 0x30000
	s_barrier
	s_branch .LBB0_1297

; #define PG8_STAGE(bufoff, gbase, voff) do { _Pragma("unroll") for (int _i = 0; _i < 2; ++_i) \
;         __builtin_amdgcn_global_load_lds((const unsigned*)((const char*)(gbase) + (voff)[_i]), (PG8_LAS unsigned*)(lds + (bufoff) + ldsw + _i * 8192), 16, 0, AUX_A); } while (0)
; #define PG8_STAGEB(bufoff, gbase, voff) do { _Pragma("unroll") for (int _i = 0; _i < 2; ++_i) \
;         __builtin_amdgcn_global_load_lds((const unsigned*)((const char*)(gbase) + (voff)[_i]), (PG8_LAS unsigned*)(lds + (bufoff) + ldsw + _i * 8192), 16, 0, AUX_B); } while (0)
; #define PG8_WAIT_V(n) asm volatile("s_waitcnt vmcnt(" #n ")" ::: "memory")
; #define PG8_WAIT_L(n) asm volatile("s_waitcnt lgkmcnt(" #n ")" ::: "memory")
; template <class Epi, class Sched, bool ALIGN_EPI = false, bool SP2 = false>
; __device__ __forceinline__ void gemm_phase(PG8_LAS unsigned char* lds, const Gemm g, const Sched& S, const Epi& E) {
;     ...
;         const bool has_next = S.next(ui + 1, nxt);
;         const char* nA = has_next ? (const char*)g.A + (size_t)nxt.pm * tstep + (size_t)nxt.kt0 * kstep : cA; const char* nB = has_next ? (const char*)g.Bt + (size_t)nxt.pn * tstep + (size_t)nxt.kt0 * kstep : cB;
;         const int nt = cur.nkt, rot = cur.krot;
;         const char* nAr = has_next ? nA + (size_t)nxt.krot * kstep : PG8_KP(cA, 0, rot, nt); const char* nBr = has_next ? nB + (size_t)nxt.krot * kstep : PG8_KP(cB, 0, rot, nt);
;         for (int t = 0; t < nt; t += 2) {
;             const bool last = (t == nt - 2);
;             const char* a1 = PG8_KP(cA, t + 1, rot, nt);
;             const char* a2 = last ? nAr : PG8_KP(cA, t + 2, rot, nt); const char* b2 = last ? nBr : PG8_KP(cB, t + 2, rot, nt);
;             const char* a3 = a2 + kstep; const char* b3 = b2 + kstep;
;             if (last && has_next) S.a_ready(nxt);
;             if constexpr (SP2) {
;             PG8_LDB(B0, 0, 0); PG8_LDB(B1, 0, 1); PG8_SCHED; PG8_LDA(At, 0, 0); PG8_STAGE(PG8_SA(1, 1), a1 + hstep, voffA);
;             PG8_WAIT_V(8); PG8_WAIT_L(0); PG8_BAR; PG8_MMA(0, 0, At, B0); PG8_MMA(0, 1, At, B1); PG8_BAR; PG8_SCHED;
;             PG8_LDA(At, 0, 1); PG8_STAGEB(PG8_SB(0, 0), b2, voffB); PG8_STAGEB(PG8_SB(0, 1), b2 + hstep, voffB); PG8_STAGE(PG8_SA(0, 0), a2, voffA);
;             PG8_WAIT_V(8); PG8_WAIT_L(0); PG8_BAR; PG8_MMA(1, 0, At, B0); PG8_MMA(1, 1, At, B1); PG8_BAR; PG8_SCHED;
.LBB0_1307:
	s_add_u32 s0, s40, 0x80080
	s_addc_u32 s1, s41, 0
	s_waitcnt vmcnt(0)
	v_lshl_add_u64 v[132:133], s[0:1], 0, v[160:161]
	v_lshl_add_u64 v[134:135], s[0:1], 0, v[162:163]
	s_mov_b32 s11, 0
	s_mov_b32 s13, 2
	s_waitcnt vmcnt(0)
	s_waitcnt lgkmcnt(0)
	s_cmp_lg_u64 s[8:9], 0
	s_cbranch_scc1 .Lrp_1308
	s_barrier
.Lrp_1308:
.Lpk_1308:
	s_or_b32 s0, s11, 1
	s_cmp_ge_i32 s0, s71
	s_cselect_b32 s2, s71, 0
	s_add_i32 s11, s11, 2
	s_cmp_ge_i32 s11, s71
	s_cselect_b32 s0, s71, 0
	s_sub_i32 s0, s13, s0
	s_ashr_i32 s1, s0, 31
	s_lshl_b64 s[0:1], s[0:1], 7
	s_add_u32 s15, s40, s0
	s_addc_u32 s29, s41, s1
	s_add_u32 s0, s34, s0
	s_addc_u32 s1, s35, s1
	s_cmp_eq_u32 s71, s13
	s_cselect_b32 s45, s43, s29
	s_cselect_b32 s44, s42, s15
	s_cselect_b32 s37, s19, s1
	s_cselect_b32 s36, s18, s0
	s_add_i32 s15, 0, 0x10000
	s_add_i32 s29, 0, 0x14000
	v_add_u32_e32 v148, s15, v99
	v_add_u32_e32 v168, s29, v99
	ds_read_b128 v[136:139], v148
	ds_read_b128 v[140:143], v148 offset:1024
	ds_read_b128 v[144:147], v148 offset:2048
	ds_read_b128 v[148:151], v148 offset:3072
	ds_read_b128 v[164:167], v168
	ds_read_b128 v[182:185], v168 offset:1024
	ds_read_b128 v[186:189], v168 offset:2048
	ds_read_b128 v[190:193], v168 offset:3072
	v_mad_i64_i32 v[168:169], s[0:1], s2, v220, v[134:135]
	s_add_i32 m0, s50, 0xc000
	ds_read_b128 v[194:197], v181
	ds_read_b128 v[198:201], v181 offset:1024
	ds_read_b128 v[222:225], v181 offset:2048
	ds_read_b128 v[226:229], v181 offset:3072
	ds_read_b128 v[230:233], v181 offset:4096
	ds_read_b128 v[234:237], v181 offset:5120
	ds_read_b128 v[238:241], v181 offset:6144
	ds_read_b128 v[242:245], v181 offset:7168
	global_load_lds_dwordx4 v[168:169], off
	v_mad_i64_i32 v[168:169], s[0:1], s2, v220, v[132:133]
	s_add_i32 m0, s50, 0xe000
	s_nop 0
	global_load_lds_dwordx4 v[168:169], off
	s_waitcnt vmcnt(8)
	s_waitcnt lgkmcnt(0)
	s_setprio 1
	s_barrier
	v_mfma_f32_16x16x32_bf16 v[128:131], v[136:139], v[194:197], 0
	v_mfma_f32_16x16x32_bf16 v[128:131], v[140:143], v[198:201], v[128:131]
	v_mfma_f32_16x16x32_bf16 v[124:127], v[144:147], v[194:197], 0
	v_mfma_f32_16x16x32_bf16 v[124:127], v[148:151], v[198:201], v[124:127]
	v_mfma_f32_16x16x32_bf16 v[120:123], v[136:139], v[222:225], 0
	v_mfma_f32_16x16x32_bf16 v[120:123], v[140:143], v[226:229], v[120:123]
	v_mfma_f32_16x16x32_bf16 v[112:115], v[144:147], v[222:225], 0
	v_mfma_f32_16x16x32_bf16 v[112:115], v[148:151], v[226:229], v[112:115]
	v_mfma_f32_16x16x32_bf16 v[104:107], v[136:139], v[230:233], 0
	v_mfma_f32_16x16x32_bf16 v[104:107], v[140:143], v[234:237], v[104:107]
	v_mfma_f32_16x16x32_bf16 v[94:97], v[144:147], v[230:233], 0
	v_mfma_f32_16x16x32_bf16 v[94:97], v[148:151], v[234:237], v[94:97]
	v_mfma_f32_16x16x32_bf16 v[86:89], v[136:139], v[238:241], 0
	v_mfma_f32_16x16x32_bf16 v[86:89], v[140:143], v[242:245], v[86:89]
	v_mfma_f32_16x16x32_bf16 v[78:81], v[144:147], v[238:241], 0
	v_mfma_f32_16x16x32_bf16 v[78:81], v[148:151], v[242:245], v[78:81]
	s_setprio 0
	s_setprio 1
	v_mfma_f32_16x16x32_bf16 v[116:119], v[164:167], v[194:197], 0
	v_mfma_f32_16x16x32_bf16 v[116:119], v[182:185], v[198:201], v[116:119]
	v_mfma_f32_16x16x32_bf16 v[108:111], v[186:189], v[194:197], 0
	v_mfma_f32_16x16x32_bf16 v[108:111], v[190:193], v[198:201], v[108:111]
	v_mfma_f32_16x16x32_bf16 v[100:103], v[164:167], v[222:225], 0
	v_mfma_f32_16x16x32_bf16 v[100:103], v[182:185], v[226:229], v[100:103]
	v_mfma_f32_16x16x32_bf16 v[90:93], v[186:189], v[222:225], 0
	v_mfma_f32_16x16x32_bf16 v[90:93], v[190:193], v[226:229], v[90:93]
	v_mfma_f32_16x16x32_bf16 v[82:85], v[164:167], v[230:233], 0
	v_mfma_f32_16x16x32_bf16 v[82:85], v[182:185], v[234:237], v[82:85]
	v_mfma_f32_16x16x32_bf16 v[74:77], v[186:189], v[230:233], 0
	v_mfma_f32_16x16x32_bf16 v[74:77], v[190:193], v[234:237], v[74:77]
	v_mfma_f32_16x16x32_bf16 v[70:73], v[164:167], v[238:241], 0
	v_mfma_f32_16x16x32_bf16 v[70:73], v[182:185], v[242:245], v[70:73]
	s_setprio 2
	s_barrier
	v_mfma_f32_16x16x32_bf16 v[66:69], v[186:189], v[238:241], 0
	v_mfma_f32_16x16x32_bf16 v[66:69], v[190:193], v[242:245], v[66:69]
	s_setprio 0
	s_add_i32 s0, s15, s49
	v_lshl_add_u64 v[168:169], s[36:37], 0, v[156:157]
	s_mov_b32 m0, s0
	ds_read_b128 v[194:197], v181 offset:16384
	ds_read_b128 v[198:201], v181 offset:17408
	ds_read_b128 v[222:225], v181 offset:18432
	ds_read_b128 v[226:229], v181 offset:19456
	ds_read_b128 v[230:233], v181 offset:20480
	ds_read_b128 v[234:237], v181 offset:21504
	ds_read_b128 v[238:241], v181 offset:22528
	ds_read_b128 v[242:245], v181 offset:23552
	global_load_lds_dwordx4 v[168:169], off
	s_add_i32 m0, s0, 0x2000
	s_add_u32 s0, s36, 0x80000
	v_lshl_add_u64 v[172:173], s[36:37], 0, v[152:153]
	s_addc_u32 s1, s37, 0
	s_add_i32 s2, s29, s49
	global_load_lds_dwordx4 v[172:173], off
	v_lshl_add_u64 v[202:203], s[0:1], 0, v[156:157]
	s_mov_b32 m0, s2
	v_lshl_add_u64 v[212:213], s[44:45], 0, v[154:155]
	global_load_lds_dwordx4 v[202:203], off
	v_lshl_add_u64 v[202:203], s[0:1], 0, v[152:153]
	s_add_i32 m0, s2, 0x2000
	s_nop 0
	global_load_lds_dwordx4 v[202:203], off
	v_lshl_add_u64 v[202:203], s[44:45], 0, v[158:159]
	s_mov_b32 m0, s50
	s_nop 0
	global_load_lds_dwordx4 v[202:203], off
	s_mov_b32 m0, s51
	s_nop 0
	global_load_lds_dwordx4 v[212:213], off
	s_waitcnt vmcnt(8)
	s_waitcnt lgkmcnt(0)
	s_setprio 1
	s_barrier
; #define PG8_STAGE(bufoff, gbase, voff) do { _Pragma("unroll") for (int _i = 0; _i < 2; ++_i) \
;         __builtin_amdgcn_global_load_lds((const unsigned*)((const char*)(gbase) + (voff)[_i]), (PG8_LAS unsigned*)(lds + (bufoff) + ldsw + _i * 8192), 16, 0, AUX_A); } while (0)
; #define PG8_STAGEB(bufoff, gbase, voff) do { _Pragma("unroll") for (int _i = 0; _i < 2; ++_i) \
;         __builtin_amdgcn_global_load_lds((const unsigned*)((const char*)(gbase) + (voff)[_i]), (PG8_LAS unsigned*)(lds + (bufoff) + ldsw + _i * 8192), 16, 0, AUX_B); } while (0)
; #define PG8_LDA(dst, b, h) do { _Pragma("unroll") for (int m = 0; m < 4; ++m) _Pragma("unroll") for (int k = 0; k < 2; ++k) dst[m][k] = *(const PG8_LAS bf16x8*)(lds + PG8_SA(b, h) + aoff + m * 2048 + k * 1024); } while (0)
; #define PG8_LDB(dst, b, h) do { _Pragma("unroll") for (int n = 0; n < 2; ++n) _Pragma("unroll") for (int k = 0; k < 2; ++k) dst[n][k] = *(const PG8_LAS bf16x8*)(lds + PG8_SB(b, h) + boff + n * 2048 + k * 1024); } while (0)
; #define PG8_MMA(ai, bj, At, Bt) do { __builtin_amdgcn_s_setprio(1); _Pragma("unroll") for (int m = 0; m < 4; ++m) _Pragma("unroll") for (int n = 0; n < 2; ++n) _Pragma("unroll") for (int k = 0; k < 2; ++k) \
;         acc[ai][bj][m][n] = __builtin_amdgcn_mfma_f32_16x16x32_bf16(Bt[n][k], At[m][k], acc[ai][bj][m][n], 0, 0, 0); __builtin_amdgcn_s_setprio(0); } while (0)
; #define PG8_WAIT_V(n) asm volatile("s_waitcnt vmcnt(" #n ")" ::: "memory")
; #define PG8_WAIT_L(n) asm volatile("s_waitcnt lgkmcnt(" #n ")" ::: "memory")
; template <class Epi, class Sched, bool ALIGN_EPI = false, bool SP2 = false>
; __device__ __forceinline__ void gemm_phase(PG8_LAS unsigned char* lds, const Gemm g, const Sched& S, const Epi& E) {
;     ...
;             PG8_WAIT_V(8); PG8_WAIT_L(0); PG8_BAR; PG8_MMA(0, 0, At, B0); PG8_MMA(0, 1, At, B1); PG8_BAR; PG8_SCHED;
;             PG8_LDA(At, 0, 1); PG8_STAGEB(PG8_SB(0, 0), b2, voffB); PG8_STAGEB(PG8_SB(0, 1), b2 + hstep, voffB); PG8_STAGE(PG8_SA(0, 0), a2, voffA);
;             PG8_WAIT_V(8); PG8_WAIT_L(0); PG8_BAR; PG8_MMA(1, 0, At, B0); PG8_MMA(1, 1, At, B1); PG8_BAR; PG8_SCHED;
;             PG8_LDB(B0, 1, 0); PG8_LDB(B1, 1, 1); PG8_SCHED; PG8_LDA(At, 1, 0); PG8_STAGE(PG8_SA(0, 1), a2 + hstep, voffA);
;             PG8_WAIT_V(8); PG8_WAIT_L(0); PG8_BAR; PG8_MMA(0, 0, At, B0); PG8_MMA(0, 1, At, B1); PG8_BAR; PG8_SCHED;
	v_mfma_f32_16x16x32_bf16 v[62:65], v[136:139], v[194:197], 0
	v_mfma_f32_16x16x32_bf16 v[62:65], v[140:143], v[198:201], v[62:65]
	v_mfma_f32_16x16x32_bf16 v[58:61], v[144:147], v[194:197], 0
	v_mfma_f32_16x16x32_bf16 v[58:61], v[148:151], v[198:201], v[58:61]
	v_mfma_f32_16x16x32_bf16 v[54:57], v[136:139], v[222:225], 0
	v_mfma_f32_16x16x32_bf16 v[54:57], v[140:143], v[226:229], v[54:57]
	v_mfma_f32_16x16x32_bf16 v[46:49], v[144:147], v[222:225], 0
	v_mfma_f32_16x16x32_bf16 v[46:49], v[148:151], v[226:229], v[46:49]
	v_mfma_f32_16x16x32_bf16 v[38:41], v[136:139], v[230:233], 0
	v_mfma_f32_16x16x32_bf16 v[38:41], v[140:143], v[234:237], v[38:41]
	v_mfma_f32_16x16x32_bf16 v[30:33], v[144:147], v[230:233], 0
	v_mfma_f32_16x16x32_bf16 v[30:33], v[148:151], v[234:237], v[30:33]
	v_mfma_f32_16x16x32_bf16 v[22:25], v[136:139], v[238:241], 0
	v_mfma_f32_16x16x32_bf16 v[22:25], v[140:143], v[242:245], v[22:25]
	v_mfma_f32_16x16x32_bf16 v[14:17], v[144:147], v[238:241], 0
	v_mfma_f32_16x16x32_bf16 v[14:17], v[148:151], v[242:245], v[14:17]
	s_setprio 0
	s_setprio 1
	v_mfma_f32_16x16x32_bf16 v[50:53], v[164:167], v[194:197], 0
	v_mfma_f32_16x16x32_bf16 v[50:53], v[182:185], v[198:201], v[50:53]
	v_mfma_f32_16x16x32_bf16 v[42:45], v[186:189], v[194:197], 0
	v_mfma_f32_16x16x32_bf16 v[42:45], v[190:193], v[198:201], v[42:45]
	v_mfma_f32_16x16x32_bf16 v[34:37], v[164:167], v[222:225], 0
	v_mfma_f32_16x16x32_bf16 v[34:37], v[182:185], v[226:229], v[34:37]
	v_mfma_f32_16x16x32_bf16 v[26:29], v[186:189], v[222:225], 0
	v_mfma_f32_16x16x32_bf16 v[26:29], v[190:193], v[226:229], v[26:29]
	v_mfma_f32_16x16x32_bf16 v[18:21], v[164:167], v[230:233], 0
	v_mfma_f32_16x16x32_bf16 v[18:21], v[182:185], v[234:237], v[18:21]
	v_mfma_f32_16x16x32_bf16 v[10:13], v[186:189], v[230:233], 0
	v_mfma_f32_16x16x32_bf16 v[10:13], v[190:193], v[234:237], v[10:13]
	v_mfma_f32_16x16x32_bf16 v[6:9], v[164:167], v[238:241], 0
	v_mfma_f32_16x16x32_bf16 v[6:9], v[182:185], v[242:245], v[6:9]
	s_setprio 2
	s_barrier
	v_mfma_f32_16x16x32_bf16 v[2:5], v[186:189], v[238:241], 0
	v_mfma_f32_16x16x32_bf16 v[2:5], v[190:193], v[242:245], v[2:5]
	s_setprio 0
	s_add_i32 s2, 0, 0x18000
	s_add_i32 s15, 0, 0x1c000
	v_add_u32_e32 v148, s2, v99
	v_add_u32_e32 v190, s15, v99
	ds_read_b128 v[136:139], v148
	ds_read_b128 v[140:143], v148 offset:1024
	ds_read_b128 v[144:147], v148 offset:2048
	ds_read_b128 v[148:151], v148 offset:3072
	ds_read_b128 v[164:167], v190
	ds_read_b128 v[182:185], v190 offset:1024
	ds_read_b128 v[186:189], v190 offset:2048
	ds_read_b128 v[190:193], v190 offset:3072
	s_add_u32 s0, s44, 0x80000
	s_addc_u32 s1, s45, 0
	s_mov_b32 m0, s52
	v_lshl_add_u64 v[246:247], s[0:1], 0, v[158:159]
	ds_read_b128 v[194:197], v181 offset:32768
	ds_read_b128 v[198:201], v181 offset:33792
	ds_read_b128 v[222:225], v181 offset:34816
	ds_read_b128 v[226:229], v181 offset:35840
	ds_read_b128 v[230:233], v181 offset:36864
	ds_read_b128 v[234:237], v181 offset:37888
	ds_read_b128 v[238:241], v181 offset:38912
	ds_read_b128 v[242:245], v181 offset:39936
	global_load_lds_dwordx4 v[246:247], off
	v_lshl_add_u64 v[246:247], s[0:1], 0, v[154:155]
	s_mov_b32 m0, s53
	s_nop 0
	global_load_lds_dwordx4 v[246:247], off
	s_waitcnt vmcnt(8)
	s_waitcnt lgkmcnt(0)
	s_setprio 1
	s_barrier
	v_mfma_f32_16x16x32_bf16 v[128:131], v[136:139], v[194:197], v[128:131]
	v_mfma_f32_16x16x32_bf16 v[128:131], v[140:143], v[198:201], v[128:131]
	v_mfma_f32_16x16x32_bf16 v[124:127], v[144:147], v[194:197], v[124:127]
	v_mfma_f32_16x16x32_bf16 v[124:127], v[148:151], v[198:201], v[124:127]
	v_mfma_f32_16x16x32_bf16 v[120:123], v[136:139], v[222:225], v[120:123]
	v_mfma_f32_16x16x32_bf16 v[120:123], v[140:143], v[226:229], v[120:123]
	v_mfma_f32_16x16x32_bf16 v[112:115], v[144:147], v[222:225], v[112:115]
	v_mfma_f32_16x16x32_bf16 v[112:115], v[148:151], v[226:229], v[112:115]
	v_mfma_f32_16x16x32_bf16 v[104:107], v[136:139], v[230:233], v[104:107]
	v_mfma_f32_16x16x32_bf16 v[104:107], v[140:143], v[234:237], v[104:107]
	v_mfma_f32_16x16x32_bf16 v[94:97], v[144:147], v[230:233], v[94:97]
	v_mfma_f32_16x16x32_bf16 v[94:97], v[148:151], v[234:237], v[94:97]
	v_mfma_f32_16x16x32_bf16 v[86:89], v[136:139], v[238:241], v[86:89]
	v_mfma_f32_16x16x32_bf16 v[86:89], v[140:143], v[242:245], v[86:89]
	v_mfma_f32_16x16x32_bf16 v[78:81], v[144:147], v[238:241], v[78:81]
	v_mfma_f32_16x16x32_bf16 v[78:81], v[148:151], v[242:245], v[78:81]
	s_setprio 0
	s_setprio 1
	v_mfma_f32_16x16x32_bf16 v[116:119], v[164:167], v[194:197], v[116:119]
	v_mfma_f32_16x16x32_bf16 v[116:119], v[182:185], v[198:201], v[116:119]
	v_mfma_f32_16x16x32_bf16 v[108:111], v[186:189], v[194:197], v[108:111]
	v_mfma_f32_16x16x32_bf16 v[108:111], v[190:193], v[198:201], v[108:111]
	v_mfma_f32_16x16x32_bf16 v[100:103], v[164:167], v[222:225], v[100:103]
	v_mfma_f32_16x16x32_bf16 v[100:103], v[182:185], v[226:229], v[100:103]
	v_mfma_f32_16x16x32_bf16 v[90:93], v[186:189], v[222:225], v[90:93]
	v_mfma_f32_16x16x32_bf16 v[90:93], v[190:193], v[226:229], v[90:93]
	v_mfma_f32_16x16x32_bf16 v[82:85], v[164:167], v[230:233], v[82:85]
	v_mfma_f32_16x16x32_bf16 v[82:85], v[182:185], v[234:237], v[82:85]
	v_mfma_f32_16x16x32_bf16 v[74:77], v[186:189], v[230:233], v[74:77]
	v_mfma_f32_16x16x32_bf16 v[74:77], v[190:193], v[234:237], v[74:77]
	v_mfma_f32_16x16x32_bf16 v[70:73], v[164:167], v[238:241], v[70:73]
	v_mfma_f32_16x16x32_bf16 v[70:73], v[182:185], v[242:245], v[70:73]
	s_setprio 2
	s_barrier
; #define PG8_STAGE(bufoff, gbase, voff) do { _Pragma("unroll") for (int _i = 0; _i < 2; ++_i) \
;         __builtin_amdgcn_global_load_lds((const unsigned*)((const char*)(gbase) + (voff)[_i]), (PG8_LAS unsigned*)(lds + (bufoff) + ldsw + _i * 8192), 16, 0, AUX_A); } while (0)
; #define PG8_STAGEB(bufoff, gbase, voff) do { _Pragma("unroll") for (int _i = 0; _i < 2; ++_i) \
;         __builtin_amdgcn_global_load_lds((const unsigned*)((const char*)(gbase) + (voff)[_i]), (PG8_LAS unsigned*)(lds + (bufoff) + ldsw + _i * 8192), 16, 0, AUX_B); } while (0)
; #define PG8_LDA(dst, b, h) do { _Pragma("unroll") for (int m = 0; m < 4; ++m) _Pragma("unroll") for (int k = 0; k < 2; ++k) dst[m][k] = *(const PG8_LAS bf16x8*)(lds + PG8_SA(b, h) + aoff + m * 2048 + k * 1024); } while (0)
; #define PG8_LDB(dst, b, h) do { _Pragma("unroll") for (int n = 0; n < 2; ++n) _Pragma("unroll") for (int k = 0; k < 2; ++k) dst[n][k] = *(const PG8_LAS bf16x8*)(lds + PG8_SB(b, h) + boff + n * 2048 + k * 1024); } while (0)
; #define PG8_MMA(ai, bj, At, Bt) do { __builtin_amdgcn_s_setprio(1); _Pragma("unroll") for (int m = 0; m < 4; ++m) _Pragma("unroll") for (int n = 0; n < 2; ++n) _Pragma("unroll") for (int k = 0; k < 2; ++k) \
;         acc[ai][bj][m][n] = __builtin_amdgcn_mfma_f32_16x16x32_bf16(Bt[n][k], At[m][k], acc[ai][bj][m][n], 0, 0, 0); __builtin_amdgcn_s_setprio(0); } while (0)
; #define PG8_WAIT_V(n) asm volatile("s_waitcnt vmcnt(" #n ")" ::: "memory")
; #define PG8_WAIT_L(n) asm volatile("s_waitcnt lgkmcnt(" #n ")" ::: "memory")
; #define PG8_BAR __builtin_amdgcn_s_barrier()
; #define PG8_SCHED __builtin_amdgcn_sched_barrier(0)
; template <class Epi, class Sched, bool ALIGN_EPI = false, bool SP2 = false>
; __device__ __forceinline__ void gemm_phase(PG8_LAS unsigned char* lds, const Gemm g, const Sched& S, const Epi& E) {
;     ...
;         for (int t = 0; t < nt; t += 2) {
;     ...
;             PG8_LDB(B0, 1, 0); PG8_LDB(B1, 1, 1); PG8_SCHED; PG8_LDA(At, 1, 0); PG8_STAGE(PG8_SA(0, 1), a2 + hstep, voffA);
;             PG8_WAIT_V(8); PG8_WAIT_L(0); PG8_BAR; PG8_MMA(0, 0, At, B0); PG8_MMA(0, 1, At, B1); PG8_BAR; PG8_SCHED;
;             PG8_LDA(At, 1, 1); PG8_STAGEB(PG8_SB(1, 0), b3, voffB); PG8_STAGEB(PG8_SB(1, 1), b3 + hstep, voffB); PG8_STAGE(PG8_SA(1, 0), a3, voffA);
;             PG8_WAIT_V(8); PG8_WAIT_L(0); PG8_BAR; PG8_MMA(1, 0, At, B0); PG8_MMA(1, 1, At, B1); PG8_BAR; PG8_SCHED;
	v_mfma_f32_16x16x32_bf16 v[66:69], v[186:189], v[238:241], v[66:69]
	v_mfma_f32_16x16x32_bf16 v[66:69], v[190:193], v[242:245], v[66:69]
	s_setprio 0
	s_add_i32 s0, s2, s49
	v_lshl_add_u64 v[168:169], v[168:169], 0, s[76:77]
	s_mov_b32 m0, s0
	ds_read_b128 v[194:197], v181 offset:49152
	ds_read_b128 v[198:201], v181 offset:50176
	ds_read_b128 v[222:225], v181 offset:51200
	ds_read_b128 v[226:229], v181 offset:52224
	ds_read_b128 v[230:233], v181 offset:53248
	ds_read_b128 v[234:237], v181 offset:54272
	ds_read_b128 v[238:241], v181 offset:55296
	ds_read_b128 v[242:245], v181 offset:56320
	global_load_lds_dwordx4 v[168:169], off
	s_add_i32 m0, s0, 0x2000
	s_add_u32 s0, s36, 0x80080
	v_lshl_add_u64 v[168:169], v[172:173], 0, s[76:77]
	s_addc_u32 s1, s37, 0
	s_add_i32 s2, s15, s49
	global_load_lds_dwordx4 v[168:169], off
	v_lshl_add_u64 v[168:169], s[0:1], 0, v[156:157]
	s_mov_b32 m0, s2
	s_nop 0
	global_load_lds_dwordx4 v[168:169], off
	v_lshl_add_u64 v[168:169], s[0:1], 0, v[152:153]
	s_add_i32 m0, s2, 0x2000
	s_nop 0
	global_load_lds_dwordx4 v[168:169], off
	v_lshl_add_u64 v[168:169], v[202:203], 0, s[76:77]
	s_mov_b32 m0, s59
	s_nop 0
	global_load_lds_dwordx4 v[168:169], off
	v_lshl_add_u64 v[168:169], v[212:213], 0, s[76:77]
	s_mov_b32 m0, s60
	s_nop 0
	global_load_lds_dwordx4 v[168:169], off
	s_waitcnt vmcnt(8)
	s_waitcnt lgkmcnt(0)
	s_setprio 1
	s_barrier
	v_mfma_f32_16x16x32_bf16 v[62:65], v[136:139], v[194:197], v[62:65]
	v_mfma_f32_16x16x32_bf16 v[62:65], v[140:143], v[198:201], v[62:65]
	v_mfma_f32_16x16x32_bf16 v[58:61], v[144:147], v[194:197], v[58:61]
	v_mfma_f32_16x16x32_bf16 v[58:61], v[148:151], v[198:201], v[58:61]
	v_mfma_f32_16x16x32_bf16 v[54:57], v[136:139], v[222:225], v[54:57]
	v_mfma_f32_16x16x32_bf16 v[54:57], v[140:143], v[226:229], v[54:57]
	v_mfma_f32_16x16x32_bf16 v[46:49], v[144:147], v[222:225], v[46:49]
	v_mfma_f32_16x16x32_bf16 v[46:49], v[148:151], v[226:229], v[46:49]
	v_mfma_f32_16x16x32_bf16 v[38:41], v[136:139], v[230:233], v[38:41]
	v_mfma_f32_16x16x32_bf16 v[38:41], v[140:143], v[234:237], v[38:41]
	v_mfma_f32_16x16x32_bf16 v[30:33], v[144:147], v[230:233], v[30:33]
	v_mfma_f32_16x16x32_bf16 v[30:33], v[148:151], v[234:237], v[30:33]
	v_mfma_f32_16x16x32_bf16 v[22:25], v[136:139], v[238:241], v[22:25]
	v_mfma_f32_16x16x32_bf16 v[22:25], v[140:143], v[242:245], v[22:25]
	v_mfma_f32_16x16x32_bf16 v[14:17], v[144:147], v[238:241], v[14:17]
	v_mfma_f32_16x16x32_bf16 v[14:17], v[148:151], v[242:245], v[14:17]
	s_setprio 0
	s_setprio 1
	v_mfma_f32_16x16x32_bf16 v[50:53], v[164:167], v[194:197], v[50:53]
	v_mfma_f32_16x16x32_bf16 v[50:53], v[182:185], v[198:201], v[50:53]
	v_mfma_f32_16x16x32_bf16 v[42:45], v[186:189], v[194:197], v[42:45]
	v_mfma_f32_16x16x32_bf16 v[42:45], v[190:193], v[198:201], v[42:45]
	v_mfma_f32_16x16x32_bf16 v[34:37], v[164:167], v[222:225], v[34:37]
	v_mfma_f32_16x16x32_bf16 v[34:37], v[182:185], v[226:229], v[34:37]
	v_mfma_f32_16x16x32_bf16 v[26:29], v[186:189], v[222:225], v[26:29]
	v_mfma_f32_16x16x32_bf16 v[26:29], v[190:193], v[226:229], v[26:29]
	v_mfma_f32_16x16x32_bf16 v[18:21], v[164:167], v[230:233], v[18:21]
	v_mfma_f32_16x16x32_bf16 v[18:21], v[182:185], v[234:237], v[18:21]
	v_mfma_f32_16x16x32_bf16 v[10:13], v[186:189], v[230:233], v[10:13]
	v_mfma_f32_16x16x32_bf16 v[10:13], v[190:193], v[234:237], v[10:13]
	v_mfma_f32_16x16x32_bf16 v[6:9], v[164:167], v[238:241], v[6:9]
	v_mfma_f32_16x16x32_bf16 v[6:9], v[182:185], v[242:245], v[6:9]
	s_setprio 2
	s_barrier
	v_mfma_f32_16x16x32_bf16 v[2:5], v[186:189], v[238:241], v[2:5]
	v_mfma_f32_16x16x32_bf16 v[2:5], v[190:193], v[242:245], v[2:5]
	s_setprio 0
	s_add_i32 s0, s13, 2
	v_lshl_add_u64 v[132:133], v[132:133], 0, s[86:87]
	v_lshl_add_u64 v[134:135], v[134:135], 0, s[86:87]
	s_cmp_ge_i32 s13, s71
	s_mov_b32 s13, s0
	s_cbranch_scc1 .Lpx_1308

; #define PG8_STAGE(bufoff, gbase, voff) do { _Pragma("unroll") for (int _i = 0; _i < 2; ++_i) \
;         __builtin_amdgcn_global_load_lds((const unsigned*)((const char*)(gbase) + (voff)[_i]), (PG8_LAS unsigned*)(lds + (bufoff) + ldsw + _i * 8192), 16, 0, AUX_A); } while (0)
; #define PG8_WAIT_V(n) asm volatile("s_waitcnt vmcnt(" #n ")" ::: "memory")
; template <class Epi, class Sched, bool ALIGN_EPI = false, bool SP2 = false>
; __device__ __forceinline__ void gemm_phase(PG8_LAS unsigned char* lds, const Gemm g, const Sched& S, const Epi& E) {
;     ...
;     const int tid = tid_l, wid = __builtin_amdgcn_readfirstlane(tid >> 6), lane = tid & 63, wr = wid >> 2, wc = wid & 3, fr = lane & 15, fq = lane >> 4;
;     const int K = g.K;
;     unsigned voffA[2], voffB[2];
; #pragma unroll
;     for (int i = 0; i < 2; ++i) { int R, C; stage_rc(tid * 16 + i * 8192, R, C); const int Rb = Epi::PERM ? ((R & ~31) + perm32(R & 31)) : R;
;         voffA[i] = (unsigned)(R * K + C) * 2u; voffB[i] = (unsigned)(Rb * K + C) * 2u; }
;     const size_t kstep = (size_t)(BK * 2);
;     const size_t hstep = (size_t)HALF * K * 2;
;     const size_t tstep = 2 * hstep;
;     const unsigned ldsw = (unsigned)wid * 1024u;
;     const int aoff = lds_byte(wr * 64 + fr, fq * 8), boff = lds_byte(wc * 32 + fr, fq * 8);
;     ...
;     { const int rot0 = cur.krot, nt0 = cur.nkt; const char* sA0 = PG8_KP(cA, 0, rot0, nt0); const char* sA1 = PG8_KP(cA, 1, rot0, nt0); const char* sB0 = PG8_KP(cB, 0, rot0, nt0); const char* sB1 = PG8_KP(cB, 1, rot0, nt0);
;     if constexpr (SP2) {
;         PG8_STAGEB(PG8_SB(0, 0), sB0, voffB); PG8_STAGEB(PG8_SB(0, 1), sB0 + hstep, voffB); PG8_STAGE(PG8_SA(0, 0), sA0, voffA); PG8_STAGE(PG8_SA(0, 1), sA0 + hstep, voffA);
;         if (wr == 1) PG8_BAR;
;         PG8_WAIT_V(2); PG8_BAR;
;         PG8_STAGEB(PG8_SB(1, 0), sB1, voffB); PG8_STAGE(PG8_SA(1, 0), sA1, voffA); PG8_STAGEB(PG8_SB(1, 1), sB1 + hstep, voffB);
;         PG8_WAIT_V(6); PG8_BAR;
;     } else {
;         PG8_STAGEB(PG8_SB(0, 0), sB0, voffB); PG8_STAGE(PG8_SA(0, 0), sA0, voffA); PG8_STAGEB(PG8_SB(0, 1), sB0 + hstep, voffB); PG8_STAGE(PG8_SA(0, 1), sA0 + hstep, voffA);
;         if (wr == 1) PG8_BAR;
;         PG8_WAIT_V(4); PG8_BAR;
;         PG8_STAGEB(PG8_SB(1, 0), sB1, voffB); PG8_STAGE(PG8_SA(1, 0), sA1, voffA); PG8_STAGEB(PG8_SB(1, 1), sB1 + hstep, voffB);
;         PG8_WAIT_V(6); PG8_BAR;
;     }
.LBB0_1448:
	s_andn2_b64 vcc, exec, s[4:5]
	s_cbranch_vccnz .LBB0_1637
	v_readlane_b32 s0, v254, 53
	v_readlane_b32 s1, v254, 54
	s_mul_i32 s33, s0, 0x2c00000
	s_mov_b64 s[4:5], s[66:67]
	v_readlane_b32 s0, v252, 28
	s_add_u32 s89, s4, 0xc000000
	v_mov_b32_e32 v16, v0
	v_readlane_b32 s1, v252, 29
	s_addc_u32 s96, s5, 0
	s_andn2_b64 vcc, exec, s[0:1]
	v_readfirstlane_b32 s10, v16
	s_cbranch_vccnz .LBB0_1465
	v_lshlrev_b32_e32 v1, 4, v16
	v_add_u32_e32 v2, 0x2000, v1
	v_ashrrev_i32_e32 v3, 31, v2
	v_lshrrev_b32_e32 v3, 22, v3
	v_add_u32_e32 v3, v2, v3
	v_ashrrev_i32_e32 v10, 10, v3
	v_mul_i32_i24_e32 v3, 0x400, v10
	v_sub_u32_e32 v2, v2, v3
	v_lshrrev_b32_e32 v3, 4, v2
	v_bitop3_b32 v2, v3, v2, 32 bitop3:0x6c
	v_ashrrev_i32_e32 v3, 31, v2
	v_lshrrev_b32_e32 v3, 26, v3
	v_add_u32_e32 v3, v2, v3
	v_lshlrev_b32_e32 v4, 3, v10
	v_ashrrev_i32_e32 v11, 6, v3
	v_and_b32_e32 v4, -16, v4
	v_add_u32_e32 v4, v11, v4
	v_and_b32_e32 v5, 3, v11
	s_mov_b32 s2, 0xfffe0
	v_lshrrev_b32_e32 v6, 2, v4
	v_lshlrev_b32_e32 v7, 1, v4
	v_and_b32_e32 v3, 0xc0, v3
	v_and_or_b32 v5, v4, s2, v5
	v_and_b32_e32 v6, 4, v6
	v_and_b32_e32 v7, 24, v7
	v_sub_u32_e32 v2, v2, v3
	v_or3_b32 v5, v5, v6, v7
	v_lshlrev_b32_e32 v6, 5, v10
	v_ashrrev_i16_sdwa v2, v207, sext(v2) dst_sel:DWORD dst_unused:UNUSED_PAD src0_sel:DWORD src1_sel:BYTE_0
	v_and_b32_e32 v6, 32, v6
	v_bfe_i32 v12, v2, 0, 16
	v_add_lshl_u32 v2, v6, v12, 1
	s_waitcnt vmcnt(0)
	v_lshl_add_u32 v132, v5, 12, v2
	v_lshl_add_u32 v134, v4, 12, v2
	v_bfe_i32 v2, v16, 27, 1
	v_lshrrev_b32_e32 v2, 22, v2
	v_add_u32_e32 v2, v1, v2
	v_and_b32_e32 v2, 0xfffffc00, v2
	v_sub_u32_e32 v1, v1, v2
	v_lshrrev_b32_e32 v2, 4, v1
	v_ashrrev_i32_e32 v3, 31, v16
	v_bitop3_b32 v1, v2, v1, 32 bitop3:0x6c
	v_lshrrev_b32_e32 v3, 26, v3
	v_ashrrev_i32_e32 v2, 31, v1
	v_add_u32_e32 v3, v16, v3
	v_lshrrev_b32_e32 v2, 26, v2
	v_ashrrev_i32_e32 v14, 6, v3
	v_add_u32_e32 v2, v1, v2
	v_lshlrev_b32_e32 v3, 3, v14
	s_add_u32 s52, s4, 0x1c800000
	v_ashrrev_i32_e32 v13, 6, v2
	v_and_b32_e32 v3, -16, v3
	s_addc_u32 s53, s5, 0
	v_add_u32_e32 v3, v13, v3
	s_add_u32 s54, s89, s33
	v_and_b32_e32 v4, 3, v13
	v_lshrrev_b32_e32 v5, 2, v3
	v_lshlrev_b32_e32 v6, 1, v3
	v_and_b32_e32 v2, 0xc0, v2
	s_addc_u32 s55, s96, 0
	s_ashr_i32 s0, s10, 6
	v_and_or_b32 v4, v3, s2, v4
	v_and_b32_e32 v5, 4, v5
	v_and_b32_e32 v6, 24, v6
	v_sub_u32_e32 v1, v1, v2
	s_ashr_i32 s1, s10, 8
	s_lshl_b32 s56, s0, 10
	v_or3_b32 v4, v4, v5, v6
	v_lshlrev_b32_e32 v5, 5, v14
	v_ashrrev_i16_sdwa v1, v207, sext(v1) dst_sel:DWORD dst_unused:UNUSED_PAD src0_sel:DWORD src1_sel:BYTE_0
	v_readlane_b32 s2, v252, 35
	v_and_b32_e32 v5, 32, v5
	v_bfe_i32 v15, v1, 0, 16
	v_readlane_b32 s3, v252, 36
	s_add_u32 s34, s54, s2
	v_add_lshl_u32 v1, v5, v15, 1
	s_addc_u32 s35, s55, s3
	s_add_i32 s57, s56, 0
	v_lshl_add_u32 v136, v4, 12, v1
	s_add_i32 m0, s57, 0x10000
	v_readlane_b32 s2, v252, 39
	global_load_lds_dwordx4 v136, s[34:35]
	s_add_i32 m0, s57, 0x12000
	v_readlane_b32 s3, v252, 40
	s_add_u32 s40, s52, s2
	s_addc_u32 s41, s53, s3
	s_add_u32 s6, s34, 0x80000
	global_load_lds_dwordx4 v132, s[34:35]
	s_addc_u32 s7, s35, 0
	s_add_i32 m0, s57, 0x14000
	s_add_i32 s58, s57, 0x2000
	global_load_lds_dwordx4 v136, s[6:7]
	s_add_i32 m0, s57, 0x16000
	v_lshl_add_u32 v138, v3, 12, v1
	global_load_lds_dwordx4 v132, s[6:7]
	s_mov_b32 m0, s57
	s_add_u32 s6, s40, 0x80000
	global_load_lds_dwordx4 v138, s[40:41]
	s_mov_b32 m0, s58
	s_addc_u32 s7, s41, 0
	s_add_i32 s59, s57, 0x4000
	global_load_lds_dwordx4 v134, s[40:41]
	s_mov_b32 m0, s59
	s_add_i32 s60, s57, 0x6000
	global_load_lds_dwordx4 v138, s[6:7]
	s_mov_b32 m0, s60
	v_mov_b32_e32 v137, v98
	global_load_lds_dwordx4 v134, s[6:7]
	v_mov_b32_e32 v133, v98
	v_mov_b32_e32 v139, v98
	v_mov_b32_e32 v135, v98
	s_cmp_eq_u32 s1, 1
	v_lshl_add_u64 v[8:9], s[34:35], 0, v[136:137]
	v_lshl_add_u64 v[6:7], s[34:35], 0, v[132:133]
	v_lshl_add_u64 v[2:3], s[40:41], 0, v[138:139]
	s_cselect_b64 s[6:7], -1, 0
	s_cmp_lg_u32 s1, 1
	v_lshl_add_u64 v[4:5], s[40:41], 0, v[134:135]
	s_cbranch_scc1 .LBB0_1452
.LBB0_1452:
	s_add_u32 s8, s4, 0x2f580000
	v_lshrrev_b32_e32 v18, 1, v16
	s_addc_u32 s9, s5, 0
	v_and_b32_e32 v18, 24, v18
	s_lshl_b32 s0, s0, 5
	v_and_b32_e32 v17, 15, v16
	v_lshlrev_b32_e32 v19, 1, v18
	v_lshlrev_b32_e32 v16, 2, v16
	s_and_b32 s2, s0, 0x60
	s_add_i32 m0, s57, 0x18000
	v_lshl_add_u64 v[8:9], v[8:9], 0, s[76:77]
	v_lshl_or_b32 v1, s1, 6, v17
	v_lshl_or_b32 v17, v17, 6, v19
	s_lshl_b32 s1, s1, 13
	v_and_b32_e32 v16, 32, v16
	s_lshl_b32 s0, s2, 7
	global_load_lds_dwordx4 v[8:9], off
	v_lshl_add_u64 v[6:7], v[6:7], 0, s[76:77]
	s_add_i32 m0, s57, 0x1a000
	s_add_i32 s61, s57, 0x8000
	s_add_i32 s62, s57, 0xa000
	v_bitop3_b32 v99, v17, s0, v16 bitop3:0xde
	global_load_lds_dwordx4 v[6:7], off
	s_add_u32 s0, s34, 0x80080
	v_bitop3_b32 v19, v17, s1, v16 bitop3:0xde
	s_addc_u32 s1, s35, 0
	s_add_i32 m0, s57, 0x1c000
	v_lshl_add_u64 v[2:3], s[0:1], 0, v[136:137]
	global_load_lds_dwordx4 v[2:3], off
	v_lshl_add_u64 v[2:3], s[0:1], 0, v[132:133]
	s_add_i32 m0, s57, 0x1e000
	s_cmpk_lt_u32 s10, 0x100
	global_load_lds_dwordx4 v[2:3], off
	s_waitcnt vmcnt(6)
	s_barrier
	v_lshlrev_b32_e32 v2, 15, v10
	v_and_b32_e32 v2, 0xffff0000, v2
	v_lshl_add_u32 v2, v11, 12, v2
	v_and_b32_e32 v3, 1, v10
	v_lshl_or_b32 v2, v3, 6, v2
	v_lshl_add_u32 v140, v12, 1, v2
	v_lshlrev_b32_e32 v2, 15, v14
	v_and_b32_e32 v2, 0xffff0000, v2
	s_waitcnt vmcnt(4)
	v_lshl_add_u32 v2, v13, 12, v2
	v_and_b32_e32 v3, 1, v14
	v_lshl_or_b32 v2, v3, 6, v2
	v_readlane_b32 s0, v252, 37
	s_cselect_b64 s[10:11], -1, 0
	v_or_b32_e32 v148, s2, v18
	v_mov_b32_e32 v141, v98
	v_lshl_add_u32 v142, v15, 1, v2
	v_mov_b32_e32 v143, v98
	s_mov_b32 s63, 0
	v_add_u32_e32 v149, 0, v19
	v_readlane_b32 s69, v253, 6
	s_mov_b32 s70, s0
	s_movk_i32 s3, 0xc7
	s_mov_b32 s64, 0x58000
	s_mov_b32 s65, 0x2c000
	s_mov_b32 s66, 0x84000
	s_barrier
	v_readlane_b32 s1, v252, 38
	s_branch .LBB0_1455

; #define PG8_STAGE(bufoff, gbase, voff) do { _Pragma("unroll") for (int _i = 0; _i < 2; ++_i) \
;         __builtin_amdgcn_global_load_lds((const unsigned*)((const char*)(gbase) + (voff)[_i]), (PG8_LAS unsigned*)(lds + (bufoff) + ldsw + _i * 8192), 16, 0, AUX_A); } while (0)
; #define PG8_STAGEB(bufoff, gbase, voff) do { _Pragma("unroll") for (int _i = 0; _i < 2; ++_i) \
;         __builtin_amdgcn_global_load_lds((const unsigned*)((const char*)(gbase) + (voff)[_i]), (PG8_LAS unsigned*)(lds + (bufoff) + ldsw + _i * 8192), 16, 0, AUX_B); } while (0)
; #define PG8_WAIT_V(n) asm volatile("s_waitcnt vmcnt(" #n ")" ::: "memory")
; #define PG8_WAIT_L(n) asm volatile("s_waitcnt lgkmcnt(" #n ")" ::: "memory")
; template <class Epi, class Sched, bool ALIGN_EPI = false, bool SP2 = false>
; __device__ __forceinline__ void gemm_phase(PG8_LAS unsigned char* lds, const Gemm g, const Sched& S, const Epi& E) {
;     ...
;         const bool has_next = S.next(ui + 1, nxt);
;         const char* nA = has_next ? (const char*)g.A + (size_t)nxt.pm * tstep + (size_t)nxt.kt0 * kstep : cA; const char* nB = has_next ? (const char*)g.Bt + (size_t)nxt.pn * tstep + (size_t)nxt.kt0 * kstep : cB;
;         const int nt = cur.nkt, rot = cur.krot;
;         const char* nAr = has_next ? nA + (size_t)nxt.krot * kstep : PG8_KP(cA, 0, rot, nt); const char* nBr = has_next ? nB + (size_t)nxt.krot * kstep : PG8_KP(cB, 0, rot, nt);
;         for (int t = 0; t < nt; t += 2) {
;             const bool last = (t == nt - 2);
;             const char* a1 = PG8_KP(cA, t + 1, rot, nt);
;             const char* a2 = last ? nAr : PG8_KP(cA, t + 2, rot, nt); const char* b2 = last ? nBr : PG8_KP(cB, t + 2, rot, nt);
;             const char* a3 = a2 + kstep; const char* b3 = b2 + kstep;
;             if (last && has_next) S.a_ready(nxt);
;             if constexpr (SP2) {
;             PG8_LDB(B0, 0, 0); PG8_LDB(B1, 0, 1); PG8_SCHED; PG8_LDA(At, 0, 0); PG8_STAGE(PG8_SA(1, 1), a1 + hstep, voffA);
;             PG8_WAIT_V(8); PG8_WAIT_L(0); PG8_BAR; PG8_MMA(0, 0, At, B0); PG8_MMA(0, 1, At, B1); PG8_BAR; PG8_SCHED;
;             PG8_LDA(At, 0, 1); PG8_STAGEB(PG8_SB(0, 0), b2, voffB); PG8_STAGEB(PG8_SB(0, 1), b2 + hstep, voffB); PG8_STAGE(PG8_SA(0, 0), a2, voffA);
;             PG8_WAIT_V(8); PG8_WAIT_L(0); PG8_BAR; PG8_MMA(1, 0, At, B0); PG8_MMA(1, 1, At, B1); PG8_BAR; PG8_SCHED;
.LBB0_1457:
	s_ashr_i32 s15, s14, 31
	s_lshl_b64 s[0:1], s[14:15], 20
	s_add_u32 s16, s52, s0
	s_addc_u32 s17, s53, s1
	s_ashr_i32 s13, s12, 31
	s_lshl_b64 s[0:1], s[12:13], 20
	s_add_u32 s18, s54, s0
	s_addc_u32 s19, s55, s1
	s_and_b64 s[0:1], s[38:39], exec
	s_cselect_b32 s13, s17, s41
	s_cselect_b32 s15, s16, s40
	s_cselect_b32 s71, s19, s35
	s_cselect_b32 s75, s18, s34
	s_add_u32 s0, s40, 0x80080
	s_addc_u32 s1, s41, 0
	v_lshl_add_u64 v[144:145], s[0:1], 0, v[140:141]
	v_lshl_add_u64 v[146:147], s[0:1], 0, v[142:143]
	s_mov_b32 s29, 0
	s_waitcnt lgkmcnt(0)
	s_cmp_lg_u64 s[10:11], 0
	s_cbranch_scc1 .Lrp_1458
	s_barrier
.Lrp_1458:
.Lpk_1458:
	s_lshl_b32 s100, s29, 7
	s_add_u32 s100, s40, s100
	s_addc_u32 s101, s41, 0
	s_add_u32 s100, s100, 0x80
	s_addc_u32 s101, s101, 0
	s_add_i32 s30, s29, 2
	s_cmp_lt_u32 s29, 30
	s_cselect_b32 s0, 0, 0xffffffe0
	s_add_i32 s0, s30, s0
	s_ashr_i32 s1, s0, 31
	s_lshl_b64 s[0:1], s[0:1], 7
	s_add_u32 s2, s40, s0
	s_addc_u32 s31, s41, s1
	s_add_u32 s0, s34, s0
	s_addc_u32 s1, s35, s1
	s_cmp_eq_u32 s29, 30
	s_cselect_b32 s45, s13, s31
	s_cselect_b32 s44, s15, s2
	s_cselect_b32 s49, s71, s1
	s_cselect_b32 s48, s75, s0
	s_add_i32 s2, 0, 0x10000
	s_add_i32 s78, s2, s56
	s_add_i32 s31, 0, 0x14000
	s_add_i32 s47, s57, 0xe000
	s_add_i32 s81, s78, 0x2000
	s_add_u32 s50, s48, 0x80000
	s_addc_u32 s51, s49, 0
	s_add_i32 s82, s31, s56
	v_add_u32_e32 v162, s2, v99
	v_add_u32_e32 v166, s31, v99
	s_add_i32 s83, s82, 0x2000
	s_add_i32 s84, 0, 0x18000
	s_add_i32 s88, 0, 0x1c000
	ds_read_b128 v[150:153], v162
	ds_read_b128 v[154:157], v162 offset:1024
	ds_read_b128 v[158:161], v162 offset:2048
	ds_read_b128 v[162:165], v162 offset:3072
	ds_read_b128 v[180:183], v166
	ds_read_b128 v[184:187], v166 offset:1024
	ds_read_b128 v[188:191], v166 offset:2048
	ds_read_b128 v[192:195], v166 offset:3072
	s_add_u32 s42, s44, 0x80000
	s_addc_u32 s43, s45, 0
	s_add_i32 s1, s84, s56
	s_add_i32 s0, s1, 0x2000
	s_add_u32 s36, s48, 0x80080
	s_addc_u32 s37, s49, 0
	s_add_i32 s46, s88, s56
	s_add_i32 s31, s46, 0x2000
	ds_read_b128 v[196:199], v149
	ds_read_b128 v[200:203], v149 offset:1024
	ds_read_b128 v[222:225], v149 offset:2048
	ds_read_b128 v[226:229], v149 offset:3072
	ds_read_b128 v[230:233], v149 offset:4096
	ds_read_b128 v[234:237], v149 offset:5120
	ds_read_b128 v[238:241], v149 offset:6144
	ds_read_b128 v[242:245], v149 offset:7168
	v_lshl_add_u64 v[166:167], s[100:101], 0, v[138:139]
	s_mov_b32 m0, s61
	v_lshl_add_u64 v[168:169], s[100:101], 0, v[134:135]
	global_load_lds_dwordx4 v[166:167], off
	s_mov_b32 m0, s62
	s_nop 0
	global_load_lds_dwordx4 v[168:169], off
	s_add_i32 m0, s57, 0xc000
	s_nop 0
	global_load_lds_dwordx4 v[146:147], off
	s_mov_b32 m0, s47
	s_nop 0
	global_load_lds_dwordx4 v[144:145], off
	s_waitcnt vmcnt(8)
	s_waitcnt lgkmcnt(0)
	s_setprio 1
	s_barrier
	v_mfma_f32_16x16x32_bf16 v[128:131], v[150:153], v[196:199], 0
	v_mfma_f32_16x16x32_bf16 v[128:131], v[154:157], v[200:203], v[128:131]
	v_mfma_f32_16x16x32_bf16 v[120:123], v[158:161], v[196:199], 0
	v_mfma_f32_16x16x32_bf16 v[120:123], v[162:165], v[200:203], v[120:123]
	v_mfma_f32_16x16x32_bf16 v[112:115], v[150:153], v[222:225], 0
	v_mfma_f32_16x16x32_bf16 v[112:115], v[154:157], v[226:229], v[112:115]
	v_mfma_f32_16x16x32_bf16 v[104:107], v[158:161], v[222:225], 0
	v_mfma_f32_16x16x32_bf16 v[104:107], v[162:165], v[226:229], v[104:107]
	v_mfma_f32_16x16x32_bf16 v[94:97], v[150:153], v[230:233], 0
	v_mfma_f32_16x16x32_bf16 v[94:97], v[154:157], v[234:237], v[94:97]
	v_mfma_f32_16x16x32_bf16 v[86:89], v[158:161], v[230:233], 0
	v_mfma_f32_16x16x32_bf16 v[86:89], v[162:165], v[234:237], v[86:89]
	v_mfma_f32_16x16x32_bf16 v[78:81], v[150:153], v[238:241], 0
	v_mfma_f32_16x16x32_bf16 v[78:81], v[154:157], v[242:245], v[78:81]
	v_mfma_f32_16x16x32_bf16 v[70:73], v[158:161], v[238:241], 0
	v_mfma_f32_16x16x32_bf16 v[70:73], v[162:165], v[242:245], v[70:73]
	s_setprio 0
	s_setprio 1
	v_mfma_f32_16x16x32_bf16 v[124:127], v[180:183], v[196:199], 0
	v_mfma_f32_16x16x32_bf16 v[124:127], v[184:187], v[200:203], v[124:127]
	v_mfma_f32_16x16x32_bf16 v[116:119], v[188:191], v[196:199], 0
	v_mfma_f32_16x16x32_bf16 v[116:119], v[192:195], v[200:203], v[116:119]
	v_mfma_f32_16x16x32_bf16 v[108:111], v[180:183], v[222:225], 0
	v_mfma_f32_16x16x32_bf16 v[108:111], v[184:187], v[226:229], v[108:111]
	v_mfma_f32_16x16x32_bf16 v[100:103], v[188:191], v[222:225], 0
	v_mfma_f32_16x16x32_bf16 v[100:103], v[192:195], v[226:229], v[100:103]
	v_mfma_f32_16x16x32_bf16 v[90:93], v[180:183], v[230:233], 0
	v_mfma_f32_16x16x32_bf16 v[90:93], v[184:187], v[234:237], v[90:93]
	v_mfma_f32_16x16x32_bf16 v[82:85], v[188:191], v[230:233], 0
	v_mfma_f32_16x16x32_bf16 v[82:85], v[192:195], v[234:237], v[82:85]
	v_mfma_f32_16x16x32_bf16 v[74:77], v[180:183], v[238:241], 0
	v_mfma_f32_16x16x32_bf16 v[74:77], v[184:187], v[242:245], v[74:77]
	s_setprio 2
	s_barrier
	v_mfma_f32_16x16x32_bf16 v[66:69], v[188:191], v[238:241], 0
	v_mfma_f32_16x16x32_bf16 v[66:69], v[192:195], v[242:245], v[66:69]
	s_setprio 0
	s_mov_b32 m0, s78
	v_lshl_add_u64 v[166:167], s[48:49], 0, v[136:137]
	ds_read_b128 v[196:199], v149 offset:16384
	ds_read_b128 v[200:203], v149 offset:17408
	ds_read_b128 v[222:225], v149 offset:18432
	ds_read_b128 v[226:229], v149 offset:19456
	ds_read_b128 v[230:233], v149 offset:20480
	ds_read_b128 v[234:237], v149 offset:21504
	ds_read_b128 v[238:241], v149 offset:22528
	ds_read_b128 v[242:245], v149 offset:23552
	global_load_lds_dwordx4 v[166:167], off
	v_lshl_add_u64 v[168:169], s[48:49], 0, v[132:133]
	s_mov_b32 m0, s81
	v_lshl_add_u64 v[172:173], s[50:51], 0, v[136:137]
	global_load_lds_dwordx4 v[168:169], off
	s_mov_b32 m0, s82
	global_load_lds_dwordx4 v[172:173], off
	v_lshl_add_u64 v[172:173], s[50:51], 0, v[132:133]
	s_mov_b32 m0, s83
	s_nop 0
	global_load_lds_dwordx4 v[172:173], off
	s_waitcnt vmcnt(6)
	s_waitcnt lgkmcnt(0)
	s_setprio 1
	s_barrier
; #define PG8_STAGE(bufoff, gbase, voff) do { _Pragma("unroll") for (int _i = 0; _i < 2; ++_i) \
;         __builtin_amdgcn_global_load_lds((const unsigned*)((const char*)(gbase) + (voff)[_i]), (PG8_LAS unsigned*)(lds + (bufoff) + ldsw + _i * 8192), 16, 0, AUX_A); } while (0)
; #define PG8_STAGEB(bufoff, gbase, voff) do { _Pragma("unroll") for (int _i = 0; _i < 2; ++_i) \
;         __builtin_amdgcn_global_load_lds((const unsigned*)((const char*)(gbase) + (voff)[_i]), (PG8_LAS unsigned*)(lds + (bufoff) + ldsw + _i * 8192), 16, 0, AUX_B); } while (0)
; #define PG8_LDA(dst, b, h) do { _Pragma("unroll") for (int m = 0; m < 4; ++m) _Pragma("unroll") for (int k = 0; k < 2; ++k) dst[m][k] = *(const PG8_LAS bf16x8*)(lds + PG8_SA(b, h) + aoff + m * 2048 + k * 1024); } while (0)
; #define PG8_LDB(dst, b, h) do { _Pragma("unroll") for (int n = 0; n < 2; ++n) _Pragma("unroll") for (int k = 0; k < 2; ++k) dst[n][k] = *(const PG8_LAS bf16x8*)(lds + PG8_SB(b, h) + boff + n * 2048 + k * 1024); } while (0)
; #define PG8_MMA(ai, bj, At, Bt) do { __builtin_amdgcn_s_setprio(1); _Pragma("unroll") for (int m = 0; m < 4; ++m) _Pragma("unroll") for (int n = 0; n < 2; ++n) _Pragma("unroll") for (int k = 0; k < 2; ++k) \
;         acc[ai][bj][m][n] = __builtin_amdgcn_mfma_f32_16x16x32_bf16(Bt[n][k], At[m][k], acc[ai][bj][m][n], 0, 0, 0); __builtin_amdgcn_s_setprio(0); } while (0)
; #define PG8_WAIT_V(n) asm volatile("s_waitcnt vmcnt(" #n ")" ::: "memory")
; #define PG8_WAIT_L(n) asm volatile("s_waitcnt lgkmcnt(" #n ")" ::: "memory")
; template <class Epi, class Sched, bool ALIGN_EPI = false, bool SP2 = false>
; __device__ __forceinline__ void gemm_phase(PG8_LAS unsigned char* lds, const Gemm g, const Sched& S, const Epi& E) {
;     ...
;             PG8_WAIT_V(8); PG8_WAIT_L(0); PG8_BAR; PG8_MMA(0, 0, At, B0); PG8_MMA(0, 1, At, B1); PG8_BAR; PG8_SCHED;
;             PG8_LDA(At, 0, 1); PG8_STAGEB(PG8_SB(0, 0), b2, voffB); PG8_STAGEB(PG8_SB(0, 1), b2 + hstep, voffB); PG8_STAGE(PG8_SA(0, 0), a2, voffA);
;             PG8_WAIT_V(8); PG8_WAIT_L(0); PG8_BAR; PG8_MMA(1, 0, At, B0); PG8_MMA(1, 1, At, B1); PG8_BAR; PG8_SCHED;
;             PG8_LDB(B0, 1, 0); PG8_LDB(B1, 1, 1); PG8_SCHED; PG8_LDA(At, 1, 0); PG8_STAGE(PG8_SA(0, 1), a2 + hstep, voffA);
;             PG8_WAIT_V(8); PG8_WAIT_L(0); PG8_BAR; PG8_MMA(0, 0, At, B0); PG8_MMA(0, 1, At, B1); PG8_BAR; PG8_SCHED;
	v_mfma_f32_16x16x32_bf16 v[62:65], v[150:153], v[196:199], 0
	v_mfma_f32_16x16x32_bf16 v[62:65], v[154:157], v[200:203], v[62:65]
	v_mfma_f32_16x16x32_bf16 v[54:57], v[158:161], v[196:199], 0
	v_mfma_f32_16x16x32_bf16 v[54:57], v[162:165], v[200:203], v[54:57]
	v_mfma_f32_16x16x32_bf16 v[46:49], v[150:153], v[222:225], 0
	v_mfma_f32_16x16x32_bf16 v[46:49], v[154:157], v[226:229], v[46:49]
	v_mfma_f32_16x16x32_bf16 v[38:41], v[158:161], v[222:225], 0
	v_mfma_f32_16x16x32_bf16 v[38:41], v[162:165], v[226:229], v[38:41]
	v_mfma_f32_16x16x32_bf16 v[30:33], v[150:153], v[230:233], 0
	v_mfma_f32_16x16x32_bf16 v[30:33], v[154:157], v[234:237], v[30:33]
	v_mfma_f32_16x16x32_bf16 v[22:25], v[158:161], v[230:233], 0
	v_mfma_f32_16x16x32_bf16 v[22:25], v[162:165], v[234:237], v[22:25]
	v_mfma_f32_16x16x32_bf16 v[14:17], v[150:153], v[238:241], 0
	v_mfma_f32_16x16x32_bf16 v[14:17], v[154:157], v[242:245], v[14:17]
	v_mfma_f32_16x16x32_bf16 v[6:9], v[158:161], v[238:241], 0
	v_mfma_f32_16x16x32_bf16 v[6:9], v[162:165], v[242:245], v[6:9]
	s_setprio 0
	s_setprio 1
	v_mfma_f32_16x16x32_bf16 v[58:61], v[180:183], v[196:199], 0
	v_mfma_f32_16x16x32_bf16 v[58:61], v[184:187], v[200:203], v[58:61]
	v_mfma_f32_16x16x32_bf16 v[50:53], v[188:191], v[196:199], 0
	v_mfma_f32_16x16x32_bf16 v[50:53], v[192:195], v[200:203], v[50:53]
	v_mfma_f32_16x16x32_bf16 v[42:45], v[180:183], v[222:225], 0
	v_mfma_f32_16x16x32_bf16 v[42:45], v[184:187], v[226:229], v[42:45]
	v_mfma_f32_16x16x32_bf16 v[34:37], v[188:191], v[222:225], 0
	v_mfma_f32_16x16x32_bf16 v[34:37], v[192:195], v[226:229], v[34:37]
	v_mfma_f32_16x16x32_bf16 v[26:29], v[180:183], v[230:233], 0
	v_mfma_f32_16x16x32_bf16 v[26:29], v[184:187], v[234:237], v[26:29]
	v_mfma_f32_16x16x32_bf16 v[18:21], v[188:191], v[230:233], 0
	v_mfma_f32_16x16x32_bf16 v[18:21], v[192:195], v[234:237], v[18:21]
	v_mfma_f32_16x16x32_bf16 v[10:13], v[180:183], v[238:241], 0
	v_mfma_f32_16x16x32_bf16 v[10:13], v[184:187], v[242:245], v[10:13]
	s_setprio 2
	s_barrier
	v_mfma_f32_16x16x32_bf16 v[2:5], v[188:191], v[238:241], 0
	v_mfma_f32_16x16x32_bf16 v[2:5], v[192:195], v[242:245], v[2:5]
	s_setprio 0
	v_add_u32_e32 v162, s84, v99
	v_add_u32_e32 v192, s88, v99
	ds_read_b128 v[150:153], v162
	ds_read_b128 v[154:157], v162 offset:1024
	ds_read_b128 v[158:161], v162 offset:2048
	ds_read_b128 v[162:165], v162 offset:3072
	ds_read_b128 v[180:183], v192
	ds_read_b128 v[184:187], v192 offset:1024
	ds_read_b128 v[188:191], v192 offset:2048
	ds_read_b128 v[192:195], v192 offset:3072
	s_mov_b32 m0, s59
	v_lshl_add_u64 v[246:247], s[42:43], 0, v[138:139]
	ds_read_b128 v[196:199], v149 offset:32768
	ds_read_b128 v[200:203], v149 offset:33792
	ds_read_b128 v[222:225], v149 offset:34816
	ds_read_b128 v[226:229], v149 offset:35840
	ds_read_b128 v[230:233], v149 offset:36864
	ds_read_b128 v[234:237], v149 offset:37888
	ds_read_b128 v[238:241], v149 offset:38912
	ds_read_b128 v[242:245], v149 offset:39936
	v_lshl_add_u64 v[172:173], s[44:45], 0, v[138:139]
	s_mov_b32 m0, s57
	v_lshl_add_u64 v[212:213], s[44:45], 0, v[134:135]
	global_load_lds_dwordx4 v[172:173], off
	s_mov_b32 m0, s58
	s_nop 0
	global_load_lds_dwordx4 v[212:213], off
	s_mov_b32 m0, s59
	s_nop 0
	global_load_lds_dwordx4 v[246:247], off
	v_lshl_add_u64 v[246:247], s[42:43], 0, v[134:135]
	s_mov_b32 m0, s60
	s_nop 0
	global_load_lds_dwordx4 v[246:247], off
	s_waitcnt vmcnt(8)
	s_waitcnt lgkmcnt(0)
	s_setprio 1
	s_barrier
	v_mfma_f32_16x16x32_bf16 v[128:131], v[150:153], v[196:199], v[128:131]
	v_mfma_f32_16x16x32_bf16 v[128:131], v[154:157], v[200:203], v[128:131]
	v_mfma_f32_16x16x32_bf16 v[120:123], v[158:161], v[196:199], v[120:123]
	v_mfma_f32_16x16x32_bf16 v[120:123], v[162:165], v[200:203], v[120:123]
	v_mfma_f32_16x16x32_bf16 v[112:115], v[150:153], v[222:225], v[112:115]
	v_mfma_f32_16x16x32_bf16 v[112:115], v[154:157], v[226:229], v[112:115]
	v_mfma_f32_16x16x32_bf16 v[104:107], v[158:161], v[222:225], v[104:107]
	v_mfma_f32_16x16x32_bf16 v[104:107], v[162:165], v[226:229], v[104:107]
	v_mfma_f32_16x16x32_bf16 v[94:97], v[150:153], v[230:233], v[94:97]
	v_mfma_f32_16x16x32_bf16 v[94:97], v[154:157], v[234:237], v[94:97]
	v_mfma_f32_16x16x32_bf16 v[86:89], v[158:161], v[230:233], v[86:89]
	v_mfma_f32_16x16x32_bf16 v[86:89], v[162:165], v[234:237], v[86:89]
	v_mfma_f32_16x16x32_bf16 v[78:81], v[150:153], v[238:241], v[78:81]
	v_mfma_f32_16x16x32_bf16 v[78:81], v[154:157], v[242:245], v[78:81]
	v_mfma_f32_16x16x32_bf16 v[70:73], v[158:161], v[238:241], v[70:73]
	v_mfma_f32_16x16x32_bf16 v[70:73], v[162:165], v[242:245], v[70:73]
	s_setprio 0
	s_setprio 1
	v_mfma_f32_16x16x32_bf16 v[124:127], v[180:183], v[196:199], v[124:127]
	v_mfma_f32_16x16x32_bf16 v[124:127], v[184:187], v[200:203], v[124:127]
	v_mfma_f32_16x16x32_bf16 v[116:119], v[188:191], v[196:199], v[116:119]
	v_mfma_f32_16x16x32_bf16 v[116:119], v[192:195], v[200:203], v[116:119]
	v_mfma_f32_16x16x32_bf16 v[108:111], v[180:183], v[222:225], v[108:111]
	v_mfma_f32_16x16x32_bf16 v[108:111], v[184:187], v[226:229], v[108:111]
	v_mfma_f32_16x16x32_bf16 v[100:103], v[188:191], v[222:225], v[100:103]
	v_mfma_f32_16x16x32_bf16 v[100:103], v[192:195], v[226:229], v[100:103]
	v_mfma_f32_16x16x32_bf16 v[90:93], v[180:183], v[230:233], v[90:93]
	v_mfma_f32_16x16x32_bf16 v[90:93], v[184:187], v[234:237], v[90:93]
	v_mfma_f32_16x16x32_bf16 v[82:85], v[188:191], v[230:233], v[82:85]
	v_mfma_f32_16x16x32_bf16 v[82:85], v[192:195], v[234:237], v[82:85]
	v_mfma_f32_16x16x32_bf16 v[74:77], v[180:183], v[238:241], v[74:77]
	v_mfma_f32_16x16x32_bf16 v[74:77], v[184:187], v[242:245], v[74:77]
	s_setprio 2
	s_barrier
; #define PG8_STAGE(bufoff, gbase, voff) do { _Pragma("unroll") for (int _i = 0; _i < 2; ++_i) \
;         __builtin_amdgcn_global_load_lds((const unsigned*)((const char*)(gbase) + (voff)[_i]), (PG8_LAS unsigned*)(lds + (bufoff) + ldsw + _i * 8192), 16, 0, AUX_A); } while (0)
; #define PG8_STAGEB(bufoff, gbase, voff) do { _Pragma("unroll") for (int _i = 0; _i < 2; ++_i) \
;         __builtin_amdgcn_global_load_lds((const unsigned*)((const char*)(gbase) + (voff)[_i]), (PG8_LAS unsigned*)(lds + (bufoff) + ldsw + _i * 8192), 16, 0, AUX_B); } while (0)
; #define PG8_LDA(dst, b, h) do { _Pragma("unroll") for (int m = 0; m < 4; ++m) _Pragma("unroll") for (int k = 0; k < 2; ++k) dst[m][k] = *(const PG8_LAS bf16x8*)(lds + PG8_SA(b, h) + aoff + m * 2048 + k * 1024); } while (0)
; #define PG8_MMA(ai, bj, At, Bt) do { __builtin_amdgcn_s_setprio(1); _Pragma("unroll") for (int m = 0; m < 4; ++m) _Pragma("unroll") for (int n = 0; n < 2; ++n) _Pragma("unroll") for (int k = 0; k < 2; ++k) \
;         acc[ai][bj][m][n] = __builtin_amdgcn_mfma_f32_16x16x32_bf16(Bt[n][k], At[m][k], acc[ai][bj][m][n], 0, 0, 0); __builtin_amdgcn_s_setprio(0); } while (0)
; #define PG8_WAIT_V(n) asm volatile("s_waitcnt vmcnt(" #n ")" ::: "memory")
; #define PG8_WAIT_L(n) asm volatile("s_waitcnt lgkmcnt(" #n ")" ::: "memory")
; #define PG8_BAR __builtin_amdgcn_s_barrier()
; #define PG8_SCHED __builtin_amdgcn_sched_barrier(0)
; template <class Epi, class Sched, bool ALIGN_EPI = false, bool SP2 = false>
; __device__ __forceinline__ void gemm_phase(PG8_LAS unsigned char* lds, const Gemm g, const Sched& S, const Epi& E) {
;     ...
;         for (int t = 0; t < nt; t += 2) {
;     ...
;             PG8_LDA(At, 1, 1); PG8_STAGEB(PG8_SB(1, 0), b3, voffB); PG8_STAGEB(PG8_SB(1, 1), b3 + hstep, voffB); PG8_STAGE(PG8_SA(1, 0), a3, voffA);
;             PG8_WAIT_V(8); PG8_WAIT_L(0); PG8_BAR; PG8_MMA(1, 0, At, B0); PG8_MMA(1, 1, At, B1); PG8_BAR; PG8_SCHED;
	v_mfma_f32_16x16x32_bf16 v[66:69], v[188:191], v[238:241], v[66:69]
	v_mfma_f32_16x16x32_bf16 v[66:69], v[192:195], v[242:245], v[66:69]
	s_setprio 0
	s_mov_b32 m0, s1
	v_lshl_add_u64 v[166:167], v[166:167], 0, s[76:77]
	ds_read_b128 v[196:199], v149 offset:49152
	ds_read_b128 v[200:203], v149 offset:50176
	ds_read_b128 v[222:225], v149 offset:51200
	ds_read_b128 v[226:229], v149 offset:52224
	ds_read_b128 v[230:233], v149 offset:53248
	ds_read_b128 v[234:237], v149 offset:54272
	ds_read_b128 v[238:241], v149 offset:55296
	ds_read_b128 v[242:245], v149 offset:56320
	global_load_lds_dwordx4 v[166:167], off
	v_lshl_add_u64 v[166:167], v[168:169], 0, s[76:77]
	s_mov_b32 m0, s0
	s_nop 0
	global_load_lds_dwordx4 v[166:167], off
	v_lshl_add_u64 v[166:167], s[36:37], 0, v[136:137]
	s_mov_b32 m0, s46
	s_nop 0
	global_load_lds_dwordx4 v[166:167], off
	v_lshl_add_u64 v[166:167], s[36:37], 0, v[132:133]
	s_mov_b32 m0, s31
	s_nop 0
	global_load_lds_dwordx4 v[166:167], off
	s_waitcnt vmcnt(6)
	s_waitcnt lgkmcnt(0)
	s_setprio 1
	s_barrier
	v_mfma_f32_16x16x32_bf16 v[62:65], v[150:153], v[196:199], v[62:65]
	v_mfma_f32_16x16x32_bf16 v[62:65], v[154:157], v[200:203], v[62:65]
	v_mfma_f32_16x16x32_bf16 v[54:57], v[158:161], v[196:199], v[54:57]
	v_mfma_f32_16x16x32_bf16 v[54:57], v[162:165], v[200:203], v[54:57]
	v_mfma_f32_16x16x32_bf16 v[46:49], v[150:153], v[222:225], v[46:49]
	v_mfma_f32_16x16x32_bf16 v[46:49], v[154:157], v[226:229], v[46:49]
	v_mfma_f32_16x16x32_bf16 v[38:41], v[158:161], v[222:225], v[38:41]
	v_mfma_f32_16x16x32_bf16 v[38:41], v[162:165], v[226:229], v[38:41]
	v_mfma_f32_16x16x32_bf16 v[30:33], v[150:153], v[230:233], v[30:33]
	v_mfma_f32_16x16x32_bf16 v[30:33], v[154:157], v[234:237], v[30:33]
	v_mfma_f32_16x16x32_bf16 v[22:25], v[158:161], v[230:233], v[22:25]
	v_mfma_f32_16x16x32_bf16 v[22:25], v[162:165], v[234:237], v[22:25]
	v_mfma_f32_16x16x32_bf16 v[14:17], v[150:153], v[238:241], v[14:17]
	v_mfma_f32_16x16x32_bf16 v[14:17], v[154:157], v[242:245], v[14:17]
	v_mfma_f32_16x16x32_bf16 v[6:9], v[158:161], v[238:241], v[6:9]
	v_mfma_f32_16x16x32_bf16 v[6:9], v[162:165], v[242:245], v[6:9]
	s_setprio 0
	s_setprio 1
	v_mfma_f32_16x16x32_bf16 v[58:61], v[180:183], v[196:199], v[58:61]
	v_mfma_f32_16x16x32_bf16 v[58:61], v[184:187], v[200:203], v[58:61]
	v_mfma_f32_16x16x32_bf16 v[50:53], v[188:191], v[196:199], v[50:53]
	v_mfma_f32_16x16x32_bf16 v[50:53], v[192:195], v[200:203], v[50:53]
	v_mfma_f32_16x16x32_bf16 v[42:45], v[180:183], v[222:225], v[42:45]
	v_mfma_f32_16x16x32_bf16 v[42:45], v[184:187], v[226:229], v[42:45]
	v_mfma_f32_16x16x32_bf16 v[34:37], v[188:191], v[222:225], v[34:37]
	v_mfma_f32_16x16x32_bf16 v[34:37], v[192:195], v[226:229], v[34:37]
	v_mfma_f32_16x16x32_bf16 v[26:29], v[180:183], v[230:233], v[26:29]
	v_mfma_f32_16x16x32_bf16 v[26:29], v[184:187], v[234:237], v[26:29]
	v_mfma_f32_16x16x32_bf16 v[18:21], v[188:191], v[230:233], v[18:21]
	v_mfma_f32_16x16x32_bf16 v[18:21], v[192:195], v[234:237], v[18:21]
	v_mfma_f32_16x16x32_bf16 v[10:13], v[180:183], v[238:241], v[10:13]
	v_mfma_f32_16x16x32_bf16 v[10:13], v[184:187], v[242:245], v[10:13]
	s_setprio 2
	s_barrier
	v_mfma_f32_16x16x32_bf16 v[2:5], v[188:191], v[238:241], v[2:5]
	v_mfma_f32_16x16x32_bf16 v[2:5], v[192:195], v[242:245], v[2:5]
	s_setprio 0
	v_lshl_add_u64 v[144:145], v[144:145], 0, s[86:87]
	v_lshl_add_u64 v[146:147], v[146:147], 0, s[86:87]
	s_cmp_gt_u32 s30, 31
	s_mov_b32 s29, s30
	s_cbranch_scc1 .Lpx_1458

; __device__ __forceinline__ u32x4 pack8(f32x4 v0, f32x4 v1) { u32x4 w; w.x = cvt_pk_bf16(v0[0], v0[1]); w.y = cvt_pk_bf16(v0[2], v0[3]); w.z = cvt_pk_bf16(v1[0], v1[1]); w.w = cvt_pk_bf16(v1[2], v1[3]); return w; }
; __device__ __forceinline__ f32x4 sigmoid4(f32x4 v) {
;     const f32x2 t0 = (f32x2){v[0], v[1]} * -1.4426950408889634f, t1 = (f32x2){v[2], v[3]} * -1.4426950408889634f;
;     const f32x2 d0 = (f32x2){__builtin_amdgcn_exp2f(t0.x), __builtin_amdgcn_exp2f(t0.y)} + 1.0f, d1 = (f32x2){__builtin_amdgcn_exp2f(t1.x), __builtin_amdgcn_exp2f(t1.y)} + 1.0f;
;     return (f32x4){__builtin_amdgcn_rcpf(d0.x), __builtin_amdgcn_rcpf(d0.y), __builtin_amdgcn_rcpf(d1.x), __builtin_amdgcn_rcpf(d1.y)}; }
;     __device__ __forceinline__ void operator()(const f32x4 (&acc)[2][2][4][2], const Unit& u, int wr, int wc, int fr, int fq) const {
;         const int row0 = u.pm * BM + wr * 64 + fr, col0 = u.pn * HALF + wc * 32 + 8 * fq;
;         bf16_t* const p0 = ACT + (size_t)row0 * 5632 + col0;
; #pragma unroll
;         for (int ai = 0; ai < 2; ++ai)
; #pragma unroll
;             for (int m = 0; m < 4; ++m) {
;                 const f32x4 g0 = acc[ai][0][m][0], g1 = acc[ai][0][m][1];
;                 const f32x4 v0 = g0 * sigmoid4(g0) * acc[ai][1][m][0], v1 = g1 * sigmoid4(g1) * acc[ai][1][m][1];
;                 store16_wt(p0 + (size_t)(ai * HALF + m * 16) * 5632, pack8(v0, v1)); }
.LBB0_1461:
	v_lshl_add_u32 v145, s70, 8, v1
	v_lshl_or_b32 v144, s69, 7, v148
	v_mov_b64_e32 v[146:147], s[8:9]
	s_movk_i32 s0, 0x2c00
	v_mad_i64_i32 v[146:147], s[0:1], v145, s0, v[146:147]
	v_ashrrev_i32_e32 v145, 31, v144
	v_lshl_add_u64 v[144:145], v[144:145], 1, v[146:147]
	v_pk_mul_f32 v[146:147], v[128:129], s[74:75] op_sel_hi:[1,0]
	v_pk_mul_f32 v[150:151], v[130:131], s[74:75] op_sel_hi:[1,0]
	v_exp_f32_e32 v146, v146
	v_exp_f32_e32 v147, v147
	v_exp_f32_e32 v150, v150
	v_exp_f32_e32 v151, v151
	s_mov_b32 s0, 0x160000
	v_pk_add_f32 v[146:147], v[146:147], 1.0 op_sel_hi:[1,0]
	s_mov_b64 s[34:35], -1
	v_pk_add_f32 v[150:151], v[150:151], 1.0 op_sel_hi:[1,0]
	v_rcp_f32_e32 v146, v146
	v_rcp_f32_e32 v147, v147
	v_rcp_f32_e32 v150, v150
	v_rcp_f32_e32 v151, v151
	v_pk_mul_f32 v[128:129], v[128:129], v[146:147]
	s_nop 0
	v_pk_mul_f32 v[124:125], v[124:125], v[128:129]
	v_pk_mul_f32 v[130:131], v[130:131], v[150:151]
	v_pk_mul_f32 v[128:129], v[120:121], s[74:75] op_sel_hi:[1,0]
	v_pk_mul_f32 v[126:127], v[126:127], v[130:131]
	v_pk_mul_f32 v[130:131], v[122:123], s[74:75] op_sel_hi:[1,0]
	v_exp_f32_e32 v128, v128
	v_exp_f32_e32 v129, v129
	v_exp_f32_e32 v130, v130
	v_exp_f32_e32 v131, v131
	v_pk_add_f32 v[128:129], v[128:129], 1.0 op_sel_hi:[1,0]
	s_nop 0
	v_rcp_f32_e32 v128, v128
	v_pk_add_f32 v[130:131], v[130:131], 1.0 op_sel_hi:[1,0]
	v_rcp_f32_e32 v129, v129
	v_rcp_f32_e32 v130, v130
	v_rcp_f32_e32 v131, v131
	v_pk_mul_f32 v[120:121], v[120:121], v[128:129]
	v_pk_mul_f32 v[122:123], v[122:123], v[130:131]
	s_nop 0
	v_pk_mul_f32 v[122:123], v[118:119], v[122:123]
	v_pk_mul_f32 v[118:119], v[116:117], v[120:121]
	v_cvt_pk_bf16_f32 v116, v124, v125
	v_cvt_pk_bf16_f32 v117, v126, v127
	v_cvt_pk_bf16_f32 v118, v118, v119
	v_cvt_pk_bf16_f32 v119, v122, v123
	global_store_dwordx4 v[144:145], v[116:119], off sc1
	s_nop 1
	v_pk_mul_f32 v[116:117], v[112:113], s[74:75] op_sel_hi:[1,0]
	v_pk_mul_f32 v[118:119], v[114:115], s[74:75] op_sel_hi:[1,0]
	v_exp_f32_e32 v116, v116
	v_exp_f32_e32 v117, v117
	v_exp_f32_e32 v118, v118
	v_exp_f32_e32 v119, v119
	v_pk_add_f32 v[116:117], v[116:117], 1.0 op_sel_hi:[1,0]
	s_nop 0
	v_rcp_f32_e32 v116, v116
	v_pk_add_f32 v[118:119], v[118:119], 1.0 op_sel_hi:[1,0]
	v_rcp_f32_e32 v117, v117
	v_rcp_f32_e32 v118, v118
	v_rcp_f32_e32 v119, v119
	v_pk_mul_f32 v[112:113], v[112:113], v[116:117]
	s_nop 0
	v_pk_mul_f32 v[108:109], v[108:109], v[112:113]
	v_pk_mul_f32 v[114:115], v[114:115], v[118:119]
	v_pk_mul_f32 v[112:113], v[104:105], s[74:75] op_sel_hi:[1,0]
	v_pk_mul_f32 v[110:111], v[110:111], v[114:115]
	v_pk_mul_f32 v[114:115], v[106:107], s[74:75] op_sel_hi:[1,0]
	v_exp_f32_e32 v112, v112
	v_exp_f32_e32 v113, v113
	v_exp_f32_e32 v114, v114
	v_exp_f32_e32 v115, v115
	v_pk_add_f32 v[112:113], v[112:113], 1.0 op_sel_hi:[1,0]
	s_nop 0
	v_rcp_f32_e32 v112, v112
	v_pk_add_f32 v[114:115], v[114:115], 1.0 op_sel_hi:[1,0]
	v_rcp_f32_e32 v113, v113
	v_rcp_f32_e32 v114, v114
	v_rcp_f32_e32 v115, v115
	v_pk_mul_f32 v[104:105], v[104:105], v[112:113]
	v_pk_mul_f32 v[106:107], v[106:107], v[114:115]
	s_nop 0
	v_pk_mul_f32 v[106:107], v[102:103], v[106:107]
	v_pk_mul_f32 v[102:103], v[100:101], v[104:105]
	v_add_co_u32_e32 v104, vcc, s65, v144
	v_cvt_pk_bf16_f32 v100, v108, v109
	v_cvt_pk_bf16_f32 v101, v110, v111
	v_cvt_pk_bf16_f32 v102, v102, v103
	v_cvt_pk_bf16_f32 v103, v106, v107
	v_addc_co_u32_e32 v105, vcc, 0, v145, vcc
	global_store_dwordx4 v[104:105], v[100:103], off sc1
	s_nop 1
	v_pk_mul_f32 v[100:101], v[94:95], s[74:75] op_sel_hi:[1,0]
	v_pk_mul_f32 v[102:103], v[96:97], s[74:75] op_sel_hi:[1,0]
	v_exp_f32_e32 v100, v100
	v_exp_f32_e32 v101, v101
	v_exp_f32_e32 v102, v102
	v_exp_f32_e32 v103, v103
	v_pk_add_f32 v[100:101], v[100:101], 1.0 op_sel_hi:[1,0]
	s_nop 0
	v_rcp_f32_e32 v100, v100
	v_pk_add_f32 v[102:103], v[102:103], 1.0 op_sel_hi:[1,0]
	v_rcp_f32_e32 v101, v101
	v_rcp_f32_e32 v102, v102
	v_rcp_f32_e32 v103, v103
	v_pk_mul_f32 v[94:95], v[94:95], v[100:101]
	s_nop 0
	v_pk_mul_f32 v[90:91], v[90:91], v[94:95]
	v_pk_mul_f32 v[96:97], v[96:97], v[102:103]
	v_pk_mul_f32 v[94:95], v[86:87], s[74:75] op_sel_hi:[1,0]
	v_pk_mul_f32 v[92:93], v[92:93], v[96:97]
	v_pk_mul_f32 v[96:97], v[88:89], s[74:75] op_sel_hi:[1,0]
	v_exp_f32_e32 v94, v94
	v_exp_f32_e32 v95, v95
	v_exp_f32_e32 v96, v96
	v_exp_f32_e32 v97, v97
	v_pk_add_f32 v[94:95], v[94:95], 1.0 op_sel_hi:[1,0]
	s_nop 0
	v_rcp_f32_e32 v94, v94
	v_pk_add_f32 v[96:97], v[96:97], 1.0 op_sel_hi:[1,0]
	v_rcp_f32_e32 v95, v95
	v_rcp_f32_e32 v96, v96
	v_rcp_f32_e32 v97, v97
	v_pk_mul_f32 v[86:87], v[86:87], v[94:95]
	v_pk_mul_f32 v[88:89], v[88:89], v[96:97]
	s_nop 0
	v_pk_mul_f32 v[88:89], v[84:85], v[88:89]
	v_pk_mul_f32 v[84:85], v[82:83], v[86:87]
	v_add_co_u32_e32 v86, vcc, s64, v144
	v_cvt_pk_bf16_f32 v82, v90, v91
	v_cvt_pk_bf16_f32 v83, v92, v93
	v_cvt_pk_bf16_f32 v84, v84, v85
	v_cvt_pk_bf16_f32 v85, v88, v89
	v_addc_co_u32_e32 v87, vcc, 0, v145, vcc
	global_store_dwordx4 v[86:87], v[82:85], off sc1
	s_nop 1
	v_pk_mul_f32 v[82:83], v[78:79], s[74:75] op_sel_hi:[1,0]
	v_pk_mul_f32 v[84:85], v[80:81], s[74:75] op_sel_hi:[1,0]
	v_exp_f32_e32 v82, v82
	v_exp_f32_e32 v83, v83
	v_exp_f32_e32 v84, v84
	v_exp_f32_e32 v85, v85
	v_pk_add_f32 v[82:83], v[82:83], 1.0 op_sel_hi:[1,0]
	s_nop 0
	v_rcp_f32_e32 v82, v82
	v_pk_add_f32 v[84:85], v[84:85], 1.0 op_sel_hi:[1,0]
	v_rcp_f32_e32 v83, v83
	v_rcp_f32_e32 v84, v84
	v_rcp_f32_e32 v85, v85
	v_pk_mul_f32 v[78:79], v[78:79], v[82:83]
	s_nop 0
	v_pk_mul_f32 v[74:75], v[74:75], v[78:79]
	v_pk_mul_f32 v[80:81], v[80:81], v[84:85]
	v_pk_mul_f32 v[78:79], v[70:71], s[74:75] op_sel_hi:[1,0]
	v_pk_mul_f32 v[76:77], v[76:77], v[80:81]
; __device__ __forceinline__ u32x4 pack8(f32x4 v0, f32x4 v1) { u32x4 w; w.x = cvt_pk_bf16(v0[0], v0[1]); w.y = cvt_pk_bf16(v0[2], v0[3]); w.z = cvt_pk_bf16(v1[0], v1[1]); w.w = cvt_pk_bf16(v1[2], v1[3]); return w; }
; #define PG8_BAR __builtin_amdgcn_s_barrier()
;     __device__ __forceinline__ void operator()(const f32x4 (&acc)[2][2][4][2], const Unit& u, int wr, int wc, int fr, int fq) const {
;     ...
; #pragma unroll
;             for (int m = 0; m < 4; ++m) {
;                 const f32x4 g0 = acc[ai][0][m][0], g1 = acc[ai][0][m][1];
;                 const f32x4 v0 = g0 * sigmoid4(g0) * acc[ai][1][m][0], v1 = g1 * sigmoid4(g1) * acc[ai][1][m][1];
;                 store16_wt(p0 + (size_t)(ai * HALF + m * 16) * 5632, pack8(v0, v1)); }
; template <class Epi, class Sched, bool ALIGN_EPI = false, bool SP2 = false>
; __device__ __forceinline__ void gemm_phase(PG8_LAS unsigned char* lds, const Gemm g, const Sched& S, const Epi& E) {
;     ...
;         if (!has_next) break;
; #pragma unroll
;         for (int a = 0; a < 2; ++a)
; #pragma unroll
;             for (int b = 0; b < 2; ++b)
; #pragma unroll
;                 for (int m = 0; m < 4; ++m)
; #pragma unroll
;                     for (int n = 0; n < 2; ++n) acc[a][b][m][n] = (f32x4){0.f, 0.f, 0.f, 0.f};
;         cur = nxt; cA = nA; cB = nB; ++ui;
;         if constexpr (ALIGN_EPI) { if (wr == 1) PG8_BAR; }
	v_pk_mul_f32 v[80:81], v[72:73], s[74:75] op_sel_hi:[1,0]
	v_exp_f32_e32 v78, v78
	v_exp_f32_e32 v79, v79
	v_exp_f32_e32 v80, v80
	v_exp_f32_e32 v81, v81
	v_pk_add_f32 v[78:79], v[78:79], 1.0 op_sel_hi:[1,0]
	s_nop 0
	v_rcp_f32_e32 v78, v78
	v_pk_add_f32 v[80:81], v[80:81], 1.0 op_sel_hi:[1,0]
	v_rcp_f32_e32 v79, v79
	v_rcp_f32_e32 v80, v80
	v_rcp_f32_e32 v81, v81
	v_pk_mul_f32 v[70:71], v[70:71], v[78:79]
	v_pk_mul_f32 v[72:73], v[72:73], v[80:81]
	s_nop 0
	v_pk_mul_f32 v[72:73], v[68:69], v[72:73]
	v_pk_mul_f32 v[68:69], v[66:67], v[70:71]
	v_add_co_u32_e32 v70, vcc, s66, v144
	v_cvt_pk_bf16_f32 v66, v74, v75
	v_cvt_pk_bf16_f32 v67, v76, v77
	v_cvt_pk_bf16_f32 v68, v68, v69
	v_cvt_pk_bf16_f32 v69, v72, v73
	v_addc_co_u32_e32 v71, vcc, 0, v145, vcc
	global_store_dwordx4 v[70:71], v[66:69], off sc1
	s_nop 1
	v_pk_mul_f32 v[66:67], v[62:63], s[74:75] op_sel_hi:[1,0]
	v_pk_mul_f32 v[68:69], v[64:65], s[74:75] op_sel_hi:[1,0]
	v_exp_f32_e32 v66, v66
	v_exp_f32_e32 v67, v67
	v_exp_f32_e32 v68, v68
	v_exp_f32_e32 v69, v69
	v_pk_add_f32 v[66:67], v[66:67], 1.0 op_sel_hi:[1,0]
	s_nop 0
	v_rcp_f32_e32 v66, v66
	v_pk_add_f32 v[68:69], v[68:69], 1.0 op_sel_hi:[1,0]
	v_rcp_f32_e32 v67, v67
	v_rcp_f32_e32 v68, v68
	v_rcp_f32_e32 v69, v69
	v_pk_mul_f32 v[62:63], v[62:63], v[66:67]
	s_nop 0
	v_pk_mul_f32 v[58:59], v[58:59], v[62:63]
	v_pk_mul_f32 v[64:65], v[64:65], v[68:69]
	v_pk_mul_f32 v[62:63], v[54:55], s[74:75] op_sel_hi:[1,0]
	v_pk_mul_f32 v[60:61], v[60:61], v[64:65]
	v_pk_mul_f32 v[64:65], v[56:57], s[74:75] op_sel_hi:[1,0]
	v_exp_f32_e32 v62, v62
	v_exp_f32_e32 v63, v63
	v_exp_f32_e32 v64, v64
	v_exp_f32_e32 v65, v65
	v_pk_add_f32 v[62:63], v[62:63], 1.0 op_sel_hi:[1,0]
	s_nop 0
	v_rcp_f32_e32 v62, v62
	v_pk_add_f32 v[64:65], v[64:65], 1.0 op_sel_hi:[1,0]
	v_rcp_f32_e32 v63, v63
	v_rcp_f32_e32 v64, v64
	v_rcp_f32_e32 v65, v65
	v_pk_mul_f32 v[54:55], v[54:55], v[62:63]
	v_pk_mul_f32 v[56:57], v[56:57], v[64:65]
	s_nop 0
	v_pk_mul_f32 v[56:57], v[52:53], v[56:57]
	v_pk_mul_f32 v[52:53], v[50:51], v[54:55]
	v_add_co_u32_e32 v54, vcc, s0, v144
	v_cvt_pk_bf16_f32 v50, v58, v59
	v_cvt_pk_bf16_f32 v51, v60, v61
	v_cvt_pk_bf16_f32 v52, v52, v53
	v_cvt_pk_bf16_f32 v53, v56, v57
	v_addc_co_u32_e32 v55, vcc, 0, v145, vcc
	global_store_dwordx4 v[54:55], v[50:53], off sc1
	s_mov_b32 s0, 0x18c000
	s_nop 0
	v_pk_mul_f32 v[50:51], v[46:47], s[74:75] op_sel_hi:[1,0]
	v_pk_mul_f32 v[52:53], v[48:49], s[74:75] op_sel_hi:[1,0]
	v_exp_f32_e32 v50, v50
	v_exp_f32_e32 v51, v51
	v_exp_f32_e32 v52, v52
	v_exp_f32_e32 v53, v53
	v_pk_add_f32 v[50:51], v[50:51], 1.0 op_sel_hi:[1,0]
	s_nop 0
	v_rcp_f32_e32 v50, v50
	v_pk_add_f32 v[52:53], v[52:53], 1.0 op_sel_hi:[1,0]
	v_rcp_f32_e32 v51, v51
	v_rcp_f32_e32 v52, v52
	v_rcp_f32_e32 v53, v53
	v_pk_mul_f32 v[46:47], v[46:47], v[50:51]
	s_nop 0
	v_pk_mul_f32 v[42:43], v[42:43], v[46:47]
	v_pk_mul_f32 v[48:49], v[48:49], v[52:53]
	v_pk_mul_f32 v[46:47], v[38:39], s[74:75] op_sel_hi:[1,0]
	v_pk_mul_f32 v[44:45], v[44:45], v[48:49]
	v_pk_mul_f32 v[48:49], v[40:41], s[74:75] op_sel_hi:[1,0]
	v_exp_f32_e32 v46, v46
	v_exp_f32_e32 v47, v47
	v_exp_f32_e32 v48, v48
	v_exp_f32_e32 v49, v49
	v_pk_add_f32 v[46:47], v[46:47], 1.0 op_sel_hi:[1,0]
	s_nop 0
	v_rcp_f32_e32 v46, v46
	v_pk_add_f32 v[48:49], v[48:49], 1.0 op_sel_hi:[1,0]
	v_rcp_f32_e32 v47, v47
	v_rcp_f32_e32 v48, v48
	v_rcp_f32_e32 v49, v49
	v_pk_mul_f32 v[38:39], v[38:39], v[46:47]
	v_pk_mul_f32 v[40:41], v[40:41], v[48:49]
	s_nop 0
	v_pk_mul_f32 v[40:41], v[36:37], v[40:41]
	v_pk_mul_f32 v[36:37], v[34:35], v[38:39]
	v_add_co_u32_e32 v38, vcc, s0, v144
	v_cvt_pk_bf16_f32 v34, v42, v43
	v_cvt_pk_bf16_f32 v35, v44, v45
	v_cvt_pk_bf16_f32 v36, v36, v37
	v_cvt_pk_bf16_f32 v37, v40, v41
	v_addc_co_u32_e32 v39, vcc, 0, v145, vcc
	global_store_dwordx4 v[38:39], v[34:37], off sc1
	s_mov_b32 s0, 0x1b8000
	s_nop 0
	v_pk_mul_f32 v[34:35], v[30:31], s[74:75] op_sel_hi:[1,0]
	v_pk_mul_f32 v[36:37], v[32:33], s[74:75] op_sel_hi:[1,0]
	v_exp_f32_e32 v34, v34
	v_exp_f32_e32 v35, v35
	v_exp_f32_e32 v36, v36
	v_exp_f32_e32 v37, v37
	v_pk_add_f32 v[34:35], v[34:35], 1.0 op_sel_hi:[1,0]
	s_nop 0
	v_rcp_f32_e32 v34, v34
	v_pk_add_f32 v[36:37], v[36:37], 1.0 op_sel_hi:[1,0]
	v_rcp_f32_e32 v35, v35
	v_rcp_f32_e32 v36, v36
	v_rcp_f32_e32 v37, v37
	v_pk_mul_f32 v[30:31], v[30:31], v[34:35]
	s_nop 0
	v_pk_mul_f32 v[26:27], v[26:27], v[30:31]
	v_pk_mul_f32 v[32:33], v[32:33], v[36:37]
	v_pk_mul_f32 v[30:31], v[22:23], s[74:75] op_sel_hi:[1,0]
	v_pk_mul_f32 v[28:29], v[28:29], v[32:33]
	v_pk_mul_f32 v[32:33], v[24:25], s[74:75] op_sel_hi:[1,0]
	v_exp_f32_e32 v30, v30
	v_exp_f32_e32 v31, v31
	v_exp_f32_e32 v32, v32
	v_exp_f32_e32 v33, v33
	v_pk_add_f32 v[30:31], v[30:31], 1.0 op_sel_hi:[1,0]
	s_nop 0
	v_rcp_f32_e32 v30, v30
	v_pk_add_f32 v[32:33], v[32:33], 1.0 op_sel_hi:[1,0]
	v_rcp_f32_e32 v31, v31
	v_rcp_f32_e32 v32, v32
	v_rcp_f32_e32 v33, v33
	v_pk_mul_f32 v[22:23], v[22:23], v[30:31]
	v_pk_mul_f32 v[24:25], v[24:25], v[32:33]
	s_nop 0
	v_pk_mul_f32 v[24:25], v[20:21], v[24:25]
	v_pk_mul_f32 v[20:21], v[18:19], v[22:23]
	v_add_co_u32_e32 v22, vcc, s0, v144
	v_cvt_pk_bf16_f32 v18, v26, v27
	v_cvt_pk_bf16_f32 v19, v28, v29
	v_cvt_pk_bf16_f32 v20, v20, v21
	v_cvt_pk_bf16_f32 v21, v24, v25
	v_addc_co_u32_e32 v23, vcc, 0, v145, vcc
	global_store_dwordx4 v[22:23], v[18:21], off sc1
	s_nop 1
	v_pk_mul_f32 v[18:19], v[14:15], s[74:75] op_sel_hi:[1,0]
	v_pk_mul_f32 v[20:21], v[16:17], s[74:75] op_sel_hi:[1,0]
	v_exp_f32_e32 v18, v18
	v_exp_f32_e32 v19, v19
	v_exp_f32_e32 v20, v20
	v_exp_f32_e32 v21, v21
	v_pk_add_f32 v[18:19], v[18:19], 1.0 op_sel_hi:[1,0]
	s_nop 0
	v_rcp_f32_e32 v18, v18
	v_pk_add_f32 v[20:21], v[20:21], 1.0 op_sel_hi:[1,0]
	v_rcp_f32_e32 v19, v19
	v_rcp_f32_e32 v20, v20
	v_rcp_f32_e32 v21, v21
	v_pk_mul_f32 v[14:15], v[14:15], v[18:19]
	s_nop 0
	v_pk_mul_f32 v[10:11], v[10:11], v[14:15]
	v_pk_mul_f32 v[16:17], v[16:17], v[20:21]
	v_pk_mul_f32 v[14:15], v[6:7], s[74:75] op_sel_hi:[1,0]
	v_pk_mul_f32 v[12:13], v[12:13], v[16:17]
	v_pk_mul_f32 v[16:17], v[8:9], s[74:75] op_sel_hi:[1,0]
	v_exp_f32_e32 v14, v14
	v_exp_f32_e32 v15, v15
	v_exp_f32_e32 v16, v16
	v_exp_f32_e32 v17, v17
	v_pk_add_f32 v[14:15], v[14:15], 1.0 op_sel_hi:[1,0]
	s_nop 0
	v_rcp_f32_e32 v14, v14
	v_pk_add_f32 v[16:17], v[16:17], 1.0 op_sel_hi:[1,0]
	v_rcp_f32_e32 v15, v15
	v_rcp_f32_e32 v16, v16
	v_rcp_f32_e32 v17, v17
	v_pk_mul_f32 v[6:7], v[6:7], v[14:15]
	v_pk_mul_f32 v[8:9], v[8:9], v[16:17]
	s_nop 0
	v_pk_mul_f32 v[8:9], v[4:5], v[8:9]
	v_pk_mul_f32 v[4:5], v[2:3], v[6:7]
	v_add_co_u32_e32 v6, vcc, 0x1e4000, v144
	v_cvt_pk_bf16_f32 v2, v10, v11
	s_nop 0
	v_addc_co_u32_e32 v7, vcc, 0, v145, vcc
	v_cvt_pk_bf16_f32 v3, v12, v13
	v_cvt_pk_bf16_f32 v4, v4, v5
	v_cvt_pk_bf16_f32 v5, v8, v9
	s_andn2_b64 vcc, exec, s[38:39]
	global_store_dwordx4 v[6:7], v[2:5], off sc1
	s_cbranch_vccnz .LBB0_1454
	s_andn2_b64 vcc, exec, s[6:7]
	s_cbranch_vccnz .LBB0_1453
	s_branch .LBB0_1453

; #define PG8_WAIT_V(n) asm volatile("s_waitcnt vmcnt(" #n ")" ::: "memory")
; #define PG8_BAR __builtin_amdgcn_s_barrier()
; template <class Epi, class Sched, bool ALIGN_EPI = false, bool SP2 = false>
; __device__ __forceinline__ void gemm_phase(PG8_LAS unsigned char* lds, const Gemm g, const Sched& S, const Epi& E) {
;     ...
;     const int tid = tid_l, wid = __builtin_amdgcn_readfirstlane(tid >> 6), lane = tid & 63, wr = wid >> 2, wc = wid & 3, fr = lane & 15, fq = lane >> 4;
;     const int K = g.K;
;     unsigned voffA[2], voffB[2];
; #pragma unroll
;     for (int i = 0; i < 2; ++i) { int R, C; stage_rc(tid * 16 + i * 8192, R, C); const int Rb = Epi::PERM ? ((R & ~31) + perm32(R & 31)) : R;
;         voffA[i] = (unsigned)(R * K + C) * 2u; voffB[i] = (unsigned)(Rb * K + C) * 2u; }
;     const size_t kstep = (size_t)(BK * 2);
;     const size_t hstep = (size_t)HALF * K * 2;
;     const size_t tstep = 2 * hstep;
;     const unsigned ldsw = (unsigned)wid * 1024u;
;     const int aoff = lds_byte(wr * 64 + fr, fq * 8), boff = lds_byte(wc * 32 + fr, fq * 8);
;     ...
;     Unit cur, nxt; int ui = 0;
;     if (!S.next(0, cur)) return;
;     f32x4 acc[2][2][4][2];
; #pragma unroll
;     for (int a = 0; a < 2; ++a)
; #pragma unroll
;         for (int b = 0; b < 2; ++b)
; #pragma unroll
;             for (int m = 0; m < 4; ++m)
; #pragma unroll
;                 for (int n = 0; n < 2; ++n) acc[a][b][m][n] = (f32x4){0.f, 0.f, 0.f, 0.f};
;     bf16x8 At[4][2], B0[2][2], B1[2][2];
;     const char* cA = (const char*)g.A + (size_t)cur.pm * tstep + (size_t)cur.kt0 * kstep; const char* cB = (const char*)g.Bt + (size_t)cur.pn * tstep + (size_t)cur.kt0 * kstep;
;     S.a_ready(cur);
;     ...
;     { const int rot0 = cur.krot, nt0 = cur.nkt; const char* sA0 = PG8_KP(cA, 0, rot0, nt0); const char* sA1 = PG8_KP(cA, 1, rot0, nt0); const char* sB0 = PG8_KP(cB, 0, rot0, nt0); const char* sB1 = PG8_KP(cB, 1, rot0, nt0);
;     if constexpr (SP2) {
;         PG8_STAGEB(PG8_SB(0, 0), sB0, voffB); PG8_STAGEB(PG8_SB(0, 1), sB0 + hstep, voffB); PG8_STAGE(PG8_SA(0, 0), sA0, voffA); PG8_STAGE(PG8_SA(0, 1), sA0 + hstep, voffA);
;         if (wr == 1) PG8_BAR;
;         PG8_WAIT_V(2); PG8_BAR;
;         PG8_STAGEB(PG8_SB(1, 0), sB1, voffB); PG8_STAGE(PG8_SA(1, 0), sA1, voffA); PG8_STAGEB(PG8_SB(1, 1), sB1 + hstep, voffB);
;         PG8_WAIT_V(6); PG8_BAR;
;     } else {
.LBB0_1638:
	v_readlane_b32 s0, v254, 58
	s_mov_b64 s[12:13], s[66:67]
	v_mov_b32_e32 v18, v0
	v_readlane_b32 s1, v254, 59
	s_and_b64 vcc, exec, s[0:1]
	v_readfirstlane_b32 s14, v18
	s_cbranch_vccnz .LBB0_1733
	v_lshlrev_b32_e32 v1, 4, v18
	v_add_u32_e32 v2, 0x2000, v1
	v_ashrrev_i32_e32 v3, 31, v2
	v_lshrrev_b32_e32 v3, 22, v3
	v_add_u32_e32 v3, v2, v3
	v_ashrrev_i32_e32 v10, 10, v3
	v_mul_i32_i24_e32 v3, 0x400, v10
	v_sub_u32_e32 v2, v2, v3
	v_lshrrev_b32_e32 v3, 4, v2
	v_bitop3_b32 v2, v3, v2, 32 bitop3:0x6c
	v_ashrrev_i32_e32 v3, 31, v2
	v_lshrrev_b32_e32 v3, 26, v3
	v_add_u32_e32 v3, v2, v3
	v_lshlrev_b32_e32 v4, 3, v10
	v_ashrrev_i32_e32 v11, 6, v3
	v_and_b32_e32 v4, -16, v4
	v_add_u32_e32 v4, v11, v4
	v_and_b32_e32 v5, 3, v11
	s_mov_b32 s3, 0x7fffe0
	v_lshrrev_b32_e32 v6, 2, v4
	v_lshlrev_b32_e32 v7, 1, v4
	v_and_b32_e32 v3, 0xc0, v3
	v_and_or_b32 v5, v4, s3, v5
	v_and_b32_e32 v6, 4, v6
	v_and_b32_e32 v7, 24, v7
	v_sub_u32_e32 v2, v2, v3
	v_or3_b32 v5, v5, v6, v7
	v_lshlrev_b32_e32 v6, 5, v10
	v_ashrrev_i16_sdwa v2, v207, sext(v2) dst_sel:DWORD dst_unused:UNUSED_PAD src0_sel:DWORD src1_sel:BYTE_0
	v_and_b32_e32 v12, 32, v6
	v_bfe_i32 v13, v2, 0, 16
	s_movk_i32 s2, 0x1600
	v_mul_u32_u24_e32 v5, 0x1600, v5
	v_add_u32_e32 v2, v12, v13
	v_mul_lo_u32 v3, v4, s2
	v_add_lshl_u32 v156, v5, v2, 1
	v_add_lshl_u32 v158, v2, v3, 1
	v_bfe_i32 v2, v18, 27, 1
	v_lshrrev_b32_e32 v2, 22, v2
	v_add_u32_e32 v2, v1, v2
	v_and_b32_e32 v2, 0xfffffc00, v2
	v_sub_u32_e32 v1, v1, v2
	v_lshrrev_b32_e32 v2, 4, v1
	v_ashrrev_i32_e32 v3, 31, v18
	v_bitop3_b32 v1, v2, v1, 32 bitop3:0x6c
	v_lshrrev_b32_e32 v3, 26, v3
	v_readlane_b32 s8, v254, 53
	s_add_u32 s30, s12, 0x2f580000
	v_ashrrev_i32_e32 v2, 31, v1
	v_add_u32_e32 v3, v18, v3
	s_mul_i32 s1, s8, 0x1600000
	s_addc_u32 s31, s13, 0
	v_lshrrev_b32_e32 v2, 26, v2
	v_ashrrev_i32_e32 v15, 6, v3
	s_mul_hi_u32 s0, s8, 0x1600000
	s_add_u32 s1, s12, s1
	v_add_u32_e32 v2, v1, v2
	v_lshlrev_b32_e32 v3, 3, v15
	s_addc_u32 s0, s13, s0
	v_ashrrev_i32_e32 v14, 6, v2
	v_and_b32_e32 v3, -16, v3
	s_add_u32 s33, s1, 0x17000000
	v_add_u32_e32 v3, v14, v3
	v_and_b32_e32 v2, 0xc0, v2
	s_addc_u32 s48, s0, 0
	s_ashr_i32 s0, s14, 6
	v_sub_u32_e32 v1, v1, v2
	v_mul_lo_u32 v2, v3, s2
	v_readlane_b32 s2, v252, 57
	s_ashr_i32 s1, s14, 8
	s_lshl_b32 s49, s0, 10
	v_and_b32_e32 v4, 3, v14
	s_mul_i32 s2, s2, 0x2c0000
	v_and_or_b32 v4, v3, s3, v4
	s_add_u32 s2, s30, s2
	v_readlane_b32 s3, v252, 59
	v_lshrrev_b32_e32 v5, 2, v3
	v_lshlrev_b32_e32 v6, 1, v3
	s_addc_u32 s4, s31, 0
	s_mul_i32 s5, s3, 0x2c0000
	v_and_b32_e32 v5, 4, v5
	v_and_b32_e32 v6, 24, v6
	s_add_u32 s5, s33, s5
	v_or3_b32 v4, v4, v5, v6
	v_lshlrev_b32_e32 v5, 5, v15
	v_ashrrev_i16_sdwa v1, v207, sext(v1) dst_sel:DWORD dst_unused:UNUSED_PAD src0_sel:DWORD src1_sel:BYTE_0
	s_addc_u32 s6, s48, 0
	v_readlane_b32 s3, v252, 43
	v_and_b32_e32 v16, 32, v5
	v_bfe_i32 v17, v1, 0, 16
	s_add_u32 s34, s5, s3
	v_mul_u32_u24_e32 v4, 0x1600, v4
	v_add_u32_e32 v1, v16, v17
	s_addc_u32 s35, s6, 0
	s_add_i32 s50, s49, 0
	v_add_lshl_u32 v160, v4, v1, 1
	s_add_i32 m0, s50, 0x10000
	v_add_lshl_u32 v162, v1, v2, 1
	global_load_lds_dwordx4 v160, s[34:35]
	s_add_i32 m0, s50, 0x12000
	s_add_u32 s38, s2, s3
	s_addc_u32 s39, s4, 0
	s_add_u32 s4, s34, 0x160000
	global_load_lds_dwordx4 v156, s[34:35]
	s_addc_u32 s5, s35, 0
	s_add_i32 m0, s50, 0x14000
	s_add_i32 s51, s50, 0x2000
	global_load_lds_dwordx4 v160, s[4:5]
	s_add_i32 m0, s50, 0x16000
	v_mov_b32_e32 v161, v98
	global_load_lds_dwordx4 v156, s[4:5]
	s_mov_b32 m0, s50
	s_add_u32 s4, s38, 0x160000
	global_load_lds_dwordx4 v162, s[38:39]
	s_mov_b32 m0, s51
	s_addc_u32 s5, s39, 0
	s_add_i32 s52, s50, 0x4000
	global_load_lds_dwordx4 v158, s[38:39]
	s_mov_b32 m0, s52
	s_add_i32 s53, s50, 0x6000
	global_load_lds_dwordx4 v162, s[4:5]
	s_mov_b32 m0, s53
	v_mov_b32_e32 v157, v98
	global_load_lds_dwordx4 v158, s[4:5]
	v_mov_b32_e32 v163, v98
	v_mov_b32_e32 v159, v98
	s_cmp_eq_u32 s1, 1
	v_lshl_add_u64 v[8:9], s[34:35], 0, v[160:161]
	v_lshl_add_u64 v[6:7], s[34:35], 0, v[156:157]
	v_lshl_add_u64 v[2:3], s[38:39], 0, v[162:163]
	s_cselect_b64 s[4:5], -1, 0
	s_cmp_lg_u32 s1, 1
	v_lshl_add_u64 v[4:5], s[38:39], 0, v[158:159]
	v_readlane_b32 s9, v254, 54
	s_cbranch_scc1 .LBB0_1641
.LBB0_1641:
	s_cmp_eq_u32 s8, 3
	s_cselect_b32 s7, s65, 0
	s_cselect_b32 s6, s64, 0
	s_cmp_lg_u64 s[6:7], 0
	s_cselect_b64 s[8:9], -1, 0
	s_add_u32 s10, s12, 0x39880000
	s_addc_u32 s11, s13, 0
	v_readlane_b32 s2, v254, 57
	s_add_u32 s2, s12, s2
	v_readlane_b32 s3, v254, 56
	s_addc_u32 s15, s13, s3
	s_add_u32 s55, s2, 0x10a000
	s_addc_u32 s56, s15, 0
	s_add_u32 s57, s12, 0x35880000
	v_lshrrev_b32_e32 v19, 1, v18
	s_addc_u32 s58, s13, 0
	v_and_b32_e32 v19, 24, v19
	s_lshl_b32 s0, s0, 5
	v_and_b32_e32 v1, 15, v18
	v_lshlrev_b32_e32 v20, 1, v19
	v_lshlrev_b32_e32 v18, 2, v18
	s_and_b32 s2, s0, 0x60
	s_add_i32 m0, s50, 0x18000
	v_lshl_add_u64 v[8:9], v[8:9], 0, s[76:77]
	s_lshl_b32 s59, s1, 6
	v_lshl_or_b32 v20, v1, 6, v20
	s_lshl_b32 s1, s1, 13
	v_and_b32_e32 v18, 32, v18
	s_lshl_b32 s0, s2, 7
	global_load_lds_dwordx4 v[8:9], off
	v_lshl_add_u64 v[6:7], v[6:7], 0, s[76:77]
	s_add_i32 m0, s50, 0x1a000
	s_add_i32 s60, s50, 0x8000
	s_add_i32 s61, s50, 0xa000
	v_bitop3_b32 v99, v20, s0, v18 bitop3:0xde
	global_load_lds_dwordx4 v[6:7], off
	v_lshl_add_u64 v[2:3], v[2:3], 0, s[76:77]
	s_mov_b32 m0, s60
	s_add_u32 s0, s34, 0x160080
	v_bitop3_b32 v21, v20, s1, v18 bitop3:0xde
	global_load_lds_dwordx4 v[2:3], off
	v_lshl_add_u64 v[2:3], v[4:5], 0, s[76:77]
	s_mov_b32 m0, s61
	s_addc_u32 s1, s35, 0
	global_load_lds_dwordx4 v[2:3], off
	s_add_i32 m0, s50, 0x1c000
	v_lshl_add_u64 v[2:3], s[0:1], 0, v[160:161]
	global_load_lds_dwordx4 v[2:3], off
	v_lshl_add_u64 v[2:3], s[0:1], 0, v[156:157]
	s_add_i32 m0, s50, 0x1e000
	v_or_b32_e32 v188, s2, v19
	global_load_lds_dwordx4 v[2:3], off
	s_waitcnt vmcnt(8)
	s_barrier
	s_movk_i32 s2, 0x1600
	v_lshrrev_b32_e32 v3, 1, v10
	v_mul_lo_u32 v2, v11, s2
	s_mov_b32 s3, 0x16000
	v_mad_u64_u32 v[2:3], s[0:1], v3, s3, v[2:3]
	v_or_b32_e32 v2, v2, v12
	v_add_lshl_u32 v164, v2, v13, 1
	v_lshrrev_b32_e32 v3, 1, v15
	v_mul_lo_u32 v2, v14, s2
	s_waitcnt vmcnt(6)
	v_mad_u64_u32 v[2:3], s[0:1], v3, s3, v[2:3]
	s_cmpk_lt_u32 s14, 0x100
	v_or_b32_e32 v2, v2, v16
	v_readlane_b32 s0, v252, 45
	s_mov_b32 s54, 0
	s_cselect_b64 s[12:13], -1, 0
	v_mov_b32_e32 v165, v98
	v_add_lshl_u32 v166, v2, v17, 1
	v_mov_b32_e32 v167, v98
	v_add_u32_e32 v189, 0, v21
	s_mov_b32 s78, s0
	v_readlane_b32 s82, v252, 42
	v_readlane_b32 s75, v252, 59
	v_readlane_b32 s71, v252, 57
	s_mov_b32 s3, 0x20000
	s_mov_b32 s47, 0x30000
	s_mov_b64 s[64:65], 0x40000
	s_mov_b64 s[66:67], 0x10000
	s_barrier
	s_branch .LBB0_1644

; #define PG8_STAGE(bufoff, gbase, voff) do { _Pragma("unroll") for (int _i = 0; _i < 2; ++_i) \
;         __builtin_amdgcn_global_load_lds((const unsigned*)((const char*)(gbase) + (voff)[_i]), (PG8_LAS unsigned*)(lds + (bufoff) + ldsw + _i * 8192), 16, 0, AUX_A); } while (0)
; #define PG8_STAGEB(bufoff, gbase, voff) do { _Pragma("unroll") for (int _i = 0; _i < 2; ++_i) \
;         __builtin_amdgcn_global_load_lds((const unsigned*)((const char*)(gbase) + (voff)[_i]), (PG8_LAS unsigned*)(lds + (bufoff) + ldsw + _i * 8192), 16, 0, AUX_B); } while (0)
; #define PG8_WAIT_V(n) asm volatile("s_waitcnt vmcnt(" #n ")" ::: "memory")
; #define PG8_WAIT_L(n) asm volatile("s_waitcnt lgkmcnt(" #n ")" ::: "memory")
; template <class Epi, class Sched, bool ALIGN_EPI = false, bool SP2 = false>
; __device__ __forceinline__ void gemm_phase(PG8_LAS unsigned char* lds, const Gemm g, const Sched& S, const Epi& E) {
;     ...
;         const char* nA = has_next ? (const char*)g.A + (size_t)nxt.pm * tstep + (size_t)nxt.kt0 * kstep : cA; const char* nB = has_next ? (const char*)g.Bt + (size_t)nxt.pn * tstep + (size_t)nxt.kt0 * kstep : cB;
;         const int nt = cur.nkt, rot = cur.krot;
;         const char* nAr = has_next ? nA + (size_t)nxt.krot * kstep : PG8_KP(cA, 0, rot, nt); const char* nBr = has_next ? nB + (size_t)nxt.krot * kstep : PG8_KP(cB, 0, rot, nt);
;         for (int t = 0; t < nt; t += 2) {
;             const bool last = (t == nt - 2);
;             const char* a1 = PG8_KP(cA, t + 1, rot, nt);
;             const char* a2 = last ? nAr : PG8_KP(cA, t + 2, rot, nt); const char* b2 = last ? nBr : PG8_KP(cB, t + 2, rot, nt);
;             const char* a3 = a2 + kstep; const char* b3 = b2 + kstep;
;             if (last && has_next) S.a_ready(nxt);
;             if constexpr (SP2) {
;             PG8_LDB(B0, 0, 0); PG8_LDB(B1, 0, 1); PG8_SCHED; PG8_LDA(At, 0, 0); PG8_STAGE(PG8_SA(1, 1), a1 + hstep, voffA);
;             PG8_WAIT_V(8); PG8_WAIT_L(0); PG8_BAR; PG8_MMA(0, 0, At, B0); PG8_MMA(0, 1, At, B1); PG8_BAR; PG8_SCHED;
;             PG8_LDA(At, 0, 1); PG8_STAGEB(PG8_SB(0, 0), b2, voffB); PG8_STAGEB(PG8_SB(0, 1), b2 + hstep, voffB); PG8_STAGE(PG8_SA(0, 0), a2, voffA);
;             PG8_WAIT_V(8); PG8_WAIT_L(0); PG8_BAR; PG8_MMA(1, 0, At, B0); PG8_MMA(1, 1, At, B1); PG8_BAR; PG8_SCHED;
;     ...
;         if constexpr (ALIGN_EPI) { if (wr == 1) PG8_BAR; }
.LBB0_1653:
	s_add_u32 s0, s38, 0x160080
	s_addc_u32 s1, s39, 0
	s_waitcnt vmcnt(0)
	v_lshl_add_u64 v[132:133], s[0:1], 0, v[164:165]
	v_lshl_add_u64 v[134:135], s[0:1], 0, v[166:167]
	s_mov_b32 s15, 0
	s_mov_b32 s83, 2
	s_waitcnt lgkmcnt(0)
	s_cmp_lg_u64 s[12:13], 0
	s_cbranch_scc1 .Lrp_1654
	s_barrier
.Lrp_1654:
.Lpk_1654:
	s_or_b32 s0, s15, 1
	s_cmp_ge_i32 s0, s82
	s_cselect_b32 s2, s82, 0
	s_add_i32 s15, s15, 2
	s_cmp_ge_i32 s15, s82
	s_cselect_b32 s0, s82, 0
	s_sub_i32 s0, s83, s0
	s_ashr_i32 s1, s0, 31
	s_lshl_b64 s[0:1], s[0:1], 7
	s_add_u32 s29, s38, s0
	s_addc_u32 s42, s39, s1
	s_add_u32 s0, s34, s0
	s_addc_u32 s1, s35, s1
	s_cmp_eq_u32 s82, s83
	s_cselect_b32 s45, s41, s42
	s_cselect_b32 s44, s40, s29
	s_cselect_b32 s43, s19, s1
	s_cselect_b32 s42, s18, s0
	s_add_i32 s29, 0, 0x10000
	s_add_i32 s46, 0, 0x14000
	v_add_u32_e32 v148, s29, v99
	v_add_u32_e32 v168, s46, v99
	ds_read_b128 v[136:139], v148
	ds_read_b128 v[140:143], v148 offset:1024
	ds_read_b128 v[144:147], v148 offset:2048
	ds_read_b128 v[148:151], v148 offset:3072
	ds_read_b128 v[152:155], v168
	ds_read_b128 v[180:183], v168 offset:1024
	ds_read_b128 v[184:187], v168 offset:2048
	ds_read_b128 v[190:193], v168 offset:3072
	v_mad_i64_i32 v[168:169], s[0:1], s2, v220, v[134:135]
	s_add_i32 m0, s50, 0xc000
	ds_read_b128 v[194:197], v189
	ds_read_b128 v[198:201], v189 offset:1024
	ds_read_b128 v[222:225], v189 offset:2048
	ds_read_b128 v[226:229], v189 offset:3072
	ds_read_b128 v[230:233], v189 offset:4096
	ds_read_b128 v[234:237], v189 offset:5120
	ds_read_b128 v[238:241], v189 offset:6144
	ds_read_b128 v[242:245], v189 offset:7168
	global_load_lds_dwordx4 v[168:169], off
	v_mad_i64_i32 v[168:169], s[0:1], s2, v220, v[132:133]
	s_add_i32 m0, s50, 0xe000
	s_nop 0
	global_load_lds_dwordx4 v[168:169], off
	s_waitcnt vmcnt(8)
	s_waitcnt lgkmcnt(0)
	s_setprio 1
	s_barrier
	v_mfma_f32_16x16x32_bf16 v[128:131], v[136:139], v[194:197], 0
	v_mfma_f32_16x16x32_bf16 v[128:131], v[140:143], v[198:201], v[128:131]
	v_mfma_f32_16x16x32_bf16 v[124:127], v[144:147], v[194:197], 0
	v_mfma_f32_16x16x32_bf16 v[124:127], v[148:151], v[198:201], v[124:127]
	v_mfma_f32_16x16x32_bf16 v[120:123], v[136:139], v[222:225], 0
	v_mfma_f32_16x16x32_bf16 v[120:123], v[140:143], v[226:229], v[120:123]
	v_mfma_f32_16x16x32_bf16 v[112:115], v[144:147], v[222:225], 0
	v_mfma_f32_16x16x32_bf16 v[112:115], v[148:151], v[226:229], v[112:115]
	v_mfma_f32_16x16x32_bf16 v[104:107], v[136:139], v[230:233], 0
	v_mfma_f32_16x16x32_bf16 v[104:107], v[140:143], v[234:237], v[104:107]
	v_mfma_f32_16x16x32_bf16 v[94:97], v[144:147], v[230:233], 0
	v_mfma_f32_16x16x32_bf16 v[94:97], v[148:151], v[234:237], v[94:97]
	v_mfma_f32_16x16x32_bf16 v[86:89], v[136:139], v[238:241], 0
	v_mfma_f32_16x16x32_bf16 v[86:89], v[140:143], v[242:245], v[86:89]
	v_mfma_f32_16x16x32_bf16 v[78:81], v[144:147], v[238:241], 0
	v_mfma_f32_16x16x32_bf16 v[78:81], v[148:151], v[242:245], v[78:81]
	s_setprio 0
	s_setprio 1
	v_mfma_f32_16x16x32_bf16 v[116:119], v[152:155], v[194:197], 0
	v_mfma_f32_16x16x32_bf16 v[116:119], v[180:183], v[198:201], v[116:119]
	v_mfma_f32_16x16x32_bf16 v[108:111], v[184:187], v[194:197], 0
	v_mfma_f32_16x16x32_bf16 v[108:111], v[190:193], v[198:201], v[108:111]
	v_mfma_f32_16x16x32_bf16 v[100:103], v[152:155], v[222:225], 0
	v_mfma_f32_16x16x32_bf16 v[100:103], v[180:183], v[226:229], v[100:103]
	v_mfma_f32_16x16x32_bf16 v[90:93], v[184:187], v[222:225], 0
	v_mfma_f32_16x16x32_bf16 v[90:93], v[190:193], v[226:229], v[90:93]
	v_mfma_f32_16x16x32_bf16 v[82:85], v[152:155], v[230:233], 0
	v_mfma_f32_16x16x32_bf16 v[82:85], v[180:183], v[234:237], v[82:85]
	v_mfma_f32_16x16x32_bf16 v[74:77], v[184:187], v[230:233], 0
	v_mfma_f32_16x16x32_bf16 v[74:77], v[190:193], v[234:237], v[74:77]
	v_mfma_f32_16x16x32_bf16 v[70:73], v[152:155], v[238:241], 0
	v_mfma_f32_16x16x32_bf16 v[70:73], v[180:183], v[242:245], v[70:73]
	s_setprio 2
	s_barrier
	v_mfma_f32_16x16x32_bf16 v[66:69], v[184:187], v[238:241], 0
	v_mfma_f32_16x16x32_bf16 v[66:69], v[190:193], v[242:245], v[66:69]
	s_setprio 0
	s_add_i32 s0, s29, s49
	v_lshl_add_u64 v[168:169], s[42:43], 0, v[160:161]
	s_mov_b32 m0, s0
	ds_read_b128 v[194:197], v189 offset:16384
	ds_read_b128 v[198:201], v189 offset:17408
	ds_read_b128 v[222:225], v189 offset:18432
	ds_read_b128 v[226:229], v189 offset:19456
	ds_read_b128 v[230:233], v189 offset:20480
	ds_read_b128 v[234:237], v189 offset:21504
	ds_read_b128 v[238:241], v189 offset:22528
	ds_read_b128 v[242:245], v189 offset:23552
	global_load_lds_dwordx4 v[168:169], off
	s_add_i32 m0, s0, 0x2000
	s_add_u32 s0, s42, 0x160000
	v_lshl_add_u64 v[172:173], s[42:43], 0, v[156:157]
	s_addc_u32 s1, s43, 0
	s_add_i32 s2, s46, s49
	global_load_lds_dwordx4 v[172:173], off
	v_lshl_add_u64 v[202:203], s[0:1], 0, v[160:161]
	s_mov_b32 m0, s2
	v_lshl_add_u64 v[212:213], s[44:45], 0, v[158:159]
	global_load_lds_dwordx4 v[202:203], off
	v_lshl_add_u64 v[202:203], s[0:1], 0, v[156:157]
	s_add_i32 m0, s2, 0x2000
	s_nop 0
	global_load_lds_dwordx4 v[202:203], off
	v_lshl_add_u64 v[202:203], s[44:45], 0, v[162:163]
	s_mov_b32 m0, s50
	s_nop 0
	global_load_lds_dwordx4 v[202:203], off
	s_mov_b32 m0, s51
	s_nop 0
	global_load_lds_dwordx4 v[212:213], off
	s_waitcnt vmcnt(8)
	s_waitcnt lgkmcnt(0)
	s_setprio 1
	s_barrier
; #define PG8_STAGE(bufoff, gbase, voff) do { _Pragma("unroll") for (int _i = 0; _i < 2; ++_i) \
;         __builtin_amdgcn_global_load_lds((const unsigned*)((const char*)(gbase) + (voff)[_i]), (PG8_LAS unsigned*)(lds + (bufoff) + ldsw + _i * 8192), 16, 0, AUX_A); } while (0)
; #define PG8_LDA(dst, b, h) do { _Pragma("unroll") for (int m = 0; m < 4; ++m) _Pragma("unroll") for (int k = 0; k < 2; ++k) dst[m][k] = *(const PG8_LAS bf16x8*)(lds + PG8_SA(b, h) + aoff + m * 2048 + k * 1024); } while (0)
; #define PG8_LDB(dst, b, h) do { _Pragma("unroll") for (int n = 0; n < 2; ++n) _Pragma("unroll") for (int k = 0; k < 2; ++k) dst[n][k] = *(const PG8_LAS bf16x8*)(lds + PG8_SB(b, h) + boff + n * 2048 + k * 1024); } while (0)
; #define PG8_MMA(ai, bj, At, Bt) do { __builtin_amdgcn_s_setprio(1); _Pragma("unroll") for (int m = 0; m < 4; ++m) _Pragma("unroll") for (int n = 0; n < 2; ++n) _Pragma("unroll") for (int k = 0; k < 2; ++k) \
;         acc[ai][bj][m][n] = __builtin_amdgcn_mfma_f32_16x16x32_bf16(Bt[n][k], At[m][k], acc[ai][bj][m][n], 0, 0, 0); __builtin_amdgcn_s_setprio(0); } while (0)
; #define PG8_WAIT_V(n) asm volatile("s_waitcnt vmcnt(" #n ")" ::: "memory")
; #define PG8_WAIT_L(n) asm volatile("s_waitcnt lgkmcnt(" #n ")" ::: "memory")
; #define PG8_BAR __builtin_amdgcn_s_barrier()
; #define PG8_SCHED __builtin_amdgcn_sched_barrier(0)
; template <class Epi, class Sched, bool ALIGN_EPI = false, bool SP2 = false>
; __device__ __forceinline__ void gemm_phase(PG8_LAS unsigned char* lds, const Gemm g, const Sched& S, const Epi& E) {
;     ...
;             PG8_WAIT_V(8); PG8_WAIT_L(0); PG8_BAR; PG8_MMA(1, 0, At, B0); PG8_MMA(1, 1, At, B1); PG8_BAR; PG8_SCHED;
;             PG8_LDB(B0, 1, 0); PG8_LDB(B1, 1, 1); PG8_SCHED; PG8_LDA(At, 1, 0); PG8_STAGE(PG8_SA(0, 1), a2 + hstep, voffA);
;             PG8_WAIT_V(8); PG8_WAIT_L(0); PG8_BAR; PG8_MMA(0, 0, At, B0); PG8_MMA(0, 1, At, B1); PG8_BAR; PG8_SCHED;
	v_mfma_f32_16x16x32_bf16 v[62:65], v[136:139], v[194:197], 0
	v_mfma_f32_16x16x32_bf16 v[62:65], v[140:143], v[198:201], v[62:65]
	v_mfma_f32_16x16x32_bf16 v[58:61], v[144:147], v[194:197], 0
	v_mfma_f32_16x16x32_bf16 v[58:61], v[148:151], v[198:201], v[58:61]
	v_mfma_f32_16x16x32_bf16 v[54:57], v[136:139], v[222:225], 0
	v_mfma_f32_16x16x32_bf16 v[54:57], v[140:143], v[226:229], v[54:57]
	v_mfma_f32_16x16x32_bf16 v[46:49], v[144:147], v[222:225], 0
	v_mfma_f32_16x16x32_bf16 v[46:49], v[148:151], v[226:229], v[46:49]
	v_mfma_f32_16x16x32_bf16 v[38:41], v[136:139], v[230:233], 0
	v_mfma_f32_16x16x32_bf16 v[38:41], v[140:143], v[234:237], v[38:41]
	v_mfma_f32_16x16x32_bf16 v[30:33], v[144:147], v[230:233], 0
	v_mfma_f32_16x16x32_bf16 v[30:33], v[148:151], v[234:237], v[30:33]
	v_mfma_f32_16x16x32_bf16 v[22:25], v[136:139], v[238:241], 0
	v_mfma_f32_16x16x32_bf16 v[22:25], v[140:143], v[242:245], v[22:25]
	v_mfma_f32_16x16x32_bf16 v[14:17], v[144:147], v[238:241], 0
	v_mfma_f32_16x16x32_bf16 v[14:17], v[148:151], v[242:245], v[14:17]
	s_setprio 0
	s_setprio 1
	v_mfma_f32_16x16x32_bf16 v[50:53], v[152:155], v[194:197], 0
	v_mfma_f32_16x16x32_bf16 v[50:53], v[180:183], v[198:201], v[50:53]
	v_mfma_f32_16x16x32_bf16 v[42:45], v[184:187], v[194:197], 0
	v_mfma_f32_16x16x32_bf16 v[42:45], v[190:193], v[198:201], v[42:45]
	v_mfma_f32_16x16x32_bf16 v[34:37], v[152:155], v[222:225], 0
	v_mfma_f32_16x16x32_bf16 v[34:37], v[180:183], v[226:229], v[34:37]
	v_mfma_f32_16x16x32_bf16 v[26:29], v[184:187], v[222:225], 0
	v_mfma_f32_16x16x32_bf16 v[26:29], v[190:193], v[226:229], v[26:29]
	v_mfma_f32_16x16x32_bf16 v[18:21], v[152:155], v[230:233], 0
	v_mfma_f32_16x16x32_bf16 v[18:21], v[180:183], v[234:237], v[18:21]
	v_mfma_f32_16x16x32_bf16 v[10:13], v[184:187], v[230:233], 0
	v_mfma_f32_16x16x32_bf16 v[10:13], v[190:193], v[234:237], v[10:13]
	v_mfma_f32_16x16x32_bf16 v[6:9], v[152:155], v[238:241], 0
	v_mfma_f32_16x16x32_bf16 v[6:9], v[180:183], v[242:245], v[6:9]
	s_setprio 2
	s_barrier
	v_mfma_f32_16x16x32_bf16 v[2:5], v[184:187], v[238:241], 0
	v_mfma_f32_16x16x32_bf16 v[2:5], v[190:193], v[242:245], v[2:5]
	s_setprio 0
	s_add_i32 s2, 0, 0x18000
	s_add_i32 s29, 0, 0x1c000
	v_add_u32_e32 v148, s2, v99
	v_add_u32_e32 v190, s29, v99
	ds_read_b128 v[136:139], v148
	ds_read_b128 v[140:143], v148 offset:1024
	ds_read_b128 v[144:147], v148 offset:2048
	ds_read_b128 v[148:151], v148 offset:3072
	ds_read_b128 v[152:155], v190
	ds_read_b128 v[180:183], v190 offset:1024
	ds_read_b128 v[184:187], v190 offset:2048
	ds_read_b128 v[190:193], v190 offset:3072
	s_add_u32 s0, s44, 0x160000
	s_addc_u32 s1, s45, 0
	s_mov_b32 m0, s52
	v_lshl_add_u64 v[246:247], s[0:1], 0, v[162:163]
	ds_read_b128 v[194:197], v189 offset:32768
	ds_read_b128 v[198:201], v189 offset:33792
	ds_read_b128 v[222:225], v189 offset:34816
	ds_read_b128 v[226:229], v189 offset:35840
	ds_read_b128 v[230:233], v189 offset:36864
	ds_read_b128 v[234:237], v189 offset:37888
	ds_read_b128 v[238:241], v189 offset:38912
	ds_read_b128 v[242:245], v189 offset:39936
	global_load_lds_dwordx4 v[246:247], off
	v_lshl_add_u64 v[246:247], s[0:1], 0, v[158:159]
	s_mov_b32 m0, s53
	s_nop 0
	global_load_lds_dwordx4 v[246:247], off
	s_waitcnt vmcnt(8)
	s_waitcnt lgkmcnt(0)
	s_setprio 1
	s_barrier
	v_mfma_f32_16x16x32_bf16 v[128:131], v[136:139], v[194:197], v[128:131]
	v_mfma_f32_16x16x32_bf16 v[128:131], v[140:143], v[198:201], v[128:131]
	v_mfma_f32_16x16x32_bf16 v[124:127], v[144:147], v[194:197], v[124:127]
	v_mfma_f32_16x16x32_bf16 v[124:127], v[148:151], v[198:201], v[124:127]
	v_mfma_f32_16x16x32_bf16 v[120:123], v[136:139], v[222:225], v[120:123]
	v_mfma_f32_16x16x32_bf16 v[120:123], v[140:143], v[226:229], v[120:123]
	v_mfma_f32_16x16x32_bf16 v[112:115], v[144:147], v[222:225], v[112:115]
	v_mfma_f32_16x16x32_bf16 v[112:115], v[148:151], v[226:229], v[112:115]
	v_mfma_f32_16x16x32_bf16 v[104:107], v[136:139], v[230:233], v[104:107]
	v_mfma_f32_16x16x32_bf16 v[104:107], v[140:143], v[234:237], v[104:107]
	v_mfma_f32_16x16x32_bf16 v[94:97], v[144:147], v[230:233], v[94:97]
	v_mfma_f32_16x16x32_bf16 v[94:97], v[148:151], v[234:237], v[94:97]
	v_mfma_f32_16x16x32_bf16 v[86:89], v[136:139], v[238:241], v[86:89]
	v_mfma_f32_16x16x32_bf16 v[86:89], v[140:143], v[242:245], v[86:89]
	v_mfma_f32_16x16x32_bf16 v[78:81], v[144:147], v[238:241], v[78:81]
	v_mfma_f32_16x16x32_bf16 v[78:81], v[148:151], v[242:245], v[78:81]
	s_setprio 0
	s_setprio 1
	v_mfma_f32_16x16x32_bf16 v[116:119], v[152:155], v[194:197], v[116:119]
	v_mfma_f32_16x16x32_bf16 v[116:119], v[180:183], v[198:201], v[116:119]
	v_mfma_f32_16x16x32_bf16 v[108:111], v[184:187], v[194:197], v[108:111]
	v_mfma_f32_16x16x32_bf16 v[108:111], v[190:193], v[198:201], v[108:111]
	v_mfma_f32_16x16x32_bf16 v[100:103], v[152:155], v[222:225], v[100:103]
	v_mfma_f32_16x16x32_bf16 v[100:103], v[180:183], v[226:229], v[100:103]
	v_mfma_f32_16x16x32_bf16 v[90:93], v[184:187], v[222:225], v[90:93]
	v_mfma_f32_16x16x32_bf16 v[90:93], v[190:193], v[226:229], v[90:93]
	v_mfma_f32_16x16x32_bf16 v[82:85], v[152:155], v[230:233], v[82:85]
	v_mfma_f32_16x16x32_bf16 v[82:85], v[180:183], v[234:237], v[82:85]
	v_mfma_f32_16x16x32_bf16 v[74:77], v[184:187], v[230:233], v[74:77]
	v_mfma_f32_16x16x32_bf16 v[74:77], v[190:193], v[234:237], v[74:77]
	v_mfma_f32_16x16x32_bf16 v[70:73], v[152:155], v[238:241], v[70:73]
	v_mfma_f32_16x16x32_bf16 v[70:73], v[180:183], v[242:245], v[70:73]
	s_setprio 2
	s_barrier
; #define PG8_STAGE(bufoff, gbase, voff) do { _Pragma("unroll") for (int _i = 0; _i < 2; ++_i) \
;         __builtin_amdgcn_global_load_lds((const unsigned*)((const char*)(gbase) + (voff)[_i]), (PG8_LAS unsigned*)(lds + (bufoff) + ldsw + _i * 8192), 16, 0, AUX_A); } while (0)
; #define PG8_STAGEB(bufoff, gbase, voff) do { _Pragma("unroll") for (int _i = 0; _i < 2; ++_i) \
;         __builtin_amdgcn_global_load_lds((const unsigned*)((const char*)(gbase) + (voff)[_i]), (PG8_LAS unsigned*)(lds + (bufoff) + ldsw + _i * 8192), 16, 0, AUX_B); } while (0)
; #define PG8_LDA(dst, b, h) do { _Pragma("unroll") for (int m = 0; m < 4; ++m) _Pragma("unroll") for (int k = 0; k < 2; ++k) dst[m][k] = *(const PG8_LAS bf16x8*)(lds + PG8_SA(b, h) + aoff + m * 2048 + k * 1024); } while (0)
; #define PG8_MMA(ai, bj, At, Bt) do { __builtin_amdgcn_s_setprio(1); _Pragma("unroll") for (int m = 0; m < 4; ++m) _Pragma("unroll") for (int n = 0; n < 2; ++n) _Pragma("unroll") for (int k = 0; k < 2; ++k) \
;         acc[ai][bj][m][n] = __builtin_amdgcn_mfma_f32_16x16x32_bf16(Bt[n][k], At[m][k], acc[ai][bj][m][n], 0, 0, 0); __builtin_amdgcn_s_setprio(0); } while (0)
; #define PG8_WAIT_V(n) asm volatile("s_waitcnt vmcnt(" #n ")" ::: "memory")
; #define PG8_WAIT_L(n) asm volatile("s_waitcnt lgkmcnt(" #n ")" ::: "memory")
; #define PG8_BAR __builtin_amdgcn_s_barrier()
; #define PG8_SCHED __builtin_amdgcn_sched_barrier(0)
; template <class Epi, class Sched, bool ALIGN_EPI = false, bool SP2 = false>
; __device__ __forceinline__ void gemm_phase(PG8_LAS unsigned char* lds, const Gemm g, const Sched& S, const Epi& E) {
;     ...
;         for (int t = 0; t < nt; t += 2) {
;     ...
;             PG8_LDA(At, 1, 1); PG8_STAGEB(PG8_SB(1, 0), b3, voffB); PG8_STAGEB(PG8_SB(1, 1), b3 + hstep, voffB); PG8_STAGE(PG8_SA(1, 0), a3, voffA);
;             PG8_WAIT_V(8); PG8_WAIT_L(0); PG8_BAR; PG8_MMA(1, 0, At, B0); PG8_MMA(1, 1, At, B1); PG8_BAR; PG8_SCHED;
	v_mfma_f32_16x16x32_bf16 v[66:69], v[184:187], v[238:241], v[66:69]
	v_mfma_f32_16x16x32_bf16 v[66:69], v[190:193], v[242:245], v[66:69]
	s_setprio 0
	s_add_i32 s0, s2, s49
	v_lshl_add_u64 v[168:169], v[168:169], 0, s[76:77]
	s_mov_b32 m0, s0
	ds_read_b128 v[194:197], v189 offset:49152
	ds_read_b128 v[198:201], v189 offset:50176
	ds_read_b128 v[222:225], v189 offset:51200
	ds_read_b128 v[226:229], v189 offset:52224
	ds_read_b128 v[230:233], v189 offset:53248
	ds_read_b128 v[234:237], v189 offset:54272
	ds_read_b128 v[238:241], v189 offset:55296
	ds_read_b128 v[242:245], v189 offset:56320
	global_load_lds_dwordx4 v[168:169], off
	s_add_i32 m0, s0, 0x2000
	s_add_u32 s0, s42, 0x160080
	v_lshl_add_u64 v[168:169], v[172:173], 0, s[76:77]
	s_addc_u32 s1, s43, 0
	s_add_i32 s2, s29, s49
	global_load_lds_dwordx4 v[168:169], off
	v_lshl_add_u64 v[168:169], s[0:1], 0, v[160:161]
	s_mov_b32 m0, s2
	s_nop 0
	global_load_lds_dwordx4 v[168:169], off
	v_lshl_add_u64 v[168:169], s[0:1], 0, v[156:157]
	s_add_i32 m0, s2, 0x2000
	s_nop 0
	global_load_lds_dwordx4 v[168:169], off
	v_lshl_add_u64 v[168:169], v[202:203], 0, s[76:77]
	s_mov_b32 m0, s60
	s_nop 0
	global_load_lds_dwordx4 v[168:169], off
	v_lshl_add_u64 v[168:169], v[212:213], 0, s[76:77]
	s_mov_b32 m0, s61
	s_nop 0
	global_load_lds_dwordx4 v[168:169], off
	s_waitcnt vmcnt(8)
	s_waitcnt lgkmcnt(0)
	s_setprio 1
	s_barrier
	v_mfma_f32_16x16x32_bf16 v[62:65], v[136:139], v[194:197], v[62:65]
	v_mfma_f32_16x16x32_bf16 v[62:65], v[140:143], v[198:201], v[62:65]
	v_mfma_f32_16x16x32_bf16 v[58:61], v[144:147], v[194:197], v[58:61]
	v_mfma_f32_16x16x32_bf16 v[58:61], v[148:151], v[198:201], v[58:61]
	v_mfma_f32_16x16x32_bf16 v[54:57], v[136:139], v[222:225], v[54:57]
	v_mfma_f32_16x16x32_bf16 v[54:57], v[140:143], v[226:229], v[54:57]
	v_mfma_f32_16x16x32_bf16 v[46:49], v[144:147], v[222:225], v[46:49]
	v_mfma_f32_16x16x32_bf16 v[46:49], v[148:151], v[226:229], v[46:49]
	v_mfma_f32_16x16x32_bf16 v[38:41], v[136:139], v[230:233], v[38:41]
	v_mfma_f32_16x16x32_bf16 v[38:41], v[140:143], v[234:237], v[38:41]
	v_mfma_f32_16x16x32_bf16 v[30:33], v[144:147], v[230:233], v[30:33]
	v_mfma_f32_16x16x32_bf16 v[30:33], v[148:151], v[234:237], v[30:33]
	v_mfma_f32_16x16x32_bf16 v[22:25], v[136:139], v[238:241], v[22:25]
	v_mfma_f32_16x16x32_bf16 v[22:25], v[140:143], v[242:245], v[22:25]
	v_mfma_f32_16x16x32_bf16 v[14:17], v[144:147], v[238:241], v[14:17]
	v_mfma_f32_16x16x32_bf16 v[14:17], v[148:151], v[242:245], v[14:17]
	s_setprio 0
	s_setprio 1
	v_mfma_f32_16x16x32_bf16 v[50:53], v[152:155], v[194:197], v[50:53]
	v_mfma_f32_16x16x32_bf16 v[50:53], v[180:183], v[198:201], v[50:53]
	v_mfma_f32_16x16x32_bf16 v[42:45], v[184:187], v[194:197], v[42:45]
	v_mfma_f32_16x16x32_bf16 v[42:45], v[190:193], v[198:201], v[42:45]
	v_mfma_f32_16x16x32_bf16 v[34:37], v[152:155], v[222:225], v[34:37]
	v_mfma_f32_16x16x32_bf16 v[34:37], v[180:183], v[226:229], v[34:37]
	v_mfma_f32_16x16x32_bf16 v[26:29], v[184:187], v[222:225], v[26:29]
	v_mfma_f32_16x16x32_bf16 v[26:29], v[190:193], v[226:229], v[26:29]
	v_mfma_f32_16x16x32_bf16 v[18:21], v[152:155], v[230:233], v[18:21]
	v_mfma_f32_16x16x32_bf16 v[18:21], v[180:183], v[234:237], v[18:21]
	v_mfma_f32_16x16x32_bf16 v[10:13], v[184:187], v[230:233], v[10:13]
	v_mfma_f32_16x16x32_bf16 v[10:13], v[190:193], v[234:237], v[10:13]
	v_mfma_f32_16x16x32_bf16 v[6:9], v[152:155], v[238:241], v[6:9]
	v_mfma_f32_16x16x32_bf16 v[6:9], v[180:183], v[242:245], v[6:9]
	s_setprio 2
	s_barrier
	v_mfma_f32_16x16x32_bf16 v[2:5], v[184:187], v[238:241], v[2:5]
	v_mfma_f32_16x16x32_bf16 v[2:5], v[190:193], v[242:245], v[2:5]
	s_setprio 0
	s_add_i32 s0, s83, 2
	v_lshl_add_u64 v[132:133], v[132:133], 0, s[86:87]
	v_lshl_add_u64 v[134:135], v[134:135], 0, s[86:87]
	s_cmp_ge_i32 s83, s82
	s_mov_b32 s83, s0
	s_cbranch_scc1 .Lpx_1654
